# stack5 + EpiRes row-stat atomics merged: sum and sumsq added by one atomic instruction (lanes 0-15 / 16-31)
# speedup vs baseline: 1.0090x; 1.0004x over previous
; DEVI unsigned pk2(float lo, float hi) { unsigned r; asm("v_cvt_pk_bf16_f32 %0, %1, %2" : "=v"(r) : "v"(lo), "v"(hi)); return r; }
;     DEVI void operator()(const f32x4 (&acc)[2][2][4][2], const pg8::Unit& u, int wr, int wc, int fr, int fq) const {
;     ...
;                         f32x4 zz = ALPHA * xv + acc[ai][bj][m][n];
;                         if (bias) zz += *(const f32x4*)(bias + col);
;                         *(f32x4*)(zdst + (size_t)row * DM + col) = zz;
;                         sum += zz[0] + zz[1] + zz[2] + zz[3]; sq += zz[0] * zz[0] + zz[1] * zz[1] + zz[2] * zz[2] + zz[3] * zz[3];
;                         z[n] = zz;
;                     }
;                     u32x4 o; o.x = pk2(z[0][0], z[0][1]); o.y = pk2(z[0][2], z[0][3]); o.z = pk2(z[1][0], z[1][1]); o.w = pk2(z[1][2], z[1][3]);
;                     if (zb) *(u32x4*)(zb + (size_t)row * DM + colb + bj * 128) = o;
;                 }
;                 sum += __shfl_xor(sum, 16); sq += __shfl_xor(sq, 16);
;                 sum += __shfl_xor(sum, 32); sq += __shfl_xor(sq, 32);
;                 if (fq == 0) { atomicAdd(stout + 2 * (size_t)row, sum); atomicAdd(stout + 2 * (size_t)row + 1, sq); }
.LBB0_515:
	v_add_f32_e32 v154, v124, v125
	v_mul_f32_e32 v125, v125, v125
	v_fmac_f32_e32 v125, v124, v124
	v_add_f32_e32 v124, v120, v121
	v_mul_f32_e32 v121, v121, v121
	v_fmac_f32_e32 v121, v120, v120
	v_add_f32_e32 v124, v122, v124
	v_fmac_f32_e32 v121, v122, v122
	v_mul_f32_e32 v122, v117, v117
	v_fmac_f32_e32 v125, v126, v126
	v_fmac_f32_e32 v122, v116, v116
	v_add_f32_e32 v154, v126, v154
	v_fmac_f32_e32 v125, v127, v127
	v_fmac_f32_e32 v121, v123, v123
	v_fmac_f32_e32 v122, v118, v118
	v_add_f32_e32 v154, v127, v154
	v_add_f32_e32 v120, v125, v121
	v_add_f32_e32 v121, v116, v117
	v_fmac_f32_e32 v122, v119, v119
	v_add_f32_e32 v154, 0, v154
	v_add_f32_e32 v124, v123, v124
	v_add_f32_e32 v121, v118, v121
	v_add_f32_e32 v120, v120, v122
	v_add_f32_e32 v122, v112, v113
	v_add_f32_e32 v124, v154, v124
	v_add_f32_e32 v121, v119, v121
	v_add_f32_e32 v122, v114, v122
	v_add_f32_e32 v121, v124, v121
	v_add_f32_e32 v122, v115, v122
	v_add_f32_e32 v121, v121, v122
	v_mul_f32_e32 v122, v113, v113
	v_fmac_f32_e32 v122, v112, v112
	v_fmac_f32_e32 v122, v114, v114
	v_fmac_f32_e32 v122, v115, v115
	v_and_b32_e32 v123, 64, v162
	v_add_f32_e32 v122, v120, v122
	v_xor_b32_e32 v120, 16, v162
	v_add_u32_e32 v123, 64, v123
	v_cmp_lt_i32_e32 vcc, v120, v123
	v_cvt_pk_bf16_f32 v124, v116, v117
	global_store_dwordx4 v[150:151], v[112:115], off offset:528
	v_cvt_pk_bf16_f32 v127, v114, v115
	s_nop 0
	v_cndmask_b32_e32 v120, v162, v120, vcc
	v_lshlrev_b32_e32 v120, 2, v120
	ds_bpermute_b32 v125, v120, v121
	ds_bpermute_b32 v126, v120, v122
	s_waitcnt lgkmcnt(0)
	v_add_f32_e32 v116, v121, v125
	v_xor_b32_e32 v121, 32, v162
	v_cmp_lt_i32_e32 vcc, v121, v123
	v_add_f32_e32 v117, v122, v126
	v_cvt_pk_bf16_f32 v125, v118, v119
	v_cvt_pk_bf16_f32 v126, v112, v113
	flat_store_dwordx4 v[152:153], v[124:127] offset:256
	v_cndmask_b32_e32 v121, v162, v121, vcc
	v_lshlrev_b32_e32 v121, 2, v121
	ds_bpermute_b32 v122, v121, v116
	ds_bpermute_b32 v123, v121, v117
	s_mov_b32 s100, -1
	s_mov_b32 s101, 0
	s_mov_b32 s98, 0xffff0000
	s_mov_b32 s99, 0
	s_and_saveexec_b64 s[28:29], s[100:101]
	s_cbranch_execz .LBB0_517
	s_waitcnt lgkmcnt(0)
	v_add_f32_e32 v115, v116, v122
	v_lshl_add_u64 v[112:113], v[148:149], 3, s[6:7]
	v_add_f32_e32 v114, v117, v123
	v_cndmask_b32_e64 v115, v115, v114, s[98:99]
	v_cndmask_b32_e64 v114, 0, 4, s[98:99]
	v_or_b32_e32 v112, v112, v114
	flat_atomic_add_f32 v[112:113], v115

; DEVI unsigned pk2(float lo, float hi) { unsigned r; asm("v_cvt_pk_bf16_f32 %0, %1, %2" : "=v"(r) : "v"(lo), "v"(hi)); return r; }
;     DEVI void operator()(const f32x4 (&acc)[2][2][4][2], const pg8::Unit& u, int wr, int wc, int fr, int fq) const {
;     ...
;                         f32x4 zz = ALPHA * xv + acc[ai][bj][m][n];
;                         if (bias) zz += *(const f32x4*)(bias + col);
;                         *(f32x4*)(zdst + (size_t)row * DM + col) = zz;
;                         sum += zz[0] + zz[1] + zz[2] + zz[3]; sq += zz[0] * zz[0] + zz[1] * zz[1] + zz[2] * zz[2] + zz[3] * zz[3];
;                         z[n] = zz;
;                     }
;                     u32x4 o; o.x = pk2(z[0][0], z[0][1]); o.y = pk2(z[0][2], z[0][3]); o.z = pk2(z[1][0], z[1][1]); o.w = pk2(z[1][2], z[1][3]);
;                     if (zb) *(u32x4*)(zb + (size_t)row * DM + colb + bj * 128) = o;
;                 }
;                 sum += __shfl_xor(sum, 16); sq += __shfl_xor(sq, 16);
;                 sum += __shfl_xor(sum, 32); sq += __shfl_xor(sq, 32);
;                 if (fq == 0) { atomicAdd(stout + 2 * (size_t)row, sum); atomicAdd(stout + 2 * (size_t)row + 1, sq); }
.LBB0_525:
	v_add_f32_e32 v118, v108, v109
	v_mul_f32_e32 v109, v109, v109
	v_fmac_f32_e32 v109, v108, v108
	v_add_f32_e32 v108, v104, v105
	v_mul_f32_e32 v105, v105, v105
	v_fmac_f32_e32 v105, v104, v104
	v_add_f32_e32 v108, v106, v108
	v_fmac_f32_e32 v105, v106, v106
	v_mul_f32_e32 v106, v101, v101
	v_fmac_f32_e32 v109, v110, v110
	v_fmac_f32_e32 v106, v100, v100
	v_add_f32_e32 v118, v110, v118
	v_fmac_f32_e32 v109, v111, v111
	v_fmac_f32_e32 v105, v107, v107
	v_fmac_f32_e32 v106, v102, v102
	v_add_f32_e32 v118, v111, v118
	v_add_f32_e32 v104, v109, v105
	v_add_f32_e32 v105, v100, v101
	v_fmac_f32_e32 v106, v103, v103
	v_add_f32_e32 v118, 0, v118
	v_add_f32_e32 v108, v107, v108
	v_add_f32_e32 v105, v102, v105
	v_add_f32_e32 v104, v104, v106
	v_add_f32_e32 v106, v96, v97
	v_add_f32_e32 v108, v118, v108
	v_add_f32_e32 v105, v103, v105
	v_add_f32_e32 v106, v98, v106
	v_add_f32_e32 v105, v108, v105
	v_add_f32_e32 v106, v99, v106
	v_add_f32_e32 v105, v105, v106
	v_mul_f32_e32 v106, v97, v97
	v_fmac_f32_e32 v106, v96, v96
	v_fmac_f32_e32 v106, v98, v98
	v_fmac_f32_e32 v106, v99, v99
	v_add_f32_e32 v104, v104, v106
	ds_bpermute_b32 v107, v120, v105
	ds_bpermute_b32 v108, v120, v104
	v_cvt_pk_bf16_f32 v106, v100, v101
	global_store_dwordx4 v[114:115], v[96:99], off offset:528
	v_cvt_pk_bf16_f32 v109, v98, v99
	s_waitcnt lgkmcnt(0)
	v_add_f32_e32 v100, v105, v107
	v_add_f32_e32 v101, v104, v108
	ds_bpermute_b32 v104, v121, v100
	ds_bpermute_b32 v105, v121, v101
	v_cvt_pk_bf16_f32 v107, v102, v103
	v_cvt_pk_bf16_f32 v108, v96, v97
	flat_store_dwordx4 v[116:117], v[106:109] offset:256
	s_mov_b32 s100, -1
	s_mov_b32 s101, 0
	s_mov_b32 s98, 0xffff0000
	s_mov_b32 s99, 0
	s_and_saveexec_b64 s[28:29], s[100:101]
	s_cbranch_execz .LBB0_527
	s_waitcnt lgkmcnt(0)
	v_add_f32_e32 v99, v100, v104
	v_lshl_add_u64 v[96:97], v[112:113], 3, s[6:7]
	v_add_f32_e32 v98, v101, v105
	v_cndmask_b32_e64 v99, v99, v98, s[98:99]
	v_cndmask_b32_e64 v98, 0, 4, s[98:99]
	v_or_b32_e32 v96, v96, v98
	flat_atomic_add_f32 v[96:97], v99

; DEVI unsigned pk2(float lo, float hi) { unsigned r; asm("v_cvt_pk_bf16_f32 %0, %1, %2" : "=v"(r) : "v"(lo), "v"(hi)); return r; }
;     DEVI void operator()(const f32x4 (&acc)[2][2][4][2], const pg8::Unit& u, int wr, int wc, int fr, int fq) const {
;     ...
;                         f32x4 zz = ALPHA * xv + acc[ai][bj][m][n];
;                         if (bias) zz += *(const f32x4*)(bias + col);
;                         *(f32x4*)(zdst + (size_t)row * DM + col) = zz;
;                         sum += zz[0] + zz[1] + zz[2] + zz[3]; sq += zz[0] * zz[0] + zz[1] * zz[1] + zz[2] * zz[2] + zz[3] * zz[3];
;                         z[n] = zz;
;                     }
;                     u32x4 o; o.x = pk2(z[0][0], z[0][1]); o.y = pk2(z[0][2], z[0][3]); o.z = pk2(z[1][0], z[1][1]); o.w = pk2(z[1][2], z[1][3]);
;                     if (zb) *(u32x4*)(zb + (size_t)row * DM + colb + bj * 128) = o;
;                 }
;                 sum += __shfl_xor(sum, 16); sq += __shfl_xor(sq, 16);
;                 sum += __shfl_xor(sum, 32); sq += __shfl_xor(sq, 32);
;                 if (fq == 0) { atomicAdd(stout + 2 * (size_t)row, sum); atomicAdd(stout + 2 * (size_t)row + 1, sq); }
.LBB0_535:
	v_add_f32_e32 v102, v92, v93
	v_mul_f32_e32 v93, v93, v93
	v_fmac_f32_e32 v93, v92, v92
	v_add_f32_e32 v92, v88, v89
	v_mul_f32_e32 v89, v89, v89
	v_fmac_f32_e32 v89, v88, v88
	v_add_f32_e32 v92, v90, v92
	v_fmac_f32_e32 v89, v90, v90
	v_mul_f32_e32 v90, v85, v85
	v_fmac_f32_e32 v93, v94, v94
	v_fmac_f32_e32 v90, v84, v84
	v_add_f32_e32 v102, v94, v102
	v_fmac_f32_e32 v93, v95, v95
	v_fmac_f32_e32 v89, v91, v91
	v_fmac_f32_e32 v90, v86, v86
	v_add_f32_e32 v102, v95, v102
	v_add_f32_e32 v88, v93, v89
	v_add_f32_e32 v89, v84, v85
	v_fmac_f32_e32 v90, v87, v87
	v_add_f32_e32 v102, 0, v102
	v_add_f32_e32 v92, v91, v92
	v_add_f32_e32 v89, v86, v89
	v_add_f32_e32 v88, v88, v90
	v_add_f32_e32 v90, v80, v81
	v_add_f32_e32 v92, v102, v92
	v_add_f32_e32 v89, v87, v89
	v_add_f32_e32 v90, v82, v90
	v_add_f32_e32 v89, v92, v89
	v_add_f32_e32 v90, v83, v90
	v_add_f32_e32 v89, v89, v90
	v_mul_f32_e32 v90, v81, v81
	v_fmac_f32_e32 v90, v80, v80
	v_fmac_f32_e32 v90, v82, v82
	v_fmac_f32_e32 v90, v83, v83
	v_add_f32_e32 v88, v88, v90
	ds_bpermute_b32 v91, v120, v89
	ds_bpermute_b32 v92, v120, v88
	v_cvt_pk_bf16_f32 v90, v84, v85
	global_store_dwordx4 v[98:99], v[80:83], off offset:528
	v_cvt_pk_bf16_f32 v93, v82, v83
	s_waitcnt lgkmcnt(0)
	v_add_f32_e32 v84, v89, v91
	v_add_f32_e32 v85, v88, v92
	ds_bpermute_b32 v88, v121, v84
	ds_bpermute_b32 v89, v121, v85
	v_cvt_pk_bf16_f32 v91, v86, v87
	v_cvt_pk_bf16_f32 v92, v80, v81
	flat_store_dwordx4 v[100:101], v[90:93] offset:256
	s_mov_b32 s100, -1
	s_mov_b32 s101, 0
	s_mov_b32 s98, 0xffff0000
	s_mov_b32 s99, 0
	s_and_saveexec_b64 s[28:29], s[100:101]
	s_cbranch_execz .LBB0_537
	s_waitcnt lgkmcnt(0)
	v_add_f32_e32 v83, v84, v88
	v_lshl_add_u64 v[80:81], v[96:97], 3, s[6:7]
	v_add_f32_e32 v82, v85, v89
	v_cndmask_b32_e64 v83, v83, v82, s[98:99]
	v_cndmask_b32_e64 v82, 0, 4, s[98:99]
	v_or_b32_e32 v80, v80, v82
	flat_atomic_add_f32 v[80:81], v83

; DEVI unsigned pk2(float lo, float hi) { unsigned r; asm("v_cvt_pk_bf16_f32 %0, %1, %2" : "=v"(r) : "v"(lo), "v"(hi)); return r; }
;     DEVI void operator()(const f32x4 (&acc)[2][2][4][2], const pg8::Unit& u, int wr, int wc, int fr, int fq) const {
;     ...
;                         f32x4 zz = ALPHA * xv + acc[ai][bj][m][n];
;                         if (bias) zz += *(const f32x4*)(bias + col);
;                         *(f32x4*)(zdst + (size_t)row * DM + col) = zz;
;                         sum += zz[0] + zz[1] + zz[2] + zz[3]; sq += zz[0] * zz[0] + zz[1] * zz[1] + zz[2] * zz[2] + zz[3] * zz[3];
;                         z[n] = zz;
;                     }
;                     u32x4 o; o.x = pk2(z[0][0], z[0][1]); o.y = pk2(z[0][2], z[0][3]); o.z = pk2(z[1][0], z[1][1]); o.w = pk2(z[1][2], z[1][3]);
;                     if (zb) *(u32x4*)(zb + (size_t)row * DM + colb + bj * 128) = o;
;                 }
;                 sum += __shfl_xor(sum, 16); sq += __shfl_xor(sq, 16);
;                 sum += __shfl_xor(sum, 32); sq += __shfl_xor(sq, 32);
;                 if (fq == 0) { atomicAdd(stout + 2 * (size_t)row, sum); atomicAdd(stout + 2 * (size_t)row + 1, sq); }
.LBB0_545:
	v_add_f32_e32 v86, v76, v77
	v_mul_f32_e32 v77, v77, v77
	v_fmac_f32_e32 v77, v76, v76
	v_add_f32_e32 v76, v72, v73
	v_mul_f32_e32 v73, v73, v73
	v_fmac_f32_e32 v73, v72, v72
	v_add_f32_e32 v76, v74, v76
	v_fmac_f32_e32 v73, v74, v74
	v_mul_f32_e32 v74, v69, v69
	v_fmac_f32_e32 v77, v78, v78
	v_fmac_f32_e32 v74, v68, v68
	v_add_f32_e32 v86, v78, v86
	v_fmac_f32_e32 v77, v79, v79
	v_fmac_f32_e32 v73, v75, v75
	v_fmac_f32_e32 v74, v70, v70
	v_add_f32_e32 v86, v79, v86
	v_add_f32_e32 v72, v77, v73
	v_add_f32_e32 v73, v68, v69
	v_fmac_f32_e32 v74, v71, v71
	v_add_f32_e32 v86, 0, v86
	v_add_f32_e32 v76, v75, v76
	v_add_f32_e32 v73, v70, v73
	v_add_f32_e32 v72, v72, v74
	v_add_f32_e32 v74, v64, v65
	v_add_f32_e32 v76, v86, v76
	v_add_f32_e32 v73, v71, v73
	v_add_f32_e32 v74, v66, v74
	v_add_f32_e32 v73, v76, v73
	v_add_f32_e32 v74, v67, v74
	v_add_f32_e32 v73, v73, v74
	v_mul_f32_e32 v74, v65, v65
	v_fmac_f32_e32 v74, v64, v64
	v_fmac_f32_e32 v74, v66, v66
	v_fmac_f32_e32 v74, v67, v67
	v_add_f32_e32 v72, v72, v74
	ds_bpermute_b32 v75, v120, v73
	ds_bpermute_b32 v76, v120, v72
	v_cvt_pk_bf16_f32 v74, v68, v69
	global_store_dwordx4 v[82:83], v[64:67], off offset:528
	v_cvt_pk_bf16_f32 v77, v66, v67
	s_waitcnt lgkmcnt(0)
	v_add_f32_e32 v68, v73, v75
	v_add_f32_e32 v69, v72, v76
	ds_bpermute_b32 v72, v121, v68
	ds_bpermute_b32 v73, v121, v69
	v_cvt_pk_bf16_f32 v75, v70, v71
	v_cvt_pk_bf16_f32 v76, v64, v65
	flat_store_dwordx4 v[84:85], v[74:77] offset:256
	s_mov_b32 s100, -1
	s_mov_b32 s101, 0
	s_mov_b32 s98, 0xffff0000
	s_mov_b32 s99, 0
	s_and_saveexec_b64 s[28:29], s[100:101]
	s_cbranch_execz .LBB0_547
	s_waitcnt lgkmcnt(0)
	v_add_f32_e32 v67, v68, v72
	v_lshl_add_u64 v[64:65], v[80:81], 3, s[6:7]
	v_add_f32_e32 v66, v69, v73
	v_cndmask_b32_e64 v67, v67, v66, s[98:99]
	v_cndmask_b32_e64 v66, 0, 4, s[98:99]
	v_or_b32_e32 v64, v64, v66
	flat_atomic_add_f32 v[64:65], v67

; DEVI unsigned pk2(float lo, float hi) { unsigned r; asm("v_cvt_pk_bf16_f32 %0, %1, %2" : "=v"(r) : "v"(lo), "v"(hi)); return r; }
;     DEVI void operator()(const f32x4 (&acc)[2][2][4][2], const pg8::Unit& u, int wr, int wc, int fr, int fq) const {
;     ...
;                         f32x4 zz = ALPHA * xv + acc[ai][bj][m][n];
;                         if (bias) zz += *(const f32x4*)(bias + col);
;                         *(f32x4*)(zdst + (size_t)row * DM + col) = zz;
;                         sum += zz[0] + zz[1] + zz[2] + zz[3]; sq += zz[0] * zz[0] + zz[1] * zz[1] + zz[2] * zz[2] + zz[3] * zz[3];
;                         z[n] = zz;
;                     }
;                     u32x4 o; o.x = pk2(z[0][0], z[0][1]); o.y = pk2(z[0][2], z[0][3]); o.z = pk2(z[1][0], z[1][1]); o.w = pk2(z[1][2], z[1][3]);
;                     if (zb) *(u32x4*)(zb + (size_t)row * DM + colb + bj * 128) = o;
;                 }
;                 sum += __shfl_xor(sum, 16); sq += __shfl_xor(sq, 16);
;                 sum += __shfl_xor(sum, 32); sq += __shfl_xor(sq, 32);
;                 if (fq == 0) { atomicAdd(stout + 2 * (size_t)row, sum); atomicAdd(stout + 2 * (size_t)row + 1, sq); }
.LBB0_555:
	v_add_f32_e32 v70, v60, v61
	v_mul_f32_e32 v61, v61, v61
	v_fmac_f32_e32 v61, v60, v60
	v_add_f32_e32 v60, v56, v57
	v_mul_f32_e32 v57, v57, v57
	v_fmac_f32_e32 v57, v56, v56
	v_add_f32_e32 v60, v58, v60
	v_fmac_f32_e32 v57, v58, v58
	v_mul_f32_e32 v58, v53, v53
	v_fmac_f32_e32 v61, v62, v62
	v_fmac_f32_e32 v58, v52, v52
	v_add_f32_e32 v70, v62, v70
	v_fmac_f32_e32 v61, v63, v63
	v_fmac_f32_e32 v57, v59, v59
	v_fmac_f32_e32 v58, v54, v54
	v_add_f32_e32 v70, v63, v70
	v_add_f32_e32 v56, v61, v57
	v_add_f32_e32 v57, v52, v53
	v_fmac_f32_e32 v58, v55, v55
	v_add_f32_e32 v70, 0, v70
	v_add_f32_e32 v60, v59, v60
	v_add_f32_e32 v57, v54, v57
	v_add_f32_e32 v56, v56, v58
	v_add_f32_e32 v58, v48, v49
	v_add_f32_e32 v60, v70, v60
	v_add_f32_e32 v57, v55, v57
	v_add_f32_e32 v58, v50, v58
	v_add_f32_e32 v57, v60, v57
	v_add_f32_e32 v58, v51, v58
	v_add_f32_e32 v57, v57, v58
	v_mul_f32_e32 v58, v49, v49
	v_fmac_f32_e32 v58, v48, v48
	v_fmac_f32_e32 v58, v50, v50
	v_fmac_f32_e32 v58, v51, v51
	v_add_f32_e32 v56, v56, v58
	ds_bpermute_b32 v59, v120, v57
	ds_bpermute_b32 v60, v120, v56
	v_cvt_pk_bf16_f32 v58, v52, v53
	global_store_dwordx4 v[66:67], v[48:51], off offset:528
	v_cvt_pk_bf16_f32 v61, v50, v51
	s_waitcnt lgkmcnt(0)
	v_add_f32_e32 v52, v57, v59
	v_add_f32_e32 v53, v56, v60
	ds_bpermute_b32 v56, v121, v52
	ds_bpermute_b32 v57, v121, v53
	v_cvt_pk_bf16_f32 v59, v54, v55
	v_cvt_pk_bf16_f32 v60, v48, v49
	flat_store_dwordx4 v[68:69], v[58:61] offset:256
	s_mov_b32 s100, -1
	s_mov_b32 s101, 0
	s_mov_b32 s98, 0xffff0000
	s_mov_b32 s99, 0
	s_and_saveexec_b64 s[28:29], s[100:101]
	s_cbranch_execz .LBB0_557
	s_waitcnt lgkmcnt(0)
	v_add_f32_e32 v51, v52, v56
	v_lshl_add_u64 v[48:49], v[64:65], 3, s[6:7]
	v_add_f32_e32 v50, v53, v57
	v_cndmask_b32_e64 v51, v51, v50, s[98:99]
	v_cndmask_b32_e64 v50, 0, 4, s[98:99]
	v_or_b32_e32 v48, v48, v50
	flat_atomic_add_f32 v[48:49], v51

; DEVI unsigned pk2(float lo, float hi) { unsigned r; asm("v_cvt_pk_bf16_f32 %0, %1, %2" : "=v"(r) : "v"(lo), "v"(hi)); return r; }
;     DEVI void operator()(const f32x4 (&acc)[2][2][4][2], const pg8::Unit& u, int wr, int wc, int fr, int fq) const {
;     ...
;                         f32x4 zz = ALPHA * xv + acc[ai][bj][m][n];
;                         if (bias) zz += *(const f32x4*)(bias + col);
;                         *(f32x4*)(zdst + (size_t)row * DM + col) = zz;
;                         sum += zz[0] + zz[1] + zz[2] + zz[3]; sq += zz[0] * zz[0] + zz[1] * zz[1] + zz[2] * zz[2] + zz[3] * zz[3];
;                         z[n] = zz;
;                     }
;                     u32x4 o; o.x = pk2(z[0][0], z[0][1]); o.y = pk2(z[0][2], z[0][3]); o.z = pk2(z[1][0], z[1][1]); o.w = pk2(z[1][2], z[1][3]);
;                     if (zb) *(u32x4*)(zb + (size_t)row * DM + colb + bj * 128) = o;
;                 }
;                 sum += __shfl_xor(sum, 16); sq += __shfl_xor(sq, 16);
;                 sum += __shfl_xor(sum, 32); sq += __shfl_xor(sq, 32);
;                 if (fq == 0) { atomicAdd(stout + 2 * (size_t)row, sum); atomicAdd(stout + 2 * (size_t)row + 1, sq); }
.LBB0_565:
	v_add_f32_e32 v54, v44, v45
	v_mul_f32_e32 v45, v45, v45
	v_fmac_f32_e32 v45, v44, v44
	v_add_f32_e32 v44, v40, v41
	v_mul_f32_e32 v41, v41, v41
	v_fmac_f32_e32 v41, v40, v40
	v_add_f32_e32 v44, v42, v44
	v_fmac_f32_e32 v41, v42, v42
	v_mul_f32_e32 v42, v37, v37
	v_fmac_f32_e32 v45, v46, v46
	v_fmac_f32_e32 v42, v36, v36
	v_add_f32_e32 v54, v46, v54
	v_fmac_f32_e32 v45, v47, v47
	v_fmac_f32_e32 v41, v43, v43
	v_fmac_f32_e32 v42, v38, v38
	v_add_f32_e32 v54, v47, v54
	v_add_f32_e32 v40, v45, v41
	v_add_f32_e32 v41, v36, v37
	v_fmac_f32_e32 v42, v39, v39
	v_add_f32_e32 v54, 0, v54
	v_add_f32_e32 v44, v43, v44
	v_add_f32_e32 v41, v38, v41
	v_add_f32_e32 v40, v40, v42
	v_add_f32_e32 v42, v32, v33
	v_add_f32_e32 v44, v54, v44
	v_add_f32_e32 v41, v39, v41
	v_add_f32_e32 v42, v34, v42
	v_add_f32_e32 v41, v44, v41
	v_add_f32_e32 v42, v35, v42
	v_add_f32_e32 v41, v41, v42
	v_mul_f32_e32 v42, v33, v33
	v_fmac_f32_e32 v42, v32, v32
	v_fmac_f32_e32 v42, v34, v34
	v_fmac_f32_e32 v42, v35, v35
	v_add_f32_e32 v40, v40, v42
	ds_bpermute_b32 v43, v120, v41
	ds_bpermute_b32 v44, v120, v40
	v_cvt_pk_bf16_f32 v42, v36, v37
	global_store_dwordx4 v[50:51], v[32:35], off offset:528
	v_cvt_pk_bf16_f32 v45, v34, v35
	s_waitcnt lgkmcnt(0)
	v_add_f32_e32 v36, v41, v43
	v_add_f32_e32 v37, v40, v44
	ds_bpermute_b32 v40, v121, v36
	ds_bpermute_b32 v41, v121, v37
	v_cvt_pk_bf16_f32 v43, v38, v39
	v_cvt_pk_bf16_f32 v44, v32, v33
	flat_store_dwordx4 v[52:53], v[42:45] offset:256
	s_mov_b32 s100, -1
	s_mov_b32 s101, 0
	s_mov_b32 s98, 0xffff0000
	s_mov_b32 s99, 0
	s_and_saveexec_b64 s[28:29], s[100:101]
	s_cbranch_execz .LBB0_567
	s_waitcnt lgkmcnt(0)
	v_add_f32_e32 v35, v36, v40
	v_lshl_add_u64 v[32:33], v[48:49], 3, s[6:7]
	v_add_f32_e32 v34, v37, v41
	v_cndmask_b32_e64 v35, v35, v34, s[98:99]
	v_cndmask_b32_e64 v34, 0, 4, s[98:99]
	v_or_b32_e32 v32, v32, v34
	flat_atomic_add_f32 v[32:33], v35

; DEVI unsigned pk2(float lo, float hi) { unsigned r; asm("v_cvt_pk_bf16_f32 %0, %1, %2" : "=v"(r) : "v"(lo), "v"(hi)); return r; }
;     DEVI void operator()(const f32x4 (&acc)[2][2][4][2], const pg8::Unit& u, int wr, int wc, int fr, int fq) const {
;     ...
;                         f32x4 zz = ALPHA * xv + acc[ai][bj][m][n];
;                         if (bias) zz += *(const f32x4*)(bias + col);
;                         *(f32x4*)(zdst + (size_t)row * DM + col) = zz;
;                         sum += zz[0] + zz[1] + zz[2] + zz[3]; sq += zz[0] * zz[0] + zz[1] * zz[1] + zz[2] * zz[2] + zz[3] * zz[3];
;                         z[n] = zz;
;                     }
;                     u32x4 o; o.x = pk2(z[0][0], z[0][1]); o.y = pk2(z[0][2], z[0][3]); o.z = pk2(z[1][0], z[1][1]); o.w = pk2(z[1][2], z[1][3]);
;                     if (zb) *(u32x4*)(zb + (size_t)row * DM + colb + bj * 128) = o;
;                 }
;                 sum += __shfl_xor(sum, 16); sq += __shfl_xor(sq, 16);
;                 sum += __shfl_xor(sum, 32); sq += __shfl_xor(sq, 32);
;                 if (fq == 0) { atomicAdd(stout + 2 * (size_t)row, sum); atomicAdd(stout + 2 * (size_t)row + 1, sq); }
.LBB0_575:
	v_add_f32_e32 v38, v28, v29
	v_mul_f32_e32 v29, v29, v29
	v_fmac_f32_e32 v29, v28, v28
	v_add_f32_e32 v28, v24, v25
	v_mul_f32_e32 v25, v25, v25
	v_fmac_f32_e32 v25, v24, v24
	v_add_f32_e32 v28, v26, v28
	v_fmac_f32_e32 v25, v26, v26
	v_mul_f32_e32 v26, v21, v21
	v_fmac_f32_e32 v29, v30, v30
	v_fmac_f32_e32 v26, v20, v20
	v_add_f32_e32 v38, v30, v38
	v_fmac_f32_e32 v29, v31, v31
	v_fmac_f32_e32 v25, v27, v27
	v_fmac_f32_e32 v26, v22, v22
	v_add_f32_e32 v38, v31, v38
	v_add_f32_e32 v24, v29, v25
	v_add_f32_e32 v25, v20, v21
	v_fmac_f32_e32 v26, v23, v23
	v_add_f32_e32 v38, 0, v38
	v_add_f32_e32 v28, v27, v28
	v_add_f32_e32 v25, v22, v25
	v_add_f32_e32 v24, v24, v26
	v_add_f32_e32 v26, v16, v17
	v_add_f32_e32 v28, v38, v28
	v_add_f32_e32 v25, v23, v25
	v_add_f32_e32 v26, v18, v26
	v_add_f32_e32 v25, v28, v25
	v_add_f32_e32 v26, v19, v26
	v_add_f32_e32 v25, v25, v26
	v_mul_f32_e32 v26, v17, v17
	v_fmac_f32_e32 v26, v16, v16
	v_fmac_f32_e32 v26, v18, v18
	v_fmac_f32_e32 v26, v19, v19
	v_add_f32_e32 v24, v24, v26
	ds_bpermute_b32 v27, v120, v25
	ds_bpermute_b32 v28, v120, v24
	v_cvt_pk_bf16_f32 v26, v20, v21
	global_store_dwordx4 v[34:35], v[16:19], off offset:528
	v_cvt_pk_bf16_f32 v29, v18, v19
	s_waitcnt lgkmcnt(0)
	v_add_f32_e32 v20, v25, v27
	v_add_f32_e32 v21, v24, v28
	ds_bpermute_b32 v24, v121, v20
	ds_bpermute_b32 v25, v121, v21
	v_cvt_pk_bf16_f32 v27, v22, v23
	v_cvt_pk_bf16_f32 v28, v16, v17
	flat_store_dwordx4 v[36:37], v[26:29] offset:256
	s_mov_b32 s100, -1
	s_mov_b32 s101, 0
	s_mov_b32 s98, 0xffff0000
	s_mov_b32 s99, 0
	s_and_saveexec_b64 s[28:29], s[100:101]
	s_cbranch_execz .LBB0_577
	s_waitcnt lgkmcnt(0)
	v_add_f32_e32 v19, v20, v24
	v_lshl_add_u64 v[16:17], v[32:33], 3, s[6:7]
	v_add_f32_e32 v18, v21, v25
	v_cndmask_b32_e64 v19, v19, v18, s[98:99]
	v_cndmask_b32_e64 v18, 0, 4, s[98:99]
	v_or_b32_e32 v16, v16, v18
	flat_atomic_add_f32 v[16:17], v19

; DEVI unsigned pk2(float lo, float hi) { unsigned r; asm("v_cvt_pk_bf16_f32 %0, %1, %2" : "=v"(r) : "v"(lo), "v"(hi)); return r; }
;     DEVI void operator()(const f32x4 (&acc)[2][2][4][2], const pg8::Unit& u, int wr, int wc, int fr, int fq) const {
;     ...
;                         f32x4 zz = ALPHA * xv + acc[ai][bj][m][n];
;                         if (bias) zz += *(const f32x4*)(bias + col);
;                         *(f32x4*)(zdst + (size_t)row * DM + col) = zz;
;                         sum += zz[0] + zz[1] + zz[2] + zz[3]; sq += zz[0] * zz[0] + zz[1] * zz[1] + zz[2] * zz[2] + zz[3] * zz[3];
;                         z[n] = zz;
;                     }
;                     u32x4 o; o.x = pk2(z[0][0], z[0][1]); o.y = pk2(z[0][2], z[0][3]); o.z = pk2(z[1][0], z[1][1]); o.w = pk2(z[1][2], z[1][3]);
;                     if (zb) *(u32x4*)(zb + (size_t)row * DM + colb + bj * 128) = o;
;                 }
;                 sum += __shfl_xor(sum, 16); sq += __shfl_xor(sq, 16);
;                 sum += __shfl_xor(sum, 32); sq += __shfl_xor(sq, 32);
;                 if (fq == 0) { atomicAdd(stout + 2 * (size_t)row, sum); atomicAdd(stout + 2 * (size_t)row + 1, sq); }
.LBB0_585:
	v_add_f32_e32 v22, v12, v13
	v_mul_f32_e32 v13, v13, v13
	v_fmac_f32_e32 v13, v12, v12
	v_add_f32_e32 v12, v8, v9
	v_mul_f32_e32 v9, v9, v9
	v_fmac_f32_e32 v9, v8, v8
	v_add_f32_e32 v12, v10, v12
	v_fmac_f32_e32 v9, v10, v10
	v_mul_f32_e32 v10, v5, v5
	v_fmac_f32_e32 v13, v14, v14
	v_fmac_f32_e32 v10, v4, v4
	v_add_f32_e32 v22, v14, v22
	v_fmac_f32_e32 v13, v15, v15
	v_fmac_f32_e32 v9, v11, v11
	v_fmac_f32_e32 v10, v6, v6
	v_add_f32_e32 v22, v15, v22
	v_add_f32_e32 v8, v13, v9
	v_add_f32_e32 v9, v4, v5
	v_fmac_f32_e32 v10, v7, v7
	v_add_f32_e32 v22, 0, v22
	v_add_f32_e32 v12, v11, v12
	v_add_f32_e32 v9, v6, v9
	v_add_f32_e32 v8, v8, v10
	v_add_f32_e32 v10, v0, v1
	v_add_f32_e32 v12, v22, v12
	v_add_f32_e32 v9, v7, v9
	v_add_f32_e32 v10, v2, v10
	v_add_f32_e32 v9, v12, v9
	v_add_f32_e32 v10, v3, v10
	v_add_f32_e32 v9, v9, v10
	v_mul_f32_e32 v10, v1, v1
	v_fmac_f32_e32 v10, v0, v0
	v_fmac_f32_e32 v10, v2, v2
	v_fmac_f32_e32 v10, v3, v3
	v_add_f32_e32 v8, v8, v10
	ds_bpermute_b32 v11, v120, v9
	ds_bpermute_b32 v12, v120, v8
	v_cvt_pk_bf16_f32 v10, v4, v5
	global_store_dwordx4 v[18:19], v[0:3], off offset:528
	v_cvt_pk_bf16_f32 v13, v2, v3
	s_waitcnt lgkmcnt(0)
	v_add_f32_e32 v4, v9, v11
	v_add_f32_e32 v5, v8, v12
	ds_bpermute_b32 v8, v121, v4
	ds_bpermute_b32 v9, v121, v5
	v_cvt_pk_bf16_f32 v11, v6, v7
	v_cvt_pk_bf16_f32 v12, v0, v1
	flat_store_dwordx4 v[20:21], v[10:13] offset:256
	s_mov_b32 s100, -1
	s_mov_b32 s101, 0
	s_mov_b32 s98, 0xffff0000
	s_mov_b32 s99, 0
	s_and_saveexec_b64 s[0:1], s[100:101]
	s_cbranch_execz .LBB0_587
	s_waitcnt lgkmcnt(0)
	v_add_f32_e32 v3, v4, v8
	v_lshl_add_u64 v[0:1], v[16:17], 3, s[6:7]
	v_add_f32_e32 v2, v5, v9
	v_cndmask_b32_e64 v3, v3, v2, s[98:99]
	v_cndmask_b32_e64 v2, 0, 4, s[98:99]
	v_or_b32_e32 v0, v0, v2
	flat_atomic_add_f32 v[0:1], v3

; DEVI unsigned pk2(float lo, float hi) { unsigned r; asm("v_cvt_pk_bf16_f32 %0, %1, %2" : "=v"(r) : "v"(lo), "v"(hi)); return r; }
;     DEVI void operator()(const f32x4 (&acc)[2][2][4][2], const pg8::Unit& u, int wr, int wc, int fr, int fq) const {
;     ...
;                         f32x4 zz = ALPHA * xv + acc[ai][bj][m][n];
;                         if (bias) zz += *(const f32x4*)(bias + col);
;                         *(f32x4*)(zdst + (size_t)row * DM + col) = zz;
;                         sum += zz[0] + zz[1] + zz[2] + zz[3]; sq += zz[0] * zz[0] + zz[1] * zz[1] + zz[2] * zz[2] + zz[3] * zz[3];
;                         z[n] = zz;
;                     }
;                     u32x4 o; o.x = pk2(z[0][0], z[0][1]); o.y = pk2(z[0][2], z[0][3]); o.z = pk2(z[1][0], z[1][1]); o.w = pk2(z[1][2], z[1][3]);
;                     if (zb) *(u32x4*)(zb + (size_t)row * DM + colb + bj * 128) = o;
;                 }
;                 sum += __shfl_xor(sum, 16); sq += __shfl_xor(sq, 16);
;                 sum += __shfl_xor(sum, 32); sq += __shfl_xor(sq, 32);
;                 if (fq == 0) { atomicAdd(stout + 2 * (size_t)row, sum); atomicAdd(stout + 2 * (size_t)row + 1, sq); }
.LBB0_807:
	v_add_f32_e32 v132, v124, v125
	v_mul_f32_e32 v125, v125, v125
	v_fmac_f32_e32 v125, v124, v124
	v_add_f32_e32 v124, v120, v121
	v_mul_f32_e32 v121, v121, v121
	v_fmac_f32_e32 v121, v120, v120
	v_fmac_f32_e32 v125, v126, v126
	v_fmac_f32_e32 v121, v122, v122
	v_add_f32_e32 v132, v126, v132
	v_fmac_f32_e32 v125, v127, v127
	v_fmac_f32_e32 v121, v123, v123
	v_add_f32_e32 v132, v127, v132
	v_add_f32_e32 v124, v122, v124
	v_add_f32_e32 v120, v125, v121
	v_add_f32_e32 v121, v116, v117
	v_add_f32_e32 v132, 0, v132
	v_add_f32_e32 v124, v123, v124
	v_add_f32_e32 v121, v118, v121
	v_add_f32_e32 v124, v132, v124
	v_add_f32_e32 v121, v119, v121
	v_add_f32_e32 v124, v124, v121
	v_mul_f32_e32 v121, v117, v117
	v_fmac_f32_e32 v121, v116, v116
	v_fmac_f32_e32 v121, v118, v118
	v_fmac_f32_e32 v121, v119, v119
	v_add_f32_e32 v125, v120, v121
	v_pk_fma_f32 v[122:123], v[130:131], s[26:27], v[114:115] op_sel_hi:[1,0,1]
	v_pk_fma_f32 v[120:121], v[128:129], s[26:27], v[112:113] op_sel_hi:[1,0,1]
	v_and_b32_e32 v115, 64, v174
	v_add_f32_e32 v112, v120, v121
	v_xor_b32_e32 v114, 16, v174
	v_add_u32_e32 v115, 64, v115
	v_add_f32_e32 v112, v122, v112
	v_cmp_lt_i32_e32 vcc, v114, v115
	v_add_f32_e32 v112, v123, v112
	v_mul_f32_e32 v113, v121, v121
	v_cndmask_b32_e32 v114, v174, v114, vcc
	v_add_f32_e32 v112, v124, v112
	v_fmac_f32_e32 v113, v120, v120
	v_lshlrev_b32_e32 v130, 2, v114
	v_fmac_f32_e32 v113, v122, v122
	ds_bpermute_b32 v114, v130, v112
	v_fmac_f32_e32 v113, v123, v123
	v_add_f32_e32 v113, v125, v113
	ds_bpermute_b32 v124, v130, v113
	global_store_dwordx4 v[160:161], v[120:123], off offset:528
	s_waitcnt lgkmcnt(0)
	v_add_f32_e32 v112, v112, v114
	v_xor_b32_e32 v114, 32, v174
	v_cmp_lt_i32_e32 vcc, v114, v115
	v_add_f32_e32 v113, v113, v124
	v_cvt_pk_bf16_f32 v116, v116, v117
	v_cvt_pk_bf16_f32 v117, v118, v119
	v_cvt_pk_bf16_f32 v118, v120, v121
	v_cvt_pk_bf16_f32 v119, v122, v123
	s_nop 0
	v_cndmask_b32_e32 v114, v174, v114, vcc
	v_lshlrev_b32_e32 v131, 2, v114
	ds_bpermute_b32 v114, v131, v112
	ds_bpermute_b32 v115, v131, v113
	flat_store_dwordx4 v[166:167], v[116:119] offset:256
	s_mov_b32 s100, -1
	s_mov_b32 s101, 0
	s_mov_b32 s98, 0xffff0000
	s_mov_b32 s99, 0
	s_and_saveexec_b64 s[30:31], s[100:101]
	s_cbranch_execz .LBB0_809
	s_waitcnt lgkmcnt(0)
	v_add_f32_e32 v115, v113, v115
	v_add_f32_e32 v114, v112, v114
	v_lshl_add_u64 v[112:113], v[158:159], 3, s[14:15]
	v_cndmask_b32_e64 v114, v114, v115, s[98:99]
	v_cndmask_b32_e64 v115, 0, 4, s[98:99]
	v_or_b32_e32 v112, v112, v115
	flat_atomic_add_f32 v[112:113], v114

; DEVI unsigned pk2(float lo, float hi) { unsigned r; asm("v_cvt_pk_bf16_f32 %0, %1, %2" : "=v"(r) : "v"(lo), "v"(hi)); return r; }
;     DEVI void operator()(const f32x4 (&acc)[2][2][4][2], const pg8::Unit& u, int wr, int wc, int fr, int fq) const {
;     ...
;                         f32x4 zz = ALPHA * xv + acc[ai][bj][m][n];
;                         if (bias) zz += *(const f32x4*)(bias + col);
;                         *(f32x4*)(zdst + (size_t)row * DM + col) = zz;
;                         sum += zz[0] + zz[1] + zz[2] + zz[3]; sq += zz[0] * zz[0] + zz[1] * zz[1] + zz[2] * zz[2] + zz[3] * zz[3];
;                         z[n] = zz;
;                     }
;                     u32x4 o; o.x = pk2(z[0][0], z[0][1]); o.y = pk2(z[0][2], z[0][3]); o.z = pk2(z[1][0], z[1][1]); o.w = pk2(z[1][2], z[1][3]);
;                     if (zb) *(u32x4*)(zb + (size_t)row * DM + colb + bj * 128) = o;
;                 }
;                 sum += __shfl_xor(sum, 16); sq += __shfl_xor(sq, 16);
;                 sum += __shfl_xor(sum, 32); sq += __shfl_xor(sq, 32);
;                 if (fq == 0) { atomicAdd(stout + 2 * (size_t)row, sum); atomicAdd(stout + 2 * (size_t)row + 1, sq); }
.LBB0_820:
	v_add_f32_e32 v116, v108, v109
	v_mul_f32_e32 v109, v109, v109
	v_fmac_f32_e32 v109, v108, v108
	v_add_f32_e32 v108, v104, v105
	v_mul_f32_e32 v105, v105, v105
	v_fmac_f32_e32 v105, v104, v104
	v_fmac_f32_e32 v109, v110, v110
	v_fmac_f32_e32 v105, v106, v106
	v_add_f32_e32 v116, v110, v116
	v_fmac_f32_e32 v109, v111, v111
	v_fmac_f32_e32 v105, v107, v107
	v_add_f32_e32 v116, v111, v116
	v_add_f32_e32 v108, v106, v108
	v_add_f32_e32 v104, v109, v105
	v_add_f32_e32 v105, v100, v101
	v_add_f32_e32 v116, 0, v116
	v_add_f32_e32 v108, v107, v108
	v_add_f32_e32 v105, v102, v105
	v_add_f32_e32 v108, v116, v108
	v_add_f32_e32 v105, v103, v105
	v_add_f32_e32 v108, v108, v105
	v_mul_f32_e32 v105, v101, v101
	v_fmac_f32_e32 v105, v100, v100
	v_fmac_f32_e32 v105, v102, v102
	v_fmac_f32_e32 v105, v103, v103
	v_add_f32_e32 v109, v104, v105
	v_pk_fma_f32 v[104:105], v[112:113], s[26:27], v[96:97] op_sel_hi:[1,0,1]
	v_pk_fma_f32 v[106:107], v[114:115], s[26:27], v[98:99] op_sel_hi:[1,0,1]
	v_mul_f32_e32 v97, v105, v105
	v_add_f32_e32 v96, v104, v105
	v_fmac_f32_e32 v97, v104, v104
	v_add_f32_e32 v96, v106, v96
	v_fmac_f32_e32 v97, v106, v106
	v_add_f32_e32 v96, v107, v96
	v_fmac_f32_e32 v97, v107, v107
	v_add_f32_e32 v96, v108, v96
	v_add_f32_e32 v97, v109, v97
	ds_bpermute_b32 v98, v130, v96
	ds_bpermute_b32 v99, v130, v97
	global_store_dwordx4 v[122:123], v[104:107], off offset:528
	v_cvt_pk_bf16_f32 v100, v100, v101
	v_cvt_pk_bf16_f32 v101, v102, v103
	s_waitcnt lgkmcnt(0)
	v_add_f32_e32 v96, v96, v98
	v_add_f32_e32 v97, v97, v99
	ds_bpermute_b32 v98, v131, v96
	ds_bpermute_b32 v99, v131, v97
	v_cvt_pk_bf16_f32 v102, v104, v105
	v_cvt_pk_bf16_f32 v103, v106, v107
	flat_store_dwordx4 v[128:129], v[100:103] offset:256
	s_mov_b32 s100, -1
	s_mov_b32 s101, 0
	s_mov_b32 s98, 0xffff0000
	s_mov_b32 s99, 0
	s_and_saveexec_b64 s[30:31], s[100:101]
	s_cbranch_execz .LBB0_822
	s_waitcnt lgkmcnt(0)
	v_add_f32_e32 v99, v97, v99
	v_add_f32_e32 v98, v96, v98
	v_lshl_add_u64 v[96:97], v[120:121], 3, s[14:15]
	v_cndmask_b32_e64 v98, v98, v99, s[98:99]
	v_cndmask_b32_e64 v99, 0, 4, s[98:99]
	v_or_b32_e32 v96, v96, v99
	flat_atomic_add_f32 v[96:97], v98

; DEVI unsigned pk2(float lo, float hi) { unsigned r; asm("v_cvt_pk_bf16_f32 %0, %1, %2" : "=v"(r) : "v"(lo), "v"(hi)); return r; }
;     DEVI void operator()(const f32x4 (&acc)[2][2][4][2], const pg8::Unit& u, int wr, int wc, int fr, int fq) const {
;     ...
;                         f32x4 zz = ALPHA * xv + acc[ai][bj][m][n];
;                         if (bias) zz += *(const f32x4*)(bias + col);
;                         *(f32x4*)(zdst + (size_t)row * DM + col) = zz;
;                         sum += zz[0] + zz[1] + zz[2] + zz[3]; sq += zz[0] * zz[0] + zz[1] * zz[1] + zz[2] * zz[2] + zz[3] * zz[3];
;                         z[n] = zz;
;                     }
;                     u32x4 o; o.x = pk2(z[0][0], z[0][1]); o.y = pk2(z[0][2], z[0][3]); o.z = pk2(z[1][0], z[1][1]); o.w = pk2(z[1][2], z[1][3]);
;                     if (zb) *(u32x4*)(zb + (size_t)row * DM + colb + bj * 128) = o;
;                 }
;                 sum += __shfl_xor(sum, 16); sq += __shfl_xor(sq, 16);
;                 sum += __shfl_xor(sum, 32); sq += __shfl_xor(sq, 32);
;                 if (fq == 0) { atomicAdd(stout + 2 * (size_t)row, sum); atomicAdd(stout + 2 * (size_t)row + 1, sq); }
.LBB0_833:
	v_add_f32_e32 v100, v92, v93
	v_mul_f32_e32 v93, v93, v93
	v_fmac_f32_e32 v93, v92, v92
	v_add_f32_e32 v92, v88, v89
	v_mul_f32_e32 v89, v89, v89
	v_fmac_f32_e32 v89, v88, v88
	v_fmac_f32_e32 v93, v94, v94
	v_fmac_f32_e32 v89, v90, v90
	v_add_f32_e32 v100, v94, v100
	v_fmac_f32_e32 v93, v95, v95
	v_fmac_f32_e32 v89, v91, v91
	v_add_f32_e32 v100, v95, v100
	v_add_f32_e32 v92, v90, v92
	v_add_f32_e32 v88, v93, v89
	v_add_f32_e32 v89, v84, v85
	v_add_f32_e32 v100, 0, v100
	v_add_f32_e32 v92, v91, v92
	v_add_f32_e32 v89, v86, v89
	v_add_f32_e32 v92, v100, v92
	v_add_f32_e32 v89, v87, v89
	v_add_f32_e32 v92, v92, v89
	v_mul_f32_e32 v89, v85, v85
	v_fmac_f32_e32 v89, v84, v84
	v_fmac_f32_e32 v89, v86, v86
	v_fmac_f32_e32 v89, v87, v87
	v_add_f32_e32 v93, v88, v89
	v_pk_fma_f32 v[88:89], v[96:97], s[26:27], v[80:81] op_sel_hi:[1,0,1]
	v_pk_fma_f32 v[90:91], v[98:99], s[26:27], v[82:83] op_sel_hi:[1,0,1]
	v_mul_f32_e32 v81, v89, v89
	v_add_f32_e32 v80, v88, v89
	v_fmac_f32_e32 v81, v88, v88
	v_add_f32_e32 v80, v90, v80
	v_fmac_f32_e32 v81, v90, v90
	v_add_f32_e32 v80, v91, v80
	v_fmac_f32_e32 v81, v91, v91
	v_add_f32_e32 v80, v92, v80
	v_add_f32_e32 v81, v93, v81
	ds_bpermute_b32 v82, v130, v80
	ds_bpermute_b32 v83, v130, v81
	global_store_dwordx4 v[106:107], v[88:91], off offset:528
	v_cvt_pk_bf16_f32 v84, v84, v85
	v_cvt_pk_bf16_f32 v85, v86, v87
	s_waitcnt lgkmcnt(0)
	v_add_f32_e32 v80, v80, v82
	v_add_f32_e32 v81, v81, v83
	ds_bpermute_b32 v82, v131, v80
	ds_bpermute_b32 v83, v131, v81
	v_cvt_pk_bf16_f32 v86, v88, v89
	v_cvt_pk_bf16_f32 v87, v90, v91
	flat_store_dwordx4 v[112:113], v[84:87] offset:256
	s_mov_b32 s100, -1
	s_mov_b32 s101, 0
	s_mov_b32 s98, 0xffff0000
	s_mov_b32 s99, 0
	s_and_saveexec_b64 s[30:31], s[100:101]
	s_cbranch_execz .LBB0_835
	s_waitcnt lgkmcnt(0)
	v_add_f32_e32 v83, v81, v83
	v_add_f32_e32 v82, v80, v82
	v_lshl_add_u64 v[80:81], v[104:105], 3, s[14:15]
	v_cndmask_b32_e64 v82, v82, v83, s[98:99]
	v_cndmask_b32_e64 v83, 0, 4, s[98:99]
	v_or_b32_e32 v80, v80, v83
	flat_atomic_add_f32 v[80:81], v82

; DEVI unsigned pk2(float lo, float hi) { unsigned r; asm("v_cvt_pk_bf16_f32 %0, %1, %2" : "=v"(r) : "v"(lo), "v"(hi)); return r; }
;     DEVI void operator()(const f32x4 (&acc)[2][2][4][2], const pg8::Unit& u, int wr, int wc, int fr, int fq) const {
;     ...
;                         f32x4 zz = ALPHA * xv + acc[ai][bj][m][n];
;                         if (bias) zz += *(const f32x4*)(bias + col);
;                         *(f32x4*)(zdst + (size_t)row * DM + col) = zz;
;                         sum += zz[0] + zz[1] + zz[2] + zz[3]; sq += zz[0] * zz[0] + zz[1] * zz[1] + zz[2] * zz[2] + zz[3] * zz[3];
;                         z[n] = zz;
;                     }
;                     u32x4 o; o.x = pk2(z[0][0], z[0][1]); o.y = pk2(z[0][2], z[0][3]); o.z = pk2(z[1][0], z[1][1]); o.w = pk2(z[1][2], z[1][3]);
;                     if (zb) *(u32x4*)(zb + (size_t)row * DM + colb + bj * 128) = o;
;                 }
;                 sum += __shfl_xor(sum, 16); sq += __shfl_xor(sq, 16);
;                 sum += __shfl_xor(sum, 32); sq += __shfl_xor(sq, 32);
;                 if (fq == 0) { atomicAdd(stout + 2 * (size_t)row, sum); atomicAdd(stout + 2 * (size_t)row + 1, sq); }
.LBB0_846:
	v_add_f32_e32 v84, v76, v77
	v_mul_f32_e32 v77, v77, v77
	v_fmac_f32_e32 v77, v76, v76
	v_add_f32_e32 v76, v72, v73
	v_mul_f32_e32 v73, v73, v73
	v_fmac_f32_e32 v73, v72, v72
	v_fmac_f32_e32 v77, v78, v78
	v_fmac_f32_e32 v73, v74, v74
	v_add_f32_e32 v84, v78, v84
	v_fmac_f32_e32 v77, v79, v79
	v_fmac_f32_e32 v73, v75, v75
	v_add_f32_e32 v84, v79, v84
	v_add_f32_e32 v76, v74, v76
	v_add_f32_e32 v72, v77, v73
	v_add_f32_e32 v73, v68, v69
	v_add_f32_e32 v84, 0, v84
	v_add_f32_e32 v76, v75, v76
	v_add_f32_e32 v73, v70, v73
	v_add_f32_e32 v76, v84, v76
	v_add_f32_e32 v73, v71, v73
	v_add_f32_e32 v76, v76, v73
	v_mul_f32_e32 v73, v69, v69
	v_fmac_f32_e32 v73, v68, v68
	v_fmac_f32_e32 v73, v70, v70
	v_fmac_f32_e32 v73, v71, v71
	v_add_f32_e32 v77, v72, v73
	v_pk_fma_f32 v[72:73], v[80:81], s[26:27], v[64:65] op_sel_hi:[1,0,1]
	v_pk_fma_f32 v[74:75], v[82:83], s[26:27], v[66:67] op_sel_hi:[1,0,1]
	v_mul_f32_e32 v65, v73, v73
	v_add_f32_e32 v64, v72, v73
	v_fmac_f32_e32 v65, v72, v72
	v_add_f32_e32 v64, v74, v64
	v_fmac_f32_e32 v65, v74, v74
	v_add_f32_e32 v64, v75, v64
	v_fmac_f32_e32 v65, v75, v75
	v_add_f32_e32 v64, v76, v64
	v_add_f32_e32 v65, v77, v65
	ds_bpermute_b32 v66, v130, v64
	ds_bpermute_b32 v67, v130, v65
	global_store_dwordx4 v[90:91], v[72:75], off offset:528
	v_cvt_pk_bf16_f32 v68, v68, v69
	v_cvt_pk_bf16_f32 v69, v70, v71
	s_waitcnt lgkmcnt(0)
	v_add_f32_e32 v64, v64, v66
	v_add_f32_e32 v65, v65, v67
	ds_bpermute_b32 v66, v131, v64
	ds_bpermute_b32 v67, v131, v65
	v_cvt_pk_bf16_f32 v70, v72, v73
	v_cvt_pk_bf16_f32 v71, v74, v75
	flat_store_dwordx4 v[96:97], v[68:71] offset:256
	s_mov_b32 s100, -1
	s_mov_b32 s101, 0
	s_mov_b32 s98, 0xffff0000
	s_mov_b32 s99, 0
	s_and_saveexec_b64 s[30:31], s[100:101]
	s_cbranch_execz .LBB0_848
	s_waitcnt lgkmcnt(0)
	v_add_f32_e32 v67, v65, v67
	v_add_f32_e32 v66, v64, v66
	v_lshl_add_u64 v[64:65], v[88:89], 3, s[14:15]
	v_cndmask_b32_e64 v66, v66, v67, s[98:99]
	v_cndmask_b32_e64 v67, 0, 4, s[98:99]
	v_or_b32_e32 v64, v64, v67
	flat_atomic_add_f32 v[64:65], v66

; DEVI unsigned pk2(float lo, float hi) { unsigned r; asm("v_cvt_pk_bf16_f32 %0, %1, %2" : "=v"(r) : "v"(lo), "v"(hi)); return r; }
;     DEVI void operator()(const f32x4 (&acc)[2][2][4][2], const pg8::Unit& u, int wr, int wc, int fr, int fq) const {
;     ...
;                         f32x4 zz = ALPHA * xv + acc[ai][bj][m][n];
;                         if (bias) zz += *(const f32x4*)(bias + col);
;                         *(f32x4*)(zdst + (size_t)row * DM + col) = zz;
;                         sum += zz[0] + zz[1] + zz[2] + zz[3]; sq += zz[0] * zz[0] + zz[1] * zz[1] + zz[2] * zz[2] + zz[3] * zz[3];
;                         z[n] = zz;
;                     }
;                     u32x4 o; o.x = pk2(z[0][0], z[0][1]); o.y = pk2(z[0][2], z[0][3]); o.z = pk2(z[1][0], z[1][1]); o.w = pk2(z[1][2], z[1][3]);
;                     if (zb) *(u32x4*)(zb + (size_t)row * DM + colb + bj * 128) = o;
;                 }
;                 sum += __shfl_xor(sum, 16); sq += __shfl_xor(sq, 16);
;                 sum += __shfl_xor(sum, 32); sq += __shfl_xor(sq, 32);
;                 if (fq == 0) { atomicAdd(stout + 2 * (size_t)row, sum); atomicAdd(stout + 2 * (size_t)row + 1, sq); }
.LBB0_859:
	v_add_f32_e32 v68, v60, v61
	v_mul_f32_e32 v61, v61, v61
	v_fmac_f32_e32 v61, v60, v60
	v_add_f32_e32 v60, v56, v57
	v_mul_f32_e32 v57, v57, v57
	v_fmac_f32_e32 v57, v56, v56
	v_fmac_f32_e32 v61, v62, v62
	v_fmac_f32_e32 v57, v58, v58
	v_add_f32_e32 v68, v62, v68
	v_fmac_f32_e32 v61, v63, v63
	v_fmac_f32_e32 v57, v59, v59
	v_add_f32_e32 v68, v63, v68
	v_add_f32_e32 v60, v58, v60
	v_add_f32_e32 v56, v61, v57
	v_add_f32_e32 v57, v52, v53
	v_add_f32_e32 v68, 0, v68
	v_add_f32_e32 v60, v59, v60
	v_add_f32_e32 v57, v54, v57
	v_add_f32_e32 v60, v68, v60
	v_add_f32_e32 v57, v55, v57
	v_add_f32_e32 v60, v60, v57
	v_mul_f32_e32 v57, v53, v53
	v_fmac_f32_e32 v57, v52, v52
	v_fmac_f32_e32 v57, v54, v54
	v_fmac_f32_e32 v57, v55, v55
	v_add_f32_e32 v61, v56, v57
	v_pk_fma_f32 v[56:57], v[64:65], s[26:27], v[48:49] op_sel_hi:[1,0,1]
	v_pk_fma_f32 v[58:59], v[66:67], s[26:27], v[50:51] op_sel_hi:[1,0,1]
	v_mul_f32_e32 v49, v57, v57
	v_add_f32_e32 v48, v56, v57
	v_fmac_f32_e32 v49, v56, v56
	v_add_f32_e32 v48, v58, v48
	v_fmac_f32_e32 v49, v58, v58
	v_add_f32_e32 v48, v59, v48
	v_fmac_f32_e32 v49, v59, v59
	v_add_f32_e32 v48, v60, v48
	v_add_f32_e32 v49, v61, v49
	ds_bpermute_b32 v50, v130, v48
	ds_bpermute_b32 v51, v130, v49
	global_store_dwordx4 v[74:75], v[56:59], off offset:528
	v_cvt_pk_bf16_f32 v52, v52, v53
	v_cvt_pk_bf16_f32 v53, v54, v55
	s_waitcnt lgkmcnt(0)
	v_add_f32_e32 v48, v48, v50
	v_add_f32_e32 v49, v49, v51
	ds_bpermute_b32 v50, v131, v48
	ds_bpermute_b32 v51, v131, v49
	v_cvt_pk_bf16_f32 v54, v56, v57
	v_cvt_pk_bf16_f32 v55, v58, v59
	flat_store_dwordx4 v[80:81], v[52:55] offset:256
	s_mov_b32 s100, -1
	s_mov_b32 s101, 0
	s_mov_b32 s98, 0xffff0000
	s_mov_b32 s99, 0
	s_and_saveexec_b64 s[30:31], s[100:101]
	s_cbranch_execz .LBB0_861
	s_waitcnt lgkmcnt(0)
	v_add_f32_e32 v51, v49, v51
	v_add_f32_e32 v50, v48, v50
	v_lshl_add_u64 v[48:49], v[72:73], 3, s[14:15]
	v_cndmask_b32_e64 v50, v50, v51, s[98:99]
	v_cndmask_b32_e64 v51, 0, 4, s[98:99]
	v_or_b32_e32 v48, v48, v51
	flat_atomic_add_f32 v[48:49], v50

; DEVI unsigned pk2(float lo, float hi) { unsigned r; asm("v_cvt_pk_bf16_f32 %0, %1, %2" : "=v"(r) : "v"(lo), "v"(hi)); return r; }
;     DEVI void operator()(const f32x4 (&acc)[2][2][4][2], const pg8::Unit& u, int wr, int wc, int fr, int fq) const {
;     ...
;                         f32x4 zz = ALPHA * xv + acc[ai][bj][m][n];
;                         if (bias) zz += *(const f32x4*)(bias + col);
;                         *(f32x4*)(zdst + (size_t)row * DM + col) = zz;
;                         sum += zz[0] + zz[1] + zz[2] + zz[3]; sq += zz[0] * zz[0] + zz[1] * zz[1] + zz[2] * zz[2] + zz[3] * zz[3];
;                         z[n] = zz;
;                     }
;                     u32x4 o; o.x = pk2(z[0][0], z[0][1]); o.y = pk2(z[0][2], z[0][3]); o.z = pk2(z[1][0], z[1][1]); o.w = pk2(z[1][2], z[1][3]);
;                     if (zb) *(u32x4*)(zb + (size_t)row * DM + colb + bj * 128) = o;
;                 }
;                 sum += __shfl_xor(sum, 16); sq += __shfl_xor(sq, 16);
;                 sum += __shfl_xor(sum, 32); sq += __shfl_xor(sq, 32);
;                 if (fq == 0) { atomicAdd(stout + 2 * (size_t)row, sum); atomicAdd(stout + 2 * (size_t)row + 1, sq); }
.LBB0_872:
	v_add_f32_e32 v52, v44, v45
	v_mul_f32_e32 v45, v45, v45
	v_fmac_f32_e32 v45, v44, v44
	v_add_f32_e32 v44, v40, v41
	v_mul_f32_e32 v41, v41, v41
	v_fmac_f32_e32 v41, v40, v40
	v_fmac_f32_e32 v45, v46, v46
	v_fmac_f32_e32 v41, v42, v42
	v_add_f32_e32 v52, v46, v52
	v_fmac_f32_e32 v45, v47, v47
	v_fmac_f32_e32 v41, v43, v43
	v_add_f32_e32 v52, v47, v52
	v_add_f32_e32 v44, v42, v44
	v_add_f32_e32 v40, v45, v41
	v_add_f32_e32 v41, v36, v37
	v_add_f32_e32 v52, 0, v52
	v_add_f32_e32 v44, v43, v44
	v_add_f32_e32 v41, v38, v41
	v_add_f32_e32 v44, v52, v44
	v_add_f32_e32 v41, v39, v41
	v_add_f32_e32 v44, v44, v41
	v_mul_f32_e32 v41, v37, v37
	v_fmac_f32_e32 v41, v36, v36
	v_fmac_f32_e32 v41, v38, v38
	v_fmac_f32_e32 v41, v39, v39
	v_add_f32_e32 v45, v40, v41
	v_pk_fma_f32 v[40:41], v[48:49], s[26:27], v[32:33] op_sel_hi:[1,0,1]
	v_pk_fma_f32 v[42:43], v[50:51], s[26:27], v[34:35] op_sel_hi:[1,0,1]
	v_mul_f32_e32 v33, v41, v41
	v_add_f32_e32 v32, v40, v41
	v_fmac_f32_e32 v33, v40, v40
	v_add_f32_e32 v32, v42, v32
	v_fmac_f32_e32 v33, v42, v42
	v_add_f32_e32 v32, v43, v32
	v_fmac_f32_e32 v33, v43, v43
	v_add_f32_e32 v32, v44, v32
	v_add_f32_e32 v33, v45, v33
	ds_bpermute_b32 v34, v130, v32
	ds_bpermute_b32 v35, v130, v33
	global_store_dwordx4 v[58:59], v[40:43], off offset:528
	v_cvt_pk_bf16_f32 v36, v36, v37
	v_cvt_pk_bf16_f32 v37, v38, v39
	s_waitcnt lgkmcnt(0)
	v_add_f32_e32 v32, v32, v34
	v_add_f32_e32 v33, v33, v35
	ds_bpermute_b32 v34, v131, v32
	ds_bpermute_b32 v35, v131, v33
	v_cvt_pk_bf16_f32 v38, v40, v41
	v_cvt_pk_bf16_f32 v39, v42, v43
	flat_store_dwordx4 v[64:65], v[36:39] offset:256
	s_mov_b32 s100, -1
	s_mov_b32 s101, 0
	s_mov_b32 s98, 0xffff0000
	s_mov_b32 s99, 0
	s_and_saveexec_b64 s[30:31], s[100:101]
	s_cbranch_execz .LBB0_874
	s_waitcnt lgkmcnt(0)
	v_add_f32_e32 v35, v33, v35
	v_add_f32_e32 v34, v32, v34
	v_lshl_add_u64 v[32:33], v[56:57], 3, s[14:15]
	v_cndmask_b32_e64 v34, v34, v35, s[98:99]
	v_cndmask_b32_e64 v35, 0, 4, s[98:99]
	v_or_b32_e32 v32, v32, v35
	flat_atomic_add_f32 v[32:33], v34

; DEVI unsigned pk2(float lo, float hi) { unsigned r; asm("v_cvt_pk_bf16_f32 %0, %1, %2" : "=v"(r) : "v"(lo), "v"(hi)); return r; }
;     DEVI void operator()(const f32x4 (&acc)[2][2][4][2], const pg8::Unit& u, int wr, int wc, int fr, int fq) const {
;     ...
;                         f32x4 zz = ALPHA * xv + acc[ai][bj][m][n];
;                         if (bias) zz += *(const f32x4*)(bias + col);
;                         *(f32x4*)(zdst + (size_t)row * DM + col) = zz;
;                         sum += zz[0] + zz[1] + zz[2] + zz[3]; sq += zz[0] * zz[0] + zz[1] * zz[1] + zz[2] * zz[2] + zz[3] * zz[3];
;                         z[n] = zz;
;                     }
;                     u32x4 o; o.x = pk2(z[0][0], z[0][1]); o.y = pk2(z[0][2], z[0][3]); o.z = pk2(z[1][0], z[1][1]); o.w = pk2(z[1][2], z[1][3]);
;                     if (zb) *(u32x4*)(zb + (size_t)row * DM + colb + bj * 128) = o;
;                 }
;                 sum += __shfl_xor(sum, 16); sq += __shfl_xor(sq, 16);
;                 sum += __shfl_xor(sum, 32); sq += __shfl_xor(sq, 32);
;                 if (fq == 0) { atomicAdd(stout + 2 * (size_t)row, sum); atomicAdd(stout + 2 * (size_t)row + 1, sq); }
.LBB0_885:
	v_add_f32_e32 v36, v28, v29
	v_mul_f32_e32 v29, v29, v29
	v_fmac_f32_e32 v29, v28, v28
	v_add_f32_e32 v28, v24, v25
	v_mul_f32_e32 v25, v25, v25
	v_fmac_f32_e32 v25, v24, v24
	v_fmac_f32_e32 v29, v30, v30
	v_fmac_f32_e32 v25, v26, v26
	v_add_f32_e32 v36, v30, v36
	v_fmac_f32_e32 v29, v31, v31
	v_fmac_f32_e32 v25, v27, v27
	v_add_f32_e32 v36, v31, v36
	v_add_f32_e32 v28, v26, v28
	v_add_f32_e32 v24, v29, v25
	v_add_f32_e32 v25, v20, v21
	v_add_f32_e32 v36, 0, v36
	v_add_f32_e32 v28, v27, v28
	v_add_f32_e32 v25, v22, v25
	v_add_f32_e32 v28, v36, v28
	v_add_f32_e32 v25, v23, v25
	v_add_f32_e32 v28, v28, v25
	v_mul_f32_e32 v25, v21, v21
	v_fmac_f32_e32 v25, v20, v20
	v_fmac_f32_e32 v25, v22, v22
	v_fmac_f32_e32 v25, v23, v23
	v_add_f32_e32 v29, v24, v25
	v_pk_fma_f32 v[24:25], v[32:33], s[26:27], v[16:17] op_sel_hi:[1,0,1]
	v_pk_fma_f32 v[26:27], v[34:35], s[26:27], v[18:19] op_sel_hi:[1,0,1]
	v_mul_f32_e32 v17, v25, v25
	v_add_f32_e32 v16, v24, v25
	v_fmac_f32_e32 v17, v24, v24
	v_add_f32_e32 v16, v26, v16
	v_fmac_f32_e32 v17, v26, v26
	v_add_f32_e32 v16, v27, v16
	v_fmac_f32_e32 v17, v27, v27
	v_add_f32_e32 v16, v28, v16
	v_add_f32_e32 v17, v29, v17
	ds_bpermute_b32 v18, v130, v16
	ds_bpermute_b32 v19, v130, v17
	global_store_dwordx4 v[42:43], v[24:27], off offset:528
	v_cvt_pk_bf16_f32 v20, v20, v21
	v_cvt_pk_bf16_f32 v21, v22, v23
	s_waitcnt lgkmcnt(0)
	v_add_f32_e32 v16, v16, v18
	v_add_f32_e32 v17, v17, v19
	ds_bpermute_b32 v18, v131, v16
	ds_bpermute_b32 v19, v131, v17
	v_cvt_pk_bf16_f32 v22, v24, v25
	v_cvt_pk_bf16_f32 v23, v26, v27
	flat_store_dwordx4 v[48:49], v[20:23] offset:256
	s_mov_b32 s100, -1
	s_mov_b32 s101, 0
	s_mov_b32 s98, 0xffff0000
	s_mov_b32 s99, 0
	s_and_saveexec_b64 s[30:31], s[100:101]
	s_cbranch_execz .LBB0_887
	s_waitcnt lgkmcnt(0)
	v_add_f32_e32 v19, v17, v19
	v_add_f32_e32 v18, v16, v18
	v_lshl_add_u64 v[16:17], v[40:41], 3, s[14:15]
	v_cndmask_b32_e64 v18, v18, v19, s[98:99]
	v_cndmask_b32_e64 v19, 0, 4, s[98:99]
	v_or_b32_e32 v16, v16, v19
	flat_atomic_add_f32 v[16:17], v18

; DEVI unsigned pk2(float lo, float hi) { unsigned r; asm("v_cvt_pk_bf16_f32 %0, %1, %2" : "=v"(r) : "v"(lo), "v"(hi)); return r; }
;     DEVI void operator()(const f32x4 (&acc)[2][2][4][2], const pg8::Unit& u, int wr, int wc, int fr, int fq) const {
;     ...
;                         f32x4 zz = ALPHA * xv + acc[ai][bj][m][n];
;                         if (bias) zz += *(const f32x4*)(bias + col);
;                         *(f32x4*)(zdst + (size_t)row * DM + col) = zz;
;                         sum += zz[0] + zz[1] + zz[2] + zz[3]; sq += zz[0] * zz[0] + zz[1] * zz[1] + zz[2] * zz[2] + zz[3] * zz[3];
;                         z[n] = zz;
;                     }
;                     u32x4 o; o.x = pk2(z[0][0], z[0][1]); o.y = pk2(z[0][2], z[0][3]); o.z = pk2(z[1][0], z[1][1]); o.w = pk2(z[1][2], z[1][3]);
;                     if (zb) *(u32x4*)(zb + (size_t)row * DM + colb + bj * 128) = o;
;                 }
;                 sum += __shfl_xor(sum, 16); sq += __shfl_xor(sq, 16);
;                 sum += __shfl_xor(sum, 32); sq += __shfl_xor(sq, 32);
;                 if (fq == 0) { atomicAdd(stout + 2 * (size_t)row, sum); atomicAdd(stout + 2 * (size_t)row + 1, sq); }
.LBB0_898:
	v_add_f32_e32 v20, v12, v13
	v_mul_f32_e32 v13, v13, v13
	v_fmac_f32_e32 v13, v12, v12
	v_add_f32_e32 v12, v8, v9
	v_mul_f32_e32 v9, v9, v9
	v_fmac_f32_e32 v9, v8, v8
	v_fmac_f32_e32 v13, v14, v14
	v_fmac_f32_e32 v9, v10, v10
	v_add_f32_e32 v20, v14, v20
	v_fmac_f32_e32 v13, v15, v15
	v_fmac_f32_e32 v9, v11, v11
	v_add_f32_e32 v20, v15, v20
	v_add_f32_e32 v12, v10, v12
	v_add_f32_e32 v8, v13, v9
	v_add_f32_e32 v9, v4, v5
	v_add_f32_e32 v20, 0, v20
	v_add_f32_e32 v12, v11, v12
	v_add_f32_e32 v9, v6, v9
	v_add_f32_e32 v12, v20, v12
	v_add_f32_e32 v9, v7, v9
	v_add_f32_e32 v12, v12, v9
	v_mul_f32_e32 v9, v5, v5
	v_fmac_f32_e32 v9, v4, v4
	v_fmac_f32_e32 v9, v6, v6
	v_fmac_f32_e32 v9, v7, v7
	v_add_f32_e32 v13, v8, v9
	v_pk_fma_f32 v[8:9], v[16:17], s[26:27], v[0:1] op_sel_hi:[1,0,1]
	v_pk_fma_f32 v[10:11], v[18:19], s[26:27], v[2:3] op_sel_hi:[1,0,1]
	v_mul_f32_e32 v1, v9, v9
	v_add_f32_e32 v0, v8, v9
	v_fmac_f32_e32 v1, v8, v8
	v_add_f32_e32 v0, v10, v0
	v_fmac_f32_e32 v1, v10, v10
	v_add_f32_e32 v0, v11, v0
	v_fmac_f32_e32 v1, v11, v11
	v_add_f32_e32 v0, v12, v0
	v_add_f32_e32 v1, v13, v1
	ds_bpermute_b32 v2, v130, v0
	ds_bpermute_b32 v3, v130, v1
	global_store_dwordx4 v[26:27], v[8:11], off offset:528
	v_cvt_pk_bf16_f32 v4, v4, v5
	v_cvt_pk_bf16_f32 v5, v6, v7
	s_waitcnt lgkmcnt(0)
	v_add_f32_e32 v0, v0, v2
	v_add_f32_e32 v1, v1, v3
	ds_bpermute_b32 v2, v131, v0
	ds_bpermute_b32 v3, v131, v1
	v_cvt_pk_bf16_f32 v6, v8, v9
	v_cvt_pk_bf16_f32 v7, v10, v11
	flat_store_dwordx4 v[32:33], v[4:7] offset:256
	s_mov_b32 s100, -1
	s_mov_b32 s101, 0
	s_mov_b32 s98, 0xffff0000
	s_mov_b32 s99, 0
	s_and_saveexec_b64 s[6:7], s[100:101]
	s_cbranch_execz .LBB0_900
	s_waitcnt lgkmcnt(0)
	v_add_f32_e32 v3, v1, v3
	v_add_f32_e32 v2, v0, v2
	v_lshl_add_u64 v[0:1], v[24:25], 3, s[14:15]
	v_cndmask_b32_e64 v2, v2, v3, s[98:99]
	v_cndmask_b32_e64 v3, 0, 4, s[98:99]
	v_or_b32_e32 v0, v0, v3
	flat_atomic_add_f32 v[0:1], v2

; DEVI unsigned pk2(float lo, float hi) { unsigned r; asm("v_cvt_pk_bf16_f32 %0, %1, %2" : "=v"(r) : "v"(lo), "v"(hi)); return r; }
; DEVI void row_stats(const float* stats, int row, float& mu, float& rs) {
;     if (stats) { const float2 st = *(const float2*)(stats + 2 * (size_t)row); mu = st.x * (1.0f / 1024.0f); const float var = st.y * (1.0f / 1024.0f) - mu * mu; rs = rsqrtf(fmaxf(var, 0.f) + LN_EPS); }
;     DEVI void operator()(const f32x4 (&acc)[2][2][4][2], const pg8::Unit& u, int wr, int wc, int fr, int fq) const {
;     ...
;                 const int row = row0 + ai * 128 + m * 16; float mu, rs; row_stats(stin, row, mu, rs);
;                 float sum = 0.f, sq = 0.f;
; #pragma unroll
;                 for (int bj = 0; bj < 2; ++bj) {
;                     f32x4 z[2];
; #pragma unroll
;                     for (int n = 0; n < 2; ++n) {
;                         const int col = colb + bj * 128 + 4 * n;
;                         f32x4 xv = *(const f32x4*)(zsrc + (size_t)row * DM + col);
;                         if (stin) { const f32x4 gv = *(const f32x4*)(gin + col), bv = *(const f32x4*)(bin + col); xv = (xv - mu) * rs * gv + bv; }
;                         f32x4 zz = ALPHA * xv + acc[ai][bj][m][n];
;                         if (bias) zz += *(const f32x4*)(bias + col);
;                         *(f32x4*)(zdst + (size_t)row * DM + col) = zz;
;                         sum += zz[0] + zz[1] + zz[2] + zz[3]; sq += zz[0] * zz[0] + zz[1] * zz[1] + zz[2] * zz[2] + zz[3] * zz[3];
;                         z[n] = zz;
;                     }
;                     u32x4 o; o.x = pk2(z[0][0], z[0][1]); o.y = pk2(z[0][2], z[0][3]); o.z = pk2(z[1][0], z[1][1]); o.w = pk2(z[1][2], z[1][3]);
;                     if (zb) *(u32x4*)(zb + (size_t)row * DM + colb + bj * 128) = o;
;                 }
;                 sum += __shfl_xor(sum, 16); sq += __shfl_xor(sq, 16);
;                 sum += __shfl_xor(sum, 32); sq += __shfl_xor(sq, 32);
;                 if (fq == 0) { atomicAdd(stout + 2 * (size_t)row, sum); atomicAdd(stout + 2 * (size_t)row + 1, sq); }
.LBB0_1329:
	v_lshl_add_u32 v150, s30, 8, v162
	v_ashrrev_i32_e32 v151, 31, v150
	v_lshlrev_b64 v[156:157], 3, v[150:151]
	v_lshl_add_u64 v[144:145], s[6:7], 0, v[156:157]
	s_waitcnt vmcnt(0)
	flat_load_dwordx2 v[154:155], v[144:145]
	v_lshl_or_b32 v148, s34, 8, v164
	v_ashrrev_i32_e32 v149, 31, v148
	v_lshlrev_b64 v[144:145], 12, v[150:151]
	v_lshl_add_u64 v[144:145], s[46:47], 0, v[144:145]
	v_lshlrev_b64 v[152:153], 2, v[148:149]
	v_lshl_add_u64 v[158:159], v[144:145], 0, v[152:153]
	v_readlane_b32 s68, v249, 37
	global_load_dwordx4 v[170:173], v[158:159], off
	v_readlane_b32 s82, v249, 51
	v_readlane_b32 s83, v249, 52
	v_lshl_add_u64 v[146:147], s[44:45], 0, v[152:153]
	v_readlane_b32 s69, v249, 38
	v_lshl_add_u64 v[144:145], s[82:83], 0, v[152:153]
	global_load_dwordx4 v[174:177], v[144:145], off
	global_load_dwordx4 v[178:181], v[146:147], off
	v_lshl_add_u64 v[152:153], s[12:13], 0, v[152:153]
	global_load_dwordx4 v[182:185], v[152:153], off
	global_load_dwordx4 v[186:189], v[158:159], off offset:16
	v_readlane_b32 s70, v249, 39
	v_readlane_b32 s71, v249, 40
	v_readlane_b32 s72, v249, 41
	v_readlane_b32 s73, v249, 42
	v_readlane_b32 s74, v249, 43
	v_readlane_b32 s75, v249, 44
	v_readlane_b32 s76, v249, 45
	v_readlane_b32 s77, v249, 46
	v_readlane_b32 s78, v249, 47
	v_readlane_b32 s79, v249, 48
	v_readlane_b32 s80, v249, 49
	v_readlane_b32 s81, v249, 50
	s_waitcnt vmcnt(0) lgkmcnt(0)
	v_pk_mul_f32 v[160:161], v[154:155], s[18:19] op_sel:[1,0] op_sel_hi:[0,0]
	v_fma_f32 v154, -v161, v161, v160
	v_max_f32_e32 v154, 0, v154
	v_add_f32_e32 v154, 0x3727c5ac, v154
	v_mul_f32_e32 v160, 0x4b800000, v154
	v_cmp_gt_f32_e32 vcc, s64, v154
	v_sub_f32_e32 v155, v173, v161
	s_nop 0
	v_cndmask_b32_e32 v154, v154, v160, vcc
	v_rsq_f32_e32 v160, v154
	v_sub_f32_e32 v154, v172, v161
	v_sub_f32_e32 v171, v171, v161
	v_sub_f32_e32 v170, v170, v161
	v_mul_f32_e32 v169, 0x45800000, v160
	v_cndmask_b32_e32 v160, v160, v169, vcc
	v_pk_mul_f32 v[170:171], v[170:171], v[160:161] op_sel_hi:[1,0]
	v_pk_mul_f32 v[154:155], v[154:155], v[160:161] op_sel_hi:[1,0]
	v_pk_fma_f32 v[170:171], v[174:175], v[170:171], v[178:179]
	v_pk_fma_f32 v[154:155], v[176:177], v[154:155], v[180:181]
	v_pk_fma_f32 v[124:125], v[170:171], s[20:21], v[124:125] op_sel_hi:[1,0,1]
	v_pk_fma_f32 v[126:127], v[154:155], s[20:21], v[126:127] op_sel_hi:[1,0,1]
	v_pk_add_f32 v[124:125], v[182:183], v[124:125]
	v_pk_add_f32 v[126:127], v[184:185], v[126:127]
	global_store_dwordx4 v[158:159], v[124:127], off
	v_or_b32_e32 v154, 4, v148
	global_load_dwordx4 v[170:173], v[144:145], off offset:16
	global_load_dwordx4 v[174:177], v[146:147], off offset:16
	v_ashrrev_i32_e32 v155, 31, v154
	v_lshl_add_u64 v[154:155], v[154:155], 2, s[12:13]
	global_load_dwordx4 v[178:181], v[154:155], off
	v_lshlrev_b64 v[182:183], 11, v[150:151]
	v_lshl_add_u64 v[182:183], s[10:11], 0, v[182:183]
	v_lshl_add_u64 v[194:195], v[148:149], 1, v[182:183]
	v_sub_f32_e32 v183, v189, v161
	v_sub_f32_e32 v182, v188, v161
	v_sub_f32_e32 v185, v187, v161
	v_sub_f32_e32 v184, v186, v161
	v_pk_mul_f32 v[184:185], v[184:185], v[160:161] op_sel_hi:[1,0]
	v_pk_mul_f32 v[186:187], v[182:183], v[160:161] op_sel_hi:[1,0]
	v_cvt_pk_bf16_f32 v182, v124, v125
	v_cvt_pk_bf16_f32 v183, v126, v127
	s_waitcnt vmcnt(1)
	v_pk_fma_f32 v[170:171], v[170:171], v[184:185], v[174:175]
	v_pk_fma_f32 v[172:173], v[172:173], v[186:187], v[176:177]
	v_pk_fma_f32 v[120:121], v[170:171], s[20:21], v[120:121] op_sel_hi:[1,0,1]
	v_pk_fma_f32 v[122:123], v[172:173], s[20:21], v[122:123] op_sel_hi:[1,0,1]
	s_waitcnt vmcnt(0)
	v_pk_add_f32 v[170:171], v[178:179], v[120:121]
	v_pk_add_f32 v[172:173], v[180:181], v[122:123]
	global_store_dwordx4 v[158:159], v[170:173], off offset:16
	v_cvt_pk_bf16_f32 v184, v170, v171
	v_cvt_pk_bf16_f32 v185, v172, v173
	flat_store_dwordx4 v[194:195], v[182:185]
	global_load_dwordx4 v[174:177], v[158:159], off offset:512
	global_load_dwordx4 v[178:181], v[144:145], off offset:512
	s_nop 0
	global_load_dwordx4 v[182:185], v[146:147], off offset:512
	v_or_b32_e32 v120, 0x80, v148
	v_ashrrev_i32_e32 v121, 31, v120
	v_lshl_add_u64 v[120:121], v[120:121], 2, s[12:13]
	global_load_dwordx4 v[186:189], v[120:121], off
	global_load_dwordx4 v[190:193], v[158:159], off offset:528
	s_waitcnt vmcnt(0)
	v_sub_f32_e32 v123, v177, v161
	v_sub_f32_e32 v122, v176, v161
	v_sub_f32_e32 v175, v175, v161
	v_sub_f32_e32 v174, v174, v161
	v_pk_mul_f32 v[174:175], v[160:161], v[174:175] op_sel_hi:[0,1]
	v_pk_mul_f32 v[122:123], v[160:161], v[122:123] op_sel_hi:[0,1]
	v_pk_fma_f32 v[122:123], v[180:181], v[122:123], v[184:185]
	v_pk_fma_f32 v[174:175], v[178:179], v[174:175], v[182:183]
	v_pk_fma_f32 v[118:119], v[122:123], s[20:21], v[118:119] op_sel_hi:[1,0,1]
	v_pk_fma_f32 v[116:117], v[174:175], s[20:21], v[116:117] op_sel_hi:[1,0,1]
	v_pk_add_f32 v[176:177], v[188:189], v[118:119]
	v_pk_add_f32 v[174:175], v[186:187], v[116:117]
	global_store_dwordx4 v[158:159], v[174:177], off offset:512
	v_or_b32_e32 v116, 0x84, v148
	global_load_dwordx4 v[178:181], v[144:145], off offset:528
	global_load_dwordx4 v[182:185], v[146:147], off offset:528
	v_ashrrev_i32_e32 v117, 31, v116
	v_lshl_add_u64 v[116:117], v[116:117], 2, s[12:13]
	global_load_dwordx4 v[186:189], v[116:117], off
	v_and_b32_e32 v119, 64, v168
	v_xor_b32_e32 v118, 16, v168
	v_add_u32_e32 v119, 64, v119
	v_xor_b32_e32 v122, 32, v168
	v_cmp_lt_i32_e32 vcc, v118, v119
	v_mul_f32_e32 v123, v125, v125
	v_fmac_f32_e32 v123, v124, v124
	v_cndmask_b32_e32 v118, v168, v118, vcc
	v_cmp_lt_i32_e32 vcc, v122, v119
	v_fmac_f32_e32 v123, v126, v126
	v_fmac_f32_e32 v123, v127, v127
	v_cndmask_b32_e32 v119, v168, v122, vcc
	v_add_f32_e32 v122, v124, v125
	v_mul_f32_e32 v125, v171, v171
	v_add_f32_e32 v122, v126, v122
	v_add_f32_e32 v124, v170, v171
	v_fmac_f32_e32 v125, v170, v170
	v_add_f32_e32 v122, v127, v122
	v_add_f32_e32 v124, v172, v124
	v_fmac_f32_e32 v125, v172, v172
	v_add_f32_e32 v122, 0, v122
	v_add_f32_e32 v124, v173, v124
	v_fmac_f32_e32 v125, v173, v173
	v_add_f32_e32 v126, v124, v122
	v_add_f32_e32 v127, v123, v125
	v_sub_f32_e32 v125, v191, v161
	v_sub_f32_e32 v124, v190, v161
	v_sub_f32_e32 v123, v193, v161
	v_sub_f32_e32 v122, v192, v161
	v_pk_mul_f32 v[124:125], v[160:161], v[124:125] op_sel_hi:[0,1]
	v_pk_mul_f32 v[122:123], v[160:161], v[122:123] op_sel_hi:[0,1]
	v_mul_f32_e32 v160, v175, v175
	v_add_f32_e32 v151, v174, v175
	v_fmac_f32_e32 v160, v174, v174
	v_add_f32_e32 v151, v176, v151
	v_fmac_f32_e32 v160, v176, v176
	v_add_f32_e32 v151, v177, v151
	v_fmac_f32_e32 v160, v177, v177
	v_add_f32_e32 v126, v126, v151
	v_add_f32_e32 v127, v127, v160
	v_lshlrev_b32_e32 v118, 2, v118
	v_lshlrev_b32_e32 v119, 2, v119
	v_cvt_pk_bf16_f32 v170, v174, v175
	v_cvt_pk_bf16_f32 v171, v176, v177
	s_waitcnt vmcnt(0)
; DEVI unsigned pk2(float lo, float hi) { unsigned r; asm("v_cvt_pk_bf16_f32 %0, %1, %2" : "=v"(r) : "v"(lo), "v"(hi)); return r; }
; DEVI void row_stats(const float* stats, int row, float& mu, float& rs) {
;     if (stats) { const float2 st = *(const float2*)(stats + 2 * (size_t)row); mu = st.x * (1.0f / 1024.0f); const float var = st.y * (1.0f / 1024.0f) - mu * mu; rs = rsqrtf(fmaxf(var, 0.f) + LN_EPS); }
;     DEVI void operator()(const f32x4 (&acc)[2][2][4][2], const pg8::Unit& u, int wr, int wc, int fr, int fq) const {
;     ...
;                 const int row = row0 + ai * 128 + m * 16; float mu, rs; row_stats(stin, row, mu, rs);
;                 float sum = 0.f, sq = 0.f;
; #pragma unroll
;                 for (int bj = 0; bj < 2; ++bj) {
;                     f32x4 z[2];
; #pragma unroll
;                     for (int n = 0; n < 2; ++n) {
;                         const int col = colb + bj * 128 + 4 * n;
;                         f32x4 xv = *(const f32x4*)(zsrc + (size_t)row * DM + col);
;                         if (stin) { const f32x4 gv = *(const f32x4*)(gin + col), bv = *(const f32x4*)(bin + col); xv = (xv - mu) * rs * gv + bv; }
;                         f32x4 zz = ALPHA * xv + acc[ai][bj][m][n];
;                         if (bias) zz += *(const f32x4*)(bias + col);
;                         *(f32x4*)(zdst + (size_t)row * DM + col) = zz;
;                         sum += zz[0] + zz[1] + zz[2] + zz[3]; sq += zz[0] * zz[0] + zz[1] * zz[1] + zz[2] * zz[2] + zz[3] * zz[3];
;                         z[n] = zz;
;                     }
;                     u32x4 o; o.x = pk2(z[0][0], z[0][1]); o.y = pk2(z[0][2], z[0][3]); o.z = pk2(z[1][0], z[1][1]); o.w = pk2(z[1][2], z[1][3]);
;                     if (zb) *(u32x4*)(zb + (size_t)row * DM + colb + bj * 128) = o;
;                 }
;                 sum += __shfl_xor(sum, 16); sq += __shfl_xor(sq, 16);
;                 sum += __shfl_xor(sum, 32); sq += __shfl_xor(sq, 32);
;                 if (fq == 0) { atomicAdd(stout + 2 * (size_t)row, sum); atomicAdd(stout + 2 * (size_t)row + 1, sq); }
	v_pk_fma_f32 v[124:125], v[178:179], v[124:125], v[182:183]
	v_pk_fma_f32 v[122:123], v[180:181], v[122:123], v[184:185]
	v_pk_fma_f32 v[112:113], v[124:125], s[20:21], v[112:113] op_sel_hi:[1,0,1]
	v_pk_fma_f32 v[114:115], v[122:123], s[20:21], v[114:115] op_sel_hi:[1,0,1]
	v_pk_add_f32 v[122:123], v[186:187], v[112:113]
	v_pk_add_f32 v[124:125], v[188:189], v[114:115]
	v_mul_f32_e32 v113, v123, v123
	v_add_f32_e32 v112, v122, v123
	v_fmac_f32_e32 v113, v122, v122
	v_add_f32_e32 v112, v124, v112
	v_fmac_f32_e32 v113, v124, v124
	v_add_f32_e32 v112, v125, v112
	v_fmac_f32_e32 v113, v125, v125
	v_add_f32_e32 v112, v126, v112
	v_add_f32_e32 v113, v127, v113
	ds_bpermute_b32 v114, v118, v112
	ds_bpermute_b32 v115, v118, v113
	global_store_dwordx4 v[158:159], v[122:125], off offset:528
	v_cvt_pk_bf16_f32 v172, v122, v123
	v_cvt_pk_bf16_f32 v173, v124, v125
	s_waitcnt lgkmcnt(0)
	v_add_f32_e32 v112, v112, v114
	v_add_f32_e32 v113, v113, v115
	ds_bpermute_b32 v114, v119, v112
	ds_bpermute_b32 v115, v119, v113
	flat_store_dwordx4 v[194:195], v[170:173] offset:256
	s_mov_b32 s100, -1
	s_mov_b32 s101, 0
	s_mov_b32 s98, 0xffff0000
	s_mov_b32 s99, 0
	s_and_saveexec_b64 s[30:31], s[100:101]
	s_cbranch_execz .LBB0_1331
	v_lshl_add_u64 v[122:123], s[8:9], 0, v[156:157]
	s_waitcnt lgkmcnt(0)
	v_add_f32_e32 v112, v112, v114
	v_add_f32_e32 v113, v113, v115
	v_cndmask_b32_e64 v112, v112, v113, s[98:99]
	v_cndmask_b32_e64 v113, 0, 4, s[98:99]
	v_or_b32_e32 v122, v122, v113
	flat_atomic_add_f32 v[122:123], v112
.LBB0_1331:
	s_or_b64 exec, exec, s[30:31]
	v_or_b32_e32 v126, 16, v150
	v_ashrrev_i32_e32 v127, 31, v126
	v_lshlrev_b64 v[112:113], 3, v[126:127]
	s_waitcnt lgkmcnt(0)
	v_lshl_add_u64 v[114:115], s[6:7], 0, v[112:113]
	flat_load_dwordx2 v[160:161], v[114:115]
	v_lshlrev_b64 v[114:115], 12, v[126:127]
	v_lshl_add_u64 v[114:115], s[46:47], 0, v[114:115]
	v_lshl_add_u64 v[114:115], v[148:149], 2, v[114:115]
	global_load_dwordx4 v[122:125], v[114:115], off
	global_load_dwordx4 v[156:159], v[144:145], off
	global_load_dwordx4 v[170:173], v[146:147], off
	global_load_dwordx4 v[174:177], v[152:153], off
	global_load_dwordx4 v[178:181], v[114:115], off offset:16
	v_lshlrev_b64 v[126:127], 11, v[126:127]
	v_lshl_add_u64 v[126:127], s[10:11], 0, v[126:127]
	v_lshl_add_u64 v[126:127], v[148:149], 1, v[126:127]
	s_waitcnt vmcnt(0) lgkmcnt(0)
	v_pk_mul_f32 v[160:161], v[160:161], s[18:19] op_sel:[1,0] op_sel_hi:[0,0]
	v_fma_f32 v151, -v161, v161, v160
	v_max_f32_e32 v151, 0, v151
	v_add_f32_e32 v151, 0x3727c5ac, v151
	v_mul_f32_e32 v160, 0x4b800000, v151
	v_cmp_gt_f32_e32 vcc, s64, v151
	v_sub_f32_e32 v125, v125, v161
	v_sub_f32_e32 v124, v124, v161
	v_cndmask_b32_e32 v151, v151, v160, vcc
	v_rsq_f32_e32 v151, v151
	v_sub_f32_e32 v123, v123, v161
	v_sub_f32_e32 v122, v122, v161
	v_mul_f32_e32 v160, 0x45800000, v151
	v_cndmask_b32_e32 v160, v151, v160, vcc
	v_pk_mul_f32 v[122:123], v[122:123], v[160:161] op_sel_hi:[1,0]
	v_pk_mul_f32 v[124:125], v[124:125], v[160:161] op_sel_hi:[1,0]
	v_pk_fma_f32 v[122:123], v[156:157], v[122:123], v[170:171]
	v_pk_fma_f32 v[124:125], v[158:159], v[124:125], v[172:173]
	v_pk_fma_f32 v[108:109], v[122:123], s[20:21], v[108:109] op_sel_hi:[1,0,1]
	v_pk_fma_f32 v[110:111], v[124:125], s[20:21], v[110:111] op_sel_hi:[1,0,1]
	v_pk_add_f32 v[108:109], v[174:175], v[108:109]
	v_pk_add_f32 v[110:111], v[176:177], v[110:111]
	global_store_dwordx4 v[114:115], v[108:111], off
	global_load_dwordx4 v[122:125], v[144:145], off offset:16
	global_load_dwordx4 v[156:159], v[146:147], off offset:16
	global_load_dwordx4 v[170:173], v[154:155], off
	v_sub_f32_e32 v175, v181, v161
	v_sub_f32_e32 v174, v180, v161
	v_sub_f32_e32 v177, v179, v161
	v_sub_f32_e32 v176, v178, v161
	v_pk_mul_f32 v[176:177], v[176:177], v[160:161] op_sel_hi:[1,0]
	v_pk_mul_f32 v[178:179], v[174:175], v[160:161] op_sel_hi:[1,0]
	v_cvt_pk_bf16_f32 v174, v108, v109
	v_cvt_pk_bf16_f32 v175, v110, v111
	v_add_f32_e32 v151, v108, v109
	v_mul_f32_e32 v109, v109, v109
	v_fmac_f32_e32 v109, v108, v108
	v_add_f32_e32 v151, v110, v151
	v_fmac_f32_e32 v109, v110, v110
	v_add_f32_e32 v108, v111, v151
	v_add_f32_e32 v108, 0, v108
	v_fmac_f32_e32 v109, v111, v111
	s_waitcnt vmcnt(1)
	v_pk_fma_f32 v[124:125], v[124:125], v[178:179], v[158:159]
	v_pk_fma_f32 v[122:123], v[122:123], v[176:177], v[156:157]
	v_pk_fma_f32 v[106:107], v[124:125], s[20:21], v[106:107] op_sel_hi:[1,0,1]
	v_pk_fma_f32 v[104:105], v[122:123], s[20:21], v[104:105] op_sel_hi:[1,0,1]
	s_waitcnt vmcnt(0)
	v_pk_add_f32 v[106:107], v[172:173], v[106:107]
	v_pk_add_f32 v[104:105], v[170:171], v[104:105]
	global_store_dwordx4 v[114:115], v[104:107], off offset:16
	v_cvt_pk_bf16_f32 v176, v104, v105
	v_cvt_pk_bf16_f32 v177, v106, v107
	flat_store_dwordx4 v[126:127], v[174:177]
	global_load_dwordx4 v[122:125], v[114:115], off offset:512
	global_load_dwordx4 v[156:159], v[144:145], off offset:512
	global_load_dwordx4 v[170:173], v[146:147], off offset:512
	s_nop 0
	global_load_dwordx4 v[174:177], v[120:121], off
	global_load_dwordx4 v[178:181], v[114:115], off offset:528
	v_add_f32_e32 v110, v104, v105
	v_mul_f32_e32 v105, v105, v105
	v_fmac_f32_e32 v105, v104, v104
	v_add_f32_e32 v110, v106, v110
	v_fmac_f32_e32 v105, v106, v106
	v_add_f32_e32 v104, v107, v110
	v_fmac_f32_e32 v105, v107, v107
	v_add_f32_e32 v108, v104, v108
	v_add_f32_e32 v109, v109, v105
	s_waitcnt vmcnt(0)
; DEVI unsigned pk2(float lo, float hi) { unsigned r; asm("v_cvt_pk_bf16_f32 %0, %1, %2" : "=v"(r) : "v"(lo), "v"(hi)); return r; }
; DEVI void row_stats(const float* stats, int row, float& mu, float& rs) {
;     if (stats) { const float2 st = *(const float2*)(stats + 2 * (size_t)row); mu = st.x * (1.0f / 1024.0f); const float var = st.y * (1.0f / 1024.0f) - mu * mu; rs = rsqrtf(fmaxf(var, 0.f) + LN_EPS); }
;     DEVI void operator()(const f32x4 (&acc)[2][2][4][2], const pg8::Unit& u, int wr, int wc, int fr, int fq) const {
;     ...
;                 const int row = row0 + ai * 128 + m * 16; float mu, rs; row_stats(stin, row, mu, rs);
;                 float sum = 0.f, sq = 0.f;
; #pragma unroll
;                 for (int bj = 0; bj < 2; ++bj) {
;                     f32x4 z[2];
; #pragma unroll
;                     for (int n = 0; n < 2; ++n) {
;                         const int col = colb + bj * 128 + 4 * n;
;                         f32x4 xv = *(const f32x4*)(zsrc + (size_t)row * DM + col);
;                         if (stin) { const f32x4 gv = *(const f32x4*)(gin + col), bv = *(const f32x4*)(bin + col); xv = (xv - mu) * rs * gv + bv; }
;                         f32x4 zz = ALPHA * xv + acc[ai][bj][m][n];
;                         if (bias) zz += *(const f32x4*)(bias + col);
;                         *(f32x4*)(zdst + (size_t)row * DM + col) = zz;
;                         sum += zz[0] + zz[1] + zz[2] + zz[3]; sq += zz[0] * zz[0] + zz[1] * zz[1] + zz[2] * zz[2] + zz[3] * zz[3];
;                         z[n] = zz;
;                     }
;                     u32x4 o; o.x = pk2(z[0][0], z[0][1]); o.y = pk2(z[0][2], z[0][3]); o.z = pk2(z[1][0], z[1][1]); o.w = pk2(z[1][2], z[1][3]);
;                     if (zb) *(u32x4*)(zb + (size_t)row * DM + colb + bj * 128) = o;
;                 }
;                 sum += __shfl_xor(sum, 16); sq += __shfl_xor(sq, 16);
;                 sum += __shfl_xor(sum, 32); sq += __shfl_xor(sq, 32);
;                 if (fq == 0) { atomicAdd(stout + 2 * (size_t)row, sum); atomicAdd(stout + 2 * (size_t)row + 1, sq); }
	v_sub_f32_e32 v125, v125, v161
	v_sub_f32_e32 v124, v124, v161
	v_sub_f32_e32 v123, v123, v161
	v_sub_f32_e32 v122, v122, v161
	v_pk_mul_f32 v[122:123], v[160:161], v[122:123] op_sel_hi:[0,1]
	v_pk_mul_f32 v[124:125], v[160:161], v[124:125] op_sel_hi:[0,1]
	v_pk_fma_f32 v[124:125], v[158:159], v[124:125], v[172:173]
	v_pk_fma_f32 v[122:123], v[156:157], v[122:123], v[170:171]
	v_pk_fma_f32 v[102:103], v[124:125], s[20:21], v[102:103] op_sel_hi:[1,0,1]
	v_pk_fma_f32 v[100:101], v[122:123], s[20:21], v[100:101] op_sel_hi:[1,0,1]
	v_pk_add_f32 v[102:103], v[176:177], v[102:103]
	v_pk_add_f32 v[100:101], v[174:175], v[100:101]
	global_store_dwordx4 v[114:115], v[100:103], off offset:512
	global_load_dwordx4 v[122:125], v[144:145], off offset:528
	global_load_dwordx4 v[156:159], v[146:147], off offset:528
	global_load_dwordx4 v[170:173], v[116:117], off
	v_sub_f32_e32 v107, v179, v161
	v_sub_f32_e32 v106, v178, v161
	v_sub_f32_e32 v105, v181, v161
	v_sub_f32_e32 v104, v180, v161
	v_pk_mul_f32 v[106:107], v[160:161], v[106:107] op_sel_hi:[0,1]
	v_pk_mul_f32 v[104:105], v[160:161], v[104:105] op_sel_hi:[0,1]
	v_mul_f32_e32 v111, v101, v101
	v_add_f32_e32 v110, v100, v101
	v_fmac_f32_e32 v111, v100, v100
	v_add_f32_e32 v110, v102, v110
	v_fmac_f32_e32 v111, v102, v102
	v_add_f32_e32 v110, v103, v110
	v_fmac_f32_e32 v111, v103, v103
	v_add_f32_e32 v108, v108, v110
	v_add_f32_e32 v109, v109, v111
	v_cvt_pk_bf16_f32 v100, v100, v101
	v_cvt_pk_bf16_f32 v101, v102, v103
	s_waitcnt vmcnt(0)
	v_pk_fma_f32 v[106:107], v[122:123], v[106:107], v[156:157]
	v_pk_fma_f32 v[104:105], v[124:125], v[104:105], v[158:159]
	v_pk_fma_f32 v[96:97], v[106:107], s[20:21], v[96:97] op_sel_hi:[1,0,1]
	v_pk_fma_f32 v[98:99], v[104:105], s[20:21], v[98:99] op_sel_hi:[1,0,1]
	v_pk_add_f32 v[104:105], v[170:171], v[96:97]
	v_pk_add_f32 v[106:107], v[172:173], v[98:99]
	v_mul_f32_e32 v97, v105, v105
	v_add_f32_e32 v96, v104, v105
	v_fmac_f32_e32 v97, v104, v104
	v_add_f32_e32 v96, v106, v96
	v_fmac_f32_e32 v97, v106, v106
	v_add_f32_e32 v96, v107, v96
	v_fmac_f32_e32 v97, v107, v107
	v_add_f32_e32 v96, v108, v96
	v_add_f32_e32 v97, v109, v97
	ds_bpermute_b32 v98, v118, v96
	ds_bpermute_b32 v99, v118, v97
	global_store_dwordx4 v[114:115], v[104:107], off offset:528
	v_cvt_pk_bf16_f32 v102, v104, v105
	v_cvt_pk_bf16_f32 v103, v106, v107
	s_waitcnt lgkmcnt(0)
	v_add_f32_e32 v96, v96, v98
	v_add_f32_e32 v97, v97, v99
	ds_bpermute_b32 v98, v119, v96
	ds_bpermute_b32 v99, v119, v97
	flat_store_dwordx4 v[126:127], v[100:103] offset:256
	s_mov_b32 s100, -1
	s_mov_b32 s101, 0
	s_mov_b32 s98, 0xffff0000
	s_mov_b32 s99, 0
	s_and_saveexec_b64 s[30:31], s[100:101]
	s_cbranch_execz .LBB0_1333
	v_lshl_add_u64 v[100:101], s[8:9], 0, v[112:113]
	s_waitcnt lgkmcnt(0)
	v_add_f32_e32 v96, v96, v98
	v_add_f32_e32 v97, v97, v99
	v_cndmask_b32_e64 v96, v96, v97, s[98:99]
	v_cndmask_b32_e64 v97, 0, 4, s[98:99]
	v_or_b32_e32 v100, v100, v97
	flat_atomic_add_f32 v[100:101], v96
.LBB0_1333:
	s_or_b64 exec, exec, s[30:31]
	v_or_b32_e32 v126, 32, v150
	v_ashrrev_i32_e32 v127, 31, v126
	v_lshlrev_b64 v[96:97], 3, v[126:127]
	s_waitcnt lgkmcnt(0)
	v_lshl_add_u64 v[98:99], s[6:7], 0, v[96:97]
	flat_load_dwordx2 v[156:157], v[98:99]
	v_lshlrev_b64 v[98:99], 12, v[126:127]
	v_lshl_add_u64 v[98:99], s[46:47], 0, v[98:99]
	v_lshl_add_u64 v[98:99], v[148:149], 2, v[98:99]
	global_load_dwordx4 v[100:103], v[98:99], off
	global_load_dwordx4 v[104:107], v[144:145], off
	global_load_dwordx4 v[108:111], v[146:147], off
	global_load_dwordx4 v[112:115], v[152:153], off
	global_load_dwordx4 v[122:125], v[98:99], off offset:16
	s_waitcnt vmcnt(0) lgkmcnt(0)
	v_pk_mul_f32 v[156:157], v[156:157], s[18:19] op_sel:[1,0] op_sel_hi:[0,0]
	v_fma_f32 v151, -v157, v157, v156
	v_max_f32_e32 v151, 0, v151
	v_add_f32_e32 v151, 0x3727c5ac, v151
	v_mul_f32_e32 v156, 0x4b800000, v151
	v_cmp_gt_f32_e32 vcc, s64, v151
	v_sub_f32_e32 v103, v103, v157
	v_sub_f32_e32 v102, v102, v157
	v_cndmask_b32_e32 v151, v151, v156, vcc
	v_rsq_f32_e32 v151, v151
	v_sub_f32_e32 v101, v101, v157
	v_sub_f32_e32 v100, v100, v157
	v_mul_f32_e32 v156, 0x45800000, v151
	v_cndmask_b32_e32 v156, v151, v156, vcc
	v_pk_mul_f32 v[100:101], v[100:101], v[156:157] op_sel_hi:[1,0]
	v_pk_mul_f32 v[102:103], v[102:103], v[156:157] op_sel_hi:[1,0]
	v_pk_fma_f32 v[100:101], v[104:105], v[100:101], v[108:109]
	v_pk_fma_f32 v[102:103], v[106:107], v[102:103], v[110:111]
	v_pk_fma_f32 v[92:93], v[100:101], s[20:21], v[92:93] op_sel_hi:[1,0,1]
	v_pk_fma_f32 v[94:95], v[102:103], s[20:21], v[94:95] op_sel_hi:[1,0,1]
	v_pk_add_f32 v[92:93], v[112:113], v[92:93]
	v_pk_add_f32 v[94:95], v[114:115], v[94:95]
	global_store_dwordx4 v[98:99], v[92:95], off
	global_load_dwordx4 v[100:103], v[144:145], off offset:16
	global_load_dwordx4 v[104:107], v[146:147], off offset:16
	global_load_dwordx4 v[108:111], v[154:155], off
	v_lshlrev_b64 v[112:113], 11, v[126:127]
	v_lshl_add_u64 v[112:113], s[10:11], 0, v[112:113]
	v_lshl_add_u64 v[126:127], v[148:149], 1, v[112:113]
	v_sub_f32_e32 v113, v125, v157
	v_sub_f32_e32 v112, v124, v157
	v_sub_f32_e32 v115, v123, v157
	v_sub_f32_e32 v114, v122, v157
	v_pk_mul_f32 v[114:115], v[114:115], v[156:157] op_sel_hi:[1,0]
	v_pk_mul_f32 v[122:123], v[112:113], v[156:157] op_sel_hi:[1,0]
	v_cvt_pk_bf16_f32 v112, v92, v93
	v_cvt_pk_bf16_f32 v113, v94, v95
	s_waitcnt vmcnt(1)
	v_pk_fma_f32 v[100:101], v[100:101], v[114:115], v[104:105]
	v_pk_fma_f32 v[102:103], v[102:103], v[122:123], v[106:107]
	v_pk_fma_f32 v[88:89], v[100:101], s[20:21], v[88:89] op_sel_hi:[1,0,1]
	v_pk_fma_f32 v[90:91], v[102:103], s[20:21], v[90:91] op_sel_hi:[1,0,1]
	s_waitcnt vmcnt(0)
; DEVI unsigned pk2(float lo, float hi) { unsigned r; asm("v_cvt_pk_bf16_f32 %0, %1, %2" : "=v"(r) : "v"(lo), "v"(hi)); return r; }
; DEVI void row_stats(const float* stats, int row, float& mu, float& rs) {
;     if (stats) { const float2 st = *(const float2*)(stats + 2 * (size_t)row); mu = st.x * (1.0f / 1024.0f); const float var = st.y * (1.0f / 1024.0f) - mu * mu; rs = rsqrtf(fmaxf(var, 0.f) + LN_EPS); }
;     DEVI void operator()(const f32x4 (&acc)[2][2][4][2], const pg8::Unit& u, int wr, int wc, int fr, int fq) const {
;     ...
;                 const int row = row0 + ai * 128 + m * 16; float mu, rs; row_stats(stin, row, mu, rs);
;                 float sum = 0.f, sq = 0.f;
; #pragma unroll
;                 for (int bj = 0; bj < 2; ++bj) {
;                     f32x4 z[2];
; #pragma unroll
;                     for (int n = 0; n < 2; ++n) {
;                         const int col = colb + bj * 128 + 4 * n;
;                         f32x4 xv = *(const f32x4*)(zsrc + (size_t)row * DM + col);
;                         if (stin) { const f32x4 gv = *(const f32x4*)(gin + col), bv = *(const f32x4*)(bin + col); xv = (xv - mu) * rs * gv + bv; }
;                         f32x4 zz = ALPHA * xv + acc[ai][bj][m][n];
;                         if (bias) zz += *(const f32x4*)(bias + col);
;                         *(f32x4*)(zdst + (size_t)row * DM + col) = zz;
;                         sum += zz[0] + zz[1] + zz[2] + zz[3]; sq += zz[0] * zz[0] + zz[1] * zz[1] + zz[2] * zz[2] + zz[3] * zz[3];
;                         z[n] = zz;
;                     }
;                     u32x4 o; o.x = pk2(z[0][0], z[0][1]); o.y = pk2(z[0][2], z[0][3]); o.z = pk2(z[1][0], z[1][1]); o.w = pk2(z[1][2], z[1][3]);
;                     if (zb) *(u32x4*)(zb + (size_t)row * DM + colb + bj * 128) = o;
;                 }
;                 sum += __shfl_xor(sum, 16); sq += __shfl_xor(sq, 16);
;                 sum += __shfl_xor(sum, 32); sq += __shfl_xor(sq, 32);
;                 if (fq == 0) { atomicAdd(stout + 2 * (size_t)row, sum); atomicAdd(stout + 2 * (size_t)row + 1, sq); }
	v_pk_add_f32 v[88:89], v[108:109], v[88:89]
	v_pk_add_f32 v[90:91], v[110:111], v[90:91]
	global_store_dwordx4 v[98:99], v[88:91], off offset:16
	v_cvt_pk_bf16_f32 v114, v88, v89
	v_cvt_pk_bf16_f32 v115, v90, v91
	flat_store_dwordx4 v[126:127], v[112:115]
	global_load_dwordx4 v[100:103], v[98:99], off offset:512
	global_load_dwordx4 v[104:107], v[144:145], off offset:512
	global_load_dwordx4 v[108:111], v[146:147], off offset:512
	s_nop 0
	global_load_dwordx4 v[112:115], v[120:121], off
	global_load_dwordx4 v[122:125], v[98:99], off offset:528
	s_waitcnt vmcnt(0)
	v_sub_f32_e32 v103, v103, v157
	v_sub_f32_e32 v102, v102, v157
	v_sub_f32_e32 v101, v101, v157
	v_sub_f32_e32 v100, v100, v157
	v_pk_mul_f32 v[100:101], v[156:157], v[100:101] op_sel_hi:[0,1]
	v_pk_mul_f32 v[102:103], v[156:157], v[102:103] op_sel_hi:[0,1]
	v_pk_fma_f32 v[102:103], v[106:107], v[102:103], v[110:111]
	v_pk_fma_f32 v[100:101], v[104:105], v[100:101], v[108:109]
	v_pk_fma_f32 v[86:87], v[102:103], s[20:21], v[86:87] op_sel_hi:[1,0,1]
	v_pk_fma_f32 v[84:85], v[100:101], s[20:21], v[84:85] op_sel_hi:[1,0,1]
	v_pk_add_f32 v[86:87], v[114:115], v[86:87]
	v_pk_add_f32 v[84:85], v[112:113], v[84:85]
	global_store_dwordx4 v[98:99], v[84:87], off offset:512
	global_load_dwordx4 v[100:103], v[144:145], off offset:528
	global_load_dwordx4 v[104:107], v[146:147], off offset:528
	global_load_dwordx4 v[108:111], v[116:117], off
	v_add_f32_e32 v112, v92, v93
	v_mul_f32_e32 v93, v93, v93
	v_fmac_f32_e32 v93, v92, v92
	v_add_f32_e32 v112, v94, v112
	v_fmac_f32_e32 v93, v94, v94
	v_add_f32_e32 v94, v88, v89
	v_mul_f32_e32 v89, v89, v89
	v_fmac_f32_e32 v89, v88, v88
	v_add_f32_e32 v92, v95, v112
	v_add_f32_e32 v94, v90, v94
	v_fmac_f32_e32 v89, v90, v90
	v_add_f32_e32 v92, 0, v92
	v_fmac_f32_e32 v93, v95, v95
	v_add_f32_e32 v88, v91, v94
	v_fmac_f32_e32 v89, v91, v91
	v_sub_f32_e32 v91, v123, v157
	v_sub_f32_e32 v90, v122, v157
	v_add_f32_e32 v92, v88, v92
	v_add_f32_e32 v93, v93, v89
	v_sub_f32_e32 v89, v125, v157
	v_sub_f32_e32 v88, v124, v157
	v_pk_mul_f32 v[90:91], v[156:157], v[90:91] op_sel_hi:[0,1]
	v_pk_mul_f32 v[88:89], v[156:157], v[88:89] op_sel_hi:[0,1]
	v_mul_f32_e32 v95, v85, v85
	v_add_f32_e32 v94, v84, v85
	v_fmac_f32_e32 v95, v84, v84
	v_add_f32_e32 v94, v86, v94
	v_fmac_f32_e32 v95, v86, v86
	v_add_f32_e32 v94, v87, v94
	v_fmac_f32_e32 v95, v87, v87
	v_add_f32_e32 v92, v92, v94
	v_add_f32_e32 v93, v93, v95
	v_cvt_pk_bf16_f32 v84, v84, v85
	v_cvt_pk_bf16_f32 v85, v86, v87
	s_waitcnt vmcnt(0)
	v_pk_fma_f32 v[90:91], v[100:101], v[90:91], v[104:105]
	v_pk_fma_f32 v[88:89], v[102:103], v[88:89], v[106:107]
	v_pk_fma_f32 v[80:81], v[90:91], s[20:21], v[80:81] op_sel_hi:[1,0,1]
	v_pk_fma_f32 v[82:83], v[88:89], s[20:21], v[82:83] op_sel_hi:[1,0,1]
	v_pk_add_f32 v[88:89], v[108:109], v[80:81]
	v_pk_add_f32 v[90:91], v[110:111], v[82:83]
	v_mul_f32_e32 v81, v89, v89
	v_add_f32_e32 v80, v88, v89
	v_fmac_f32_e32 v81, v88, v88
	v_add_f32_e32 v80, v90, v80
	v_fmac_f32_e32 v81, v90, v90
	v_add_f32_e32 v80, v91, v80
	v_fmac_f32_e32 v81, v91, v91
	v_add_f32_e32 v80, v92, v80
	v_add_f32_e32 v81, v93, v81
	ds_bpermute_b32 v82, v118, v80
	ds_bpermute_b32 v83, v118, v81
	global_store_dwordx4 v[98:99], v[88:91], off offset:528
	v_cvt_pk_bf16_f32 v86, v88, v89
	v_cvt_pk_bf16_f32 v87, v90, v91
	s_waitcnt lgkmcnt(0)
	v_add_f32_e32 v80, v80, v82
	v_add_f32_e32 v81, v81, v83
	ds_bpermute_b32 v82, v119, v80
	ds_bpermute_b32 v83, v119, v81
	flat_store_dwordx4 v[126:127], v[84:87] offset:256
	s_mov_b32 s100, -1
	s_mov_b32 s101, 0
	s_mov_b32 s98, 0xffff0000
	s_mov_b32 s99, 0
	s_and_saveexec_b64 s[30:31], s[100:101]
	s_cbranch_execz .LBB0_1335
	v_lshl_add_u64 v[84:85], s[8:9], 0, v[96:97]
	s_waitcnt lgkmcnt(0)
	v_add_f32_e32 v80, v80, v82
	v_add_f32_e32 v81, v81, v83
	v_cndmask_b32_e64 v80, v80, v81, s[98:99]
	v_cndmask_b32_e64 v81, 0, 4, s[98:99]
	v_or_b32_e32 v84, v84, v81
	flat_atomic_add_f32 v[84:85], v80
.LBB0_1335:
	s_or_b64 exec, exec, s[30:31]
	v_or_b32_e32 v104, 48, v150
	v_ashrrev_i32_e32 v105, 31, v104
	v_lshlrev_b64 v[80:81], 3, v[104:105]
	s_waitcnt lgkmcnt(0)
	v_lshl_add_u64 v[82:83], s[6:7], 0, v[80:81]
	flat_load_dwordx2 v[106:107], v[82:83]
	v_lshlrev_b64 v[82:83], 12, v[104:105]
	v_lshl_add_u64 v[82:83], s[46:47], 0, v[82:83]
	v_lshl_add_u64 v[82:83], v[148:149], 2, v[82:83]
	global_load_dwordx4 v[84:87], v[82:83], off
	global_load_dwordx4 v[88:91], v[144:145], off
	global_load_dwordx4 v[92:95], v[146:147], off
	global_load_dwordx4 v[96:99], v[152:153], off
	global_load_dwordx4 v[100:103], v[82:83], off offset:16
	s_waitcnt vmcnt(0) lgkmcnt(0)
	v_pk_mul_f32 v[106:107], v[106:107], s[18:19] op_sel:[1,0] op_sel_hi:[0,0]
	v_fma_f32 v106, -v107, v107, v106
	v_max_f32_e32 v106, 0, v106
	v_add_f32_e32 v106, 0x3727c5ac, v106
	v_mul_f32_e32 v108, 0x4b800000, v106
	v_cmp_gt_f32_e32 vcc, s64, v106
	v_sub_f32_e32 v87, v87, v107
	v_sub_f32_e32 v86, v86, v107
	v_cndmask_b32_e32 v106, v106, v108, vcc
	v_rsq_f32_e32 v106, v106
	v_sub_f32_e32 v85, v85, v107
	v_sub_f32_e32 v84, v84, v107
	v_mul_f32_e32 v108, 0x45800000, v106
	v_cndmask_b32_e32 v106, v106, v108, vcc
	v_pk_mul_f32 v[84:85], v[84:85], v[106:107] op_sel_hi:[1,0]
	v_pk_mul_f32 v[86:87], v[86:87], v[106:107] op_sel_hi:[1,0]
	v_pk_fma_f32 v[84:85], v[88:89], v[84:85], v[92:93]
	v_pk_fma_f32 v[86:87], v[90:91], v[86:87], v[94:95]
	v_pk_fma_f32 v[76:77], v[84:85], s[20:21], v[76:77] op_sel_hi:[1,0,1]
	v_pk_fma_f32 v[78:79], v[86:87], s[20:21], v[78:79] op_sel_hi:[1,0,1]
	v_pk_add_f32 v[76:77], v[96:97], v[76:77]
	v_pk_add_f32 v[78:79], v[98:99], v[78:79]
	global_store_dwordx4 v[82:83], v[76:79], off
	global_load_dwordx4 v[84:87], v[144:145], off offset:16
	global_load_dwordx4 v[88:91], v[146:147], off offset:16
	global_load_dwordx4 v[92:95], v[154:155], off
	v_lshlrev_b64 v[96:97], 11, v[104:105]
	v_lshl_add_u64 v[96:97], s[10:11], 0, v[96:97]
	v_lshl_add_u64 v[104:105], v[148:149], 1, v[96:97]
	v_sub_f32_e32 v97, v103, v107
	v_sub_f32_e32 v96, v102, v107
	v_sub_f32_e32 v99, v101, v107
	v_sub_f32_e32 v98, v100, v107
	v_pk_mul_f32 v[98:99], v[98:99], v[106:107] op_sel_hi:[1,0]
	v_pk_mul_f32 v[100:101], v[96:97], v[106:107] op_sel_hi:[1,0]
	v_cvt_pk_bf16_f32 v96, v76, v77
	v_cvt_pk_bf16_f32 v97, v78, v79
	s_waitcnt vmcnt(1)
; DEVI unsigned pk2(float lo, float hi) { unsigned r; asm("v_cvt_pk_bf16_f32 %0, %1, %2" : "=v"(r) : "v"(lo), "v"(hi)); return r; }
; DEVI void row_stats(const float* stats, int row, float& mu, float& rs) {
;     if (stats) { const float2 st = *(const float2*)(stats + 2 * (size_t)row); mu = st.x * (1.0f / 1024.0f); const float var = st.y * (1.0f / 1024.0f) - mu * mu; rs = rsqrtf(fmaxf(var, 0.f) + LN_EPS); }
;     DEVI void operator()(const f32x4 (&acc)[2][2][4][2], const pg8::Unit& u, int wr, int wc, int fr, int fq) const {
;     ...
;                 const int row = row0 + ai * 128 + m * 16; float mu, rs; row_stats(stin, row, mu, rs);
;                 float sum = 0.f, sq = 0.f;
; #pragma unroll
;                 for (int bj = 0; bj < 2; ++bj) {
;                     f32x4 z[2];
; #pragma unroll
;                     for (int n = 0; n < 2; ++n) {
;                         const int col = colb + bj * 128 + 4 * n;
;                         f32x4 xv = *(const f32x4*)(zsrc + (size_t)row * DM + col);
;                         if (stin) { const f32x4 gv = *(const f32x4*)(gin + col), bv = *(const f32x4*)(bin + col); xv = (xv - mu) * rs * gv + bv; }
;                         f32x4 zz = ALPHA * xv + acc[ai][bj][m][n];
;                         if (bias) zz += *(const f32x4*)(bias + col);
;                         *(f32x4*)(zdst + (size_t)row * DM + col) = zz;
;                         sum += zz[0] + zz[1] + zz[2] + zz[3]; sq += zz[0] * zz[0] + zz[1] * zz[1] + zz[2] * zz[2] + zz[3] * zz[3];
;                         z[n] = zz;
;                     }
;                     u32x4 o; o.x = pk2(z[0][0], z[0][1]); o.y = pk2(z[0][2], z[0][3]); o.z = pk2(z[1][0], z[1][1]); o.w = pk2(z[1][2], z[1][3]);
;                     if (zb) *(u32x4*)(zb + (size_t)row * DM + colb + bj * 128) = o;
;                 }
;                 sum += __shfl_xor(sum, 16); sq += __shfl_xor(sq, 16);
;                 sum += __shfl_xor(sum, 32); sq += __shfl_xor(sq, 32);
;                 if (fq == 0) { atomicAdd(stout + 2 * (size_t)row, sum); atomicAdd(stout + 2 * (size_t)row + 1, sq); }
	v_pk_fma_f32 v[84:85], v[84:85], v[98:99], v[88:89]
	v_pk_fma_f32 v[86:87], v[86:87], v[100:101], v[90:91]
	v_pk_fma_f32 v[72:73], v[84:85], s[20:21], v[72:73] op_sel_hi:[1,0,1]
	v_pk_fma_f32 v[74:75], v[86:87], s[20:21], v[74:75] op_sel_hi:[1,0,1]
	s_waitcnt vmcnt(0)
	v_pk_add_f32 v[72:73], v[92:93], v[72:73]
	v_pk_add_f32 v[74:75], v[94:95], v[74:75]
	global_store_dwordx4 v[82:83], v[72:75], off offset:16
	v_cvt_pk_bf16_f32 v98, v72, v73
	v_cvt_pk_bf16_f32 v99, v74, v75
	flat_store_dwordx4 v[104:105], v[96:99]
	global_load_dwordx4 v[84:87], v[82:83], off offset:512
	global_load_dwordx4 v[88:91], v[144:145], off offset:512
	global_load_dwordx4 v[92:95], v[146:147], off offset:512
	s_nop 0
	global_load_dwordx4 v[96:99], v[120:121], off
	global_load_dwordx4 v[100:103], v[82:83], off offset:528
	s_waitcnt vmcnt(0)
	v_sub_f32_e32 v87, v87, v107
	v_sub_f32_e32 v86, v86, v107
	v_sub_f32_e32 v85, v85, v107
	v_sub_f32_e32 v84, v84, v107
	v_pk_mul_f32 v[84:85], v[106:107], v[84:85] op_sel_hi:[0,1]
	v_pk_mul_f32 v[86:87], v[106:107], v[86:87] op_sel_hi:[0,1]
	v_pk_fma_f32 v[86:87], v[90:91], v[86:87], v[94:95]
	v_pk_fma_f32 v[84:85], v[88:89], v[84:85], v[92:93]
	v_pk_fma_f32 v[70:71], v[86:87], s[20:21], v[70:71] op_sel_hi:[1,0,1]
	v_pk_fma_f32 v[68:69], v[84:85], s[20:21], v[68:69] op_sel_hi:[1,0,1]
	v_pk_add_f32 v[70:71], v[98:99], v[70:71]
	v_pk_add_f32 v[68:69], v[96:97], v[68:69]
	global_store_dwordx4 v[82:83], v[68:71], off offset:512
	global_load_dwordx4 v[84:87], v[144:145], off offset:528
	global_load_dwordx4 v[88:91], v[146:147], off offset:528
	global_load_dwordx4 v[92:95], v[116:117], off
	v_add_f32_e32 v96, v76, v77
	v_mul_f32_e32 v77, v77, v77
	v_fmac_f32_e32 v77, v76, v76
	v_add_f32_e32 v96, v78, v96
	v_fmac_f32_e32 v77, v78, v78
	v_add_f32_e32 v78, v72, v73
	v_mul_f32_e32 v73, v73, v73
	v_fmac_f32_e32 v73, v72, v72
	v_add_f32_e32 v76, v79, v96
	v_add_f32_e32 v78, v74, v78
	v_fmac_f32_e32 v73, v74, v74
	v_add_f32_e32 v76, 0, v76
	v_fmac_f32_e32 v77, v79, v79
	v_add_f32_e32 v72, v75, v78
	v_fmac_f32_e32 v73, v75, v75
	v_sub_f32_e32 v75, v101, v107
	v_sub_f32_e32 v74, v100, v107
	v_add_f32_e32 v76, v72, v76
	v_add_f32_e32 v77, v77, v73
	v_sub_f32_e32 v73, v103, v107
	v_sub_f32_e32 v72, v102, v107
	v_pk_mul_f32 v[74:75], v[106:107], v[74:75] op_sel_hi:[0,1]
	v_pk_mul_f32 v[72:73], v[106:107], v[72:73] op_sel_hi:[0,1]
	v_mul_f32_e32 v79, v69, v69
	v_add_f32_e32 v78, v68, v69
	v_fmac_f32_e32 v79, v68, v68
	v_add_f32_e32 v78, v70, v78
	v_fmac_f32_e32 v79, v70, v70
	v_add_f32_e32 v78, v71, v78
	v_fmac_f32_e32 v79, v71, v71
	v_add_f32_e32 v76, v76, v78
	v_add_f32_e32 v77, v77, v79
	v_cvt_pk_bf16_f32 v68, v68, v69
	v_cvt_pk_bf16_f32 v69, v70, v71
	s_waitcnt vmcnt(0)
	v_pk_fma_f32 v[74:75], v[84:85], v[74:75], v[88:89]
	v_pk_fma_f32 v[72:73], v[86:87], v[72:73], v[90:91]
	v_pk_fma_f32 v[64:65], v[74:75], s[20:21], v[64:65] op_sel_hi:[1,0,1]
	v_pk_fma_f32 v[66:67], v[72:73], s[20:21], v[66:67] op_sel_hi:[1,0,1]
	v_pk_add_f32 v[72:73], v[92:93], v[64:65]
	v_pk_add_f32 v[74:75], v[94:95], v[66:67]
	v_mul_f32_e32 v65, v73, v73
	v_add_f32_e32 v64, v72, v73
	v_fmac_f32_e32 v65, v72, v72
	v_add_f32_e32 v64, v74, v64
	v_fmac_f32_e32 v65, v74, v74
	v_add_f32_e32 v64, v75, v64
	v_fmac_f32_e32 v65, v75, v75
	v_add_f32_e32 v64, v76, v64
	v_add_f32_e32 v65, v77, v65
	ds_bpermute_b32 v66, v118, v64
	ds_bpermute_b32 v67, v118, v65
	global_store_dwordx4 v[82:83], v[72:75], off offset:528
	v_cvt_pk_bf16_f32 v70, v72, v73
	v_cvt_pk_bf16_f32 v71, v74, v75
	s_waitcnt lgkmcnt(0)
	v_add_f32_e32 v64, v64, v66
	v_add_f32_e32 v65, v65, v67
	ds_bpermute_b32 v66, v119, v64
	ds_bpermute_b32 v67, v119, v65
	flat_store_dwordx4 v[104:105], v[68:71] offset:256
	s_mov_b32 s100, -1
	s_mov_b32 s101, 0
	s_mov_b32 s98, 0xffff0000
	s_mov_b32 s99, 0
	s_and_saveexec_b64 s[30:31], s[100:101]
	s_cbranch_execz .LBB0_1337
	v_lshl_add_u64 v[68:69], s[8:9], 0, v[80:81]
	s_waitcnt lgkmcnt(0)
	v_add_f32_e32 v64, v64, v66
	v_add_f32_e32 v65, v65, v67
	v_cndmask_b32_e64 v64, v64, v65, s[98:99]
	v_cndmask_b32_e64 v65, 0, 4, s[98:99]
	v_or_b32_e32 v68, v68, v65
	flat_atomic_add_f32 v[68:69], v64
.LBB0_1337:
	s_or_b64 exec, exec, s[30:31]
	v_add_u32_e32 v88, 0x80, v150
	v_ashrrev_i32_e32 v89, 31, v88
	v_lshlrev_b64 v[64:65], 3, v[88:89]
	s_waitcnt lgkmcnt(0)
	v_lshl_add_u64 v[66:67], s[6:7], 0, v[64:65]
	flat_load_dwordx2 v[90:91], v[66:67]
	v_lshlrev_b64 v[66:67], 12, v[88:89]
	v_lshl_add_u64 v[66:67], s[46:47], 0, v[66:67]
	v_lshl_add_u64 v[66:67], v[148:149], 2, v[66:67]
	global_load_dwordx4 v[68:71], v[66:67], off
	global_load_dwordx4 v[72:75], v[144:145], off
	global_load_dwordx4 v[76:79], v[146:147], off
	global_load_dwordx4 v[80:83], v[152:153], off
	global_load_dwordx4 v[84:87], v[66:67], off offset:16
	s_waitcnt vmcnt(0) lgkmcnt(0)
	v_pk_mul_f32 v[90:91], v[90:91], s[18:19] op_sel:[1,0] op_sel_hi:[0,0]
	v_fma_f32 v90, -v91, v91, v90
	v_max_f32_e32 v90, 0, v90
	v_add_f32_e32 v90, 0x3727c5ac, v90
	v_mul_f32_e32 v92, 0x4b800000, v90
	v_cmp_gt_f32_e32 vcc, s64, v90
	v_sub_f32_e32 v71, v71, v91
	v_sub_f32_e32 v70, v70, v91
	v_cndmask_b32_e32 v90, v90, v92, vcc
	v_rsq_f32_e32 v90, v90
	v_sub_f32_e32 v69, v69, v91
	v_sub_f32_e32 v68, v68, v91
	v_mul_f32_e32 v92, 0x45800000, v90
	v_cndmask_b32_e32 v90, v90, v92, vcc
	v_pk_mul_f32 v[68:69], v[68:69], v[90:91] op_sel_hi:[1,0]
	v_pk_mul_f32 v[70:71], v[70:71], v[90:91] op_sel_hi:[1,0]
	v_pk_fma_f32 v[68:69], v[72:73], v[68:69], v[76:77]
	v_pk_fma_f32 v[70:71], v[74:75], v[70:71], v[78:79]
	v_pk_fma_f32 v[60:61], v[68:69], s[20:21], v[60:61] op_sel_hi:[1,0,1]
	v_pk_fma_f32 v[62:63], v[70:71], s[20:21], v[62:63] op_sel_hi:[1,0,1]
	v_pk_add_f32 v[60:61], v[80:81], v[60:61]
	v_pk_add_f32 v[62:63], v[82:83], v[62:63]
	global_store_dwordx4 v[66:67], v[60:63], off
	global_load_dwordx4 v[68:71], v[144:145], off offset:16
	global_load_dwordx4 v[72:75], v[146:147], off offset:16
	global_load_dwordx4 v[76:79], v[154:155], off
	v_lshlrev_b64 v[80:81], 11, v[88:89]
	v_lshl_add_u64 v[80:81], s[10:11], 0, v[80:81]
	v_lshl_add_u64 v[88:89], v[148:149], 1, v[80:81]
	v_sub_f32_e32 v81, v87, v91
	v_sub_f32_e32 v80, v86, v91
	v_sub_f32_e32 v83, v85, v91
	v_sub_f32_e32 v82, v84, v91
	v_pk_mul_f32 v[82:83], v[82:83], v[90:91] op_sel_hi:[1,0]
	v_pk_mul_f32 v[84:85], v[80:81], v[90:91] op_sel_hi:[1,0]
	v_cvt_pk_bf16_f32 v80, v60, v61
	v_cvt_pk_bf16_f32 v81, v62, v63
	s_waitcnt vmcnt(1)
; DEVI unsigned pk2(float lo, float hi) { unsigned r; asm("v_cvt_pk_bf16_f32 %0, %1, %2" : "=v"(r) : "v"(lo), "v"(hi)); return r; }
; DEVI void row_stats(const float* stats, int row, float& mu, float& rs) {
;     if (stats) { const float2 st = *(const float2*)(stats + 2 * (size_t)row); mu = st.x * (1.0f / 1024.0f); const float var = st.y * (1.0f / 1024.0f) - mu * mu; rs = rsqrtf(fmaxf(var, 0.f) + LN_EPS); }
;     DEVI void operator()(const f32x4 (&acc)[2][2][4][2], const pg8::Unit& u, int wr, int wc, int fr, int fq) const {
;     ...
;                 const int row = row0 + ai * 128 + m * 16; float mu, rs; row_stats(stin, row, mu, rs);
;                 float sum = 0.f, sq = 0.f;
; #pragma unroll
;                 for (int bj = 0; bj < 2; ++bj) {
;                     f32x4 z[2];
; #pragma unroll
;                     for (int n = 0; n < 2; ++n) {
;                         const int col = colb + bj * 128 + 4 * n;
;                         f32x4 xv = *(const f32x4*)(zsrc + (size_t)row * DM + col);
;                         if (stin) { const f32x4 gv = *(const f32x4*)(gin + col), bv = *(const f32x4*)(bin + col); xv = (xv - mu) * rs * gv + bv; }
;                         f32x4 zz = ALPHA * xv + acc[ai][bj][m][n];
;                         if (bias) zz += *(const f32x4*)(bias + col);
;                         *(f32x4*)(zdst + (size_t)row * DM + col) = zz;
;                         sum += zz[0] + zz[1] + zz[2] + zz[3]; sq += zz[0] * zz[0] + zz[1] * zz[1] + zz[2] * zz[2] + zz[3] * zz[3];
;                         z[n] = zz;
;                     }
;                     u32x4 o; o.x = pk2(z[0][0], z[0][1]); o.y = pk2(z[0][2], z[0][3]); o.z = pk2(z[1][0], z[1][1]); o.w = pk2(z[1][2], z[1][3]);
;                     if (zb) *(u32x4*)(zb + (size_t)row * DM + colb + bj * 128) = o;
;                 }
;                 sum += __shfl_xor(sum, 16); sq += __shfl_xor(sq, 16);
;                 sum += __shfl_xor(sum, 32); sq += __shfl_xor(sq, 32);
;                 if (fq == 0) { atomicAdd(stout + 2 * (size_t)row, sum); atomicAdd(stout + 2 * (size_t)row + 1, sq); }
	v_pk_fma_f32 v[68:69], v[68:69], v[82:83], v[72:73]
	v_pk_fma_f32 v[70:71], v[70:71], v[84:85], v[74:75]
	v_pk_fma_f32 v[56:57], v[68:69], s[20:21], v[56:57] op_sel_hi:[1,0,1]
	v_pk_fma_f32 v[58:59], v[70:71], s[20:21], v[58:59] op_sel_hi:[1,0,1]
	s_waitcnt vmcnt(0)
	v_pk_add_f32 v[56:57], v[76:77], v[56:57]
	v_pk_add_f32 v[58:59], v[78:79], v[58:59]
	global_store_dwordx4 v[66:67], v[56:59], off offset:16
	v_cvt_pk_bf16_f32 v82, v56, v57
	v_cvt_pk_bf16_f32 v83, v58, v59
	flat_store_dwordx4 v[88:89], v[80:83]
	global_load_dwordx4 v[68:71], v[66:67], off offset:512
	global_load_dwordx4 v[72:75], v[144:145], off offset:512
	global_load_dwordx4 v[76:79], v[146:147], off offset:512
	s_nop 0
	global_load_dwordx4 v[80:83], v[120:121], off
	global_load_dwordx4 v[84:87], v[66:67], off offset:528
	s_waitcnt vmcnt(0)
	v_sub_f32_e32 v71, v71, v91
	v_sub_f32_e32 v70, v70, v91
	v_sub_f32_e32 v69, v69, v91
	v_sub_f32_e32 v68, v68, v91
	v_pk_mul_f32 v[68:69], v[90:91], v[68:69] op_sel_hi:[0,1]
	v_pk_mul_f32 v[70:71], v[90:91], v[70:71] op_sel_hi:[0,1]
	v_pk_fma_f32 v[70:71], v[74:75], v[70:71], v[78:79]
	v_pk_fma_f32 v[68:69], v[72:73], v[68:69], v[76:77]
	v_pk_fma_f32 v[54:55], v[70:71], s[20:21], v[54:55] op_sel_hi:[1,0,1]
	v_pk_fma_f32 v[52:53], v[68:69], s[20:21], v[52:53] op_sel_hi:[1,0,1]
	v_pk_add_f32 v[54:55], v[82:83], v[54:55]
	v_pk_add_f32 v[52:53], v[80:81], v[52:53]
	global_store_dwordx4 v[66:67], v[52:55], off offset:512
	global_load_dwordx4 v[68:71], v[144:145], off offset:528
	global_load_dwordx4 v[72:75], v[146:147], off offset:528
	global_load_dwordx4 v[76:79], v[116:117], off
	v_add_f32_e32 v80, v60, v61
	v_mul_f32_e32 v61, v61, v61
	v_fmac_f32_e32 v61, v60, v60
	v_add_f32_e32 v80, v62, v80
	v_fmac_f32_e32 v61, v62, v62
	v_add_f32_e32 v62, v56, v57
	v_mul_f32_e32 v57, v57, v57
	v_fmac_f32_e32 v57, v56, v56
	v_add_f32_e32 v60, v63, v80
	v_add_f32_e32 v62, v58, v62
	v_fmac_f32_e32 v57, v58, v58
	v_add_f32_e32 v60, 0, v60
	v_fmac_f32_e32 v61, v63, v63
	v_add_f32_e32 v56, v59, v62
	v_fmac_f32_e32 v57, v59, v59
	v_sub_f32_e32 v59, v85, v91
	v_sub_f32_e32 v58, v84, v91
	v_add_f32_e32 v60, v56, v60
	v_add_f32_e32 v61, v61, v57
	v_sub_f32_e32 v57, v87, v91
	v_sub_f32_e32 v56, v86, v91
	v_pk_mul_f32 v[58:59], v[90:91], v[58:59] op_sel_hi:[0,1]
	v_pk_mul_f32 v[56:57], v[90:91], v[56:57] op_sel_hi:[0,1]
	v_mul_f32_e32 v63, v53, v53
	v_add_f32_e32 v62, v52, v53
	v_fmac_f32_e32 v63, v52, v52
	v_add_f32_e32 v62, v54, v62
	v_fmac_f32_e32 v63, v54, v54
	v_add_f32_e32 v62, v55, v62
	v_fmac_f32_e32 v63, v55, v55
	v_add_f32_e32 v60, v60, v62
	v_add_f32_e32 v61, v61, v63
	v_cvt_pk_bf16_f32 v52, v52, v53
	v_cvt_pk_bf16_f32 v53, v54, v55
	s_waitcnt vmcnt(0)
	v_pk_fma_f32 v[58:59], v[68:69], v[58:59], v[72:73]
	v_pk_fma_f32 v[56:57], v[70:71], v[56:57], v[74:75]
	v_pk_fma_f32 v[48:49], v[58:59], s[20:21], v[48:49] op_sel_hi:[1,0,1]
	v_pk_fma_f32 v[50:51], v[56:57], s[20:21], v[50:51] op_sel_hi:[1,0,1]
	v_pk_add_f32 v[56:57], v[76:77], v[48:49]
	v_pk_add_f32 v[58:59], v[78:79], v[50:51]
	v_mul_f32_e32 v49, v57, v57
	v_add_f32_e32 v48, v56, v57
	v_fmac_f32_e32 v49, v56, v56
	v_add_f32_e32 v48, v58, v48
	v_fmac_f32_e32 v49, v58, v58
	v_add_f32_e32 v48, v59, v48
	v_fmac_f32_e32 v49, v59, v59
	v_add_f32_e32 v48, v60, v48
	v_add_f32_e32 v49, v61, v49
	ds_bpermute_b32 v50, v118, v48
	ds_bpermute_b32 v51, v118, v49
	global_store_dwordx4 v[66:67], v[56:59], off offset:528
	v_cvt_pk_bf16_f32 v54, v56, v57
	v_cvt_pk_bf16_f32 v55, v58, v59
	s_waitcnt lgkmcnt(0)
	v_add_f32_e32 v48, v48, v50
	v_add_f32_e32 v49, v49, v51
	ds_bpermute_b32 v50, v119, v48
	ds_bpermute_b32 v51, v119, v49
	flat_store_dwordx4 v[88:89], v[52:55] offset:256
	s_mov_b32 s100, -1
	s_mov_b32 s101, 0
	s_mov_b32 s98, 0xffff0000
	s_mov_b32 s99, 0
	s_and_saveexec_b64 s[30:31], s[100:101]
	s_cbranch_execz .LBB0_1339
	v_lshl_add_u64 v[52:53], s[8:9], 0, v[64:65]
	s_waitcnt lgkmcnt(0)
	v_add_f32_e32 v48, v48, v50
	v_add_f32_e32 v49, v49, v51
	v_cndmask_b32_e64 v48, v48, v49, s[98:99]
	v_cndmask_b32_e64 v49, 0, 4, s[98:99]
	v_or_b32_e32 v52, v52, v49
	flat_atomic_add_f32 v[52:53], v48
.LBB0_1339:
	s_or_b64 exec, exec, s[30:31]
	v_add_u32_e32 v72, 0x90, v150
	v_ashrrev_i32_e32 v73, 31, v72
	v_lshlrev_b64 v[48:49], 3, v[72:73]
	s_waitcnt lgkmcnt(0)
	v_lshl_add_u64 v[50:51], s[6:7], 0, v[48:49]
	flat_load_dwordx2 v[74:75], v[50:51]
	v_lshlrev_b64 v[50:51], 12, v[72:73]
	v_lshl_add_u64 v[50:51], s[46:47], 0, v[50:51]
	v_lshl_add_u64 v[50:51], v[148:149], 2, v[50:51]
	global_load_dwordx4 v[52:55], v[50:51], off
	global_load_dwordx4 v[56:59], v[144:145], off
	global_load_dwordx4 v[60:63], v[146:147], off
	global_load_dwordx4 v[64:67], v[152:153], off
	global_load_dwordx4 v[68:71], v[50:51], off offset:16
	s_waitcnt vmcnt(0) lgkmcnt(0)
	v_pk_mul_f32 v[74:75], v[74:75], s[18:19] op_sel:[1,0] op_sel_hi:[0,0]
	v_fma_f32 v74, -v75, v75, v74
	v_max_f32_e32 v74, 0, v74
	v_add_f32_e32 v74, 0x3727c5ac, v74
	v_mul_f32_e32 v76, 0x4b800000, v74
	v_cmp_gt_f32_e32 vcc, s64, v74
	v_sub_f32_e32 v55, v55, v75
	v_sub_f32_e32 v54, v54, v75
	v_cndmask_b32_e32 v74, v74, v76, vcc
	v_rsq_f32_e32 v74, v74
	v_sub_f32_e32 v53, v53, v75
	v_sub_f32_e32 v52, v52, v75
	v_mul_f32_e32 v76, 0x45800000, v74
	v_cndmask_b32_e32 v74, v74, v76, vcc
	v_pk_mul_f32 v[52:53], v[52:53], v[74:75] op_sel_hi:[1,0]
	v_pk_mul_f32 v[54:55], v[54:55], v[74:75] op_sel_hi:[1,0]
	v_pk_fma_f32 v[52:53], v[56:57], v[52:53], v[60:61]
	v_pk_fma_f32 v[54:55], v[58:59], v[54:55], v[62:63]
	v_pk_fma_f32 v[44:45], v[52:53], s[20:21], v[44:45] op_sel_hi:[1,0,1]
	v_pk_fma_f32 v[46:47], v[54:55], s[20:21], v[46:47] op_sel_hi:[1,0,1]
	v_pk_add_f32 v[44:45], v[64:65], v[44:45]
	v_pk_add_f32 v[46:47], v[66:67], v[46:47]
	global_store_dwordx4 v[50:51], v[44:47], off
	global_load_dwordx4 v[52:55], v[144:145], off offset:16
	global_load_dwordx4 v[56:59], v[146:147], off offset:16
	global_load_dwordx4 v[60:63], v[154:155], off
	v_lshlrev_b64 v[64:65], 11, v[72:73]
	v_lshl_add_u64 v[64:65], s[10:11], 0, v[64:65]
	v_lshl_add_u64 v[72:73], v[148:149], 1, v[64:65]
	v_sub_f32_e32 v65, v71, v75
	v_sub_f32_e32 v64, v70, v75
	v_sub_f32_e32 v67, v69, v75
	v_sub_f32_e32 v66, v68, v75
	v_pk_mul_f32 v[66:67], v[66:67], v[74:75] op_sel_hi:[1,0]
	v_pk_mul_f32 v[68:69], v[64:65], v[74:75] op_sel_hi:[1,0]
	v_cvt_pk_bf16_f32 v64, v44, v45
	v_cvt_pk_bf16_f32 v65, v46, v47
	s_waitcnt vmcnt(1)
; DEVI unsigned pk2(float lo, float hi) { unsigned r; asm("v_cvt_pk_bf16_f32 %0, %1, %2" : "=v"(r) : "v"(lo), "v"(hi)); return r; }
; DEVI void row_stats(const float* stats, int row, float& mu, float& rs) {
;     if (stats) { const float2 st = *(const float2*)(stats + 2 * (size_t)row); mu = st.x * (1.0f / 1024.0f); const float var = st.y * (1.0f / 1024.0f) - mu * mu; rs = rsqrtf(fmaxf(var, 0.f) + LN_EPS); }
;     DEVI void operator()(const f32x4 (&acc)[2][2][4][2], const pg8::Unit& u, int wr, int wc, int fr, int fq) const {
;     ...
;                 const int row = row0 + ai * 128 + m * 16; float mu, rs; row_stats(stin, row, mu, rs);
;                 float sum = 0.f, sq = 0.f;
; #pragma unroll
;                 for (int bj = 0; bj < 2; ++bj) {
;                     f32x4 z[2];
; #pragma unroll
;                     for (int n = 0; n < 2; ++n) {
;                         const int col = colb + bj * 128 + 4 * n;
;                         f32x4 xv = *(const f32x4*)(zsrc + (size_t)row * DM + col);
;                         if (stin) { const f32x4 gv = *(const f32x4*)(gin + col), bv = *(const f32x4*)(bin + col); xv = (xv - mu) * rs * gv + bv; }
;                         f32x4 zz = ALPHA * xv + acc[ai][bj][m][n];
;                         if (bias) zz += *(const f32x4*)(bias + col);
;                         *(f32x4*)(zdst + (size_t)row * DM + col) = zz;
;                         sum += zz[0] + zz[1] + zz[2] + zz[3]; sq += zz[0] * zz[0] + zz[1] * zz[1] + zz[2] * zz[2] + zz[3] * zz[3];
;                         z[n] = zz;
;                     }
;                     u32x4 o; o.x = pk2(z[0][0], z[0][1]); o.y = pk2(z[0][2], z[0][3]); o.z = pk2(z[1][0], z[1][1]); o.w = pk2(z[1][2], z[1][3]);
;                     if (zb) *(u32x4*)(zb + (size_t)row * DM + colb + bj * 128) = o;
;                 }
;                 sum += __shfl_xor(sum, 16); sq += __shfl_xor(sq, 16);
;                 sum += __shfl_xor(sum, 32); sq += __shfl_xor(sq, 32);
;                 if (fq == 0) { atomicAdd(stout + 2 * (size_t)row, sum); atomicAdd(stout + 2 * (size_t)row + 1, sq); }
	v_pk_fma_f32 v[52:53], v[52:53], v[66:67], v[56:57]
	v_pk_fma_f32 v[54:55], v[54:55], v[68:69], v[58:59]
	v_pk_fma_f32 v[40:41], v[52:53], s[20:21], v[40:41] op_sel_hi:[1,0,1]
	v_pk_fma_f32 v[42:43], v[54:55], s[20:21], v[42:43] op_sel_hi:[1,0,1]
	s_waitcnt vmcnt(0)
	v_pk_add_f32 v[40:41], v[60:61], v[40:41]
	v_pk_add_f32 v[42:43], v[62:63], v[42:43]
	global_store_dwordx4 v[50:51], v[40:43], off offset:16
	v_cvt_pk_bf16_f32 v66, v40, v41
	v_cvt_pk_bf16_f32 v67, v42, v43
	flat_store_dwordx4 v[72:73], v[64:67]
	global_load_dwordx4 v[52:55], v[50:51], off offset:512
	global_load_dwordx4 v[56:59], v[144:145], off offset:512
	global_load_dwordx4 v[60:63], v[146:147], off offset:512
	s_nop 0
	global_load_dwordx4 v[64:67], v[120:121], off
	global_load_dwordx4 v[68:71], v[50:51], off offset:528
	s_waitcnt vmcnt(0)
	v_sub_f32_e32 v55, v55, v75
	v_sub_f32_e32 v54, v54, v75
	v_sub_f32_e32 v53, v53, v75
	v_sub_f32_e32 v52, v52, v75
	v_pk_mul_f32 v[52:53], v[74:75], v[52:53] op_sel_hi:[0,1]
	v_pk_mul_f32 v[54:55], v[74:75], v[54:55] op_sel_hi:[0,1]
	v_pk_fma_f32 v[54:55], v[58:59], v[54:55], v[62:63]
	v_pk_fma_f32 v[52:53], v[56:57], v[52:53], v[60:61]
	v_pk_fma_f32 v[38:39], v[54:55], s[20:21], v[38:39] op_sel_hi:[1,0,1]
	v_pk_fma_f32 v[36:37], v[52:53], s[20:21], v[36:37] op_sel_hi:[1,0,1]
	v_pk_add_f32 v[38:39], v[66:67], v[38:39]
	v_pk_add_f32 v[36:37], v[64:65], v[36:37]
	global_store_dwordx4 v[50:51], v[36:39], off offset:512
	global_load_dwordx4 v[52:55], v[144:145], off offset:528
	global_load_dwordx4 v[56:59], v[146:147], off offset:528
	global_load_dwordx4 v[60:63], v[116:117], off
	v_add_f32_e32 v64, v44, v45
	v_mul_f32_e32 v45, v45, v45
	v_fmac_f32_e32 v45, v44, v44
	v_add_f32_e32 v64, v46, v64
	v_fmac_f32_e32 v45, v46, v46
	v_add_f32_e32 v46, v40, v41
	v_mul_f32_e32 v41, v41, v41
	v_fmac_f32_e32 v41, v40, v40
	v_add_f32_e32 v44, v47, v64
	v_add_f32_e32 v46, v42, v46
	v_fmac_f32_e32 v41, v42, v42
	v_add_f32_e32 v44, 0, v44
	v_fmac_f32_e32 v45, v47, v47
	v_add_f32_e32 v40, v43, v46
	v_fmac_f32_e32 v41, v43, v43
	v_sub_f32_e32 v43, v69, v75
	v_sub_f32_e32 v42, v68, v75
	v_add_f32_e32 v44, v40, v44
	v_add_f32_e32 v45, v45, v41
	v_sub_f32_e32 v41, v71, v75
	v_sub_f32_e32 v40, v70, v75
	v_pk_mul_f32 v[42:43], v[74:75], v[42:43] op_sel_hi:[0,1]
	v_pk_mul_f32 v[40:41], v[74:75], v[40:41] op_sel_hi:[0,1]
	v_mul_f32_e32 v47, v37, v37
	v_add_f32_e32 v46, v36, v37
	v_fmac_f32_e32 v47, v36, v36
	v_add_f32_e32 v46, v38, v46
	v_fmac_f32_e32 v47, v38, v38
	v_add_f32_e32 v46, v39, v46
	v_fmac_f32_e32 v47, v39, v39
	v_add_f32_e32 v44, v44, v46
	v_add_f32_e32 v45, v45, v47
	v_cvt_pk_bf16_f32 v36, v36, v37
	v_cvt_pk_bf16_f32 v37, v38, v39
	s_waitcnt vmcnt(0)
	v_pk_fma_f32 v[42:43], v[52:53], v[42:43], v[56:57]
	v_pk_fma_f32 v[40:41], v[54:55], v[40:41], v[58:59]
	v_pk_fma_f32 v[32:33], v[42:43], s[20:21], v[32:33] op_sel_hi:[1,0,1]
	v_pk_fma_f32 v[34:35], v[40:41], s[20:21], v[34:35] op_sel_hi:[1,0,1]
	v_pk_add_f32 v[40:41], v[60:61], v[32:33]
	v_pk_add_f32 v[42:43], v[62:63], v[34:35]
	v_mul_f32_e32 v33, v41, v41
	v_add_f32_e32 v32, v40, v41
	v_fmac_f32_e32 v33, v40, v40
	v_add_f32_e32 v32, v42, v32
	v_fmac_f32_e32 v33, v42, v42
	v_add_f32_e32 v32, v43, v32
	v_fmac_f32_e32 v33, v43, v43
	v_add_f32_e32 v32, v44, v32
	v_add_f32_e32 v33, v45, v33
	ds_bpermute_b32 v34, v118, v32
	ds_bpermute_b32 v35, v118, v33
	global_store_dwordx4 v[50:51], v[40:43], off offset:528
	v_cvt_pk_bf16_f32 v38, v40, v41
	v_cvt_pk_bf16_f32 v39, v42, v43
	s_waitcnt lgkmcnt(0)
	v_add_f32_e32 v32, v32, v34
	v_add_f32_e32 v33, v33, v35
	ds_bpermute_b32 v34, v119, v32
	ds_bpermute_b32 v35, v119, v33
	flat_store_dwordx4 v[72:73], v[36:39] offset:256
	s_mov_b32 s100, -1
	s_mov_b32 s101, 0
	s_mov_b32 s98, 0xffff0000
	s_mov_b32 s99, 0
	s_and_saveexec_b64 s[30:31], s[100:101]
	s_cbranch_execz .LBB0_1341
	v_lshl_add_u64 v[36:37], s[8:9], 0, v[48:49]
	s_waitcnt lgkmcnt(0)
	v_add_f32_e32 v32, v32, v34
	v_add_f32_e32 v33, v33, v35
	v_cndmask_b32_e64 v32, v32, v33, s[98:99]
	v_cndmask_b32_e64 v33, 0, 4, s[98:99]
	v_or_b32_e32 v36, v36, v33
	flat_atomic_add_f32 v[36:37], v32
.LBB0_1341:
	s_or_b64 exec, exec, s[30:31]
	v_add_u32_e32 v56, 0xa0, v150
	v_ashrrev_i32_e32 v57, 31, v56
	v_lshlrev_b64 v[32:33], 3, v[56:57]
	s_waitcnt lgkmcnt(0)
	v_lshl_add_u64 v[34:35], s[6:7], 0, v[32:33]
	flat_load_dwordx2 v[58:59], v[34:35]
	v_lshlrev_b64 v[34:35], 12, v[56:57]
	v_lshl_add_u64 v[34:35], s[46:47], 0, v[34:35]
	v_lshl_add_u64 v[34:35], v[148:149], 2, v[34:35]
	global_load_dwordx4 v[36:39], v[34:35], off
	global_load_dwordx4 v[40:43], v[144:145], off
	global_load_dwordx4 v[44:47], v[146:147], off
	global_load_dwordx4 v[48:51], v[152:153], off
	global_load_dwordx4 v[52:55], v[34:35], off offset:16
	s_waitcnt vmcnt(0) lgkmcnt(0)
	v_pk_mul_f32 v[58:59], v[58:59], s[18:19] op_sel:[1,0] op_sel_hi:[0,0]
	v_fma_f32 v58, -v59, v59, v58
	v_max_f32_e32 v58, 0, v58
	v_add_f32_e32 v58, 0x3727c5ac, v58
	v_mul_f32_e32 v60, 0x4b800000, v58
	v_cmp_gt_f32_e32 vcc, s64, v58
	v_sub_f32_e32 v39, v39, v59
	v_sub_f32_e32 v38, v38, v59
	v_cndmask_b32_e32 v58, v58, v60, vcc
	v_rsq_f32_e32 v58, v58
	v_sub_f32_e32 v37, v37, v59
	v_sub_f32_e32 v36, v36, v59
	v_mul_f32_e32 v60, 0x45800000, v58
	v_cndmask_b32_e32 v58, v58, v60, vcc
	v_pk_mul_f32 v[36:37], v[36:37], v[58:59] op_sel_hi:[1,0]
	v_pk_mul_f32 v[38:39], v[38:39], v[58:59] op_sel_hi:[1,0]
	v_pk_fma_f32 v[36:37], v[40:41], v[36:37], v[44:45]
	v_pk_fma_f32 v[38:39], v[42:43], v[38:39], v[46:47]
	v_pk_fma_f32 v[28:29], v[36:37], s[20:21], v[28:29] op_sel_hi:[1,0,1]
	v_pk_fma_f32 v[30:31], v[38:39], s[20:21], v[30:31] op_sel_hi:[1,0,1]
	v_pk_add_f32 v[28:29], v[48:49], v[28:29]
	v_pk_add_f32 v[30:31], v[50:51], v[30:31]
	global_store_dwordx4 v[34:35], v[28:31], off
	global_load_dwordx4 v[36:39], v[144:145], off offset:16
	global_load_dwordx4 v[40:43], v[146:147], off offset:16
	global_load_dwordx4 v[44:47], v[154:155], off
	v_lshlrev_b64 v[48:49], 11, v[56:57]
	v_lshl_add_u64 v[48:49], s[10:11], 0, v[48:49]
	v_lshl_add_u64 v[56:57], v[148:149], 1, v[48:49]
	v_sub_f32_e32 v49, v55, v59
	v_sub_f32_e32 v48, v54, v59
	v_sub_f32_e32 v51, v53, v59
	v_sub_f32_e32 v50, v52, v59
	v_pk_mul_f32 v[50:51], v[50:51], v[58:59] op_sel_hi:[1,0]
	v_pk_mul_f32 v[52:53], v[48:49], v[58:59] op_sel_hi:[1,0]
	v_cvt_pk_bf16_f32 v48, v28, v29
	v_cvt_pk_bf16_f32 v49, v30, v31
	s_waitcnt vmcnt(1)
; DEVI unsigned pk2(float lo, float hi) { unsigned r; asm("v_cvt_pk_bf16_f32 %0, %1, %2" : "=v"(r) : "v"(lo), "v"(hi)); return r; }
; DEVI void row_stats(const float* stats, int row, float& mu, float& rs) {
;     if (stats) { const float2 st = *(const float2*)(stats + 2 * (size_t)row); mu = st.x * (1.0f / 1024.0f); const float var = st.y * (1.0f / 1024.0f) - mu * mu; rs = rsqrtf(fmaxf(var, 0.f) + LN_EPS); }
;     DEVI void operator()(const f32x4 (&acc)[2][2][4][2], const pg8::Unit& u, int wr, int wc, int fr, int fq) const {
;     ...
;                 const int row = row0 + ai * 128 + m * 16; float mu, rs; row_stats(stin, row, mu, rs);
;                 float sum = 0.f, sq = 0.f;
; #pragma unroll
;                 for (int bj = 0; bj < 2; ++bj) {
;                     f32x4 z[2];
; #pragma unroll
;                     for (int n = 0; n < 2; ++n) {
;                         const int col = colb + bj * 128 + 4 * n;
;                         f32x4 xv = *(const f32x4*)(zsrc + (size_t)row * DM + col);
;                         if (stin) { const f32x4 gv = *(const f32x4*)(gin + col), bv = *(const f32x4*)(bin + col); xv = (xv - mu) * rs * gv + bv; }
;                         f32x4 zz = ALPHA * xv + acc[ai][bj][m][n];
;                         if (bias) zz += *(const f32x4*)(bias + col);
;                         *(f32x4*)(zdst + (size_t)row * DM + col) = zz;
;                         sum += zz[0] + zz[1] + zz[2] + zz[3]; sq += zz[0] * zz[0] + zz[1] * zz[1] + zz[2] * zz[2] + zz[3] * zz[3];
;                         z[n] = zz;
;                     }
;                     u32x4 o; o.x = pk2(z[0][0], z[0][1]); o.y = pk2(z[0][2], z[0][3]); o.z = pk2(z[1][0], z[1][1]); o.w = pk2(z[1][2], z[1][3]);
;                     if (zb) *(u32x4*)(zb + (size_t)row * DM + colb + bj * 128) = o;
;                 }
;                 sum += __shfl_xor(sum, 16); sq += __shfl_xor(sq, 16);
;                 sum += __shfl_xor(sum, 32); sq += __shfl_xor(sq, 32);
;                 if (fq == 0) { atomicAdd(stout + 2 * (size_t)row, sum); atomicAdd(stout + 2 * (size_t)row + 1, sq); }
	v_pk_fma_f32 v[36:37], v[36:37], v[50:51], v[40:41]
	v_pk_fma_f32 v[38:39], v[38:39], v[52:53], v[42:43]
	v_pk_fma_f32 v[24:25], v[36:37], s[20:21], v[24:25] op_sel_hi:[1,0,1]
	v_pk_fma_f32 v[26:27], v[38:39], s[20:21], v[26:27] op_sel_hi:[1,0,1]
	s_waitcnt vmcnt(0)
	v_pk_add_f32 v[24:25], v[44:45], v[24:25]
	v_pk_add_f32 v[26:27], v[46:47], v[26:27]
	global_store_dwordx4 v[34:35], v[24:27], off offset:16
	v_cvt_pk_bf16_f32 v50, v24, v25
	v_cvt_pk_bf16_f32 v51, v26, v27
	flat_store_dwordx4 v[56:57], v[48:51]
	global_load_dwordx4 v[36:39], v[34:35], off offset:512
	global_load_dwordx4 v[40:43], v[144:145], off offset:512
	global_load_dwordx4 v[44:47], v[146:147], off offset:512
	s_nop 0
	global_load_dwordx4 v[48:51], v[120:121], off
	global_load_dwordx4 v[52:55], v[34:35], off offset:528
	s_waitcnt vmcnt(0)
	v_sub_f32_e32 v39, v39, v59
	v_sub_f32_e32 v38, v38, v59
	v_sub_f32_e32 v37, v37, v59
	v_sub_f32_e32 v36, v36, v59
	v_pk_mul_f32 v[36:37], v[58:59], v[36:37] op_sel_hi:[0,1]
	v_pk_mul_f32 v[38:39], v[58:59], v[38:39] op_sel_hi:[0,1]
	v_pk_fma_f32 v[38:39], v[42:43], v[38:39], v[46:47]
	v_pk_fma_f32 v[36:37], v[40:41], v[36:37], v[44:45]
	v_pk_fma_f32 v[22:23], v[38:39], s[20:21], v[22:23] op_sel_hi:[1,0,1]
	v_pk_fma_f32 v[20:21], v[36:37], s[20:21], v[20:21] op_sel_hi:[1,0,1]
	v_pk_add_f32 v[22:23], v[50:51], v[22:23]
	v_pk_add_f32 v[20:21], v[48:49], v[20:21]
	global_store_dwordx4 v[34:35], v[20:23], off offset:512
	global_load_dwordx4 v[36:39], v[144:145], off offset:528
	global_load_dwordx4 v[40:43], v[146:147], off offset:528
	global_load_dwordx4 v[44:47], v[116:117], off
	v_add_f32_e32 v48, v28, v29
	v_mul_f32_e32 v29, v29, v29
	v_fmac_f32_e32 v29, v28, v28
	v_add_f32_e32 v48, v30, v48
	v_fmac_f32_e32 v29, v30, v30
	v_add_f32_e32 v30, v24, v25
	v_mul_f32_e32 v25, v25, v25
	v_fmac_f32_e32 v25, v24, v24
	v_add_f32_e32 v28, v31, v48
	v_add_f32_e32 v30, v26, v30
	v_fmac_f32_e32 v25, v26, v26
	v_add_f32_e32 v28, 0, v28
	v_fmac_f32_e32 v29, v31, v31
	v_add_f32_e32 v24, v27, v30
	v_fmac_f32_e32 v25, v27, v27
	v_sub_f32_e32 v27, v53, v59
	v_sub_f32_e32 v26, v52, v59
	v_add_f32_e32 v28, v24, v28
	v_add_f32_e32 v29, v29, v25
	v_sub_f32_e32 v25, v55, v59
	v_sub_f32_e32 v24, v54, v59
	v_pk_mul_f32 v[26:27], v[58:59], v[26:27] op_sel_hi:[0,1]
	v_pk_mul_f32 v[24:25], v[58:59], v[24:25] op_sel_hi:[0,1]
	v_mul_f32_e32 v31, v21, v21
	v_add_f32_e32 v30, v20, v21
	v_fmac_f32_e32 v31, v20, v20
	v_add_f32_e32 v30, v22, v30
	v_fmac_f32_e32 v31, v22, v22
	v_add_f32_e32 v30, v23, v30
	v_fmac_f32_e32 v31, v23, v23
	v_add_f32_e32 v28, v28, v30
	v_add_f32_e32 v29, v29, v31
	v_cvt_pk_bf16_f32 v20, v20, v21
	v_cvt_pk_bf16_f32 v21, v22, v23
	s_waitcnt vmcnt(0)
	v_pk_fma_f32 v[26:27], v[36:37], v[26:27], v[40:41]
	v_pk_fma_f32 v[24:25], v[38:39], v[24:25], v[42:43]
	v_pk_fma_f32 v[16:17], v[26:27], s[20:21], v[16:17] op_sel_hi:[1,0,1]
	v_pk_fma_f32 v[18:19], v[24:25], s[20:21], v[18:19] op_sel_hi:[1,0,1]
	v_pk_add_f32 v[24:25], v[44:45], v[16:17]
	v_pk_add_f32 v[26:27], v[46:47], v[18:19]
	v_mul_f32_e32 v17, v25, v25
	v_add_f32_e32 v16, v24, v25
	v_fmac_f32_e32 v17, v24, v24
	v_add_f32_e32 v16, v26, v16
	v_fmac_f32_e32 v17, v26, v26
	v_add_f32_e32 v16, v27, v16
	v_fmac_f32_e32 v17, v27, v27
	v_add_f32_e32 v16, v28, v16
	v_add_f32_e32 v17, v29, v17
	ds_bpermute_b32 v18, v118, v16
	ds_bpermute_b32 v19, v118, v17
	global_store_dwordx4 v[34:35], v[24:27], off offset:528
	v_cvt_pk_bf16_f32 v22, v24, v25
	v_cvt_pk_bf16_f32 v23, v26, v27
	s_waitcnt lgkmcnt(0)
	v_add_f32_e32 v16, v16, v18
	v_add_f32_e32 v17, v17, v19
	ds_bpermute_b32 v18, v119, v16
	ds_bpermute_b32 v19, v119, v17
	flat_store_dwordx4 v[56:57], v[20:23] offset:256
	s_mov_b32 s100, -1
	s_mov_b32 s101, 0
	s_mov_b32 s98, 0xffff0000
	s_mov_b32 s99, 0
	s_and_saveexec_b64 s[30:31], s[100:101]
	s_cbranch_execz .LBB0_1343
	v_lshl_add_u64 v[20:21], s[8:9], 0, v[32:33]
	s_waitcnt lgkmcnt(0)
	v_add_f32_e32 v16, v16, v18
	v_add_f32_e32 v17, v17, v19
	v_cndmask_b32_e64 v16, v16, v17, s[98:99]
	v_cndmask_b32_e64 v17, 0, 4, s[98:99]
	v_or_b32_e32 v20, v20, v17
	flat_atomic_add_f32 v[20:21], v16
; DEVI unsigned pk2(float lo, float hi) { unsigned r; asm("v_cvt_pk_bf16_f32 %0, %1, %2" : "=v"(r) : "v"(lo), "v"(hi)); return r; }
; DEVI void row_stats(const float* stats, int row, float& mu, float& rs) {
;     if (stats) { const float2 st = *(const float2*)(stats + 2 * (size_t)row); mu = st.x * (1.0f / 1024.0f); const float var = st.y * (1.0f / 1024.0f) - mu * mu; rs = rsqrtf(fmaxf(var, 0.f) + LN_EPS); }
;     DEVI void operator()(const f32x4 (&acc)[2][2][4][2], const pg8::Unit& u, int wr, int wc, int fr, int fq) const {
;     ...
;                 const int row = row0 + ai * 128 + m * 16; float mu, rs; row_stats(stin, row, mu, rs);
;                 float sum = 0.f, sq = 0.f;
; #pragma unroll
;                 for (int bj = 0; bj < 2; ++bj) {
;                     f32x4 z[2];
; #pragma unroll
;                     for (int n = 0; n < 2; ++n) {
;                         const int col = colb + bj * 128 + 4 * n;
;                         f32x4 xv = *(const f32x4*)(zsrc + (size_t)row * DM + col);
;                         if (stin) { const f32x4 gv = *(const f32x4*)(gin + col), bv = *(const f32x4*)(bin + col); xv = (xv - mu) * rs * gv + bv; }
;                         f32x4 zz = ALPHA * xv + acc[ai][bj][m][n];
;                         if (bias) zz += *(const f32x4*)(bias + col);
;                         *(f32x4*)(zdst + (size_t)row * DM + col) = zz;
;                         sum += zz[0] + zz[1] + zz[2] + zz[3]; sq += zz[0] * zz[0] + zz[1] * zz[1] + zz[2] * zz[2] + zz[3] * zz[3];
;                         z[n] = zz;
;                     }
;                     u32x4 o; o.x = pk2(z[0][0], z[0][1]); o.y = pk2(z[0][2], z[0][3]); o.z = pk2(z[1][0], z[1][1]); o.w = pk2(z[1][2], z[1][3]);
;                     if (zb) *(u32x4*)(zb + (size_t)row * DM + colb + bj * 128) = o;
;                 }
;                 sum += __shfl_xor(sum, 16); sq += __shfl_xor(sq, 16);
;                 sum += __shfl_xor(sum, 32); sq += __shfl_xor(sq, 32);
;                 if (fq == 0) { atomicAdd(stout + 2 * (size_t)row, sum); atomicAdd(stout + 2 * (size_t)row + 1, sq); }
.LBB0_1343:
	s_or_b64 exec, exec, s[30:31]
	v_add_u32_e32 v40, 0xb0, v150
	v_ashrrev_i32_e32 v41, 31, v40
	v_lshlrev_b64 v[16:17], 3, v[40:41]
	s_waitcnt lgkmcnt(0)
	v_lshl_add_u64 v[18:19], s[6:7], 0, v[16:17]
	flat_load_dwordx2 v[42:43], v[18:19]
	v_lshlrev_b64 v[18:19], 12, v[40:41]
	v_lshl_add_u64 v[18:19], s[46:47], 0, v[18:19]
	v_lshl_add_u64 v[18:19], v[148:149], 2, v[18:19]
	global_load_dwordx4 v[20:23], v[18:19], off
	global_load_dwordx4 v[24:27], v[144:145], off
	global_load_dwordx4 v[28:31], v[146:147], off
	global_load_dwordx4 v[32:35], v[152:153], off
	global_load_dwordx4 v[36:39], v[18:19], off offset:16
	s_waitcnt vmcnt(0) lgkmcnt(0)
	v_pk_mul_f32 v[42:43], v[42:43], s[18:19] op_sel:[1,0] op_sel_hi:[0,0]
	v_fma_f32 v42, -v43, v43, v42
	v_max_f32_e32 v42, 0, v42
	v_add_f32_e32 v42, 0x3727c5ac, v42
	v_mul_f32_e32 v44, 0x4b800000, v42
	v_cmp_gt_f32_e32 vcc, s64, v42
	v_sub_f32_e32 v23, v23, v43
	v_sub_f32_e32 v22, v22, v43
	v_cndmask_b32_e32 v42, v42, v44, vcc
	v_rsq_f32_e32 v42, v42
	v_sub_f32_e32 v21, v21, v43
	v_sub_f32_e32 v20, v20, v43
	v_mul_f32_e32 v44, 0x45800000, v42
	v_cndmask_b32_e32 v42, v42, v44, vcc
	v_pk_mul_f32 v[20:21], v[20:21], v[42:43] op_sel_hi:[1,0]
	v_pk_mul_f32 v[22:23], v[22:23], v[42:43] op_sel_hi:[1,0]
	v_pk_fma_f32 v[20:21], v[24:25], v[20:21], v[28:29]
	v_pk_fma_f32 v[22:23], v[26:27], v[22:23], v[30:31]
	v_pk_fma_f32 v[12:13], v[20:21], s[20:21], v[12:13] op_sel_hi:[1,0,1]
	v_pk_fma_f32 v[14:15], v[22:23], s[20:21], v[14:15] op_sel_hi:[1,0,1]
	v_pk_add_f32 v[12:13], v[32:33], v[12:13]
	v_pk_add_f32 v[14:15], v[34:35], v[14:15]
	global_store_dwordx4 v[18:19], v[12:15], off
	global_load_dwordx4 v[20:23], v[144:145], off offset:16
	global_load_dwordx4 v[24:27], v[146:147], off offset:16
	global_load_dwordx4 v[28:31], v[154:155], off
	v_lshlrev_b64 v[32:33], 11, v[40:41]
	v_lshl_add_u64 v[32:33], s[10:11], 0, v[32:33]
	v_lshl_add_u64 v[40:41], v[148:149], 1, v[32:33]
	v_sub_f32_e32 v33, v39, v43
	v_sub_f32_e32 v32, v38, v43
	v_sub_f32_e32 v35, v37, v43
	v_sub_f32_e32 v34, v36, v43
	v_pk_mul_f32 v[34:35], v[34:35], v[42:43] op_sel_hi:[1,0]
	v_pk_mul_f32 v[36:37], v[32:33], v[42:43] op_sel_hi:[1,0]
	v_cvt_pk_bf16_f32 v32, v12, v13
	v_cvt_pk_bf16_f32 v33, v14, v15
	s_waitcnt vmcnt(1)
	v_pk_fma_f32 v[20:21], v[20:21], v[34:35], v[24:25]
	v_pk_fma_f32 v[22:23], v[22:23], v[36:37], v[26:27]
	v_pk_fma_f32 v[8:9], v[20:21], s[20:21], v[8:9] op_sel_hi:[1,0,1]
	v_pk_fma_f32 v[10:11], v[22:23], s[20:21], v[10:11] op_sel_hi:[1,0,1]
	s_waitcnt vmcnt(0)
	v_pk_add_f32 v[8:9], v[28:29], v[8:9]
	v_pk_add_f32 v[10:11], v[30:31], v[10:11]
	global_store_dwordx4 v[18:19], v[8:11], off offset:16
	v_cvt_pk_bf16_f32 v34, v8, v9
	v_cvt_pk_bf16_f32 v35, v10, v11
	flat_store_dwordx4 v[40:41], v[32:35]
	global_load_dwordx4 v[20:23], v[18:19], off offset:512
	global_load_dwordx4 v[24:27], v[144:145], off offset:512
	global_load_dwordx4 v[28:31], v[146:147], off offset:512
	s_nop 0
	global_load_dwordx4 v[32:35], v[120:121], off
	global_load_dwordx4 v[36:39], v[18:19], off offset:528
	s_waitcnt vmcnt(0)
	v_sub_f32_e32 v23, v23, v43
	v_sub_f32_e32 v22, v22, v43
	v_sub_f32_e32 v21, v21, v43
	v_sub_f32_e32 v20, v20, v43
	v_pk_mul_f32 v[20:21], v[42:43], v[20:21] op_sel_hi:[0,1]
	v_pk_mul_f32 v[22:23], v[42:43], v[22:23] op_sel_hi:[0,1]
	v_pk_fma_f32 v[22:23], v[26:27], v[22:23], v[30:31]
	v_pk_fma_f32 v[20:21], v[24:25], v[20:21], v[28:29]
	v_pk_fma_f32 v[6:7], v[22:23], s[20:21], v[6:7] op_sel_hi:[1,0,1]
	v_pk_fma_f32 v[4:5], v[20:21], s[20:21], v[4:5] op_sel_hi:[1,0,1]
	v_pk_add_f32 v[6:7], v[34:35], v[6:7]
	v_pk_add_f32 v[4:5], v[32:33], v[4:5]
	global_store_dwordx4 v[18:19], v[4:7], off offset:512
	global_load_dwordx4 v[20:23], v[144:145], off offset:528
	global_load_dwordx4 v[24:27], v[146:147], off offset:528
	global_load_dwordx4 v[28:31], v[116:117], off
	v_add_f32_e32 v32, v12, v13
	v_mul_f32_e32 v13, v13, v13
	v_fmac_f32_e32 v13, v12, v12
	v_add_f32_e32 v32, v14, v32
	v_fmac_f32_e32 v13, v14, v14
	v_add_f32_e32 v14, v8, v9
	v_mul_f32_e32 v9, v9, v9
	v_fmac_f32_e32 v9, v8, v8
	v_add_f32_e32 v12, v15, v32
	v_add_f32_e32 v14, v10, v14
	v_fmac_f32_e32 v9, v10, v10
	v_add_f32_e32 v12, 0, v12
	v_fmac_f32_e32 v13, v15, v15
	v_add_f32_e32 v8, v11, v14
	v_fmac_f32_e32 v9, v11, v11
	v_sub_f32_e32 v11, v37, v43
	v_sub_f32_e32 v10, v36, v43
	v_add_f32_e32 v12, v8, v12
	v_add_f32_e32 v13, v13, v9
	v_sub_f32_e32 v9, v39, v43
	v_sub_f32_e32 v8, v38, v43
	v_pk_mul_f32 v[10:11], v[42:43], v[10:11] op_sel_hi:[0,1]
	v_pk_mul_f32 v[8:9], v[42:43], v[8:9] op_sel_hi:[0,1]
	v_mul_f32_e32 v15, v5, v5
	v_add_f32_e32 v14, v4, v5
	v_fmac_f32_e32 v15, v4, v4
	v_add_f32_e32 v14, v6, v14
	v_fmac_f32_e32 v15, v6, v6
	v_add_f32_e32 v14, v7, v14
	v_fmac_f32_e32 v15, v7, v7
	v_add_f32_e32 v12, v12, v14
	v_add_f32_e32 v13, v13, v15
	v_cvt_pk_bf16_f32 v4, v4, v5
	v_cvt_pk_bf16_f32 v5, v6, v7
	s_waitcnt vmcnt(0)
	v_pk_fma_f32 v[10:11], v[20:21], v[10:11], v[24:25]
	v_pk_fma_f32 v[8:9], v[22:23], v[8:9], v[26:27]
	v_pk_fma_f32 v[0:1], v[10:11], s[20:21], v[0:1] op_sel_hi:[1,0,1]
	v_pk_fma_f32 v[2:3], v[8:9], s[20:21], v[2:3] op_sel_hi:[1,0,1]
	v_pk_add_f32 v[8:9], v[28:29], v[0:1]
	v_pk_add_f32 v[10:11], v[30:31], v[2:3]
	v_mul_f32_e32 v1, v9, v9
	v_add_f32_e32 v0, v8, v9
	v_fmac_f32_e32 v1, v8, v8
	v_add_f32_e32 v0, v10, v0
	v_fmac_f32_e32 v1, v10, v10
	v_add_f32_e32 v0, v11, v0
	v_fmac_f32_e32 v1, v11, v11
	v_add_f32_e32 v0, v12, v0
	v_add_f32_e32 v1, v13, v1
	ds_bpermute_b32 v2, v118, v0
	ds_bpermute_b32 v3, v118, v1
	global_store_dwordx4 v[18:19], v[8:11], off offset:528
	v_cvt_pk_bf16_f32 v6, v8, v9
	v_cvt_pk_bf16_f32 v7, v10, v11
	s_waitcnt lgkmcnt(0)
	v_add_f32_e32 v0, v0, v2
	v_add_f32_e32 v1, v1, v3
	ds_bpermute_b32 v2, v119, v0
	ds_bpermute_b32 v3, v119, v1
	flat_store_dwordx4 v[40:41], v[4:7] offset:256
	s_mov_b32 s100, -1
	s_mov_b32 s101, 0
	s_mov_b32 s98, 0xffff0000
	s_mov_b32 s99, 0
	s_and_saveexec_b64 s[30:31], s[100:101]
	s_cbranch_execz .LBB0_1345
	v_lshl_add_u64 v[4:5], s[8:9], 0, v[16:17]
	s_waitcnt lgkmcnt(0)
	v_add_f32_e32 v0, v0, v2
	v_add_f32_e32 v1, v1, v3
	v_cndmask_b32_e64 v0, v0, v1, s[98:99]
	v_cndmask_b32_e64 v1, 0, 4, s[98:99]
	v_or_b32_e32 v4, v4, v1
	flat_atomic_add_f32 v[4:5], v0

; DEVI unsigned pk2(float lo, float hi) { unsigned r; asm("v_cvt_pk_bf16_f32 %0, %1, %2" : "=v"(r) : "v"(lo), "v"(hi)); return r; }
; DEVI void row_stats(const float* stats, int row, float& mu, float& rs) {
;     if (stats) { const float2 st = *(const float2*)(stats + 2 * (size_t)row); mu = st.x * (1.0f / 1024.0f); const float var = st.y * (1.0f / 1024.0f) - mu * mu; rs = rsqrtf(fmaxf(var, 0.f) + LN_EPS); }
;     DEVI void operator()(const f32x4 (&acc)[2][2][4][2], const pg8::Unit& u, int wr, int wc, int fr, int fq) const {
;     ...
;                 const int row = row0 + ai * 128 + m * 16; float mu, rs; row_stats(stin, row, mu, rs);
;                 float sum = 0.f, sq = 0.f;
; #pragma unroll
;                 for (int bj = 0; bj < 2; ++bj) {
;                     f32x4 z[2];
; #pragma unroll
;                     for (int n = 0; n < 2; ++n) {
;                         const int col = colb + bj * 128 + 4 * n;
;                         f32x4 xv = *(const f32x4*)(zsrc + (size_t)row * DM + col);
;                         if (stin) { const f32x4 gv = *(const f32x4*)(gin + col), bv = *(const f32x4*)(bin + col); xv = (xv - mu) * rs * gv + bv; }
;                         f32x4 zz = ALPHA * xv + acc[ai][bj][m][n];
;                         if (bias) zz += *(const f32x4*)(bias + col);
;                         *(f32x4*)(zdst + (size_t)row * DM + col) = zz;
;                         sum += zz[0] + zz[1] + zz[2] + zz[3]; sq += zz[0] * zz[0] + zz[1] * zz[1] + zz[2] * zz[2] + zz[3] * zz[3];
;                         z[n] = zz;
;                     }
;                     u32x4 o; o.x = pk2(z[0][0], z[0][1]); o.y = pk2(z[0][2], z[0][3]); o.z = pk2(z[1][0], z[1][1]); o.w = pk2(z[1][2], z[1][3]);
;                     if (zb) *(u32x4*)(zb + (size_t)row * DM + colb + bj * 128) = o;
;                 }
;                 sum += __shfl_xor(sum, 16); sq += __shfl_xor(sq, 16);
;                 sum += __shfl_xor(sum, 32); sq += __shfl_xor(sq, 32);
;                 if (fq == 0) { atomicAdd(stout + 2 * (size_t)row, sum); atomicAdd(stout + 2 * (size_t)row + 1, sq); }
.LBB0_1538:
	v_lshl_add_u32 v154, s64, 8, v162
	v_ashrrev_i32_e32 v155, 31, v154
	v_lshlrev_b64 v[156:157], 3, v[154:155]
	v_lshl_add_u64 v[146:147], s[12:13], 0, v[156:157]
	s_waitcnt vmcnt(0)
	flat_load_dwordx2 v[160:161], v[146:147]
	v_lshl_or_b32 v144, s65, 8, v164
	v_ashrrev_i32_e32 v145, 31, v144
	v_lshlrev_b64 v[146:147], 12, v[154:155]
	v_lshl_add_u64 v[146:147], s[46:47], 0, v[146:147]
	v_lshlrev_b64 v[148:149], 2, v[144:145]
	v_lshl_add_u64 v[158:159], v[146:147], 0, v[148:149]
	global_load_dwordx4 v[170:173], v[158:159], off
	v_lshl_add_u64 v[150:151], s[16:17], 0, v[148:149]
	v_lshl_add_u64 v[152:153], s[18:19], 0, v[148:149]
	global_load_dwordx4 v[174:177], v[150:151], off
	global_load_dwordx4 v[178:181], v[152:153], off
	global_load_dwordx4 v[182:185], v[158:159], off offset:16
	v_or_b32_e32 v146, 4, v144
	v_ashrrev_i32_e32 v147, 31, v146
	v_lshlrev_b64 v[148:149], 2, v[146:147]
	v_lshl_add_u64 v[146:147], s[16:17], 0, v[148:149]
	v_lshl_add_u64 v[148:149], s[18:19], 0, v[148:149]
	v_or_b32_e32 v186, 0x80, v144
	v_ashrrev_i32_e32 v187, 31, v186
	s_waitcnt vmcnt(0) lgkmcnt(0)
	v_pk_mul_f32 v[160:161], v[160:161], s[24:25] op_sel:[1,0] op_sel_hi:[0,0]
	v_fma_f32 v160, -v161, v161, v160
	v_max_f32_e32 v160, 0, v160
	v_add_f32_e32 v160, 0x3727c5ac, v160
	v_mul_f32_e32 v169, 0x4b800000, v160
	v_cmp_gt_f32_e32 vcc, s61, v160
	v_sub_f32_e32 v171, v171, v161
	s_nop 0
	v_cndmask_b32_e32 v160, v160, v169, vcc
	v_rsq_f32_e32 v160, v160
	v_sub_f32_e32 v170, v170, v161
	v_sub_f32_e32 v173, v173, v161
	v_sub_f32_e32 v172, v172, v161
	v_mul_f32_e32 v169, 0x45800000, v160
	v_cndmask_b32_e32 v160, v160, v169, vcc
	v_pk_mul_f32 v[172:173], v[172:173], v[160:161] op_sel_hi:[1,0]
	v_pk_mul_f32 v[170:171], v[170:171], v[160:161] op_sel_hi:[1,0]
	v_pk_fma_f32 v[172:173], v[176:177], v[172:173], v[180:181]
	v_pk_fma_f32 v[170:171], v[174:175], v[170:171], v[178:179]
	v_pk_fma_f32 v[172:173], v[172:173], s[26:27], v[126:127] op_sel_hi:[1,0,1]
	v_pk_fma_f32 v[170:171], v[170:171], s[26:27], v[124:125] op_sel_hi:[1,0,1]
	global_store_dwordx4 v[158:159], v[170:173], off
	global_load_dwordx4 v[124:127], v[146:147], off
	global_load_dwordx4 v[174:177], v[148:149], off
	v_lshlrev_b64 v[178:179], 11, v[154:155]
	v_lshl_add_u64 v[178:179], s[14:15], 0, v[178:179]
	v_lshl_add_u64 v[194:195], v[144:145], 1, v[178:179]
	v_sub_f32_e32 v179, v183, v161
	v_sub_f32_e32 v178, v182, v161
	v_sub_f32_e32 v181, v185, v161
	v_sub_f32_e32 v180, v184, v161
	v_pk_mul_f32 v[180:181], v[180:181], v[160:161] op_sel_hi:[1,0]
	v_pk_mul_f32 v[182:183], v[178:179], v[160:161] op_sel_hi:[1,0]
	v_cvt_pk_bf16_f32 v178, v170, v171
	v_cvt_pk_bf16_f32 v179, v172, v173
	s_waitcnt vmcnt(0)
	v_pk_fma_f32 v[126:127], v[126:127], v[180:181], v[176:177]
	v_pk_fma_f32 v[124:125], v[124:125], v[182:183], v[174:175]
	v_pk_fma_f32 v[176:177], v[126:127], s[26:27], v[122:123] op_sel_hi:[1,0,1]
	v_pk_fma_f32 v[174:175], v[124:125], s[26:27], v[120:121] op_sel_hi:[1,0,1]
	global_store_dwordx4 v[158:159], v[174:177], off offset:16
	v_cvt_pk_bf16_f32 v180, v174, v175
	v_cvt_pk_bf16_f32 v181, v176, v177
	flat_store_dwordx4 v[194:195], v[178:181]
	global_load_dwordx4 v[178:181], v[158:159], off offset:512
	v_lshlrev_b64 v[122:123], 2, v[186:187]
	v_lshl_add_u64 v[120:121], s[16:17], 0, v[122:123]
	v_lshl_add_u64 v[122:123], s[18:19], 0, v[122:123]
	global_load_dwordx4 v[182:185], v[120:121], off
	global_load_dwordx4 v[186:189], v[122:123], off
	global_load_dwordx4 v[190:193], v[158:159], off offset:528
	v_or_b32_e32 v124, 0x84, v144
	v_ashrrev_i32_e32 v125, 31, v124
	v_lshlrev_b64 v[126:127], 2, v[124:125]
	v_lshl_add_u64 v[124:125], s[16:17], 0, v[126:127]
	v_lshl_add_u64 v[126:127], s[18:19], 0, v[126:127]
	v_mul_f32_e32 v169, v175, v175
	v_add_f32_e32 v155, v174, v175
	v_fmac_f32_e32 v169, v174, v174
	v_add_f32_e32 v155, v176, v155
	v_fmac_f32_e32 v169, v176, v176
	v_add_f32_e32 v155, v177, v155
	v_fmac_f32_e32 v169, v177, v177
	s_waitcnt vmcnt(0)
	v_sub_f32_e32 v179, v179, v161
	v_sub_f32_e32 v178, v178, v161
	v_sub_f32_e32 v181, v181, v161
	v_sub_f32_e32 v180, v180, v161
	v_pk_mul_f32 v[180:181], v[160:161], v[180:181] op_sel_hi:[0,1]
	v_pk_mul_f32 v[178:179], v[160:161], v[178:179] op_sel_hi:[0,1]
	v_pk_fma_f32 v[178:179], v[182:183], v[178:179], v[186:187]
	v_pk_fma_f32 v[180:181], v[184:185], v[180:181], v[188:189]
	v_pk_fma_f32 v[178:179], v[178:179], s[26:27], v[116:117] op_sel_hi:[1,0,1]
	v_pk_fma_f32 v[180:181], v[180:181], s[26:27], v[118:119] op_sel_hi:[1,0,1]
	global_store_dwordx4 v[158:159], v[178:181], off offset:512
	global_load_dwordx4 v[182:185], v[124:125], off
	global_load_dwordx4 v[186:189], v[126:127], off
	v_and_b32_e32 v117, 64, v168
	v_xor_b32_e32 v116, 16, v168
	v_add_u32_e32 v117, 64, v117
	v_xor_b32_e32 v118, 32, v168
	v_cmp_lt_i32_e32 vcc, v116, v117
	v_mul_f32_e32 v119, v171, v171
	v_fmac_f32_e32 v119, v170, v170
	v_cndmask_b32_e32 v116, v168, v116, vcc
	v_cmp_lt_i32_e32 vcc, v118, v117
	v_fmac_f32_e32 v119, v172, v172
	v_fmac_f32_e32 v119, v173, v173
	v_cndmask_b32_e32 v117, v168, v118, vcc
	v_add_f32_e32 v118, v170, v171
	v_add_f32_e32 v118, v172, v118
	v_add_f32_e32 v118, v173, v118
	v_add_f32_e32 v118, 0, v118
	v_add_f32_e32 v155, v155, v118
	v_add_f32_e32 v169, v119, v169
	v_sub_f32_e32 v119, v191, v161
	v_sub_f32_e32 v118, v190, v161
	v_sub_f32_e32 v171, v193, v161
	v_sub_f32_e32 v170, v192, v161
	v_pk_mul_f32 v[170:171], v[160:161], v[170:171] op_sel_hi:[0,1]
	v_pk_mul_f32 v[118:119], v[160:161], v[118:119] op_sel_hi:[0,1]
	v_mul_f32_e32 v161, v179, v179
	v_add_f32_e32 v160, v178, v179
	v_fmac_f32_e32 v161, v178, v178
	v_add_f32_e32 v160, v180, v160
	v_fmac_f32_e32 v161, v180, v180
	v_add_f32_e32 v160, v181, v160
	v_fmac_f32_e32 v161, v181, v181
	v_add_f32_e32 v155, v155, v160
	v_add_f32_e32 v169, v169, v161
	v_lshlrev_b32_e32 v116, 2, v116
	v_lshlrev_b32_e32 v117, 2, v117
	v_cvt_pk_bf16_f32 v174, v178, v179
	v_cvt_pk_bf16_f32 v175, v180, v181
	s_waitcnt vmcnt(0)
; DEVI unsigned pk2(float lo, float hi) { unsigned r; asm("v_cvt_pk_bf16_f32 %0, %1, %2" : "=v"(r) : "v"(lo), "v"(hi)); return r; }
; DEVI void row_stats(const float* stats, int row, float& mu, float& rs) {
;     if (stats) { const float2 st = *(const float2*)(stats + 2 * (size_t)row); mu = st.x * (1.0f / 1024.0f); const float var = st.y * (1.0f / 1024.0f) - mu * mu; rs = rsqrtf(fmaxf(var, 0.f) + LN_EPS); }
;     DEVI void operator()(const f32x4 (&acc)[2][2][4][2], const pg8::Unit& u, int wr, int wc, int fr, int fq) const {
;     ...
;                 const int row = row0 + ai * 128 + m * 16; float mu, rs; row_stats(stin, row, mu, rs);
;                 float sum = 0.f, sq = 0.f;
; #pragma unroll
;                 for (int bj = 0; bj < 2; ++bj) {
;                     f32x4 z[2];
; #pragma unroll
;                     for (int n = 0; n < 2; ++n) {
;                         const int col = colb + bj * 128 + 4 * n;
;                         f32x4 xv = *(const f32x4*)(zsrc + (size_t)row * DM + col);
;                         if (stin) { const f32x4 gv = *(const f32x4*)(gin + col), bv = *(const f32x4*)(bin + col); xv = (xv - mu) * rs * gv + bv; }
;                         f32x4 zz = ALPHA * xv + acc[ai][bj][m][n];
;                         if (bias) zz += *(const f32x4*)(bias + col);
;                         *(f32x4*)(zdst + (size_t)row * DM + col) = zz;
;                         sum += zz[0] + zz[1] + zz[2] + zz[3]; sq += zz[0] * zz[0] + zz[1] * zz[1] + zz[2] * zz[2] + zz[3] * zz[3];
;                         z[n] = zz;
;                     }
;                     u32x4 o; o.x = pk2(z[0][0], z[0][1]); o.y = pk2(z[0][2], z[0][3]); o.z = pk2(z[1][0], z[1][1]); o.w = pk2(z[1][2], z[1][3]);
;                     if (zb) *(u32x4*)(zb + (size_t)row * DM + colb + bj * 128) = o;
;                 }
;                 sum += __shfl_xor(sum, 16); sq += __shfl_xor(sq, 16);
;                 sum += __shfl_xor(sum, 32); sq += __shfl_xor(sq, 32);
;                 if (fq == 0) { atomicAdd(stout + 2 * (size_t)row, sum); atomicAdd(stout + 2 * (size_t)row + 1, sq); }
	v_pk_fma_f32 v[118:119], v[182:183], v[118:119], v[186:187]
	v_pk_fma_f32 v[160:161], v[184:185], v[170:171], v[188:189]
	v_pk_fma_f32 v[170:171], v[118:119], s[26:27], v[112:113] op_sel_hi:[1,0,1]
	v_pk_fma_f32 v[172:173], v[160:161], s[26:27], v[114:115] op_sel_hi:[1,0,1]
	v_mul_f32_e32 v113, v171, v171
	v_add_f32_e32 v112, v170, v171
	v_fmac_f32_e32 v113, v170, v170
	v_add_f32_e32 v112, v172, v112
	v_fmac_f32_e32 v113, v172, v172
	v_add_f32_e32 v112, v173, v112
	v_fmac_f32_e32 v113, v173, v173
	v_add_f32_e32 v112, v155, v112
	v_add_f32_e32 v113, v169, v113
	ds_bpermute_b32 v114, v116, v112
	ds_bpermute_b32 v115, v116, v113
	global_store_dwordx4 v[158:159], v[170:173], off offset:528
	v_cvt_pk_bf16_f32 v176, v170, v171
	v_cvt_pk_bf16_f32 v177, v172, v173
	s_waitcnt lgkmcnt(0)
	v_add_f32_e32 v112, v112, v114
	v_add_f32_e32 v113, v113, v115
	ds_bpermute_b32 v114, v117, v112
	ds_bpermute_b32 v115, v117, v113
	flat_store_dwordx4 v[194:195], v[174:177] offset:256
	s_mov_b32 s100, -1
	s_mov_b32 s101, 0
	s_mov_b32 s98, 0xffff0000
	s_mov_b32 s99, 0
	s_and_saveexec_b64 s[30:31], s[100:101]
	s_cbranch_execz .LBB0_1540
	v_lshl_add_u64 v[118:119], s[10:11], 0, v[156:157]
	s_waitcnt lgkmcnt(0)
	v_add_f32_e32 v112, v112, v114
	v_add_f32_e32 v113, v113, v115
	v_cndmask_b32_e64 v112, v112, v113, s[98:99]
	v_cndmask_b32_e64 v113, 0, 4, s[98:99]
	v_or_b32_e32 v118, v118, v113
	flat_atomic_add_f32 v[118:119], v112
.LBB0_1540:
	s_or_b64 exec, exec, s[30:31]
	v_or_b32_e32 v118, 16, v154
	v_ashrrev_i32_e32 v119, 31, v118
	v_lshlrev_b64 v[112:113], 3, v[118:119]
	s_waitcnt lgkmcnt(0)
	v_lshl_add_u64 v[114:115], s[12:13], 0, v[112:113]
	flat_load_dwordx2 v[160:161], v[114:115]
	v_lshlrev_b64 v[114:115], 12, v[118:119]
	v_lshl_add_u64 v[114:115], s[46:47], 0, v[114:115]
	v_lshl_add_u64 v[114:115], v[144:145], 2, v[114:115]
	global_load_dwordx4 v[156:159], v[114:115], off
	global_load_dwordx4 v[170:173], v[150:151], off
	global_load_dwordx4 v[174:177], v[152:153], off
	global_load_dwordx4 v[178:181], v[114:115], off offset:16
	v_lshlrev_b64 v[118:119], 11, v[118:119]
	v_lshl_add_u64 v[118:119], s[14:15], 0, v[118:119]
	v_lshl_add_u64 v[118:119], v[144:145], 1, v[118:119]
	s_waitcnt vmcnt(0) lgkmcnt(0)
	v_pk_mul_f32 v[160:161], v[160:161], s[24:25] op_sel:[1,0] op_sel_hi:[0,0]
	v_fma_f32 v155, -v161, v161, v160
	v_max_f32_e32 v155, 0, v155
	v_add_f32_e32 v155, 0x3727c5ac, v155
	v_mul_f32_e32 v160, 0x4b800000, v155
	v_cmp_gt_f32_e32 vcc, s61, v155
	v_sub_f32_e32 v157, v157, v161
	v_sub_f32_e32 v156, v156, v161
	v_cndmask_b32_e32 v155, v155, v160, vcc
	v_rsq_f32_e32 v155, v155
	v_sub_f32_e32 v159, v159, v161
	v_sub_f32_e32 v158, v158, v161
	v_mul_f32_e32 v160, 0x45800000, v155
	v_cndmask_b32_e32 v160, v155, v160, vcc
	v_pk_mul_f32 v[158:159], v[158:159], v[160:161] op_sel_hi:[1,0]
	v_pk_mul_f32 v[156:157], v[156:157], v[160:161] op_sel_hi:[1,0]
	v_pk_fma_f32 v[158:159], v[172:173], v[158:159], v[176:177]
	v_pk_fma_f32 v[156:157], v[170:171], v[156:157], v[174:175]
	v_pk_fma_f32 v[110:111], v[158:159], s[26:27], v[110:111] op_sel_hi:[1,0,1]
	v_pk_fma_f32 v[108:109], v[156:157], s[26:27], v[108:109] op_sel_hi:[1,0,1]
	global_store_dwordx4 v[114:115], v[108:111], off
	global_load_dwordx4 v[156:159], v[146:147], off
	global_load_dwordx4 v[170:173], v[148:149], off
	v_sub_f32_e32 v175, v179, v161
	v_sub_f32_e32 v174, v178, v161
	v_sub_f32_e32 v177, v181, v161
	v_sub_f32_e32 v176, v180, v161
	v_pk_mul_f32 v[176:177], v[176:177], v[160:161] op_sel_hi:[1,0]
	v_pk_mul_f32 v[178:179], v[174:175], v[160:161] op_sel_hi:[1,0]
	v_cvt_pk_bf16_f32 v174, v108, v109
	v_cvt_pk_bf16_f32 v175, v110, v111
	v_add_f32_e32 v155, v108, v109
	v_mul_f32_e32 v109, v109, v109
	v_fmac_f32_e32 v109, v108, v108
	v_add_f32_e32 v155, v110, v155
	v_fmac_f32_e32 v109, v110, v110
	v_add_f32_e32 v108, v111, v155
	v_add_f32_e32 v108, 0, v108
	v_fmac_f32_e32 v109, v111, v111
	s_waitcnt vmcnt(0)
	v_pk_fma_f32 v[156:157], v[156:157], v[178:179], v[170:171]
	v_pk_fma_f32 v[158:159], v[158:159], v[176:177], v[172:173]
	v_pk_fma_f32 v[104:105], v[156:157], s[26:27], v[104:105] op_sel_hi:[1,0,1]
	v_pk_fma_f32 v[106:107], v[158:159], s[26:27], v[106:107] op_sel_hi:[1,0,1]
	global_store_dwordx4 v[114:115], v[104:107], off offset:16
	v_cvt_pk_bf16_f32 v176, v104, v105
	v_cvt_pk_bf16_f32 v177, v106, v107
	flat_store_dwordx4 v[118:119], v[174:177]
	global_load_dwordx4 v[156:159], v[114:115], off offset:512
	global_load_dwordx4 v[170:173], v[120:121], off
	s_nop 0
	global_load_dwordx4 v[174:177], v[122:123], off
	global_load_dwordx4 v[178:181], v[114:115], off offset:528
	v_add_f32_e32 v110, v104, v105
	v_mul_f32_e32 v105, v105, v105
	v_fmac_f32_e32 v105, v104, v104
	v_add_f32_e32 v110, v106, v110
	v_fmac_f32_e32 v105, v106, v106
	v_add_f32_e32 v104, v107, v110
	v_fmac_f32_e32 v105, v107, v107
	v_add_f32_e32 v108, v104, v108
	v_add_f32_e32 v109, v109, v105
	s_waitcnt vmcnt(0)
	v_sub_f32_e32 v157, v157, v161
	v_sub_f32_e32 v156, v156, v161
	v_sub_f32_e32 v159, v159, v161
	v_sub_f32_e32 v158, v158, v161
	v_pk_mul_f32 v[158:159], v[160:161], v[158:159] op_sel_hi:[0,1]
	v_pk_mul_f32 v[156:157], v[160:161], v[156:157] op_sel_hi:[0,1]
	v_pk_fma_f32 v[156:157], v[170:171], v[156:157], v[174:175]
	v_pk_fma_f32 v[158:159], v[172:173], v[158:159], v[176:177]
	v_pk_fma_f32 v[100:101], v[156:157], s[26:27], v[100:101] op_sel_hi:[1,0,1]
	v_pk_fma_f32 v[102:103], v[158:159], s[26:27], v[102:103] op_sel_hi:[1,0,1]
	global_store_dwordx4 v[114:115], v[100:103], off offset:512
	global_load_dwordx4 v[156:159], v[124:125], off
	global_load_dwordx4 v[170:173], v[126:127], off
	v_sub_f32_e32 v105, v179, v161
	v_sub_f32_e32 v104, v178, v161
	v_pk_mul_f32 v[104:105], v[160:161], v[104:105] op_sel_hi:[0,1]
	v_sub_f32_e32 v107, v181, v161
	v_sub_f32_e32 v106, v180, v161
	v_pk_mul_f32 v[106:107], v[160:161], v[106:107] op_sel_hi:[0,1]
	v_mul_f32_e32 v111, v101, v101
	v_add_f32_e32 v110, v100, v101
	v_fmac_f32_e32 v111, v100, v100
	v_add_f32_e32 v110, v102, v110
	v_fmac_f32_e32 v111, v102, v102
	v_add_f32_e32 v110, v103, v110
	v_fmac_f32_e32 v111, v103, v103
	v_add_f32_e32 v108, v108, v110
	v_add_f32_e32 v109, v109, v111
	v_cvt_pk_bf16_f32 v100, v100, v101
	v_cvt_pk_bf16_f32 v101, v102, v103
	s_waitcnt vmcnt(0)
; DEVI unsigned pk2(float lo, float hi) { unsigned r; asm("v_cvt_pk_bf16_f32 %0, %1, %2" : "=v"(r) : "v"(lo), "v"(hi)); return r; }
; DEVI void row_stats(const float* stats, int row, float& mu, float& rs) {
;     if (stats) { const float2 st = *(const float2*)(stats + 2 * (size_t)row); mu = st.x * (1.0f / 1024.0f); const float var = st.y * (1.0f / 1024.0f) - mu * mu; rs = rsqrtf(fmaxf(var, 0.f) + LN_EPS); }
;     DEVI void operator()(const f32x4 (&acc)[2][2][4][2], const pg8::Unit& u, int wr, int wc, int fr, int fq) const {
;     ...
;                 const int row = row0 + ai * 128 + m * 16; float mu, rs; row_stats(stin, row, mu, rs);
;                 float sum = 0.f, sq = 0.f;
; #pragma unroll
;                 for (int bj = 0; bj < 2; ++bj) {
;                     f32x4 z[2];
; #pragma unroll
;                     for (int n = 0; n < 2; ++n) {
;                         const int col = colb + bj * 128 + 4 * n;
;                         f32x4 xv = *(const f32x4*)(zsrc + (size_t)row * DM + col);
;                         if (stin) { const f32x4 gv = *(const f32x4*)(gin + col), bv = *(const f32x4*)(bin + col); xv = (xv - mu) * rs * gv + bv; }
;                         f32x4 zz = ALPHA * xv + acc[ai][bj][m][n];
;                         if (bias) zz += *(const f32x4*)(bias + col);
;                         *(f32x4*)(zdst + (size_t)row * DM + col) = zz;
;                         sum += zz[0] + zz[1] + zz[2] + zz[3]; sq += zz[0] * zz[0] + zz[1] * zz[1] + zz[2] * zz[2] + zz[3] * zz[3];
;                         z[n] = zz;
;                     }
;                     u32x4 o; o.x = pk2(z[0][0], z[0][1]); o.y = pk2(z[0][2], z[0][3]); o.z = pk2(z[1][0], z[1][1]); o.w = pk2(z[1][2], z[1][3]);
;                     if (zb) *(u32x4*)(zb + (size_t)row * DM + colb + bj * 128) = o;
;                 }
;                 sum += __shfl_xor(sum, 16); sq += __shfl_xor(sq, 16);
;                 sum += __shfl_xor(sum, 32); sq += __shfl_xor(sq, 32);
;                 if (fq == 0) { atomicAdd(stout + 2 * (size_t)row, sum); atomicAdd(stout + 2 * (size_t)row + 1, sq); }
	v_pk_fma_f32 v[104:105], v[156:157], v[104:105], v[170:171]
	s_nop 0
	v_pk_fma_f32 v[104:105], v[104:105], s[26:27], v[96:97] op_sel_hi:[1,0,1]
	v_pk_fma_f32 v[106:107], v[158:159], v[106:107], v[172:173]
	v_mul_f32_e32 v97, v105, v105
	v_pk_fma_f32 v[106:107], v[106:107], s[26:27], v[98:99] op_sel_hi:[1,0,1]
	v_add_f32_e32 v96, v104, v105
	v_fmac_f32_e32 v97, v104, v104
	v_add_f32_e32 v96, v106, v96
	v_fmac_f32_e32 v97, v106, v106
	v_add_f32_e32 v96, v107, v96
	v_fmac_f32_e32 v97, v107, v107
	v_add_f32_e32 v96, v108, v96
	v_add_f32_e32 v97, v109, v97
	ds_bpermute_b32 v98, v116, v96
	ds_bpermute_b32 v99, v116, v97
	global_store_dwordx4 v[114:115], v[104:107], off offset:528
	v_cvt_pk_bf16_f32 v102, v104, v105
	v_cvt_pk_bf16_f32 v103, v106, v107
	s_waitcnt lgkmcnt(0)
	v_add_f32_e32 v96, v96, v98
	v_add_f32_e32 v97, v97, v99
	ds_bpermute_b32 v98, v117, v96
	ds_bpermute_b32 v99, v117, v97
	flat_store_dwordx4 v[118:119], v[100:103] offset:256
	s_mov_b32 s100, -1
	s_mov_b32 s101, 0
	s_mov_b32 s98, 0xffff0000
	s_mov_b32 s99, 0
	s_and_saveexec_b64 s[30:31], s[100:101]
	s_cbranch_execz .LBB0_1542
	v_lshl_add_u64 v[100:101], s[10:11], 0, v[112:113]
	s_waitcnt lgkmcnt(0)
	v_add_f32_e32 v96, v96, v98
	v_add_f32_e32 v97, v97, v99
	v_cndmask_b32_e64 v96, v96, v97, s[98:99]
	v_cndmask_b32_e64 v97, 0, 4, s[98:99]
	v_or_b32_e32 v100, v100, v97
	flat_atomic_add_f32 v[100:101], v96
.LBB0_1542:
	s_or_b64 exec, exec, s[30:31]
	v_or_b32_e32 v118, 32, v154
	v_ashrrev_i32_e32 v119, 31, v118
	v_lshlrev_b64 v[96:97], 3, v[118:119]
	s_waitcnt lgkmcnt(0)
	v_lshl_add_u64 v[98:99], s[12:13], 0, v[96:97]
	flat_load_dwordx2 v[156:157], v[98:99]
	v_lshlrev_b64 v[98:99], 12, v[118:119]
	v_lshl_add_u64 v[98:99], s[46:47], 0, v[98:99]
	v_lshl_add_u64 v[98:99], v[144:145], 2, v[98:99]
	global_load_dwordx4 v[100:103], v[98:99], off
	global_load_dwordx4 v[104:107], v[150:151], off
	global_load_dwordx4 v[108:111], v[152:153], off
	global_load_dwordx4 v[112:115], v[98:99], off offset:16
	s_waitcnt vmcnt(0) lgkmcnt(0)
	v_pk_mul_f32 v[156:157], v[156:157], s[24:25] op_sel:[1,0] op_sel_hi:[0,0]
	v_fma_f32 v155, -v157, v157, v156
	v_max_f32_e32 v155, 0, v155
	v_add_f32_e32 v155, 0x3727c5ac, v155
	v_mul_f32_e32 v156, 0x4b800000, v155
	v_cmp_gt_f32_e32 vcc, s61, v155
	v_sub_f32_e32 v101, v101, v157
	v_sub_f32_e32 v100, v100, v157
	v_cndmask_b32_e32 v155, v155, v156, vcc
	v_rsq_f32_e32 v155, v155
	v_sub_f32_e32 v103, v103, v157
	v_sub_f32_e32 v102, v102, v157
	v_mul_f32_e32 v156, 0x45800000, v155
	v_cndmask_b32_e32 v156, v155, v156, vcc
	v_pk_mul_f32 v[102:103], v[102:103], v[156:157] op_sel_hi:[1,0]
	v_pk_mul_f32 v[100:101], v[100:101], v[156:157] op_sel_hi:[1,0]
	v_pk_fma_f32 v[102:103], v[106:107], v[102:103], v[110:111]
	v_pk_fma_f32 v[100:101], v[104:105], v[100:101], v[108:109]
	v_pk_fma_f32 v[94:95], v[102:103], s[26:27], v[94:95] op_sel_hi:[1,0,1]
	v_pk_fma_f32 v[92:93], v[100:101], s[26:27], v[92:93] op_sel_hi:[1,0,1]
	global_store_dwordx4 v[98:99], v[92:95], off
	global_load_dwordx4 v[100:103], v[146:147], off
	global_load_dwordx4 v[104:107], v[148:149], off
	v_lshlrev_b64 v[108:109], 11, v[118:119]
	v_lshl_add_u64 v[108:109], s[14:15], 0, v[108:109]
	v_lshl_add_u64 v[118:119], v[144:145], 1, v[108:109]
	v_sub_f32_e32 v109, v113, v157
	v_sub_f32_e32 v108, v112, v157
	v_sub_f32_e32 v111, v115, v157
	v_sub_f32_e32 v110, v114, v157
	v_pk_mul_f32 v[110:111], v[110:111], v[156:157] op_sel_hi:[1,0]
	v_pk_mul_f32 v[112:113], v[108:109], v[156:157] op_sel_hi:[1,0]
	v_cvt_pk_bf16_f32 v108, v92, v93
	v_cvt_pk_bf16_f32 v109, v94, v95
	s_waitcnt vmcnt(0)
	v_pk_fma_f32 v[102:103], v[102:103], v[110:111], v[106:107]
	v_pk_fma_f32 v[100:101], v[100:101], v[112:113], v[104:105]
	v_pk_fma_f32 v[90:91], v[102:103], s[26:27], v[90:91] op_sel_hi:[1,0,1]
	v_pk_fma_f32 v[88:89], v[100:101], s[26:27], v[88:89] op_sel_hi:[1,0,1]
	global_store_dwordx4 v[98:99], v[88:91], off offset:16
	v_cvt_pk_bf16_f32 v110, v88, v89
	v_cvt_pk_bf16_f32 v111, v90, v91
	flat_store_dwordx4 v[118:119], v[108:111]
	global_load_dwordx4 v[100:103], v[98:99], off offset:512
	global_load_dwordx4 v[104:107], v[120:121], off
	s_nop 0
	global_load_dwordx4 v[108:111], v[122:123], off
	global_load_dwordx4 v[112:115], v[98:99], off offset:528
	s_waitcnt vmcnt(0)
	v_sub_f32_e32 v101, v101, v157
	v_sub_f32_e32 v100, v100, v157
	v_sub_f32_e32 v103, v103, v157
	v_sub_f32_e32 v102, v102, v157
	v_pk_mul_f32 v[102:103], v[156:157], v[102:103] op_sel_hi:[0,1]
	v_pk_mul_f32 v[100:101], v[156:157], v[100:101] op_sel_hi:[0,1]
	v_pk_fma_f32 v[100:101], v[104:105], v[100:101], v[108:109]
	v_pk_fma_f32 v[102:103], v[106:107], v[102:103], v[110:111]
	v_pk_fma_f32 v[84:85], v[100:101], s[26:27], v[84:85] op_sel_hi:[1,0,1]
	v_pk_fma_f32 v[86:87], v[102:103], s[26:27], v[86:87] op_sel_hi:[1,0,1]
	global_store_dwordx4 v[98:99], v[84:87], off offset:512
	global_load_dwordx4 v[100:103], v[124:125], off
	global_load_dwordx4 v[104:107], v[126:127], off
	v_add_f32_e32 v108, v92, v93
	v_mul_f32_e32 v93, v93, v93
	v_fmac_f32_e32 v93, v92, v92
	v_add_f32_e32 v108, v94, v108
	v_fmac_f32_e32 v93, v94, v94
	v_add_f32_e32 v94, v88, v89
	v_mul_f32_e32 v89, v89, v89
	v_fmac_f32_e32 v89, v88, v88
	v_add_f32_e32 v92, v95, v108
	v_add_f32_e32 v94, v90, v94
	v_fmac_f32_e32 v89, v90, v90
	v_add_f32_e32 v92, 0, v92
	v_fmac_f32_e32 v93, v95, v95
	v_add_f32_e32 v88, v91, v94
	v_fmac_f32_e32 v89, v91, v91
	v_add_f32_e32 v92, v88, v92
	v_add_f32_e32 v93, v93, v89
	v_sub_f32_e32 v89, v113, v157
	v_sub_f32_e32 v88, v112, v157
	v_pk_mul_f32 v[88:89], v[156:157], v[88:89] op_sel_hi:[0,1]
	v_sub_f32_e32 v91, v115, v157
	v_sub_f32_e32 v90, v114, v157
	v_pk_mul_f32 v[90:91], v[156:157], v[90:91] op_sel_hi:[0,1]
	v_mul_f32_e32 v95, v85, v85
	v_add_f32_e32 v94, v84, v85
	v_fmac_f32_e32 v95, v84, v84
	v_add_f32_e32 v94, v86, v94
	v_fmac_f32_e32 v95, v86, v86
	v_add_f32_e32 v94, v87, v94
	v_fmac_f32_e32 v95, v87, v87
	v_add_f32_e32 v92, v92, v94
	v_add_f32_e32 v93, v93, v95
	v_cvt_pk_bf16_f32 v84, v84, v85
	v_cvt_pk_bf16_f32 v85, v86, v87
	s_waitcnt vmcnt(0)
; DEVI unsigned pk2(float lo, float hi) { unsigned r; asm("v_cvt_pk_bf16_f32 %0, %1, %2" : "=v"(r) : "v"(lo), "v"(hi)); return r; }
; DEVI void row_stats(const float* stats, int row, float& mu, float& rs) {
;     if (stats) { const float2 st = *(const float2*)(stats + 2 * (size_t)row); mu = st.x * (1.0f / 1024.0f); const float var = st.y * (1.0f / 1024.0f) - mu * mu; rs = rsqrtf(fmaxf(var, 0.f) + LN_EPS); }
;     DEVI void operator()(const f32x4 (&acc)[2][2][4][2], const pg8::Unit& u, int wr, int wc, int fr, int fq) const {
;     ...
;                 const int row = row0 + ai * 128 + m * 16; float mu, rs; row_stats(stin, row, mu, rs);
;                 float sum = 0.f, sq = 0.f;
; #pragma unroll
;                 for (int bj = 0; bj < 2; ++bj) {
;                     f32x4 z[2];
; #pragma unroll
;                     for (int n = 0; n < 2; ++n) {
;                         const int col = colb + bj * 128 + 4 * n;
;                         f32x4 xv = *(const f32x4*)(zsrc + (size_t)row * DM + col);
;                         if (stin) { const f32x4 gv = *(const f32x4*)(gin + col), bv = *(const f32x4*)(bin + col); xv = (xv - mu) * rs * gv + bv; }
;                         f32x4 zz = ALPHA * xv + acc[ai][bj][m][n];
;                         if (bias) zz += *(const f32x4*)(bias + col);
;                         *(f32x4*)(zdst + (size_t)row * DM + col) = zz;
;                         sum += zz[0] + zz[1] + zz[2] + zz[3]; sq += zz[0] * zz[0] + zz[1] * zz[1] + zz[2] * zz[2] + zz[3] * zz[3];
;                         z[n] = zz;
;                     }
;                     u32x4 o; o.x = pk2(z[0][0], z[0][1]); o.y = pk2(z[0][2], z[0][3]); o.z = pk2(z[1][0], z[1][1]); o.w = pk2(z[1][2], z[1][3]);
;                     if (zb) *(u32x4*)(zb + (size_t)row * DM + colb + bj * 128) = o;
;                 }
;                 sum += __shfl_xor(sum, 16); sq += __shfl_xor(sq, 16);
;                 sum += __shfl_xor(sum, 32); sq += __shfl_xor(sq, 32);
;                 if (fq == 0) { atomicAdd(stout + 2 * (size_t)row, sum); atomicAdd(stout + 2 * (size_t)row + 1, sq); }
	v_pk_fma_f32 v[88:89], v[100:101], v[88:89], v[104:105]
	s_nop 0
	v_pk_fma_f32 v[88:89], v[88:89], s[26:27], v[80:81] op_sel_hi:[1,0,1]
	v_pk_fma_f32 v[90:91], v[102:103], v[90:91], v[106:107]
	v_mul_f32_e32 v81, v89, v89
	v_pk_fma_f32 v[90:91], v[90:91], s[26:27], v[82:83] op_sel_hi:[1,0,1]
	v_add_f32_e32 v80, v88, v89
	v_fmac_f32_e32 v81, v88, v88
	v_add_f32_e32 v80, v90, v80
	v_fmac_f32_e32 v81, v90, v90
	v_add_f32_e32 v80, v91, v80
	v_fmac_f32_e32 v81, v91, v91
	v_add_f32_e32 v80, v92, v80
	v_add_f32_e32 v81, v93, v81
	ds_bpermute_b32 v82, v116, v80
	ds_bpermute_b32 v83, v116, v81
	global_store_dwordx4 v[98:99], v[88:91], off offset:528
	v_cvt_pk_bf16_f32 v86, v88, v89
	v_cvt_pk_bf16_f32 v87, v90, v91
	s_waitcnt lgkmcnt(0)
	v_add_f32_e32 v80, v80, v82
	v_add_f32_e32 v81, v81, v83
	ds_bpermute_b32 v82, v117, v80
	ds_bpermute_b32 v83, v117, v81
	flat_store_dwordx4 v[118:119], v[84:87] offset:256
	s_mov_b32 s100, -1
	s_mov_b32 s101, 0
	s_mov_b32 s98, 0xffff0000
	s_mov_b32 s99, 0
	s_and_saveexec_b64 s[30:31], s[100:101]
	s_cbranch_execz .LBB0_1544
	v_lshl_add_u64 v[84:85], s[10:11], 0, v[96:97]
	s_waitcnt lgkmcnt(0)
	v_add_f32_e32 v80, v80, v82
	v_add_f32_e32 v81, v81, v83
	v_cndmask_b32_e64 v80, v80, v81, s[98:99]
	v_cndmask_b32_e64 v81, 0, 4, s[98:99]
	v_or_b32_e32 v84, v84, v81
	flat_atomic_add_f32 v[84:85], v80
.LBB0_1544:
	s_or_b64 exec, exec, s[30:31]
	v_or_b32_e32 v100, 48, v154
	v_ashrrev_i32_e32 v101, 31, v100
	v_lshlrev_b64 v[80:81], 3, v[100:101]
	s_waitcnt lgkmcnt(0)
	v_lshl_add_u64 v[82:83], s[12:13], 0, v[80:81]
	flat_load_dwordx2 v[102:103], v[82:83]
	v_lshlrev_b64 v[82:83], 12, v[100:101]
	v_lshl_add_u64 v[82:83], s[46:47], 0, v[82:83]
	v_lshl_add_u64 v[82:83], v[144:145], 2, v[82:83]
	global_load_dwordx4 v[84:87], v[82:83], off
	global_load_dwordx4 v[88:91], v[150:151], off
	global_load_dwordx4 v[92:95], v[152:153], off
	global_load_dwordx4 v[96:99], v[82:83], off offset:16
	s_waitcnt vmcnt(0) lgkmcnt(0)
	v_pk_mul_f32 v[102:103], v[102:103], s[24:25] op_sel:[1,0] op_sel_hi:[0,0]
	v_fma_f32 v102, -v103, v103, v102
	v_max_f32_e32 v102, 0, v102
	v_add_f32_e32 v102, 0x3727c5ac, v102
	v_mul_f32_e32 v104, 0x4b800000, v102
	v_cmp_gt_f32_e32 vcc, s61, v102
	v_sub_f32_e32 v85, v85, v103
	v_sub_f32_e32 v84, v84, v103
	v_cndmask_b32_e32 v102, v102, v104, vcc
	v_rsq_f32_e32 v102, v102
	v_sub_f32_e32 v87, v87, v103
	v_sub_f32_e32 v86, v86, v103
	v_mul_f32_e32 v104, 0x45800000, v102
	v_cndmask_b32_e32 v102, v102, v104, vcc
	v_pk_mul_f32 v[86:87], v[86:87], v[102:103] op_sel_hi:[1,0]
	v_pk_mul_f32 v[84:85], v[84:85], v[102:103] op_sel_hi:[1,0]
	v_pk_fma_f32 v[86:87], v[90:91], v[86:87], v[94:95]
	v_pk_fma_f32 v[84:85], v[88:89], v[84:85], v[92:93]
	v_pk_fma_f32 v[78:79], v[86:87], s[26:27], v[78:79] op_sel_hi:[1,0,1]
	v_pk_fma_f32 v[76:77], v[84:85], s[26:27], v[76:77] op_sel_hi:[1,0,1]
	global_store_dwordx4 v[82:83], v[76:79], off
	global_load_dwordx4 v[84:87], v[146:147], off
	global_load_dwordx4 v[88:91], v[148:149], off
	v_lshlrev_b64 v[92:93], 11, v[100:101]
	v_lshl_add_u64 v[92:93], s[14:15], 0, v[92:93]
	v_lshl_add_u64 v[100:101], v[144:145], 1, v[92:93]
	v_sub_f32_e32 v93, v97, v103
	v_sub_f32_e32 v92, v96, v103
	v_sub_f32_e32 v95, v99, v103
	v_sub_f32_e32 v94, v98, v103
	v_pk_mul_f32 v[94:95], v[94:95], v[102:103] op_sel_hi:[1,0]
	v_pk_mul_f32 v[96:97], v[92:93], v[102:103] op_sel_hi:[1,0]
	v_cvt_pk_bf16_f32 v92, v76, v77
	v_cvt_pk_bf16_f32 v93, v78, v79
	s_waitcnt vmcnt(0)
	v_pk_fma_f32 v[86:87], v[86:87], v[94:95], v[90:91]
	v_pk_fma_f32 v[84:85], v[84:85], v[96:97], v[88:89]
	v_pk_fma_f32 v[74:75], v[86:87], s[26:27], v[74:75] op_sel_hi:[1,0,1]
	v_pk_fma_f32 v[72:73], v[84:85], s[26:27], v[72:73] op_sel_hi:[1,0,1]
	global_store_dwordx4 v[82:83], v[72:75], off offset:16
	v_cvt_pk_bf16_f32 v94, v72, v73
	v_cvt_pk_bf16_f32 v95, v74, v75
	flat_store_dwordx4 v[100:101], v[92:95]
	global_load_dwordx4 v[84:87], v[82:83], off offset:512
	global_load_dwordx4 v[88:91], v[120:121], off
	s_nop 0
	global_load_dwordx4 v[92:95], v[122:123], off
	global_load_dwordx4 v[96:99], v[82:83], off offset:528
	s_waitcnt vmcnt(0)
	v_sub_f32_e32 v85, v85, v103
	v_sub_f32_e32 v84, v84, v103
	v_sub_f32_e32 v87, v87, v103
	v_sub_f32_e32 v86, v86, v103
	v_pk_mul_f32 v[86:87], v[102:103], v[86:87] op_sel_hi:[0,1]
	v_pk_mul_f32 v[84:85], v[102:103], v[84:85] op_sel_hi:[0,1]
	v_pk_fma_f32 v[84:85], v[88:89], v[84:85], v[92:93]
	v_pk_fma_f32 v[86:87], v[90:91], v[86:87], v[94:95]
	v_pk_fma_f32 v[68:69], v[84:85], s[26:27], v[68:69] op_sel_hi:[1,0,1]
	v_pk_fma_f32 v[70:71], v[86:87], s[26:27], v[70:71] op_sel_hi:[1,0,1]
	global_store_dwordx4 v[82:83], v[68:71], off offset:512
	global_load_dwordx4 v[84:87], v[124:125], off
	global_load_dwordx4 v[88:91], v[126:127], off
	v_add_f32_e32 v92, v76, v77
	v_mul_f32_e32 v77, v77, v77
	v_fmac_f32_e32 v77, v76, v76
	v_add_f32_e32 v92, v78, v92
	v_fmac_f32_e32 v77, v78, v78
	v_add_f32_e32 v78, v72, v73
	v_mul_f32_e32 v73, v73, v73
	v_fmac_f32_e32 v73, v72, v72
	v_add_f32_e32 v76, v79, v92
	v_add_f32_e32 v78, v74, v78
	v_fmac_f32_e32 v73, v74, v74
	v_add_f32_e32 v76, 0, v76
	v_fmac_f32_e32 v77, v79, v79
	v_add_f32_e32 v72, v75, v78
	v_fmac_f32_e32 v73, v75, v75
	v_add_f32_e32 v76, v72, v76
	v_add_f32_e32 v77, v77, v73
	v_sub_f32_e32 v73, v97, v103
	v_sub_f32_e32 v72, v96, v103
	v_pk_mul_f32 v[72:73], v[102:103], v[72:73] op_sel_hi:[0,1]
	v_sub_f32_e32 v75, v99, v103
	v_sub_f32_e32 v74, v98, v103
	v_pk_mul_f32 v[74:75], v[102:103], v[74:75] op_sel_hi:[0,1]
	v_mul_f32_e32 v79, v69, v69
	v_add_f32_e32 v78, v68, v69
	v_fmac_f32_e32 v79, v68, v68
	v_add_f32_e32 v78, v70, v78
	v_fmac_f32_e32 v79, v70, v70
	v_add_f32_e32 v78, v71, v78
	v_fmac_f32_e32 v79, v71, v71
	v_add_f32_e32 v76, v76, v78
	v_add_f32_e32 v77, v77, v79
	v_cvt_pk_bf16_f32 v68, v68, v69
	v_cvt_pk_bf16_f32 v69, v70, v71
	s_waitcnt vmcnt(0)
	v_pk_fma_f32 v[72:73], v[84:85], v[72:73], v[88:89]
	s_nop 0
	v_pk_fma_f32 v[72:73], v[72:73], s[26:27], v[64:65] op_sel_hi:[1,0,1]
	v_pk_fma_f32 v[74:75], v[86:87], v[74:75], v[90:91]
	v_mul_f32_e32 v65, v73, v73
	v_pk_fma_f32 v[74:75], v[74:75], s[26:27], v[66:67] op_sel_hi:[1,0,1]
	v_add_f32_e32 v64, v72, v73
	v_fmac_f32_e32 v65, v72, v72
	v_add_f32_e32 v64, v74, v64
	v_fmac_f32_e32 v65, v74, v74
	v_add_f32_e32 v64, v75, v64
	v_fmac_f32_e32 v65, v75, v75
	v_add_f32_e32 v64, v76, v64
	v_add_f32_e32 v65, v77, v65
	ds_bpermute_b32 v66, v116, v64
	ds_bpermute_b32 v67, v116, v65
	global_store_dwordx4 v[82:83], v[72:75], off offset:528
	v_cvt_pk_bf16_f32 v70, v72, v73
	v_cvt_pk_bf16_f32 v71, v74, v75
	s_waitcnt lgkmcnt(0)
	v_add_f32_e32 v64, v64, v66
	v_add_f32_e32 v65, v65, v67
	ds_bpermute_b32 v66, v117, v64
	ds_bpermute_b32 v67, v117, v65
	flat_store_dwordx4 v[100:101], v[68:71] offset:256
	s_mov_b32 s100, -1
	s_mov_b32 s101, 0
	s_mov_b32 s98, 0xffff0000
	s_mov_b32 s99, 0
	s_and_saveexec_b64 s[30:31], s[100:101]
	s_cbranch_execz .LBB0_1546
; DEVI unsigned pk2(float lo, float hi) { unsigned r; asm("v_cvt_pk_bf16_f32 %0, %1, %2" : "=v"(r) : "v"(lo), "v"(hi)); return r; }
; DEVI void row_stats(const float* stats, int row, float& mu, float& rs) {
;     if (stats) { const float2 st = *(const float2*)(stats + 2 * (size_t)row); mu = st.x * (1.0f / 1024.0f); const float var = st.y * (1.0f / 1024.0f) - mu * mu; rs = rsqrtf(fmaxf(var, 0.f) + LN_EPS); }
;     DEVI void operator()(const f32x4 (&acc)[2][2][4][2], const pg8::Unit& u, int wr, int wc, int fr, int fq) const {
;     ...
;                 const int row = row0 + ai * 128 + m * 16; float mu, rs; row_stats(stin, row, mu, rs);
;                 float sum = 0.f, sq = 0.f;
; #pragma unroll
;                 for (int bj = 0; bj < 2; ++bj) {
;                     f32x4 z[2];
; #pragma unroll
;                     for (int n = 0; n < 2; ++n) {
;                         const int col = colb + bj * 128 + 4 * n;
;                         f32x4 xv = *(const f32x4*)(zsrc + (size_t)row * DM + col);
;                         if (stin) { const f32x4 gv = *(const f32x4*)(gin + col), bv = *(const f32x4*)(bin + col); xv = (xv - mu) * rs * gv + bv; }
;                         f32x4 zz = ALPHA * xv + acc[ai][bj][m][n];
;                         if (bias) zz += *(const f32x4*)(bias + col);
;                         *(f32x4*)(zdst + (size_t)row * DM + col) = zz;
;                         sum += zz[0] + zz[1] + zz[2] + zz[3]; sq += zz[0] * zz[0] + zz[1] * zz[1] + zz[2] * zz[2] + zz[3] * zz[3];
;                         z[n] = zz;
;                     }
;                     u32x4 o; o.x = pk2(z[0][0], z[0][1]); o.y = pk2(z[0][2], z[0][3]); o.z = pk2(z[1][0], z[1][1]); o.w = pk2(z[1][2], z[1][3]);
;                     if (zb) *(u32x4*)(zb + (size_t)row * DM + colb + bj * 128) = o;
;                 }
;                 sum += __shfl_xor(sum, 16); sq += __shfl_xor(sq, 16);
;                 sum += __shfl_xor(sum, 32); sq += __shfl_xor(sq, 32);
;                 if (fq == 0) { atomicAdd(stout + 2 * (size_t)row, sum); atomicAdd(stout + 2 * (size_t)row + 1, sq); }
	v_lshl_add_u64 v[68:69], s[10:11], 0, v[80:81]
	s_waitcnt lgkmcnt(0)
	v_add_f32_e32 v64, v64, v66
	v_add_f32_e32 v65, v65, v67
	v_cndmask_b32_e64 v64, v64, v65, s[98:99]
	v_cndmask_b32_e64 v65, 0, 4, s[98:99]
	v_or_b32_e32 v68, v68, v65
	flat_atomic_add_f32 v[68:69], v64
.LBB0_1546:
	s_or_b64 exec, exec, s[30:31]
	v_add_u32_e32 v84, 0x80, v154
	v_ashrrev_i32_e32 v85, 31, v84
	v_lshlrev_b64 v[64:65], 3, v[84:85]
	s_waitcnt lgkmcnt(0)
	v_lshl_add_u64 v[66:67], s[12:13], 0, v[64:65]
	flat_load_dwordx2 v[86:87], v[66:67]
	v_lshlrev_b64 v[66:67], 12, v[84:85]
	v_lshl_add_u64 v[66:67], s[46:47], 0, v[66:67]
	v_lshl_add_u64 v[66:67], v[144:145], 2, v[66:67]
	global_load_dwordx4 v[68:71], v[66:67], off
	global_load_dwordx4 v[72:75], v[150:151], off
	global_load_dwordx4 v[76:79], v[152:153], off
	global_load_dwordx4 v[80:83], v[66:67], off offset:16
	s_waitcnt vmcnt(0) lgkmcnt(0)
	v_pk_mul_f32 v[86:87], v[86:87], s[24:25] op_sel:[1,0] op_sel_hi:[0,0]
	v_fma_f32 v86, -v87, v87, v86
	v_max_f32_e32 v86, 0, v86
	v_add_f32_e32 v86, 0x3727c5ac, v86
	v_mul_f32_e32 v88, 0x4b800000, v86
	v_cmp_gt_f32_e32 vcc, s61, v86
	v_sub_f32_e32 v69, v69, v87
	v_sub_f32_e32 v68, v68, v87
	v_cndmask_b32_e32 v86, v86, v88, vcc
	v_rsq_f32_e32 v86, v86
	v_sub_f32_e32 v71, v71, v87
	v_sub_f32_e32 v70, v70, v87
	v_mul_f32_e32 v88, 0x45800000, v86
	v_cndmask_b32_e32 v86, v86, v88, vcc
	v_pk_mul_f32 v[70:71], v[70:71], v[86:87] op_sel_hi:[1,0]
	v_pk_mul_f32 v[68:69], v[68:69], v[86:87] op_sel_hi:[1,0]
	v_pk_fma_f32 v[70:71], v[74:75], v[70:71], v[78:79]
	v_pk_fma_f32 v[68:69], v[72:73], v[68:69], v[76:77]
	v_pk_fma_f32 v[62:63], v[70:71], s[26:27], v[62:63] op_sel_hi:[1,0,1]
	v_pk_fma_f32 v[60:61], v[68:69], s[26:27], v[60:61] op_sel_hi:[1,0,1]
	global_store_dwordx4 v[66:67], v[60:63], off
	global_load_dwordx4 v[68:71], v[146:147], off
	global_load_dwordx4 v[72:75], v[148:149], off
	v_lshlrev_b64 v[76:77], 11, v[84:85]
	v_lshl_add_u64 v[76:77], s[14:15], 0, v[76:77]
	v_lshl_add_u64 v[84:85], v[144:145], 1, v[76:77]
	v_sub_f32_e32 v77, v81, v87
	v_sub_f32_e32 v76, v80, v87
	v_sub_f32_e32 v79, v83, v87
	v_sub_f32_e32 v78, v82, v87
	v_pk_mul_f32 v[78:79], v[78:79], v[86:87] op_sel_hi:[1,0]
	v_pk_mul_f32 v[80:81], v[76:77], v[86:87] op_sel_hi:[1,0]
	v_cvt_pk_bf16_f32 v76, v60, v61
	v_cvt_pk_bf16_f32 v77, v62, v63
	s_waitcnt vmcnt(0)
	v_pk_fma_f32 v[70:71], v[70:71], v[78:79], v[74:75]
	v_pk_fma_f32 v[68:69], v[68:69], v[80:81], v[72:73]
	v_pk_fma_f32 v[58:59], v[70:71], s[26:27], v[58:59] op_sel_hi:[1,0,1]
	v_pk_fma_f32 v[56:57], v[68:69], s[26:27], v[56:57] op_sel_hi:[1,0,1]
	global_store_dwordx4 v[66:67], v[56:59], off offset:16
	v_cvt_pk_bf16_f32 v78, v56, v57
	v_cvt_pk_bf16_f32 v79, v58, v59
	flat_store_dwordx4 v[84:85], v[76:79]
	global_load_dwordx4 v[68:71], v[66:67], off offset:512
	global_load_dwordx4 v[72:75], v[120:121], off
	s_nop 0
	global_load_dwordx4 v[76:79], v[122:123], off
	global_load_dwordx4 v[80:83], v[66:67], off offset:528
	s_waitcnt vmcnt(0)
	v_sub_f32_e32 v69, v69, v87
	v_sub_f32_e32 v68, v68, v87
	v_sub_f32_e32 v71, v71, v87
	v_sub_f32_e32 v70, v70, v87
	v_pk_mul_f32 v[70:71], v[86:87], v[70:71] op_sel_hi:[0,1]
	v_pk_mul_f32 v[68:69], v[86:87], v[68:69] op_sel_hi:[0,1]
	v_pk_fma_f32 v[68:69], v[72:73], v[68:69], v[76:77]
	v_pk_fma_f32 v[70:71], v[74:75], v[70:71], v[78:79]
	v_pk_fma_f32 v[52:53], v[68:69], s[26:27], v[52:53] op_sel_hi:[1,0,1]
	v_pk_fma_f32 v[54:55], v[70:71], s[26:27], v[54:55] op_sel_hi:[1,0,1]
	global_store_dwordx4 v[66:67], v[52:55], off offset:512
	global_load_dwordx4 v[68:71], v[124:125], off
	global_load_dwordx4 v[72:75], v[126:127], off
	v_add_f32_e32 v76, v60, v61
	v_mul_f32_e32 v61, v61, v61
	v_fmac_f32_e32 v61, v60, v60
	v_add_f32_e32 v76, v62, v76
	v_fmac_f32_e32 v61, v62, v62
	v_add_f32_e32 v62, v56, v57
	v_mul_f32_e32 v57, v57, v57
	v_fmac_f32_e32 v57, v56, v56
	v_add_f32_e32 v60, v63, v76
	v_add_f32_e32 v62, v58, v62
	v_fmac_f32_e32 v57, v58, v58
	v_add_f32_e32 v60, 0, v60
	v_fmac_f32_e32 v61, v63, v63
	v_add_f32_e32 v56, v59, v62
	v_fmac_f32_e32 v57, v59, v59
	v_add_f32_e32 v60, v56, v60
	v_add_f32_e32 v61, v61, v57
	v_sub_f32_e32 v57, v81, v87
	v_sub_f32_e32 v56, v80, v87
	v_pk_mul_f32 v[56:57], v[86:87], v[56:57] op_sel_hi:[0,1]
	v_sub_f32_e32 v59, v83, v87
	v_sub_f32_e32 v58, v82, v87
	v_pk_mul_f32 v[58:59], v[86:87], v[58:59] op_sel_hi:[0,1]
	v_mul_f32_e32 v63, v53, v53
	v_add_f32_e32 v62, v52, v53
	v_fmac_f32_e32 v63, v52, v52
	v_add_f32_e32 v62, v54, v62
	v_fmac_f32_e32 v63, v54, v54
	v_add_f32_e32 v62, v55, v62
	v_fmac_f32_e32 v63, v55, v55
	v_add_f32_e32 v60, v60, v62
	v_add_f32_e32 v61, v61, v63
	v_cvt_pk_bf16_f32 v52, v52, v53
	v_cvt_pk_bf16_f32 v53, v54, v55
	s_waitcnt vmcnt(0)
	v_pk_fma_f32 v[56:57], v[68:69], v[56:57], v[72:73]
	s_nop 0
	v_pk_fma_f32 v[56:57], v[56:57], s[26:27], v[48:49] op_sel_hi:[1,0,1]
	v_pk_fma_f32 v[58:59], v[70:71], v[58:59], v[74:75]
	v_mul_f32_e32 v49, v57, v57
	v_pk_fma_f32 v[58:59], v[58:59], s[26:27], v[50:51] op_sel_hi:[1,0,1]
	v_add_f32_e32 v48, v56, v57
	v_fmac_f32_e32 v49, v56, v56
	v_add_f32_e32 v48, v58, v48
	v_fmac_f32_e32 v49, v58, v58
	v_add_f32_e32 v48, v59, v48
	v_fmac_f32_e32 v49, v59, v59
	v_add_f32_e32 v48, v60, v48
	v_add_f32_e32 v49, v61, v49
	ds_bpermute_b32 v50, v116, v48
	ds_bpermute_b32 v51, v116, v49
	global_store_dwordx4 v[66:67], v[56:59], off offset:528
	v_cvt_pk_bf16_f32 v54, v56, v57
	v_cvt_pk_bf16_f32 v55, v58, v59
	s_waitcnt lgkmcnt(0)
	v_add_f32_e32 v48, v48, v50
	v_add_f32_e32 v49, v49, v51
	ds_bpermute_b32 v50, v117, v48
	ds_bpermute_b32 v51, v117, v49
	flat_store_dwordx4 v[84:85], v[52:55] offset:256
	s_mov_b32 s100, -1
	s_mov_b32 s101, 0
	s_mov_b32 s98, 0xffff0000
	s_mov_b32 s99, 0
	s_and_saveexec_b64 s[30:31], s[100:101]
	s_cbranch_execz .LBB0_1548
	v_lshl_add_u64 v[52:53], s[10:11], 0, v[64:65]
	s_waitcnt lgkmcnt(0)
	v_add_f32_e32 v48, v48, v50
	v_add_f32_e32 v49, v49, v51
	v_cndmask_b32_e64 v48, v48, v49, s[98:99]
	v_cndmask_b32_e64 v49, 0, 4, s[98:99]
	v_or_b32_e32 v52, v52, v49
	flat_atomic_add_f32 v[52:53], v48
; DEVI unsigned pk2(float lo, float hi) { unsigned r; asm("v_cvt_pk_bf16_f32 %0, %1, %2" : "=v"(r) : "v"(lo), "v"(hi)); return r; }
; DEVI void row_stats(const float* stats, int row, float& mu, float& rs) {
;     if (stats) { const float2 st = *(const float2*)(stats + 2 * (size_t)row); mu = st.x * (1.0f / 1024.0f); const float var = st.y * (1.0f / 1024.0f) - mu * mu; rs = rsqrtf(fmaxf(var, 0.f) + LN_EPS); }
;     DEVI void operator()(const f32x4 (&acc)[2][2][4][2], const pg8::Unit& u, int wr, int wc, int fr, int fq) const {
;     ...
;                 const int row = row0 + ai * 128 + m * 16; float mu, rs; row_stats(stin, row, mu, rs);
;                 float sum = 0.f, sq = 0.f;
; #pragma unroll
;                 for (int bj = 0; bj < 2; ++bj) {
;                     f32x4 z[2];
; #pragma unroll
;                     for (int n = 0; n < 2; ++n) {
;                         const int col = colb + bj * 128 + 4 * n;
;                         f32x4 xv = *(const f32x4*)(zsrc + (size_t)row * DM + col);
;                         if (stin) { const f32x4 gv = *(const f32x4*)(gin + col), bv = *(const f32x4*)(bin + col); xv = (xv - mu) * rs * gv + bv; }
;                         f32x4 zz = ALPHA * xv + acc[ai][bj][m][n];
;                         if (bias) zz += *(const f32x4*)(bias + col);
;                         *(f32x4*)(zdst + (size_t)row * DM + col) = zz;
;                         sum += zz[0] + zz[1] + zz[2] + zz[3]; sq += zz[0] * zz[0] + zz[1] * zz[1] + zz[2] * zz[2] + zz[3] * zz[3];
;                         z[n] = zz;
;                     }
;                     u32x4 o; o.x = pk2(z[0][0], z[0][1]); o.y = pk2(z[0][2], z[0][3]); o.z = pk2(z[1][0], z[1][1]); o.w = pk2(z[1][2], z[1][3]);
;                     if (zb) *(u32x4*)(zb + (size_t)row * DM + colb + bj * 128) = o;
;                 }
;                 sum += __shfl_xor(sum, 16); sq += __shfl_xor(sq, 16);
;                 sum += __shfl_xor(sum, 32); sq += __shfl_xor(sq, 32);
;                 if (fq == 0) { atomicAdd(stout + 2 * (size_t)row, sum); atomicAdd(stout + 2 * (size_t)row + 1, sq); }
.LBB0_1548:
	s_or_b64 exec, exec, s[30:31]
	v_add_u32_e32 v68, 0x90, v154
	v_ashrrev_i32_e32 v69, 31, v68
	v_lshlrev_b64 v[48:49], 3, v[68:69]
	s_waitcnt lgkmcnt(0)
	v_lshl_add_u64 v[50:51], s[12:13], 0, v[48:49]
	flat_load_dwordx2 v[70:71], v[50:51]
	v_lshlrev_b64 v[50:51], 12, v[68:69]
	v_lshl_add_u64 v[50:51], s[46:47], 0, v[50:51]
	v_lshl_add_u64 v[50:51], v[144:145], 2, v[50:51]
	global_load_dwordx4 v[52:55], v[50:51], off
	global_load_dwordx4 v[56:59], v[150:151], off
	global_load_dwordx4 v[60:63], v[152:153], off
	global_load_dwordx4 v[64:67], v[50:51], off offset:16
	s_waitcnt vmcnt(0) lgkmcnt(0)
	v_pk_mul_f32 v[70:71], v[70:71], s[24:25] op_sel:[1,0] op_sel_hi:[0,0]
	v_fma_f32 v70, -v71, v71, v70
	v_max_f32_e32 v70, 0, v70
	v_add_f32_e32 v70, 0x3727c5ac, v70
	v_mul_f32_e32 v72, 0x4b800000, v70
	v_cmp_gt_f32_e32 vcc, s61, v70
	v_sub_f32_e32 v53, v53, v71
	v_sub_f32_e32 v52, v52, v71
	v_cndmask_b32_e32 v70, v70, v72, vcc
	v_rsq_f32_e32 v70, v70
	v_sub_f32_e32 v55, v55, v71
	v_sub_f32_e32 v54, v54, v71
	v_mul_f32_e32 v72, 0x45800000, v70
	v_cndmask_b32_e32 v70, v70, v72, vcc
	v_pk_mul_f32 v[54:55], v[54:55], v[70:71] op_sel_hi:[1,0]
	v_pk_mul_f32 v[52:53], v[52:53], v[70:71] op_sel_hi:[1,0]
	v_pk_fma_f32 v[54:55], v[58:59], v[54:55], v[62:63]
	v_pk_fma_f32 v[52:53], v[56:57], v[52:53], v[60:61]
	v_pk_fma_f32 v[46:47], v[54:55], s[26:27], v[46:47] op_sel_hi:[1,0,1]
	v_pk_fma_f32 v[44:45], v[52:53], s[26:27], v[44:45] op_sel_hi:[1,0,1]
	global_store_dwordx4 v[50:51], v[44:47], off
	global_load_dwordx4 v[52:55], v[146:147], off
	global_load_dwordx4 v[56:59], v[148:149], off
	v_lshlrev_b64 v[60:61], 11, v[68:69]
	v_lshl_add_u64 v[60:61], s[14:15], 0, v[60:61]
	v_lshl_add_u64 v[68:69], v[144:145], 1, v[60:61]
	v_sub_f32_e32 v61, v65, v71
	v_sub_f32_e32 v60, v64, v71
	v_sub_f32_e32 v63, v67, v71
	v_sub_f32_e32 v62, v66, v71
	v_pk_mul_f32 v[62:63], v[62:63], v[70:71] op_sel_hi:[1,0]
	v_pk_mul_f32 v[64:65], v[60:61], v[70:71] op_sel_hi:[1,0]
	v_cvt_pk_bf16_f32 v60, v44, v45
	v_cvt_pk_bf16_f32 v61, v46, v47
	s_waitcnt vmcnt(0)
	v_pk_fma_f32 v[54:55], v[54:55], v[62:63], v[58:59]
	v_pk_fma_f32 v[52:53], v[52:53], v[64:65], v[56:57]
	v_pk_fma_f32 v[42:43], v[54:55], s[26:27], v[42:43] op_sel_hi:[1,0,1]
	v_pk_fma_f32 v[40:41], v[52:53], s[26:27], v[40:41] op_sel_hi:[1,0,1]
	global_store_dwordx4 v[50:51], v[40:43], off offset:16
	v_cvt_pk_bf16_f32 v62, v40, v41
	v_cvt_pk_bf16_f32 v63, v42, v43
	flat_store_dwordx4 v[68:69], v[60:63]
	global_load_dwordx4 v[52:55], v[50:51], off offset:512
	global_load_dwordx4 v[56:59], v[120:121], off
	s_nop 0
	global_load_dwordx4 v[60:63], v[122:123], off
	global_load_dwordx4 v[64:67], v[50:51], off offset:528
	s_waitcnt vmcnt(0)
	v_sub_f32_e32 v53, v53, v71
	v_sub_f32_e32 v52, v52, v71
	v_sub_f32_e32 v55, v55, v71
	v_sub_f32_e32 v54, v54, v71
	v_pk_mul_f32 v[54:55], v[70:71], v[54:55] op_sel_hi:[0,1]
	v_pk_mul_f32 v[52:53], v[70:71], v[52:53] op_sel_hi:[0,1]
	v_pk_fma_f32 v[52:53], v[56:57], v[52:53], v[60:61]
	v_pk_fma_f32 v[54:55], v[58:59], v[54:55], v[62:63]
	v_pk_fma_f32 v[36:37], v[52:53], s[26:27], v[36:37] op_sel_hi:[1,0,1]
	v_pk_fma_f32 v[38:39], v[54:55], s[26:27], v[38:39] op_sel_hi:[1,0,1]
	global_store_dwordx4 v[50:51], v[36:39], off offset:512
	global_load_dwordx4 v[52:55], v[124:125], off
	global_load_dwordx4 v[56:59], v[126:127], off
	v_add_f32_e32 v60, v44, v45
	v_mul_f32_e32 v45, v45, v45
	v_fmac_f32_e32 v45, v44, v44
	v_add_f32_e32 v60, v46, v60
	v_fmac_f32_e32 v45, v46, v46
	v_add_f32_e32 v46, v40, v41
	v_mul_f32_e32 v41, v41, v41
	v_fmac_f32_e32 v41, v40, v40
	v_add_f32_e32 v44, v47, v60
	v_add_f32_e32 v46, v42, v46
	v_fmac_f32_e32 v41, v42, v42
	v_add_f32_e32 v44, 0, v44
	v_fmac_f32_e32 v45, v47, v47
	v_add_f32_e32 v40, v43, v46
	v_fmac_f32_e32 v41, v43, v43
	v_add_f32_e32 v44, v40, v44
	v_add_f32_e32 v45, v45, v41
	v_sub_f32_e32 v41, v65, v71
	v_sub_f32_e32 v40, v64, v71
	v_pk_mul_f32 v[40:41], v[70:71], v[40:41] op_sel_hi:[0,1]
	v_sub_f32_e32 v43, v67, v71
	v_sub_f32_e32 v42, v66, v71
	v_pk_mul_f32 v[42:43], v[70:71], v[42:43] op_sel_hi:[0,1]
	v_mul_f32_e32 v47, v37, v37
	v_add_f32_e32 v46, v36, v37
	v_fmac_f32_e32 v47, v36, v36
	v_add_f32_e32 v46, v38, v46
	v_fmac_f32_e32 v47, v38, v38
	v_add_f32_e32 v46, v39, v46
	v_fmac_f32_e32 v47, v39, v39
	v_add_f32_e32 v44, v44, v46
	v_add_f32_e32 v45, v45, v47
	v_cvt_pk_bf16_f32 v36, v36, v37
	v_cvt_pk_bf16_f32 v37, v38, v39
	s_waitcnt vmcnt(0)
	v_pk_fma_f32 v[40:41], v[52:53], v[40:41], v[56:57]
	s_nop 0
	v_pk_fma_f32 v[40:41], v[40:41], s[26:27], v[32:33] op_sel_hi:[1,0,1]
	v_pk_fma_f32 v[42:43], v[54:55], v[42:43], v[58:59]
	v_mul_f32_e32 v33, v41, v41
	v_pk_fma_f32 v[42:43], v[42:43], s[26:27], v[34:35] op_sel_hi:[1,0,1]
	v_add_f32_e32 v32, v40, v41
	v_fmac_f32_e32 v33, v40, v40
	v_add_f32_e32 v32, v42, v32
	v_fmac_f32_e32 v33, v42, v42
	v_add_f32_e32 v32, v43, v32
	v_fmac_f32_e32 v33, v43, v43
	v_add_f32_e32 v32, v44, v32
	v_add_f32_e32 v33, v45, v33
	ds_bpermute_b32 v34, v116, v32
	ds_bpermute_b32 v35, v116, v33
	global_store_dwordx4 v[50:51], v[40:43], off offset:528
	v_cvt_pk_bf16_f32 v38, v40, v41
	v_cvt_pk_bf16_f32 v39, v42, v43
	s_waitcnt lgkmcnt(0)
	v_add_f32_e32 v32, v32, v34
	v_add_f32_e32 v33, v33, v35
	ds_bpermute_b32 v34, v117, v32
	ds_bpermute_b32 v35, v117, v33
	flat_store_dwordx4 v[68:69], v[36:39] offset:256
	s_mov_b32 s100, -1
	s_mov_b32 s101, 0
	s_mov_b32 s98, 0xffff0000
	s_mov_b32 s99, 0
	s_and_saveexec_b64 s[30:31], s[100:101]
	s_cbranch_execz .LBB0_1550
	v_lshl_add_u64 v[36:37], s[10:11], 0, v[48:49]
	s_waitcnt lgkmcnt(0)
	v_add_f32_e32 v32, v32, v34
	v_add_f32_e32 v33, v33, v35
	v_cndmask_b32_e64 v32, v32, v33, s[98:99]
	v_cndmask_b32_e64 v33, 0, 4, s[98:99]
	v_or_b32_e32 v36, v36, v33
	flat_atomic_add_f32 v[36:37], v32
; DEVI unsigned pk2(float lo, float hi) { unsigned r; asm("v_cvt_pk_bf16_f32 %0, %1, %2" : "=v"(r) : "v"(lo), "v"(hi)); return r; }
; DEVI void row_stats(const float* stats, int row, float& mu, float& rs) {
;     if (stats) { const float2 st = *(const float2*)(stats + 2 * (size_t)row); mu = st.x * (1.0f / 1024.0f); const float var = st.y * (1.0f / 1024.0f) - mu * mu; rs = rsqrtf(fmaxf(var, 0.f) + LN_EPS); }
;     DEVI void operator()(const f32x4 (&acc)[2][2][4][2], const pg8::Unit& u, int wr, int wc, int fr, int fq) const {
;     ...
;                 const int row = row0 + ai * 128 + m * 16; float mu, rs; row_stats(stin, row, mu, rs);
;                 float sum = 0.f, sq = 0.f;
; #pragma unroll
;                 for (int bj = 0; bj < 2; ++bj) {
;                     f32x4 z[2];
; #pragma unroll
;                     for (int n = 0; n < 2; ++n) {
;                         const int col = colb + bj * 128 + 4 * n;
;                         f32x4 xv = *(const f32x4*)(zsrc + (size_t)row * DM + col);
;                         if (stin) { const f32x4 gv = *(const f32x4*)(gin + col), bv = *(const f32x4*)(bin + col); xv = (xv - mu) * rs * gv + bv; }
;                         f32x4 zz = ALPHA * xv + acc[ai][bj][m][n];
;                         if (bias) zz += *(const f32x4*)(bias + col);
;                         *(f32x4*)(zdst + (size_t)row * DM + col) = zz;
;                         sum += zz[0] + zz[1] + zz[2] + zz[3]; sq += zz[0] * zz[0] + zz[1] * zz[1] + zz[2] * zz[2] + zz[3] * zz[3];
;                         z[n] = zz;
;                     }
;                     u32x4 o; o.x = pk2(z[0][0], z[0][1]); o.y = pk2(z[0][2], z[0][3]); o.z = pk2(z[1][0], z[1][1]); o.w = pk2(z[1][2], z[1][3]);
;                     if (zb) *(u32x4*)(zb + (size_t)row * DM + colb + bj * 128) = o;
;                 }
;                 sum += __shfl_xor(sum, 16); sq += __shfl_xor(sq, 16);
;                 sum += __shfl_xor(sum, 32); sq += __shfl_xor(sq, 32);
;                 if (fq == 0) { atomicAdd(stout + 2 * (size_t)row, sum); atomicAdd(stout + 2 * (size_t)row + 1, sq); }
.LBB0_1550:
	s_or_b64 exec, exec, s[30:31]
	v_add_u32_e32 v52, 0xa0, v154
	v_ashrrev_i32_e32 v53, 31, v52
	v_lshlrev_b64 v[32:33], 3, v[52:53]
	s_waitcnt lgkmcnt(0)
	v_lshl_add_u64 v[34:35], s[12:13], 0, v[32:33]
	flat_load_dwordx2 v[54:55], v[34:35]
	v_lshlrev_b64 v[34:35], 12, v[52:53]
	v_lshl_add_u64 v[34:35], s[46:47], 0, v[34:35]
	v_lshl_add_u64 v[34:35], v[144:145], 2, v[34:35]
	global_load_dwordx4 v[36:39], v[34:35], off
	global_load_dwordx4 v[40:43], v[150:151], off
	global_load_dwordx4 v[44:47], v[152:153], off
	global_load_dwordx4 v[48:51], v[34:35], off offset:16
	s_waitcnt vmcnt(0) lgkmcnt(0)
	v_pk_mul_f32 v[54:55], v[54:55], s[24:25] op_sel:[1,0] op_sel_hi:[0,0]
	v_fma_f32 v54, -v55, v55, v54
	v_max_f32_e32 v54, 0, v54
	v_add_f32_e32 v54, 0x3727c5ac, v54
	v_mul_f32_e32 v56, 0x4b800000, v54
	v_cmp_gt_f32_e32 vcc, s61, v54
	v_sub_f32_e32 v37, v37, v55
	v_sub_f32_e32 v36, v36, v55
	v_cndmask_b32_e32 v54, v54, v56, vcc
	v_rsq_f32_e32 v54, v54
	v_sub_f32_e32 v39, v39, v55
	v_sub_f32_e32 v38, v38, v55
	v_mul_f32_e32 v56, 0x45800000, v54
	v_cndmask_b32_e32 v54, v54, v56, vcc
	v_pk_mul_f32 v[38:39], v[38:39], v[54:55] op_sel_hi:[1,0]
	v_pk_mul_f32 v[36:37], v[36:37], v[54:55] op_sel_hi:[1,0]
	v_pk_fma_f32 v[38:39], v[42:43], v[38:39], v[46:47]
	v_pk_fma_f32 v[36:37], v[40:41], v[36:37], v[44:45]
	v_pk_fma_f32 v[30:31], v[38:39], s[26:27], v[30:31] op_sel_hi:[1,0,1]
	v_pk_fma_f32 v[28:29], v[36:37], s[26:27], v[28:29] op_sel_hi:[1,0,1]
	global_store_dwordx4 v[34:35], v[28:31], off
	global_load_dwordx4 v[36:39], v[146:147], off
	global_load_dwordx4 v[40:43], v[148:149], off
	v_lshlrev_b64 v[44:45], 11, v[52:53]
	v_lshl_add_u64 v[44:45], s[14:15], 0, v[44:45]
	v_lshl_add_u64 v[52:53], v[144:145], 1, v[44:45]
	v_sub_f32_e32 v45, v49, v55
	v_sub_f32_e32 v44, v48, v55
	v_sub_f32_e32 v47, v51, v55
	v_sub_f32_e32 v46, v50, v55
	v_pk_mul_f32 v[46:47], v[46:47], v[54:55] op_sel_hi:[1,0]
	v_pk_mul_f32 v[48:49], v[44:45], v[54:55] op_sel_hi:[1,0]
	v_cvt_pk_bf16_f32 v44, v28, v29
	v_cvt_pk_bf16_f32 v45, v30, v31
	s_waitcnt vmcnt(0)
	v_pk_fma_f32 v[38:39], v[38:39], v[46:47], v[42:43]
	v_pk_fma_f32 v[36:37], v[36:37], v[48:49], v[40:41]
	v_pk_fma_f32 v[26:27], v[38:39], s[26:27], v[26:27] op_sel_hi:[1,0,1]
	v_pk_fma_f32 v[24:25], v[36:37], s[26:27], v[24:25] op_sel_hi:[1,0,1]
	global_store_dwordx4 v[34:35], v[24:27], off offset:16
	v_cvt_pk_bf16_f32 v46, v24, v25
	v_cvt_pk_bf16_f32 v47, v26, v27
	flat_store_dwordx4 v[52:53], v[44:47]
	global_load_dwordx4 v[36:39], v[34:35], off offset:512
	global_load_dwordx4 v[40:43], v[120:121], off
	s_nop 0
	global_load_dwordx4 v[44:47], v[122:123], off
	global_load_dwordx4 v[48:51], v[34:35], off offset:528
	s_waitcnt vmcnt(0)
	v_sub_f32_e32 v37, v37, v55
	v_sub_f32_e32 v36, v36, v55
	v_sub_f32_e32 v39, v39, v55
	v_sub_f32_e32 v38, v38, v55
	v_pk_mul_f32 v[38:39], v[54:55], v[38:39] op_sel_hi:[0,1]
	v_pk_mul_f32 v[36:37], v[54:55], v[36:37] op_sel_hi:[0,1]
	v_pk_fma_f32 v[36:37], v[40:41], v[36:37], v[44:45]
	v_pk_fma_f32 v[38:39], v[42:43], v[38:39], v[46:47]
	v_pk_fma_f32 v[20:21], v[36:37], s[26:27], v[20:21] op_sel_hi:[1,0,1]
	v_pk_fma_f32 v[22:23], v[38:39], s[26:27], v[22:23] op_sel_hi:[1,0,1]
	global_store_dwordx4 v[34:35], v[20:23], off offset:512
	global_load_dwordx4 v[36:39], v[124:125], off
	global_load_dwordx4 v[40:43], v[126:127], off
	v_add_f32_e32 v44, v28, v29
	v_mul_f32_e32 v29, v29, v29
	v_fmac_f32_e32 v29, v28, v28
	v_add_f32_e32 v44, v30, v44
	v_fmac_f32_e32 v29, v30, v30
	v_add_f32_e32 v30, v24, v25
	v_mul_f32_e32 v25, v25, v25
	v_fmac_f32_e32 v25, v24, v24
	v_add_f32_e32 v28, v31, v44
	v_add_f32_e32 v30, v26, v30
	v_fmac_f32_e32 v25, v26, v26
	v_add_f32_e32 v28, 0, v28
	v_fmac_f32_e32 v29, v31, v31
	v_add_f32_e32 v24, v27, v30
	v_fmac_f32_e32 v25, v27, v27
	v_add_f32_e32 v28, v24, v28
	v_add_f32_e32 v29, v29, v25
	v_sub_f32_e32 v25, v49, v55
	v_sub_f32_e32 v24, v48, v55
	v_pk_mul_f32 v[24:25], v[54:55], v[24:25] op_sel_hi:[0,1]
	v_sub_f32_e32 v27, v51, v55
	v_sub_f32_e32 v26, v50, v55
	v_pk_mul_f32 v[26:27], v[54:55], v[26:27] op_sel_hi:[0,1]
	v_mul_f32_e32 v31, v21, v21
	v_add_f32_e32 v30, v20, v21
	v_fmac_f32_e32 v31, v20, v20
	v_add_f32_e32 v30, v22, v30
	v_fmac_f32_e32 v31, v22, v22
	v_add_f32_e32 v30, v23, v30
	v_fmac_f32_e32 v31, v23, v23
	v_add_f32_e32 v28, v28, v30
	v_add_f32_e32 v29, v29, v31
	v_cvt_pk_bf16_f32 v20, v20, v21
	v_cvt_pk_bf16_f32 v21, v22, v23
	s_waitcnt vmcnt(0)
	v_pk_fma_f32 v[24:25], v[36:37], v[24:25], v[40:41]
	s_nop 0
	v_pk_fma_f32 v[24:25], v[24:25], s[26:27], v[16:17] op_sel_hi:[1,0,1]
	v_pk_fma_f32 v[26:27], v[38:39], v[26:27], v[42:43]
	v_mul_f32_e32 v17, v25, v25
	v_pk_fma_f32 v[26:27], v[26:27], s[26:27], v[18:19] op_sel_hi:[1,0,1]
	v_add_f32_e32 v16, v24, v25
	v_fmac_f32_e32 v17, v24, v24
	v_add_f32_e32 v16, v26, v16
	v_fmac_f32_e32 v17, v26, v26
	v_add_f32_e32 v16, v27, v16
	v_fmac_f32_e32 v17, v27, v27
	v_add_f32_e32 v16, v28, v16
	v_add_f32_e32 v17, v29, v17
	ds_bpermute_b32 v18, v116, v16
	ds_bpermute_b32 v19, v116, v17
	global_store_dwordx4 v[34:35], v[24:27], off offset:528
	v_cvt_pk_bf16_f32 v22, v24, v25
	v_cvt_pk_bf16_f32 v23, v26, v27
	s_waitcnt lgkmcnt(0)
	v_add_f32_e32 v16, v16, v18
	v_add_f32_e32 v17, v17, v19
	ds_bpermute_b32 v18, v117, v16
	ds_bpermute_b32 v19, v117, v17
	flat_store_dwordx4 v[52:53], v[20:23] offset:256
	s_mov_b32 s100, -1
	s_mov_b32 s101, 0
	s_mov_b32 s98, 0xffff0000
	s_mov_b32 s99, 0
	s_and_saveexec_b64 s[30:31], s[100:101]
	s_cbranch_execz .LBB0_1552
	v_lshl_add_u64 v[20:21], s[10:11], 0, v[32:33]
	s_waitcnt lgkmcnt(0)
	v_add_f32_e32 v16, v16, v18
	v_add_f32_e32 v17, v17, v19
	v_cndmask_b32_e64 v16, v16, v17, s[98:99]
	v_cndmask_b32_e64 v17, 0, 4, s[98:99]
	v_or_b32_e32 v20, v20, v17
	flat_atomic_add_f32 v[20:21], v16
; DEVI unsigned pk2(float lo, float hi) { unsigned r; asm("v_cvt_pk_bf16_f32 %0, %1, %2" : "=v"(r) : "v"(lo), "v"(hi)); return r; }
; DEVI void row_stats(const float* stats, int row, float& mu, float& rs) {
;     if (stats) { const float2 st = *(const float2*)(stats + 2 * (size_t)row); mu = st.x * (1.0f / 1024.0f); const float var = st.y * (1.0f / 1024.0f) - mu * mu; rs = rsqrtf(fmaxf(var, 0.f) + LN_EPS); }
;     DEVI void operator()(const f32x4 (&acc)[2][2][4][2], const pg8::Unit& u, int wr, int wc, int fr, int fq) const {
;     ...
;                 const int row = row0 + ai * 128 + m * 16; float mu, rs; row_stats(stin, row, mu, rs);
;                 float sum = 0.f, sq = 0.f;
; #pragma unroll
;                 for (int bj = 0; bj < 2; ++bj) {
;                     f32x4 z[2];
; #pragma unroll
;                     for (int n = 0; n < 2; ++n) {
;                         const int col = colb + bj * 128 + 4 * n;
;                         f32x4 xv = *(const f32x4*)(zsrc + (size_t)row * DM + col);
;                         if (stin) { const f32x4 gv = *(const f32x4*)(gin + col), bv = *(const f32x4*)(bin + col); xv = (xv - mu) * rs * gv + bv; }
;                         f32x4 zz = ALPHA * xv + acc[ai][bj][m][n];
;                         if (bias) zz += *(const f32x4*)(bias + col);
;                         *(f32x4*)(zdst + (size_t)row * DM + col) = zz;
;                         sum += zz[0] + zz[1] + zz[2] + zz[3]; sq += zz[0] * zz[0] + zz[1] * zz[1] + zz[2] * zz[2] + zz[3] * zz[3];
;                         z[n] = zz;
;                     }
;                     u32x4 o; o.x = pk2(z[0][0], z[0][1]); o.y = pk2(z[0][2], z[0][3]); o.z = pk2(z[1][0], z[1][1]); o.w = pk2(z[1][2], z[1][3]);
;                     if (zb) *(u32x4*)(zb + (size_t)row * DM + colb + bj * 128) = o;
;                 }
;                 sum += __shfl_xor(sum, 16); sq += __shfl_xor(sq, 16);
;                 sum += __shfl_xor(sum, 32); sq += __shfl_xor(sq, 32);
;                 if (fq == 0) { atomicAdd(stout + 2 * (size_t)row, sum); atomicAdd(stout + 2 * (size_t)row + 1, sq); }
.LBB0_1552:
	s_or_b64 exec, exec, s[30:31]
	v_add_u32_e32 v36, 0xb0, v154
	v_ashrrev_i32_e32 v37, 31, v36
	v_lshlrev_b64 v[16:17], 3, v[36:37]
	s_waitcnt lgkmcnt(0)
	v_lshl_add_u64 v[18:19], s[12:13], 0, v[16:17]
	flat_load_dwordx2 v[38:39], v[18:19]
	v_lshlrev_b64 v[18:19], 12, v[36:37]
	v_lshl_add_u64 v[18:19], s[46:47], 0, v[18:19]
	v_lshl_add_u64 v[18:19], v[144:145], 2, v[18:19]
	global_load_dwordx4 v[20:23], v[18:19], off
	global_load_dwordx4 v[24:27], v[150:151], off
	global_load_dwordx4 v[28:31], v[152:153], off
	global_load_dwordx4 v[32:35], v[18:19], off offset:16
	s_waitcnt vmcnt(0) lgkmcnt(0)
	v_pk_mul_f32 v[38:39], v[38:39], s[24:25] op_sel:[1,0] op_sel_hi:[0,0]
	v_fma_f32 v38, -v39, v39, v38
	v_max_f32_e32 v38, 0, v38
	v_add_f32_e32 v38, 0x3727c5ac, v38
	v_mul_f32_e32 v40, 0x4b800000, v38
	v_cmp_gt_f32_e32 vcc, s61, v38
	v_sub_f32_e32 v21, v21, v39
	v_sub_f32_e32 v20, v20, v39
	v_cndmask_b32_e32 v38, v38, v40, vcc
	v_rsq_f32_e32 v38, v38
	v_sub_f32_e32 v23, v23, v39
	v_sub_f32_e32 v22, v22, v39
	v_mul_f32_e32 v40, 0x45800000, v38
	v_cndmask_b32_e32 v38, v38, v40, vcc
	v_pk_mul_f32 v[22:23], v[22:23], v[38:39] op_sel_hi:[1,0]
	v_pk_mul_f32 v[20:21], v[20:21], v[38:39] op_sel_hi:[1,0]
	v_pk_fma_f32 v[22:23], v[26:27], v[22:23], v[30:31]
	v_pk_fma_f32 v[20:21], v[24:25], v[20:21], v[28:29]
	v_pk_fma_f32 v[14:15], v[22:23], s[26:27], v[14:15] op_sel_hi:[1,0,1]
	v_pk_fma_f32 v[12:13], v[20:21], s[26:27], v[12:13] op_sel_hi:[1,0,1]
	global_store_dwordx4 v[18:19], v[12:15], off
	global_load_dwordx4 v[20:23], v[146:147], off
	global_load_dwordx4 v[24:27], v[148:149], off
	v_lshlrev_b64 v[28:29], 11, v[36:37]
	v_lshl_add_u64 v[28:29], s[14:15], 0, v[28:29]
	v_lshl_add_u64 v[36:37], v[144:145], 1, v[28:29]
	v_sub_f32_e32 v29, v33, v39
	v_sub_f32_e32 v28, v32, v39
	v_sub_f32_e32 v31, v35, v39
	v_sub_f32_e32 v30, v34, v39
	v_pk_mul_f32 v[30:31], v[30:31], v[38:39] op_sel_hi:[1,0]
	v_pk_mul_f32 v[32:33], v[28:29], v[38:39] op_sel_hi:[1,0]
	v_cvt_pk_bf16_f32 v28, v12, v13
	v_cvt_pk_bf16_f32 v29, v14, v15
	s_waitcnt vmcnt(0)
	v_pk_fma_f32 v[22:23], v[22:23], v[30:31], v[26:27]
	v_pk_fma_f32 v[20:21], v[20:21], v[32:33], v[24:25]
	v_pk_fma_f32 v[10:11], v[22:23], s[26:27], v[10:11] op_sel_hi:[1,0,1]
	v_pk_fma_f32 v[8:9], v[20:21], s[26:27], v[8:9] op_sel_hi:[1,0,1]
	global_store_dwordx4 v[18:19], v[8:11], off offset:16
	v_cvt_pk_bf16_f32 v30, v8, v9
	v_cvt_pk_bf16_f32 v31, v10, v11
	flat_store_dwordx4 v[36:37], v[28:31]
	global_load_dwordx4 v[20:23], v[18:19], off offset:512
	global_load_dwordx4 v[24:27], v[120:121], off
	s_nop 0
	global_load_dwordx4 v[28:31], v[122:123], off
	global_load_dwordx4 v[32:35], v[18:19], off offset:528
	s_waitcnt vmcnt(0)
	v_sub_f32_e32 v21, v21, v39
	v_sub_f32_e32 v20, v20, v39
	v_sub_f32_e32 v23, v23, v39
	v_sub_f32_e32 v22, v22, v39
	v_pk_mul_f32 v[22:23], v[38:39], v[22:23] op_sel_hi:[0,1]
	v_pk_mul_f32 v[20:21], v[38:39], v[20:21] op_sel_hi:[0,1]
	v_pk_fma_f32 v[20:21], v[24:25], v[20:21], v[28:29]
	v_pk_fma_f32 v[22:23], v[26:27], v[22:23], v[30:31]
	v_pk_fma_f32 v[4:5], v[20:21], s[26:27], v[4:5] op_sel_hi:[1,0,1]
	v_pk_fma_f32 v[6:7], v[22:23], s[26:27], v[6:7] op_sel_hi:[1,0,1]
	global_store_dwordx4 v[18:19], v[4:7], off offset:512
	global_load_dwordx4 v[20:23], v[124:125], off
	global_load_dwordx4 v[24:27], v[126:127], off
	v_add_f32_e32 v28, v12, v13
	v_mul_f32_e32 v13, v13, v13
	v_fmac_f32_e32 v13, v12, v12
	v_add_f32_e32 v28, v14, v28
	v_fmac_f32_e32 v13, v14, v14
	v_add_f32_e32 v14, v8, v9
	v_mul_f32_e32 v9, v9, v9
	v_fmac_f32_e32 v9, v8, v8
	v_add_f32_e32 v12, v15, v28
	v_add_f32_e32 v14, v10, v14
	v_fmac_f32_e32 v9, v10, v10
	v_add_f32_e32 v12, 0, v12
	v_fmac_f32_e32 v13, v15, v15
	v_add_f32_e32 v8, v11, v14
	v_fmac_f32_e32 v9, v11, v11
	v_add_f32_e32 v12, v8, v12
	v_add_f32_e32 v13, v13, v9
	v_sub_f32_e32 v9, v33, v39
	v_sub_f32_e32 v8, v32, v39
	v_pk_mul_f32 v[8:9], v[38:39], v[8:9] op_sel_hi:[0,1]
	v_sub_f32_e32 v11, v35, v39
	v_sub_f32_e32 v10, v34, v39
	v_pk_mul_f32 v[10:11], v[38:39], v[10:11] op_sel_hi:[0,1]
	v_mul_f32_e32 v15, v5, v5
	v_add_f32_e32 v14, v4, v5
	v_fmac_f32_e32 v15, v4, v4
	v_add_f32_e32 v14, v6, v14
	v_fmac_f32_e32 v15, v6, v6
	v_add_f32_e32 v14, v7, v14
	v_fmac_f32_e32 v15, v7, v7
	v_add_f32_e32 v12, v12, v14
	v_add_f32_e32 v13, v13, v15
	v_cvt_pk_bf16_f32 v4, v4, v5
	v_cvt_pk_bf16_f32 v5, v6, v7
	s_waitcnt vmcnt(0)
	v_pk_fma_f32 v[8:9], v[20:21], v[8:9], v[24:25]
	s_nop 0
	v_pk_fma_f32 v[8:9], v[8:9], s[26:27], v[0:1] op_sel_hi:[1,0,1]
	v_pk_fma_f32 v[10:11], v[22:23], v[10:11], v[26:27]
	v_mul_f32_e32 v1, v9, v9
	v_pk_fma_f32 v[10:11], v[10:11], s[26:27], v[2:3] op_sel_hi:[1,0,1]
	v_add_f32_e32 v0, v8, v9
	v_fmac_f32_e32 v1, v8, v8
	v_add_f32_e32 v0, v10, v0
	v_fmac_f32_e32 v1, v10, v10
	v_add_f32_e32 v0, v11, v0
	v_fmac_f32_e32 v1, v11, v11
	v_add_f32_e32 v0, v12, v0
	v_add_f32_e32 v1, v13, v1
	ds_bpermute_b32 v2, v116, v0
	ds_bpermute_b32 v3, v116, v1
	global_store_dwordx4 v[18:19], v[8:11], off offset:528
	v_cvt_pk_bf16_f32 v6, v8, v9
	v_cvt_pk_bf16_f32 v7, v10, v11
	s_waitcnt lgkmcnt(0)
	v_add_f32_e32 v0, v0, v2
	v_add_f32_e32 v1, v1, v3
	ds_bpermute_b32 v2, v117, v0
	ds_bpermute_b32 v3, v117, v1
	flat_store_dwordx4 v[36:37], v[4:7] offset:256
	s_mov_b32 s100, -1
	s_mov_b32 s101, 0
	s_mov_b32 s98, 0xffff0000
	s_mov_b32 s99, 0
	s_and_saveexec_b64 s[30:31], s[100:101]
	s_cbranch_execz .LBB0_1554
	v_lshl_add_u64 v[4:5], s[10:11], 0, v[16:17]
	s_waitcnt lgkmcnt(0)
	v_add_f32_e32 v0, v0, v2
	v_add_f32_e32 v1, v1, v3
	v_cndmask_b32_e64 v0, v0, v1, s[98:99]
	v_cndmask_b32_e64 v1, 0, 4, s[98:99]
	v_or_b32_e32 v4, v4, v1
	flat_atomic_add_f32 v[4:5], v0

; DEVI void row_stats(const float* stats, int row, float& mu, float& rs) {
;     if (stats) { const float2 st = *(const float2*)(stats + 2 * (size_t)row); mu = st.x * (1.0f / 1024.0f); const float var = st.y * (1.0f / 1024.0f) - mu * mu; rs = rsqrtf(fmaxf(var, 0.f) + LN_EPS); }
;     DEVI void operator()(const f32x4 (&acc)[2][2][4][2], const pg8::Unit& u, int wr, int wc, int fr, int fq) const {
;         const int row0 = u.pm * 256 + wr * 64 + fr, colb = u.pn * 256 + wc * 32 + 8 * fq;
; #pragma unroll
;         for (int ai = 0; ai < 2; ++ai)
; #pragma unroll
;             for (int m = 0; m < 4; ++m) {
;                 const int row = row0 + ai * 128 + m * 16; float mu, rs; row_stats(stin, row, mu, rs);
;                 float sum = 0.f, sq = 0.f;
; #pragma unroll
;                 for (int bj = 0; bj < 2; ++bj) {
;                     f32x4 z[2];
; #pragma unroll
;                     for (int n = 0; n < 2; ++n) {
;                         const int col = colb + bj * 128 + 4 * n;
;                         f32x4 xv = *(const f32x4*)(zsrc + (size_t)row * DM + col);
;                         if (stin) { const f32x4 gv = *(const f32x4*)(gin + col), bv = *(const f32x4*)(bin + col); xv = (xv - mu) * rs * gv + bv; }
;                         f32x4 zz = ALPHA * xv + acc[ai][bj][m][n];
;                         if (bias) zz += *(const f32x4*)(bias + col);
;                         *(f32x4*)(zdst + (size_t)row * DM + col) = zz;
;                         sum += zz[0] + zz[1] + zz[2] + zz[3]; sq += zz[0] * zz[0] + zz[1] * zz[1] + zz[2] * zz[2] + zz[3] * zz[3];
;                         z[n] = zz;
.LBB0_1983:
	v_lshl_add_u32 v154, s36, 8, v168
	v_ashrrev_i32_e32 v155, 31, v154
	v_lshlrev_b64 v[162:163], 3, v[154:155]
	v_lshl_add_u64 v[146:147], s[6:7], 0, v[162:163]
	s_waitcnt vmcnt(0)
	flat_load_dwordx2 v[166:167], v[146:147]
	v_lshl_or_b32 v144, s38, 8, v170
	v_ashrrev_i32_e32 v145, 31, v144
	v_lshlrev_b64 v[146:147], 12, v[154:155]
	v_lshl_add_u64 v[146:147], s[46:47], 0, v[146:147]
	v_lshlrev_b64 v[148:149], 2, v[144:145]
	v_lshl_add_u64 v[164:165], v[146:147], 0, v[148:149]
	global_load_dwordx4 v[158:161], v[164:165], off
	v_lshl_add_u64 v[150:151], s[12:13], 0, v[148:149]
	v_lshl_add_u64 v[152:153], s[14:15], 0, v[148:149]
	global_load_dwordx4 v[176:179], v[150:151], off
	global_load_dwordx4 v[180:183], v[152:153], off
	v_lshl_add_u64 v[156:157], s[16:17], 0, v[148:149]
	global_load_dwordx4 v[184:187], v[156:157], off
	global_load_dwordx4 v[188:191], v[164:165], off offset:16
	v_or_b32_e32 v146, 4, v144
	v_ashrrev_i32_e32 v147, 31, v146
	v_lshlrev_b64 v[192:193], 2, v[146:147]
	v_lshl_add_u64 v[146:147], s[12:13], 0, v[192:193]
	v_lshl_add_u64 v[148:149], s[14:15], 0, v[192:193]
	s_waitcnt vmcnt(0) lgkmcnt(0)
	v_pk_mul_f32 v[166:167], v[166:167], s[22:23] op_sel:[1,0] op_sel_hi:[0,0]
	v_fma_f32 v166, -v167, v167, v166
	v_max_f32_e32 v166, 0, v166
	v_add_f32_e32 v166, 0x3727c5ac, v166
	v_mul_f32_e32 v175, 0x4b800000, v166
	v_cmp_gt_f32_e32 vcc, s72, v166
	v_sub_f32_e32 v161, v161, v167
	s_nop 0
	v_cndmask_b32_e32 v166, v166, v175, vcc
	v_rsq_f32_e32 v166, v166
	v_sub_f32_e32 v160, v160, v167
	v_sub_f32_e32 v159, v159, v167
	v_sub_f32_e32 v158, v158, v167
	v_mul_f32_e32 v175, 0x45800000, v166
	v_cndmask_b32_e32 v166, v166, v175, vcc
	v_pk_mul_f32 v[158:159], v[158:159], v[166:167] op_sel_hi:[1,0]
	v_pk_mul_f32 v[160:161], v[160:161], v[166:167] op_sel_hi:[1,0]
	v_pk_fma_f32 v[158:159], v[176:177], v[158:159], v[180:181]
	v_pk_fma_f32 v[160:161], v[178:179], v[160:161], v[182:183]
	v_pk_fma_f32 v[124:125], v[158:159], s[24:25], v[124:125] op_sel_hi:[1,0,1]
	v_pk_fma_f32 v[126:127], v[160:161], s[24:25], v[126:127] op_sel_hi:[1,0,1]
	v_pk_add_f32 v[176:177], v[184:185], v[124:125]
	v_pk_add_f32 v[178:179], v[186:187], v[126:127]
	global_store_dwordx4 v[164:165], v[176:179], off
	global_load_dwordx4 v[158:161], v[146:147], off
	global_load_dwordx4 v[180:183], v[148:149], off
	v_lshl_add_u64 v[124:125], s[16:17], 0, v[192:193]
	global_load_dwordx4 v[184:187], v[124:125], off
	v_lshlrev_b64 v[192:193], 11, v[154:155]
	v_lshl_add_u64 v[192:193], s[10:11], 0, v[192:193]
	v_sub_f32_e32 v191, v191, v167
	v_sub_f32_e32 v190, v190, v167
	v_sub_f32_e32 v189, v189, v167
	v_sub_f32_e32 v188, v188, v167
	v_lshl_add_u64 v[204:205], v[144:145], 1, v[192:193]
	v_pk_mul_f32 v[192:193], v[188:189], v[166:167] op_sel_hi:[1,0]
	v_pk_mul_f32 v[190:191], v[190:191], v[166:167] op_sel_hi:[1,0]
	v_or_b32_e32 v126, 0x80, v144
	v_cvt_pk_bf16_f32 v188, v176, v177
	v_cvt_pk_bf16_f32 v189, v178, v179
	v_ashrrev_i32_e32 v127, 31, v126
	v_xor_b32_e32 v155, 32, v174
	v_mul_f32_e32 v175, v177, v177
	v_fmac_f32_e32 v175, v176, v176
	v_fmac_f32_e32 v175, v178, v178
	v_fmac_f32_e32 v175, v179, v179
	s_waitcnt vmcnt(1)
	v_pk_fma_f32 v[160:161], v[160:161], v[190:191], v[182:183]
	v_pk_fma_f32 v[158:159], v[158:159], v[192:193], v[180:181]
	v_pk_fma_f32 v[122:123], v[160:161], s[24:25], v[122:123] op_sel_hi:[1,0,1]
	v_pk_fma_f32 v[120:121], v[158:159], s[24:25], v[120:121] op_sel_hi:[1,0,1]
	s_waitcnt vmcnt(0)
	v_pk_add_f32 v[182:183], v[186:187], v[122:123]
	v_pk_add_f32 v[180:181], v[184:185], v[120:121]
	global_store_dwordx4 v[164:165], v[180:183], off offset:16
	v_cvt_pk_bf16_f32 v190, v180, v181
	v_cvt_pk_bf16_f32 v191, v182, v183
	flat_store_dwordx4 v[204:205], v[188:191]
	global_load_dwordx4 v[184:187], v[164:165], off offset:512
	v_lshlrev_b64 v[120:121], 2, v[126:127]
	v_lshl_add_u64 v[126:127], s[12:13], 0, v[120:121]
	v_lshl_add_u64 v[158:159], s[14:15], 0, v[120:121]
	global_load_dwordx4 v[188:191], v[126:127], off
	global_load_dwordx4 v[192:195], v[158:159], off
	v_lshl_add_u64 v[160:161], s[16:17], 0, v[120:121]
	global_load_dwordx4 v[196:199], v[160:161], off
	global_load_dwordx4 v[200:203], v[164:165], off offset:528
	v_or_b32_e32 v120, 0x84, v144
	v_ashrrev_i32_e32 v121, 31, v120
	v_lshlrev_b64 v[206:207], 2, v[120:121]
	v_lshl_add_u64 v[120:121], s[12:13], 0, v[206:207]
	v_lshl_add_u64 v[122:123], s[14:15], 0, v[206:207]
	s_waitcnt vmcnt(0)
	v_sub_f32_e32 v187, v187, v167
	v_sub_f32_e32 v186, v186, v167
	v_sub_f32_e32 v185, v185, v167
	v_sub_f32_e32 v184, v184, v167
	v_pk_mul_f32 v[184:185], v[166:167], v[184:185] op_sel_hi:[0,1]
	v_pk_mul_f32 v[186:187], v[166:167], v[186:187] op_sel_hi:[0,1]
	v_pk_fma_f32 v[186:187], v[190:191], v[186:187], v[194:195]
	v_pk_fma_f32 v[184:185], v[188:189], v[184:185], v[192:193]
	v_pk_fma_f32 v[118:119], v[186:187], s[24:25], v[118:119] op_sel_hi:[1,0,1]
	v_pk_fma_f32 v[116:117], v[184:185], s[24:25], v[116:117] op_sel_hi:[1,0,1]
	v_pk_add_f32 v[186:187], v[198:199], v[118:119]
	v_pk_add_f32 v[184:185], v[196:197], v[116:117]
	global_store_dwordx4 v[164:165], v[184:187], off offset:512
	global_load_dwordx4 v[188:191], v[120:121], off
	global_load_dwordx4 v[192:195], v[122:123], off
	v_lshl_add_u64 v[116:117], s[16:17], 0, v[206:207]
	global_load_dwordx4 v[196:199], v[116:117], off
	v_and_b32_e32 v119, 64, v174
	v_xor_b32_e32 v118, 16, v174
	v_add_u32_e32 v119, 64, v119
	v_cmp_lt_i32_e32 vcc, v118, v119
	s_nop 1
	v_cndmask_b32_e32 v118, v174, v118, vcc
	v_cmp_lt_i32_e32 vcc, v155, v119
	v_lshlrev_b32_e32 v118, 2, v118
	s_nop 0
	v_cndmask_b32_e32 v119, v174, v155, vcc
	v_add_f32_e32 v155, v176, v177
	v_mul_f32_e32 v177, v181, v181
	v_add_f32_e32 v155, v178, v155
	v_add_f32_e32 v176, v180, v181
	v_fmac_f32_e32 v177, v180, v180
	v_add_f32_e32 v155, v179, v155
	v_add_f32_e32 v176, v182, v176
	v_fmac_f32_e32 v177, v182, v182
	v_add_f32_e32 v155, 0, v155
	v_add_f32_e32 v176, v183, v176
	v_fmac_f32_e32 v177, v183, v183
	v_add_f32_e32 v155, v176, v155
	v_add_f32_e32 v175, v175, v177
	v_sub_f32_e32 v177, v203, v167
	v_sub_f32_e32 v176, v202, v167
	v_sub_f32_e32 v179, v201, v167
	v_sub_f32_e32 v178, v200, v167
	v_pk_mul_f32 v[178:179], v[166:167], v[178:179] op_sel_hi:[0,1]
	v_pk_mul_f32 v[166:167], v[166:167], v[176:177] op_sel_hi:[0,1]
	v_mul_f32_e32 v177, v185, v185
	v_add_f32_e32 v176, v184, v185
	v_fmac_f32_e32 v177, v184, v184
	v_add_f32_e32 v176, v186, v176
	v_fmac_f32_e32 v177, v186, v186
	v_add_f32_e32 v176, v187, v176
	v_fmac_f32_e32 v177, v187, v187
	v_add_f32_e32 v155, v155, v176
	v_add_f32_e32 v175, v175, v177
	v_lshlrev_b32_e32 v119, 2, v119
	v_cvt_pk_bf16_f32 v180, v184, v185
	v_cvt_pk_bf16_f32 v181, v186, v187
	s_waitcnt vmcnt(0)
; DEVI unsigned pk2(float lo, float hi) { unsigned r; asm("v_cvt_pk_bf16_f32 %0, %1, %2" : "=v"(r) : "v"(lo), "v"(hi)); return r; }
; DEVI void row_stats(const float* stats, int row, float& mu, float& rs) {
;     if (stats) { const float2 st = *(const float2*)(stats + 2 * (size_t)row); mu = st.x * (1.0f / 1024.0f); const float var = st.y * (1.0f / 1024.0f) - mu * mu; rs = rsqrtf(fmaxf(var, 0.f) + LN_EPS); }
;     DEVI void operator()(const f32x4 (&acc)[2][2][4][2], const pg8::Unit& u, int wr, int wc, int fr, int fq) const {
;     ...
;                 const int row = row0 + ai * 128 + m * 16; float mu, rs; row_stats(stin, row, mu, rs);
;                 float sum = 0.f, sq = 0.f;
; #pragma unroll
;                 for (int bj = 0; bj < 2; ++bj) {
;                     f32x4 z[2];
; #pragma unroll
;                     for (int n = 0; n < 2; ++n) {
;                         const int col = colb + bj * 128 + 4 * n;
;                         f32x4 xv = *(const f32x4*)(zsrc + (size_t)row * DM + col);
;                         if (stin) { const f32x4 gv = *(const f32x4*)(gin + col), bv = *(const f32x4*)(bin + col); xv = (xv - mu) * rs * gv + bv; }
;                         f32x4 zz = ALPHA * xv + acc[ai][bj][m][n];
;                         if (bias) zz += *(const f32x4*)(bias + col);
;                         *(f32x4*)(zdst + (size_t)row * DM + col) = zz;
;                         sum += zz[0] + zz[1] + zz[2] + zz[3]; sq += zz[0] * zz[0] + zz[1] * zz[1] + zz[2] * zz[2] + zz[3] * zz[3];
;                         z[n] = zz;
;                     }
;                     u32x4 o; o.x = pk2(z[0][0], z[0][1]); o.y = pk2(z[0][2], z[0][3]); o.z = pk2(z[1][0], z[1][1]); o.w = pk2(z[1][2], z[1][3]);
;                     if (zb) *(u32x4*)(zb + (size_t)row * DM + colb + bj * 128) = o;
;                 }
;                 sum += __shfl_xor(sum, 16); sq += __shfl_xor(sq, 16);
;                 sum += __shfl_xor(sum, 32); sq += __shfl_xor(sq, 32);
;                 if (fq == 0) { atomicAdd(stout + 2 * (size_t)row, sum); atomicAdd(stout + 2 * (size_t)row + 1, sq); }
	v_pk_fma_f32 v[176:177], v[188:189], v[178:179], v[192:193]
	s_nop 0
	v_pk_fma_f32 v[112:113], v[176:177], s[24:25], v[112:113] op_sel_hi:[1,0,1]
	v_pk_fma_f32 v[166:167], v[190:191], v[166:167], v[194:195]
	v_pk_add_f32 v[176:177], v[196:197], v[112:113]
	v_pk_fma_f32 v[114:115], v[166:167], s[24:25], v[114:115] op_sel_hi:[1,0,1]
	v_mul_f32_e32 v113, v177, v177
	v_pk_add_f32 v[178:179], v[198:199], v[114:115]
	v_add_f32_e32 v112, v176, v177
	v_fmac_f32_e32 v113, v176, v176
	v_add_f32_e32 v112, v178, v112
	v_fmac_f32_e32 v113, v178, v178
	v_add_f32_e32 v112, v179, v112
	v_fmac_f32_e32 v113, v179, v179
	v_add_f32_e32 v112, v155, v112
	v_add_f32_e32 v113, v175, v113
	ds_bpermute_b32 v114, v118, v112
	ds_bpermute_b32 v115, v118, v113
	global_store_dwordx4 v[164:165], v[176:179], off offset:528
	v_cvt_pk_bf16_f32 v182, v176, v177
	v_cvt_pk_bf16_f32 v183, v178, v179
	s_waitcnt lgkmcnt(0)
	v_add_f32_e32 v112, v112, v114
	v_add_f32_e32 v113, v113, v115
	ds_bpermute_b32 v114, v119, v112
	ds_bpermute_b32 v115, v119, v113
	flat_store_dwordx4 v[204:205], v[180:183] offset:256
	s_mov_b32 s100, -1
	s_mov_b32 s101, 0
	s_mov_b32 s98, 0xffff0000
	s_mov_b32 s99, 0
	s_and_saveexec_b64 s[36:37], s[100:101]
	s_cbranch_execz .LBB0_1985
	s_waitcnt lgkmcnt(0)
	v_add_f32_e32 v115, v113, v115
	v_add_f32_e32 v114, v112, v114
	v_lshl_add_u64 v[112:113], s[8:9], 0, v[162:163]
	v_cndmask_b32_e64 v114, v114, v115, s[98:99]
	v_cndmask_b32_e64 v115, 0, 4, s[98:99]
	v_or_b32_e32 v112, v112, v115
	flat_atomic_add_f32 v[112:113], v114
.LBB0_1985:
	s_or_b64 exec, exec, s[36:37]
	v_or_b32_e32 v166, 16, v154
	v_ashrrev_i32_e32 v167, 31, v166
	v_lshlrev_b64 v[112:113], 3, v[166:167]
	s_waitcnt lgkmcnt(0)
	v_lshl_add_u64 v[114:115], s[6:7], 0, v[112:113]
	flat_load_dwordx2 v[192:193], v[114:115]
	v_lshlrev_b64 v[114:115], 12, v[166:167]
	v_lshl_add_u64 v[114:115], s[46:47], 0, v[114:115]
	v_lshl_add_u64 v[114:115], v[144:145], 2, v[114:115]
	global_load_dwordx4 v[162:165], v[114:115], off
	global_load_dwordx4 v[176:179], v[150:151], off
	global_load_dwordx4 v[180:183], v[152:153], off
	global_load_dwordx4 v[184:187], v[156:157], off
	global_load_dwordx4 v[188:191], v[114:115], off offset:16
	v_lshlrev_b64 v[166:167], 11, v[166:167]
	v_lshl_add_u64 v[166:167], s[10:11], 0, v[166:167]
	v_lshl_add_u64 v[166:167], v[144:145], 1, v[166:167]
	s_waitcnt vmcnt(0) lgkmcnt(0)
	v_pk_mul_f32 v[192:193], v[192:193], s[22:23] op_sel:[1,0] op_sel_hi:[0,0]
	v_fma_f32 v155, -v193, v193, v192
	v_max_f32_e32 v155, 0, v155
	v_add_f32_e32 v155, 0x3727c5ac, v155
	v_mul_f32_e32 v175, 0x4b800000, v155
	v_cmp_gt_f32_e32 vcc, s72, v155
	v_sub_f32_e32 v165, v165, v193
	v_sub_f32_e32 v164, v164, v193
	v_cndmask_b32_e32 v155, v155, v175, vcc
	v_rsq_f32_e32 v155, v155
	v_sub_f32_e32 v163, v163, v193
	v_sub_f32_e32 v162, v162, v193
	v_mul_f32_e32 v175, 0x45800000, v155
	v_cndmask_b32_e32 v192, v155, v175, vcc
	v_pk_mul_f32 v[162:163], v[162:163], v[192:193] op_sel_hi:[1,0]
	v_pk_mul_f32 v[164:165], v[164:165], v[192:193] op_sel_hi:[1,0]
	v_pk_fma_f32 v[162:163], v[176:177], v[162:163], v[180:181]
	v_pk_fma_f32 v[164:165], v[178:179], v[164:165], v[182:183]
	v_pk_fma_f32 v[108:109], v[162:163], s[24:25], v[108:109] op_sel_hi:[1,0,1]
	v_pk_fma_f32 v[110:111], v[164:165], s[24:25], v[110:111] op_sel_hi:[1,0,1]
	v_pk_add_f32 v[108:109], v[184:185], v[108:109]
	v_pk_add_f32 v[110:111], v[186:187], v[110:111]
	global_store_dwordx4 v[114:115], v[108:111], off
	global_load_dwordx4 v[162:165], v[146:147], off
	global_load_dwordx4 v[176:179], v[148:149], off
	global_load_dwordx4 v[180:183], v[124:125], off
	v_sub_f32_e32 v185, v191, v193
	v_sub_f32_e32 v184, v190, v193
	v_sub_f32_e32 v187, v189, v193
	v_sub_f32_e32 v186, v188, v193
	v_pk_mul_f32 v[186:187], v[186:187], v[192:193] op_sel_hi:[1,0]
	v_pk_mul_f32 v[188:189], v[184:185], v[192:193] op_sel_hi:[1,0]
	v_cvt_pk_bf16_f32 v184, v108, v109
	v_cvt_pk_bf16_f32 v185, v110, v111
	v_add_f32_e32 v155, v108, v109
	v_mul_f32_e32 v109, v109, v109
	v_fmac_f32_e32 v109, v108, v108
	v_add_f32_e32 v155, v110, v155
	v_fmac_f32_e32 v109, v110, v110
	v_add_f32_e32 v108, v111, v155
	v_add_f32_e32 v108, 0, v108
	v_fmac_f32_e32 v109, v111, v111
	s_waitcnt vmcnt(1)
	v_pk_fma_f32 v[164:165], v[164:165], v[188:189], v[178:179]
	v_pk_fma_f32 v[162:163], v[162:163], v[186:187], v[176:177]
	v_pk_fma_f32 v[106:107], v[164:165], s[24:25], v[106:107] op_sel_hi:[1,0,1]
	v_pk_fma_f32 v[104:105], v[162:163], s[24:25], v[104:105] op_sel_hi:[1,0,1]
	s_waitcnt vmcnt(0)
	v_pk_add_f32 v[106:107], v[182:183], v[106:107]
	v_pk_add_f32 v[104:105], v[180:181], v[104:105]
	global_store_dwordx4 v[114:115], v[104:107], off offset:16
	v_cvt_pk_bf16_f32 v186, v104, v105
	v_cvt_pk_bf16_f32 v187, v106, v107
	flat_store_dwordx4 v[166:167], v[184:187]
	global_load_dwordx4 v[162:165], v[114:115], off offset:512
	global_load_dwordx4 v[176:179], v[126:127], off
	global_load_dwordx4 v[180:183], v[158:159], off
	s_nop 0
	global_load_dwordx4 v[184:187], v[160:161], off
	global_load_dwordx4 v[188:191], v[114:115], off offset:528
	v_add_f32_e32 v110, v104, v105
	v_mul_f32_e32 v105, v105, v105
	v_fmac_f32_e32 v105, v104, v104
	v_add_f32_e32 v110, v106, v110
	v_fmac_f32_e32 v105, v106, v106
	v_add_f32_e32 v104, v107, v110
	v_fmac_f32_e32 v105, v107, v107
	v_add_f32_e32 v108, v104, v108
	v_add_f32_e32 v109, v109, v105
	s_waitcnt vmcnt(0)
; DEVI unsigned pk2(float lo, float hi) { unsigned r; asm("v_cvt_pk_bf16_f32 %0, %1, %2" : "=v"(r) : "v"(lo), "v"(hi)); return r; }
; DEVI void row_stats(const float* stats, int row, float& mu, float& rs) {
;     if (stats) { const float2 st = *(const float2*)(stats + 2 * (size_t)row); mu = st.x * (1.0f / 1024.0f); const float var = st.y * (1.0f / 1024.0f) - mu * mu; rs = rsqrtf(fmaxf(var, 0.f) + LN_EPS); }
;     DEVI void operator()(const f32x4 (&acc)[2][2][4][2], const pg8::Unit& u, int wr, int wc, int fr, int fq) const {
;     ...
;                 const int row = row0 + ai * 128 + m * 16; float mu, rs; row_stats(stin, row, mu, rs);
;                 float sum = 0.f, sq = 0.f;
; #pragma unroll
;                 for (int bj = 0; bj < 2; ++bj) {
;                     f32x4 z[2];
; #pragma unroll
;                     for (int n = 0; n < 2; ++n) {
;                         const int col = colb + bj * 128 + 4 * n;
;                         f32x4 xv = *(const f32x4*)(zsrc + (size_t)row * DM + col);
;                         if (stin) { const f32x4 gv = *(const f32x4*)(gin + col), bv = *(const f32x4*)(bin + col); xv = (xv - mu) * rs * gv + bv; }
;                         f32x4 zz = ALPHA * xv + acc[ai][bj][m][n];
;                         if (bias) zz += *(const f32x4*)(bias + col);
;                         *(f32x4*)(zdst + (size_t)row * DM + col) = zz;
;                         sum += zz[0] + zz[1] + zz[2] + zz[3]; sq += zz[0] * zz[0] + zz[1] * zz[1] + zz[2] * zz[2] + zz[3] * zz[3];
;                         z[n] = zz;
;                     }
;                     u32x4 o; o.x = pk2(z[0][0], z[0][1]); o.y = pk2(z[0][2], z[0][3]); o.z = pk2(z[1][0], z[1][1]); o.w = pk2(z[1][2], z[1][3]);
;                     if (zb) *(u32x4*)(zb + (size_t)row * DM + colb + bj * 128) = o;
;                 }
;                 sum += __shfl_xor(sum, 16); sq += __shfl_xor(sq, 16);
;                 sum += __shfl_xor(sum, 32); sq += __shfl_xor(sq, 32);
;                 if (fq == 0) { atomicAdd(stout + 2 * (size_t)row, sum); atomicAdd(stout + 2 * (size_t)row + 1, sq); }
	v_sub_f32_e32 v165, v165, v193
	v_sub_f32_e32 v164, v164, v193
	v_sub_f32_e32 v163, v163, v193
	v_sub_f32_e32 v162, v162, v193
	v_pk_mul_f32 v[162:163], v[192:193], v[162:163] op_sel_hi:[0,1]
	v_pk_mul_f32 v[164:165], v[192:193], v[164:165] op_sel_hi:[0,1]
	v_pk_fma_f32 v[164:165], v[178:179], v[164:165], v[182:183]
	v_pk_fma_f32 v[162:163], v[176:177], v[162:163], v[180:181]
	v_pk_fma_f32 v[102:103], v[164:165], s[24:25], v[102:103] op_sel_hi:[1,0,1]
	v_pk_fma_f32 v[100:101], v[162:163], s[24:25], v[100:101] op_sel_hi:[1,0,1]
	v_pk_add_f32 v[102:103], v[186:187], v[102:103]
	v_pk_add_f32 v[100:101], v[184:185], v[100:101]
	global_store_dwordx4 v[114:115], v[100:103], off offset:512
	global_load_dwordx4 v[162:165], v[120:121], off
	global_load_dwordx4 v[176:179], v[122:123], off
	global_load_dwordx4 v[180:183], v[116:117], off
	v_sub_f32_e32 v107, v189, v193
	v_sub_f32_e32 v106, v188, v193
	v_sub_f32_e32 v105, v191, v193
	v_sub_f32_e32 v104, v190, v193
	v_pk_mul_f32 v[106:107], v[192:193], v[106:107] op_sel_hi:[0,1]
	v_pk_mul_f32 v[104:105], v[192:193], v[104:105] op_sel_hi:[0,1]
	v_mul_f32_e32 v111, v101, v101
	v_add_f32_e32 v110, v100, v101
	v_fmac_f32_e32 v111, v100, v100
	v_add_f32_e32 v110, v102, v110
	v_fmac_f32_e32 v111, v102, v102
	v_add_f32_e32 v110, v103, v110
	v_fmac_f32_e32 v111, v103, v103
	v_add_f32_e32 v108, v108, v110
	v_add_f32_e32 v109, v109, v111
	v_cvt_pk_bf16_f32 v100, v100, v101
	v_cvt_pk_bf16_f32 v101, v102, v103
	s_waitcnt vmcnt(0)
	v_pk_fma_f32 v[106:107], v[162:163], v[106:107], v[176:177]
	v_pk_fma_f32 v[104:105], v[164:165], v[104:105], v[178:179]
	v_pk_fma_f32 v[96:97], v[106:107], s[24:25], v[96:97] op_sel_hi:[1,0,1]
	v_pk_fma_f32 v[98:99], v[104:105], s[24:25], v[98:99] op_sel_hi:[1,0,1]
	v_pk_add_f32 v[104:105], v[180:181], v[96:97]
	v_pk_add_f32 v[106:107], v[182:183], v[98:99]
	v_mul_f32_e32 v97, v105, v105
	v_add_f32_e32 v96, v104, v105
	v_fmac_f32_e32 v97, v104, v104
	v_add_f32_e32 v96, v106, v96
	v_fmac_f32_e32 v97, v106, v106
	v_add_f32_e32 v96, v107, v96
	v_fmac_f32_e32 v97, v107, v107
	v_add_f32_e32 v96, v108, v96
	v_add_f32_e32 v97, v109, v97
	ds_bpermute_b32 v98, v118, v96
	ds_bpermute_b32 v99, v118, v97
	global_store_dwordx4 v[114:115], v[104:107], off offset:528
	v_cvt_pk_bf16_f32 v102, v104, v105
	v_cvt_pk_bf16_f32 v103, v106, v107
	s_waitcnt lgkmcnt(0)
	v_add_f32_e32 v96, v96, v98
	v_add_f32_e32 v97, v97, v99
	ds_bpermute_b32 v98, v119, v96
	ds_bpermute_b32 v99, v119, v97
	flat_store_dwordx4 v[166:167], v[100:103] offset:256
	s_mov_b32 s100, -1
	s_mov_b32 s101, 0
	s_mov_b32 s98, 0xffff0000
	s_mov_b32 s99, 0
	s_and_saveexec_b64 s[36:37], s[100:101]
	s_cbranch_execz .LBB0_1987
	s_waitcnt lgkmcnt(0)
	v_add_f32_e32 v99, v97, v99
	v_add_f32_e32 v98, v96, v98
	v_lshl_add_u64 v[96:97], s[8:9], 0, v[112:113]
	v_cndmask_b32_e64 v98, v98, v99, s[98:99]
	v_cndmask_b32_e64 v99, 0, 4, s[98:99]
	v_or_b32_e32 v96, v96, v99
	flat_atomic_add_f32 v[96:97], v98
.LBB0_1987:
	s_or_b64 exec, exec, s[36:37]
	v_or_b32_e32 v166, 32, v154
	v_ashrrev_i32_e32 v167, 31, v166
	v_lshlrev_b64 v[96:97], 3, v[166:167]
	s_waitcnt lgkmcnt(0)
	v_lshl_add_u64 v[98:99], s[6:7], 0, v[96:97]
	flat_load_dwordx2 v[176:177], v[98:99]
	v_lshlrev_b64 v[98:99], 12, v[166:167]
	v_lshl_add_u64 v[98:99], s[46:47], 0, v[98:99]
	v_lshl_add_u64 v[98:99], v[144:145], 2, v[98:99]
	global_load_dwordx4 v[100:103], v[98:99], off
	global_load_dwordx4 v[104:107], v[150:151], off
	global_load_dwordx4 v[108:111], v[152:153], off
	global_load_dwordx4 v[112:115], v[156:157], off
	global_load_dwordx4 v[162:165], v[98:99], off offset:16
	s_waitcnt vmcnt(0) lgkmcnt(0)
	v_pk_mul_f32 v[176:177], v[176:177], s[22:23] op_sel:[1,0] op_sel_hi:[0,0]
	v_fma_f32 v155, -v177, v177, v176
	v_max_f32_e32 v155, 0, v155
	v_add_f32_e32 v155, 0x3727c5ac, v155
	v_mul_f32_e32 v175, 0x4b800000, v155
	v_cmp_gt_f32_e32 vcc, s72, v155
	v_sub_f32_e32 v103, v103, v177
	v_sub_f32_e32 v102, v102, v177
	v_cndmask_b32_e32 v155, v155, v175, vcc
	v_rsq_f32_e32 v155, v155
	v_sub_f32_e32 v101, v101, v177
	v_sub_f32_e32 v100, v100, v177
	v_mul_f32_e32 v175, 0x45800000, v155
	v_cndmask_b32_e32 v176, v155, v175, vcc
	v_pk_mul_f32 v[100:101], v[100:101], v[176:177] op_sel_hi:[1,0]
	v_pk_mul_f32 v[102:103], v[102:103], v[176:177] op_sel_hi:[1,0]
	v_pk_fma_f32 v[100:101], v[104:105], v[100:101], v[108:109]
	v_pk_fma_f32 v[102:103], v[106:107], v[102:103], v[110:111]
	v_pk_fma_f32 v[92:93], v[100:101], s[24:25], v[92:93] op_sel_hi:[1,0,1]
	v_pk_fma_f32 v[94:95], v[102:103], s[24:25], v[94:95] op_sel_hi:[1,0,1]
	v_pk_add_f32 v[92:93], v[112:113], v[92:93]
	v_pk_add_f32 v[94:95], v[114:115], v[94:95]
	global_store_dwordx4 v[98:99], v[92:95], off
	global_load_dwordx4 v[100:103], v[146:147], off
	global_load_dwordx4 v[104:107], v[148:149], off
	global_load_dwordx4 v[108:111], v[124:125], off
	v_lshlrev_b64 v[112:113], 11, v[166:167]
	v_lshl_add_u64 v[112:113], s[10:11], 0, v[112:113]
	v_lshl_add_u64 v[166:167], v[144:145], 1, v[112:113]
	v_sub_f32_e32 v113, v165, v177
	v_sub_f32_e32 v112, v164, v177
	v_sub_f32_e32 v115, v163, v177
	v_sub_f32_e32 v114, v162, v177
	v_pk_mul_f32 v[114:115], v[114:115], v[176:177] op_sel_hi:[1,0]
	v_pk_mul_f32 v[162:163], v[112:113], v[176:177] op_sel_hi:[1,0]
	v_cvt_pk_bf16_f32 v112, v92, v93
	v_cvt_pk_bf16_f32 v113, v94, v95
	s_waitcnt vmcnt(1)
	v_pk_fma_f32 v[100:101], v[100:101], v[114:115], v[104:105]
	v_pk_fma_f32 v[102:103], v[102:103], v[162:163], v[106:107]
	v_pk_fma_f32 v[88:89], v[100:101], s[24:25], v[88:89] op_sel_hi:[1,0,1]
	v_pk_fma_f32 v[90:91], v[102:103], s[24:25], v[90:91] op_sel_hi:[1,0,1]
	s_waitcnt vmcnt(0)
; DEVI unsigned pk2(float lo, float hi) { unsigned r; asm("v_cvt_pk_bf16_f32 %0, %1, %2" : "=v"(r) : "v"(lo), "v"(hi)); return r; }
; DEVI void row_stats(const float* stats, int row, float& mu, float& rs) {
;     if (stats) { const float2 st = *(const float2*)(stats + 2 * (size_t)row); mu = st.x * (1.0f / 1024.0f); const float var = st.y * (1.0f / 1024.0f) - mu * mu; rs = rsqrtf(fmaxf(var, 0.f) + LN_EPS); }
;     DEVI void operator()(const f32x4 (&acc)[2][2][4][2], const pg8::Unit& u, int wr, int wc, int fr, int fq) const {
;     ...
;                 const int row = row0 + ai * 128 + m * 16; float mu, rs; row_stats(stin, row, mu, rs);
;                 float sum = 0.f, sq = 0.f;
; #pragma unroll
;                 for (int bj = 0; bj < 2; ++bj) {
;                     f32x4 z[2];
; #pragma unroll
;                     for (int n = 0; n < 2; ++n) {
;                         const int col = colb + bj * 128 + 4 * n;
;                         f32x4 xv = *(const f32x4*)(zsrc + (size_t)row * DM + col);
;                         if (stin) { const f32x4 gv = *(const f32x4*)(gin + col), bv = *(const f32x4*)(bin + col); xv = (xv - mu) * rs * gv + bv; }
;                         f32x4 zz = ALPHA * xv + acc[ai][bj][m][n];
;                         if (bias) zz += *(const f32x4*)(bias + col);
;                         *(f32x4*)(zdst + (size_t)row * DM + col) = zz;
;                         sum += zz[0] + zz[1] + zz[2] + zz[3]; sq += zz[0] * zz[0] + zz[1] * zz[1] + zz[2] * zz[2] + zz[3] * zz[3];
;                         z[n] = zz;
;                     }
;                     u32x4 o; o.x = pk2(z[0][0], z[0][1]); o.y = pk2(z[0][2], z[0][3]); o.z = pk2(z[1][0], z[1][1]); o.w = pk2(z[1][2], z[1][3]);
;                     if (zb) *(u32x4*)(zb + (size_t)row * DM + colb + bj * 128) = o;
;                 }
;                 sum += __shfl_xor(sum, 16); sq += __shfl_xor(sq, 16);
;                 sum += __shfl_xor(sum, 32); sq += __shfl_xor(sq, 32);
;                 if (fq == 0) { atomicAdd(stout + 2 * (size_t)row, sum); atomicAdd(stout + 2 * (size_t)row + 1, sq); }
	v_pk_add_f32 v[88:89], v[108:109], v[88:89]
	v_pk_add_f32 v[90:91], v[110:111], v[90:91]
	global_store_dwordx4 v[98:99], v[88:91], off offset:16
	v_cvt_pk_bf16_f32 v114, v88, v89
	v_cvt_pk_bf16_f32 v115, v90, v91
	flat_store_dwordx4 v[166:167], v[112:115]
	global_load_dwordx4 v[100:103], v[98:99], off offset:512
	global_load_dwordx4 v[104:107], v[126:127], off
	global_load_dwordx4 v[108:111], v[158:159], off
	s_nop 0
	global_load_dwordx4 v[112:115], v[160:161], off
	global_load_dwordx4 v[162:165], v[98:99], off offset:528
	s_waitcnt vmcnt(0)
	v_sub_f32_e32 v103, v103, v177
	v_sub_f32_e32 v102, v102, v177
	v_sub_f32_e32 v101, v101, v177
	v_sub_f32_e32 v100, v100, v177
	v_pk_mul_f32 v[100:101], v[176:177], v[100:101] op_sel_hi:[0,1]
	v_pk_mul_f32 v[102:103], v[176:177], v[102:103] op_sel_hi:[0,1]
	v_pk_fma_f32 v[102:103], v[106:107], v[102:103], v[110:111]
	v_pk_fma_f32 v[100:101], v[104:105], v[100:101], v[108:109]
	v_pk_fma_f32 v[86:87], v[102:103], s[24:25], v[86:87] op_sel_hi:[1,0,1]
	v_pk_fma_f32 v[84:85], v[100:101], s[24:25], v[84:85] op_sel_hi:[1,0,1]
	v_pk_add_f32 v[86:87], v[114:115], v[86:87]
	v_pk_add_f32 v[84:85], v[112:113], v[84:85]
	global_store_dwordx4 v[98:99], v[84:87], off offset:512
	global_load_dwordx4 v[100:103], v[120:121], off
	global_load_dwordx4 v[104:107], v[122:123], off
	global_load_dwordx4 v[108:111], v[116:117], off
	v_add_f32_e32 v112, v92, v93
	v_mul_f32_e32 v93, v93, v93
	v_fmac_f32_e32 v93, v92, v92
	v_add_f32_e32 v112, v94, v112
	v_fmac_f32_e32 v93, v94, v94
	v_add_f32_e32 v94, v88, v89
	v_mul_f32_e32 v89, v89, v89
	v_fmac_f32_e32 v89, v88, v88
	v_add_f32_e32 v92, v95, v112
	v_add_f32_e32 v94, v90, v94
	v_fmac_f32_e32 v89, v90, v90
	v_add_f32_e32 v92, 0, v92
	v_fmac_f32_e32 v93, v95, v95
	v_add_f32_e32 v88, v91, v94
	v_fmac_f32_e32 v89, v91, v91
	v_sub_f32_e32 v91, v163, v177
	v_sub_f32_e32 v90, v162, v177
	v_add_f32_e32 v92, v88, v92
	v_add_f32_e32 v93, v93, v89
	v_sub_f32_e32 v89, v165, v177
	v_sub_f32_e32 v88, v164, v177
	v_pk_mul_f32 v[90:91], v[176:177], v[90:91] op_sel_hi:[0,1]
	v_pk_mul_f32 v[88:89], v[176:177], v[88:89] op_sel_hi:[0,1]
	v_mul_f32_e32 v95, v85, v85
	v_add_f32_e32 v94, v84, v85
	v_fmac_f32_e32 v95, v84, v84
	v_add_f32_e32 v94, v86, v94
	v_fmac_f32_e32 v95, v86, v86
	v_add_f32_e32 v94, v87, v94
	v_fmac_f32_e32 v95, v87, v87
	v_add_f32_e32 v92, v92, v94
	v_add_f32_e32 v93, v93, v95
	v_cvt_pk_bf16_f32 v84, v84, v85
	v_cvt_pk_bf16_f32 v85, v86, v87
	s_waitcnt vmcnt(0)
	v_pk_fma_f32 v[90:91], v[100:101], v[90:91], v[104:105]
	v_pk_fma_f32 v[88:89], v[102:103], v[88:89], v[106:107]
	v_pk_fma_f32 v[80:81], v[90:91], s[24:25], v[80:81] op_sel_hi:[1,0,1]
	v_pk_fma_f32 v[82:83], v[88:89], s[24:25], v[82:83] op_sel_hi:[1,0,1]
	v_pk_add_f32 v[88:89], v[108:109], v[80:81]
	v_pk_add_f32 v[90:91], v[110:111], v[82:83]
	v_mul_f32_e32 v81, v89, v89
	v_add_f32_e32 v80, v88, v89
	v_fmac_f32_e32 v81, v88, v88
	v_add_f32_e32 v80, v90, v80
	v_fmac_f32_e32 v81, v90, v90
	v_add_f32_e32 v80, v91, v80
	v_fmac_f32_e32 v81, v91, v91
	v_add_f32_e32 v80, v92, v80
	v_add_f32_e32 v81, v93, v81
	ds_bpermute_b32 v82, v118, v80
	ds_bpermute_b32 v83, v118, v81
	global_store_dwordx4 v[98:99], v[88:91], off offset:528
	v_cvt_pk_bf16_f32 v86, v88, v89
	v_cvt_pk_bf16_f32 v87, v90, v91
	s_waitcnt lgkmcnt(0)
	v_add_f32_e32 v80, v80, v82
	v_add_f32_e32 v81, v81, v83
	ds_bpermute_b32 v82, v119, v80
	ds_bpermute_b32 v83, v119, v81
	flat_store_dwordx4 v[166:167], v[84:87] offset:256
	s_mov_b32 s100, -1
	s_mov_b32 s101, 0
	s_mov_b32 s98, 0xffff0000
	s_mov_b32 s99, 0
	s_and_saveexec_b64 s[36:37], s[100:101]
	s_cbranch_execz .LBB0_1989
	s_waitcnt lgkmcnt(0)
	v_add_f32_e32 v83, v81, v83
	v_add_f32_e32 v82, v80, v82
	v_lshl_add_u64 v[80:81], s[8:9], 0, v[96:97]
	v_cndmask_b32_e64 v82, v82, v83, s[98:99]
	v_cndmask_b32_e64 v83, 0, 4, s[98:99]
	v_or_b32_e32 v80, v80, v83
	flat_atomic_add_f32 v[80:81], v82
.LBB0_1989:
	s_or_b64 exec, exec, s[36:37]
	v_or_b32_e32 v104, 48, v154
	v_ashrrev_i32_e32 v105, 31, v104
	v_lshlrev_b64 v[80:81], 3, v[104:105]
	s_waitcnt lgkmcnt(0)
	v_lshl_add_u64 v[82:83], s[6:7], 0, v[80:81]
	flat_load_dwordx2 v[106:107], v[82:83]
	v_lshlrev_b64 v[82:83], 12, v[104:105]
	v_lshl_add_u64 v[82:83], s[46:47], 0, v[82:83]
	v_lshl_add_u64 v[82:83], v[144:145], 2, v[82:83]
	global_load_dwordx4 v[84:87], v[82:83], off
	global_load_dwordx4 v[88:91], v[150:151], off
	global_load_dwordx4 v[92:95], v[152:153], off
	global_load_dwordx4 v[96:99], v[156:157], off
	global_load_dwordx4 v[100:103], v[82:83], off offset:16
	s_waitcnt vmcnt(0) lgkmcnt(0)
	v_pk_mul_f32 v[106:107], v[106:107], s[22:23] op_sel:[1,0] op_sel_hi:[0,0]
	v_fma_f32 v106, -v107, v107, v106
	v_max_f32_e32 v106, 0, v106
	v_add_f32_e32 v106, 0x3727c5ac, v106
	v_mul_f32_e32 v108, 0x4b800000, v106
	v_cmp_gt_f32_e32 vcc, s72, v106
	v_sub_f32_e32 v87, v87, v107
	v_sub_f32_e32 v86, v86, v107
	v_cndmask_b32_e32 v106, v106, v108, vcc
	v_rsq_f32_e32 v106, v106
	v_sub_f32_e32 v85, v85, v107
	v_sub_f32_e32 v84, v84, v107
	v_mul_f32_e32 v108, 0x45800000, v106
	v_cndmask_b32_e32 v106, v106, v108, vcc
	v_pk_mul_f32 v[84:85], v[84:85], v[106:107] op_sel_hi:[1,0]
	v_pk_mul_f32 v[86:87], v[86:87], v[106:107] op_sel_hi:[1,0]
	v_pk_fma_f32 v[84:85], v[88:89], v[84:85], v[92:93]
	v_pk_fma_f32 v[86:87], v[90:91], v[86:87], v[94:95]
	v_pk_fma_f32 v[76:77], v[84:85], s[24:25], v[76:77] op_sel_hi:[1,0,1]
	v_pk_fma_f32 v[78:79], v[86:87], s[24:25], v[78:79] op_sel_hi:[1,0,1]
	v_pk_add_f32 v[76:77], v[96:97], v[76:77]
	v_pk_add_f32 v[78:79], v[98:99], v[78:79]
	global_store_dwordx4 v[82:83], v[76:79], off
	global_load_dwordx4 v[84:87], v[146:147], off
	global_load_dwordx4 v[88:91], v[148:149], off
	global_load_dwordx4 v[92:95], v[124:125], off
	v_lshlrev_b64 v[96:97], 11, v[104:105]
	v_lshl_add_u64 v[96:97], s[10:11], 0, v[96:97]
	v_lshl_add_u64 v[104:105], v[144:145], 1, v[96:97]
	v_sub_f32_e32 v97, v103, v107
	v_sub_f32_e32 v96, v102, v107
	v_sub_f32_e32 v99, v101, v107
	v_sub_f32_e32 v98, v100, v107
	v_pk_mul_f32 v[98:99], v[98:99], v[106:107] op_sel_hi:[1,0]
	v_pk_mul_f32 v[100:101], v[96:97], v[106:107] op_sel_hi:[1,0]
	v_cvt_pk_bf16_f32 v96, v76, v77
	v_cvt_pk_bf16_f32 v97, v78, v79
	s_waitcnt vmcnt(1)
; DEVI unsigned pk2(float lo, float hi) { unsigned r; asm("v_cvt_pk_bf16_f32 %0, %1, %2" : "=v"(r) : "v"(lo), "v"(hi)); return r; }
; DEVI void row_stats(const float* stats, int row, float& mu, float& rs) {
;     if (stats) { const float2 st = *(const float2*)(stats + 2 * (size_t)row); mu = st.x * (1.0f / 1024.0f); const float var = st.y * (1.0f / 1024.0f) - mu * mu; rs = rsqrtf(fmaxf(var, 0.f) + LN_EPS); }
;     DEVI void operator()(const f32x4 (&acc)[2][2][4][2], const pg8::Unit& u, int wr, int wc, int fr, int fq) const {
;     ...
;                 const int row = row0 + ai * 128 + m * 16; float mu, rs; row_stats(stin, row, mu, rs);
;                 float sum = 0.f, sq = 0.f;
; #pragma unroll
;                 for (int bj = 0; bj < 2; ++bj) {
;                     f32x4 z[2];
; #pragma unroll
;                     for (int n = 0; n < 2; ++n) {
;                         const int col = colb + bj * 128 + 4 * n;
;                         f32x4 xv = *(const f32x4*)(zsrc + (size_t)row * DM + col);
;                         if (stin) { const f32x4 gv = *(const f32x4*)(gin + col), bv = *(const f32x4*)(bin + col); xv = (xv - mu) * rs * gv + bv; }
;                         f32x4 zz = ALPHA * xv + acc[ai][bj][m][n];
;                         if (bias) zz += *(const f32x4*)(bias + col);
;                         *(f32x4*)(zdst + (size_t)row * DM + col) = zz;
;                         sum += zz[0] + zz[1] + zz[2] + zz[3]; sq += zz[0] * zz[0] + zz[1] * zz[1] + zz[2] * zz[2] + zz[3] * zz[3];
;                         z[n] = zz;
;                     }
;                     u32x4 o; o.x = pk2(z[0][0], z[0][1]); o.y = pk2(z[0][2], z[0][3]); o.z = pk2(z[1][0], z[1][1]); o.w = pk2(z[1][2], z[1][3]);
;                     if (zb) *(u32x4*)(zb + (size_t)row * DM + colb + bj * 128) = o;
;                 }
;                 sum += __shfl_xor(sum, 16); sq += __shfl_xor(sq, 16);
;                 sum += __shfl_xor(sum, 32); sq += __shfl_xor(sq, 32);
;                 if (fq == 0) { atomicAdd(stout + 2 * (size_t)row, sum); atomicAdd(stout + 2 * (size_t)row + 1, sq); }
	v_pk_fma_f32 v[84:85], v[84:85], v[98:99], v[88:89]
	v_pk_fma_f32 v[86:87], v[86:87], v[100:101], v[90:91]
	v_pk_fma_f32 v[72:73], v[84:85], s[24:25], v[72:73] op_sel_hi:[1,0,1]
	v_pk_fma_f32 v[74:75], v[86:87], s[24:25], v[74:75] op_sel_hi:[1,0,1]
	s_waitcnt vmcnt(0)
	v_pk_add_f32 v[72:73], v[92:93], v[72:73]
	v_pk_add_f32 v[74:75], v[94:95], v[74:75]
	global_store_dwordx4 v[82:83], v[72:75], off offset:16
	v_cvt_pk_bf16_f32 v98, v72, v73
	v_cvt_pk_bf16_f32 v99, v74, v75
	flat_store_dwordx4 v[104:105], v[96:99]
	global_load_dwordx4 v[84:87], v[82:83], off offset:512
	global_load_dwordx4 v[88:91], v[126:127], off
	global_load_dwordx4 v[92:95], v[158:159], off
	s_nop 0
	global_load_dwordx4 v[96:99], v[160:161], off
	global_load_dwordx4 v[100:103], v[82:83], off offset:528
	s_waitcnt vmcnt(0)
	v_sub_f32_e32 v87, v87, v107
	v_sub_f32_e32 v86, v86, v107
	v_sub_f32_e32 v85, v85, v107
	v_sub_f32_e32 v84, v84, v107
	v_pk_mul_f32 v[84:85], v[106:107], v[84:85] op_sel_hi:[0,1]
	v_pk_mul_f32 v[86:87], v[106:107], v[86:87] op_sel_hi:[0,1]
	v_pk_fma_f32 v[86:87], v[90:91], v[86:87], v[94:95]
	v_pk_fma_f32 v[84:85], v[88:89], v[84:85], v[92:93]
	v_pk_fma_f32 v[70:71], v[86:87], s[24:25], v[70:71] op_sel_hi:[1,0,1]
	v_pk_fma_f32 v[68:69], v[84:85], s[24:25], v[68:69] op_sel_hi:[1,0,1]
	v_pk_add_f32 v[70:71], v[98:99], v[70:71]
	v_pk_add_f32 v[68:69], v[96:97], v[68:69]
	global_store_dwordx4 v[82:83], v[68:71], off offset:512
	global_load_dwordx4 v[84:87], v[120:121], off
	global_load_dwordx4 v[88:91], v[122:123], off
	global_load_dwordx4 v[92:95], v[116:117], off
	v_add_f32_e32 v96, v76, v77
	v_mul_f32_e32 v77, v77, v77
	v_fmac_f32_e32 v77, v76, v76
	v_add_f32_e32 v96, v78, v96
	v_fmac_f32_e32 v77, v78, v78
	v_add_f32_e32 v78, v72, v73
	v_mul_f32_e32 v73, v73, v73
	v_fmac_f32_e32 v73, v72, v72
	v_add_f32_e32 v76, v79, v96
	v_add_f32_e32 v78, v74, v78
	v_fmac_f32_e32 v73, v74, v74
	v_add_f32_e32 v76, 0, v76
	v_fmac_f32_e32 v77, v79, v79
	v_add_f32_e32 v72, v75, v78
	v_fmac_f32_e32 v73, v75, v75
	v_sub_f32_e32 v75, v101, v107
	v_sub_f32_e32 v74, v100, v107
	v_add_f32_e32 v76, v72, v76
	v_add_f32_e32 v77, v77, v73
	v_sub_f32_e32 v73, v103, v107
	v_sub_f32_e32 v72, v102, v107
	v_pk_mul_f32 v[74:75], v[106:107], v[74:75] op_sel_hi:[0,1]
	v_pk_mul_f32 v[72:73], v[106:107], v[72:73] op_sel_hi:[0,1]
	v_mul_f32_e32 v79, v69, v69
	v_add_f32_e32 v78, v68, v69
	v_fmac_f32_e32 v79, v68, v68
	v_add_f32_e32 v78, v70, v78
	v_fmac_f32_e32 v79, v70, v70
	v_add_f32_e32 v78, v71, v78
	v_fmac_f32_e32 v79, v71, v71
	v_add_f32_e32 v76, v76, v78
	v_add_f32_e32 v77, v77, v79
	v_cvt_pk_bf16_f32 v68, v68, v69
	v_cvt_pk_bf16_f32 v69, v70, v71
	s_waitcnt vmcnt(0)
	v_pk_fma_f32 v[74:75], v[84:85], v[74:75], v[88:89]
	v_pk_fma_f32 v[72:73], v[86:87], v[72:73], v[90:91]
	v_pk_fma_f32 v[64:65], v[74:75], s[24:25], v[64:65] op_sel_hi:[1,0,1]
	v_pk_fma_f32 v[66:67], v[72:73], s[24:25], v[66:67] op_sel_hi:[1,0,1]
	v_pk_add_f32 v[72:73], v[92:93], v[64:65]
	v_pk_add_f32 v[74:75], v[94:95], v[66:67]
	v_mul_f32_e32 v65, v73, v73
	v_add_f32_e32 v64, v72, v73
	v_fmac_f32_e32 v65, v72, v72
	v_add_f32_e32 v64, v74, v64
	v_fmac_f32_e32 v65, v74, v74
	v_add_f32_e32 v64, v75, v64
	v_fmac_f32_e32 v65, v75, v75
	v_add_f32_e32 v64, v76, v64
	v_add_f32_e32 v65, v77, v65
	ds_bpermute_b32 v66, v118, v64
	ds_bpermute_b32 v67, v118, v65
	global_store_dwordx4 v[82:83], v[72:75], off offset:528
	v_cvt_pk_bf16_f32 v70, v72, v73
	v_cvt_pk_bf16_f32 v71, v74, v75
	s_waitcnt lgkmcnt(0)
	v_add_f32_e32 v64, v64, v66
	v_add_f32_e32 v65, v65, v67
	ds_bpermute_b32 v66, v119, v64
	ds_bpermute_b32 v67, v119, v65
	flat_store_dwordx4 v[104:105], v[68:71] offset:256
	s_mov_b32 s100, -1
	s_mov_b32 s101, 0
	s_mov_b32 s98, 0xffff0000
	s_mov_b32 s99, 0
	s_and_saveexec_b64 s[36:37], s[100:101]
	s_cbranch_execz .LBB0_1991
	s_waitcnt lgkmcnt(0)
	v_add_f32_e32 v67, v65, v67
	v_add_f32_e32 v66, v64, v66
	v_lshl_add_u64 v[64:65], s[8:9], 0, v[80:81]
	v_cndmask_b32_e64 v66, v66, v67, s[98:99]
	v_cndmask_b32_e64 v67, 0, 4, s[98:99]
	v_or_b32_e32 v64, v64, v67
	flat_atomic_add_f32 v[64:65], v66
.LBB0_1991:
	s_or_b64 exec, exec, s[36:37]
	v_add_u32_e32 v88, 0x80, v154
	v_ashrrev_i32_e32 v89, 31, v88
	v_lshlrev_b64 v[64:65], 3, v[88:89]
	s_waitcnt lgkmcnt(0)
	v_lshl_add_u64 v[66:67], s[6:7], 0, v[64:65]
	flat_load_dwordx2 v[90:91], v[66:67]
	v_lshlrev_b64 v[66:67], 12, v[88:89]
	v_lshl_add_u64 v[66:67], s[46:47], 0, v[66:67]
	v_lshl_add_u64 v[66:67], v[144:145], 2, v[66:67]
	global_load_dwordx4 v[68:71], v[66:67], off
	global_load_dwordx4 v[72:75], v[150:151], off
	global_load_dwordx4 v[76:79], v[152:153], off
	global_load_dwordx4 v[80:83], v[156:157], off
	global_load_dwordx4 v[84:87], v[66:67], off offset:16
	s_waitcnt vmcnt(0) lgkmcnt(0)
	v_pk_mul_f32 v[90:91], v[90:91], s[22:23] op_sel:[1,0] op_sel_hi:[0,0]
	v_fma_f32 v90, -v91, v91, v90
	v_max_f32_e32 v90, 0, v90
	v_add_f32_e32 v90, 0x3727c5ac, v90
	v_mul_f32_e32 v92, 0x4b800000, v90
	v_cmp_gt_f32_e32 vcc, s72, v90
	v_sub_f32_e32 v71, v71, v91
	v_sub_f32_e32 v70, v70, v91
	v_cndmask_b32_e32 v90, v90, v92, vcc
	v_rsq_f32_e32 v90, v90
	v_sub_f32_e32 v69, v69, v91
	v_sub_f32_e32 v68, v68, v91
	v_mul_f32_e32 v92, 0x45800000, v90
	v_cndmask_b32_e32 v90, v90, v92, vcc
	v_pk_mul_f32 v[68:69], v[68:69], v[90:91] op_sel_hi:[1,0]
	v_pk_mul_f32 v[70:71], v[70:71], v[90:91] op_sel_hi:[1,0]
	v_pk_fma_f32 v[68:69], v[72:73], v[68:69], v[76:77]
	v_pk_fma_f32 v[70:71], v[74:75], v[70:71], v[78:79]
	v_pk_fma_f32 v[60:61], v[68:69], s[24:25], v[60:61] op_sel_hi:[1,0,1]
	v_pk_fma_f32 v[62:63], v[70:71], s[24:25], v[62:63] op_sel_hi:[1,0,1]
	v_pk_add_f32 v[60:61], v[80:81], v[60:61]
	v_pk_add_f32 v[62:63], v[82:83], v[62:63]
	global_store_dwordx4 v[66:67], v[60:63], off
	global_load_dwordx4 v[68:71], v[146:147], off
	global_load_dwordx4 v[72:75], v[148:149], off
	global_load_dwordx4 v[76:79], v[124:125], off
	v_lshlrev_b64 v[80:81], 11, v[88:89]
	v_lshl_add_u64 v[80:81], s[10:11], 0, v[80:81]
	v_lshl_add_u64 v[88:89], v[144:145], 1, v[80:81]
	v_sub_f32_e32 v81, v87, v91
	v_sub_f32_e32 v80, v86, v91
	v_sub_f32_e32 v83, v85, v91
	v_sub_f32_e32 v82, v84, v91
	v_pk_mul_f32 v[82:83], v[82:83], v[90:91] op_sel_hi:[1,0]
	v_pk_mul_f32 v[84:85], v[80:81], v[90:91] op_sel_hi:[1,0]
	v_cvt_pk_bf16_f32 v80, v60, v61
	v_cvt_pk_bf16_f32 v81, v62, v63
	s_waitcnt vmcnt(1)
; DEVI unsigned pk2(float lo, float hi) { unsigned r; asm("v_cvt_pk_bf16_f32 %0, %1, %2" : "=v"(r) : "v"(lo), "v"(hi)); return r; }
; DEVI void row_stats(const float* stats, int row, float& mu, float& rs) {
;     if (stats) { const float2 st = *(const float2*)(stats + 2 * (size_t)row); mu = st.x * (1.0f / 1024.0f); const float var = st.y * (1.0f / 1024.0f) - mu * mu; rs = rsqrtf(fmaxf(var, 0.f) + LN_EPS); }
;     DEVI void operator()(const f32x4 (&acc)[2][2][4][2], const pg8::Unit& u, int wr, int wc, int fr, int fq) const {
;     ...
;                 const int row = row0 + ai * 128 + m * 16; float mu, rs; row_stats(stin, row, mu, rs);
;                 float sum = 0.f, sq = 0.f;
; #pragma unroll
;                 for (int bj = 0; bj < 2; ++bj) {
;                     f32x4 z[2];
; #pragma unroll
;                     for (int n = 0; n < 2; ++n) {
;                         const int col = colb + bj * 128 + 4 * n;
;                         f32x4 xv = *(const f32x4*)(zsrc + (size_t)row * DM + col);
;                         if (stin) { const f32x4 gv = *(const f32x4*)(gin + col), bv = *(const f32x4*)(bin + col); xv = (xv - mu) * rs * gv + bv; }
;                         f32x4 zz = ALPHA * xv + acc[ai][bj][m][n];
;                         if (bias) zz += *(const f32x4*)(bias + col);
;                         *(f32x4*)(zdst + (size_t)row * DM + col) = zz;
;                         sum += zz[0] + zz[1] + zz[2] + zz[3]; sq += zz[0] * zz[0] + zz[1] * zz[1] + zz[2] * zz[2] + zz[3] * zz[3];
;                         z[n] = zz;
;                     }
;                     u32x4 o; o.x = pk2(z[0][0], z[0][1]); o.y = pk2(z[0][2], z[0][3]); o.z = pk2(z[1][0], z[1][1]); o.w = pk2(z[1][2], z[1][3]);
;                     if (zb) *(u32x4*)(zb + (size_t)row * DM + colb + bj * 128) = o;
;                 }
;                 sum += __shfl_xor(sum, 16); sq += __shfl_xor(sq, 16);
;                 sum += __shfl_xor(sum, 32); sq += __shfl_xor(sq, 32);
;                 if (fq == 0) { atomicAdd(stout + 2 * (size_t)row, sum); atomicAdd(stout + 2 * (size_t)row + 1, sq); }
	v_pk_fma_f32 v[68:69], v[68:69], v[82:83], v[72:73]
	v_pk_fma_f32 v[70:71], v[70:71], v[84:85], v[74:75]
	v_pk_fma_f32 v[56:57], v[68:69], s[24:25], v[56:57] op_sel_hi:[1,0,1]
	v_pk_fma_f32 v[58:59], v[70:71], s[24:25], v[58:59] op_sel_hi:[1,0,1]
	s_waitcnt vmcnt(0)
	v_pk_add_f32 v[56:57], v[76:77], v[56:57]
	v_pk_add_f32 v[58:59], v[78:79], v[58:59]
	global_store_dwordx4 v[66:67], v[56:59], off offset:16
	v_cvt_pk_bf16_f32 v82, v56, v57
	v_cvt_pk_bf16_f32 v83, v58, v59
	flat_store_dwordx4 v[88:89], v[80:83]
	global_load_dwordx4 v[68:71], v[66:67], off offset:512
	global_load_dwordx4 v[72:75], v[126:127], off
	global_load_dwordx4 v[76:79], v[158:159], off
	s_nop 0
	global_load_dwordx4 v[80:83], v[160:161], off
	global_load_dwordx4 v[84:87], v[66:67], off offset:528
	s_waitcnt vmcnt(0)
	v_sub_f32_e32 v71, v71, v91
	v_sub_f32_e32 v70, v70, v91
	v_sub_f32_e32 v69, v69, v91
	v_sub_f32_e32 v68, v68, v91
	v_pk_mul_f32 v[68:69], v[90:91], v[68:69] op_sel_hi:[0,1]
	v_pk_mul_f32 v[70:71], v[90:91], v[70:71] op_sel_hi:[0,1]
	v_pk_fma_f32 v[70:71], v[74:75], v[70:71], v[78:79]
	v_pk_fma_f32 v[68:69], v[72:73], v[68:69], v[76:77]
	v_pk_fma_f32 v[54:55], v[70:71], s[24:25], v[54:55] op_sel_hi:[1,0,1]
	v_pk_fma_f32 v[52:53], v[68:69], s[24:25], v[52:53] op_sel_hi:[1,0,1]
	v_pk_add_f32 v[54:55], v[82:83], v[54:55]
	v_pk_add_f32 v[52:53], v[80:81], v[52:53]
	global_store_dwordx4 v[66:67], v[52:55], off offset:512
	global_load_dwordx4 v[68:71], v[120:121], off
	global_load_dwordx4 v[72:75], v[122:123], off
	global_load_dwordx4 v[76:79], v[116:117], off
	v_add_f32_e32 v80, v60, v61
	v_mul_f32_e32 v61, v61, v61
	v_fmac_f32_e32 v61, v60, v60
	v_add_f32_e32 v80, v62, v80
	v_fmac_f32_e32 v61, v62, v62
	v_add_f32_e32 v62, v56, v57
	v_mul_f32_e32 v57, v57, v57
	v_fmac_f32_e32 v57, v56, v56
	v_add_f32_e32 v60, v63, v80
	v_add_f32_e32 v62, v58, v62
	v_fmac_f32_e32 v57, v58, v58
	v_add_f32_e32 v60, 0, v60
	v_fmac_f32_e32 v61, v63, v63
	v_add_f32_e32 v56, v59, v62
	v_fmac_f32_e32 v57, v59, v59
	v_sub_f32_e32 v59, v85, v91
	v_sub_f32_e32 v58, v84, v91
	v_add_f32_e32 v60, v56, v60
	v_add_f32_e32 v61, v61, v57
	v_sub_f32_e32 v57, v87, v91
	v_sub_f32_e32 v56, v86, v91
	v_pk_mul_f32 v[58:59], v[90:91], v[58:59] op_sel_hi:[0,1]
	v_pk_mul_f32 v[56:57], v[90:91], v[56:57] op_sel_hi:[0,1]
	v_mul_f32_e32 v63, v53, v53
	v_add_f32_e32 v62, v52, v53
	v_fmac_f32_e32 v63, v52, v52
	v_add_f32_e32 v62, v54, v62
	v_fmac_f32_e32 v63, v54, v54
	v_add_f32_e32 v62, v55, v62
	v_fmac_f32_e32 v63, v55, v55
	v_add_f32_e32 v60, v60, v62
	v_add_f32_e32 v61, v61, v63
	v_cvt_pk_bf16_f32 v52, v52, v53
	v_cvt_pk_bf16_f32 v53, v54, v55
	s_waitcnt vmcnt(0)
	v_pk_fma_f32 v[58:59], v[68:69], v[58:59], v[72:73]
	v_pk_fma_f32 v[56:57], v[70:71], v[56:57], v[74:75]
	v_pk_fma_f32 v[48:49], v[58:59], s[24:25], v[48:49] op_sel_hi:[1,0,1]
	v_pk_fma_f32 v[50:51], v[56:57], s[24:25], v[50:51] op_sel_hi:[1,0,1]
	v_pk_add_f32 v[56:57], v[76:77], v[48:49]
	v_pk_add_f32 v[58:59], v[78:79], v[50:51]
	v_mul_f32_e32 v49, v57, v57
	v_add_f32_e32 v48, v56, v57
	v_fmac_f32_e32 v49, v56, v56
	v_add_f32_e32 v48, v58, v48
	v_fmac_f32_e32 v49, v58, v58
	v_add_f32_e32 v48, v59, v48
	v_fmac_f32_e32 v49, v59, v59
	v_add_f32_e32 v48, v60, v48
	v_add_f32_e32 v49, v61, v49
	ds_bpermute_b32 v50, v118, v48
	ds_bpermute_b32 v51, v118, v49
	global_store_dwordx4 v[66:67], v[56:59], off offset:528
	v_cvt_pk_bf16_f32 v54, v56, v57
	v_cvt_pk_bf16_f32 v55, v58, v59
	s_waitcnt lgkmcnt(0)
	v_add_f32_e32 v48, v48, v50
	v_add_f32_e32 v49, v49, v51
	ds_bpermute_b32 v50, v119, v48
	ds_bpermute_b32 v51, v119, v49
	flat_store_dwordx4 v[88:89], v[52:55] offset:256
	s_mov_b32 s100, -1
	s_mov_b32 s101, 0
	s_mov_b32 s98, 0xffff0000
	s_mov_b32 s99, 0
	s_and_saveexec_b64 s[36:37], s[100:101]
	s_cbranch_execz .LBB0_1993
	s_waitcnt lgkmcnt(0)
	v_add_f32_e32 v51, v49, v51
	v_add_f32_e32 v50, v48, v50
	v_lshl_add_u64 v[48:49], s[8:9], 0, v[64:65]
	v_cndmask_b32_e64 v50, v50, v51, s[98:99]
	v_cndmask_b32_e64 v51, 0, 4, s[98:99]
	v_or_b32_e32 v48, v48, v51
	flat_atomic_add_f32 v[48:49], v50
.LBB0_1993:
	s_or_b64 exec, exec, s[36:37]
	v_add_u32_e32 v72, 0x90, v154
	v_ashrrev_i32_e32 v73, 31, v72
	v_lshlrev_b64 v[48:49], 3, v[72:73]
	s_waitcnt lgkmcnt(0)
	v_lshl_add_u64 v[50:51], s[6:7], 0, v[48:49]
	flat_load_dwordx2 v[74:75], v[50:51]
	v_lshlrev_b64 v[50:51], 12, v[72:73]
	v_lshl_add_u64 v[50:51], s[46:47], 0, v[50:51]
	v_lshl_add_u64 v[50:51], v[144:145], 2, v[50:51]
	global_load_dwordx4 v[52:55], v[50:51], off
	global_load_dwordx4 v[56:59], v[150:151], off
	global_load_dwordx4 v[60:63], v[152:153], off
	global_load_dwordx4 v[64:67], v[156:157], off
	global_load_dwordx4 v[68:71], v[50:51], off offset:16
	s_waitcnt vmcnt(0) lgkmcnt(0)
	v_pk_mul_f32 v[74:75], v[74:75], s[22:23] op_sel:[1,0] op_sel_hi:[0,0]
	v_fma_f32 v74, -v75, v75, v74
	v_max_f32_e32 v74, 0, v74
	v_add_f32_e32 v74, 0x3727c5ac, v74
	v_mul_f32_e32 v76, 0x4b800000, v74
	v_cmp_gt_f32_e32 vcc, s72, v74
	v_sub_f32_e32 v55, v55, v75
	v_sub_f32_e32 v54, v54, v75
	v_cndmask_b32_e32 v74, v74, v76, vcc
	v_rsq_f32_e32 v74, v74
	v_sub_f32_e32 v53, v53, v75
	v_sub_f32_e32 v52, v52, v75
	v_mul_f32_e32 v76, 0x45800000, v74
	v_cndmask_b32_e32 v74, v74, v76, vcc
	v_pk_mul_f32 v[52:53], v[52:53], v[74:75] op_sel_hi:[1,0]
	v_pk_mul_f32 v[54:55], v[54:55], v[74:75] op_sel_hi:[1,0]
	v_pk_fma_f32 v[52:53], v[56:57], v[52:53], v[60:61]
	v_pk_fma_f32 v[54:55], v[58:59], v[54:55], v[62:63]
	v_pk_fma_f32 v[44:45], v[52:53], s[24:25], v[44:45] op_sel_hi:[1,0,1]
	v_pk_fma_f32 v[46:47], v[54:55], s[24:25], v[46:47] op_sel_hi:[1,0,1]
	v_pk_add_f32 v[44:45], v[64:65], v[44:45]
	v_pk_add_f32 v[46:47], v[66:67], v[46:47]
	global_store_dwordx4 v[50:51], v[44:47], off
	global_load_dwordx4 v[52:55], v[146:147], off
	global_load_dwordx4 v[56:59], v[148:149], off
	global_load_dwordx4 v[60:63], v[124:125], off
	v_lshlrev_b64 v[64:65], 11, v[72:73]
	v_lshl_add_u64 v[64:65], s[10:11], 0, v[64:65]
	v_lshl_add_u64 v[72:73], v[144:145], 1, v[64:65]
	v_sub_f32_e32 v65, v71, v75
	v_sub_f32_e32 v64, v70, v75
	v_sub_f32_e32 v67, v69, v75
	v_sub_f32_e32 v66, v68, v75
	v_pk_mul_f32 v[66:67], v[66:67], v[74:75] op_sel_hi:[1,0]
	v_pk_mul_f32 v[68:69], v[64:65], v[74:75] op_sel_hi:[1,0]
	v_cvt_pk_bf16_f32 v64, v44, v45
	v_cvt_pk_bf16_f32 v65, v46, v47
	s_waitcnt vmcnt(1)
; DEVI unsigned pk2(float lo, float hi) { unsigned r; asm("v_cvt_pk_bf16_f32 %0, %1, %2" : "=v"(r) : "v"(lo), "v"(hi)); return r; }
; DEVI void row_stats(const float* stats, int row, float& mu, float& rs) {
;     if (stats) { const float2 st = *(const float2*)(stats + 2 * (size_t)row); mu = st.x * (1.0f / 1024.0f); const float var = st.y * (1.0f / 1024.0f) - mu * mu; rs = rsqrtf(fmaxf(var, 0.f) + LN_EPS); }
;     DEVI void operator()(const f32x4 (&acc)[2][2][4][2], const pg8::Unit& u, int wr, int wc, int fr, int fq) const {
;     ...
;                 const int row = row0 + ai * 128 + m * 16; float mu, rs; row_stats(stin, row, mu, rs);
;                 float sum = 0.f, sq = 0.f;
; #pragma unroll
;                 for (int bj = 0; bj < 2; ++bj) {
;                     f32x4 z[2];
; #pragma unroll
;                     for (int n = 0; n < 2; ++n) {
;                         const int col = colb + bj * 128 + 4 * n;
;                         f32x4 xv = *(const f32x4*)(zsrc + (size_t)row * DM + col);
;                         if (stin) { const f32x4 gv = *(const f32x4*)(gin + col), bv = *(const f32x4*)(bin + col); xv = (xv - mu) * rs * gv + bv; }
;                         f32x4 zz = ALPHA * xv + acc[ai][bj][m][n];
;                         if (bias) zz += *(const f32x4*)(bias + col);
;                         *(f32x4*)(zdst + (size_t)row * DM + col) = zz;
;                         sum += zz[0] + zz[1] + zz[2] + zz[3]; sq += zz[0] * zz[0] + zz[1] * zz[1] + zz[2] * zz[2] + zz[3] * zz[3];
;                         z[n] = zz;
;                     }
;                     u32x4 o; o.x = pk2(z[0][0], z[0][1]); o.y = pk2(z[0][2], z[0][3]); o.z = pk2(z[1][0], z[1][1]); o.w = pk2(z[1][2], z[1][3]);
;                     if (zb) *(u32x4*)(zb + (size_t)row * DM + colb + bj * 128) = o;
;                 }
;                 sum += __shfl_xor(sum, 16); sq += __shfl_xor(sq, 16);
;                 sum += __shfl_xor(sum, 32); sq += __shfl_xor(sq, 32);
;                 if (fq == 0) { atomicAdd(stout + 2 * (size_t)row, sum); atomicAdd(stout + 2 * (size_t)row + 1, sq); }
	v_pk_fma_f32 v[52:53], v[52:53], v[66:67], v[56:57]
	v_pk_fma_f32 v[54:55], v[54:55], v[68:69], v[58:59]
	v_pk_fma_f32 v[40:41], v[52:53], s[24:25], v[40:41] op_sel_hi:[1,0,1]
	v_pk_fma_f32 v[42:43], v[54:55], s[24:25], v[42:43] op_sel_hi:[1,0,1]
	s_waitcnt vmcnt(0)
	v_pk_add_f32 v[40:41], v[60:61], v[40:41]
	v_pk_add_f32 v[42:43], v[62:63], v[42:43]
	global_store_dwordx4 v[50:51], v[40:43], off offset:16
	v_cvt_pk_bf16_f32 v66, v40, v41
	v_cvt_pk_bf16_f32 v67, v42, v43
	flat_store_dwordx4 v[72:73], v[64:67]
	global_load_dwordx4 v[52:55], v[50:51], off offset:512
	global_load_dwordx4 v[56:59], v[126:127], off
	global_load_dwordx4 v[60:63], v[158:159], off
	s_nop 0
	global_load_dwordx4 v[64:67], v[160:161], off
	global_load_dwordx4 v[68:71], v[50:51], off offset:528
	s_waitcnt vmcnt(0)
	v_sub_f32_e32 v55, v55, v75
	v_sub_f32_e32 v54, v54, v75
	v_sub_f32_e32 v53, v53, v75
	v_sub_f32_e32 v52, v52, v75
	v_pk_mul_f32 v[52:53], v[74:75], v[52:53] op_sel_hi:[0,1]
	v_pk_mul_f32 v[54:55], v[74:75], v[54:55] op_sel_hi:[0,1]
	v_pk_fma_f32 v[54:55], v[58:59], v[54:55], v[62:63]
	v_pk_fma_f32 v[52:53], v[56:57], v[52:53], v[60:61]
	v_pk_fma_f32 v[38:39], v[54:55], s[24:25], v[38:39] op_sel_hi:[1,0,1]
	v_pk_fma_f32 v[36:37], v[52:53], s[24:25], v[36:37] op_sel_hi:[1,0,1]
	v_pk_add_f32 v[38:39], v[66:67], v[38:39]
	v_pk_add_f32 v[36:37], v[64:65], v[36:37]
	global_store_dwordx4 v[50:51], v[36:39], off offset:512
	global_load_dwordx4 v[52:55], v[120:121], off
	global_load_dwordx4 v[56:59], v[122:123], off
	global_load_dwordx4 v[60:63], v[116:117], off
	v_add_f32_e32 v64, v44, v45
	v_mul_f32_e32 v45, v45, v45
	v_fmac_f32_e32 v45, v44, v44
	v_add_f32_e32 v64, v46, v64
	v_fmac_f32_e32 v45, v46, v46
	v_add_f32_e32 v46, v40, v41
	v_mul_f32_e32 v41, v41, v41
	v_fmac_f32_e32 v41, v40, v40
	v_add_f32_e32 v44, v47, v64
	v_add_f32_e32 v46, v42, v46
	v_fmac_f32_e32 v41, v42, v42
	v_add_f32_e32 v44, 0, v44
	v_fmac_f32_e32 v45, v47, v47
	v_add_f32_e32 v40, v43, v46
	v_fmac_f32_e32 v41, v43, v43
	v_sub_f32_e32 v43, v69, v75
	v_sub_f32_e32 v42, v68, v75
	v_add_f32_e32 v44, v40, v44
	v_add_f32_e32 v45, v45, v41
	v_sub_f32_e32 v41, v71, v75
	v_sub_f32_e32 v40, v70, v75
	v_pk_mul_f32 v[42:43], v[74:75], v[42:43] op_sel_hi:[0,1]
	v_pk_mul_f32 v[40:41], v[74:75], v[40:41] op_sel_hi:[0,1]
	v_mul_f32_e32 v47, v37, v37
	v_add_f32_e32 v46, v36, v37
	v_fmac_f32_e32 v47, v36, v36
	v_add_f32_e32 v46, v38, v46
	v_fmac_f32_e32 v47, v38, v38
	v_add_f32_e32 v46, v39, v46
	v_fmac_f32_e32 v47, v39, v39
	v_add_f32_e32 v44, v44, v46
	v_add_f32_e32 v45, v45, v47
	v_cvt_pk_bf16_f32 v36, v36, v37
	v_cvt_pk_bf16_f32 v37, v38, v39
	s_waitcnt vmcnt(0)
	v_pk_fma_f32 v[42:43], v[52:53], v[42:43], v[56:57]
	v_pk_fma_f32 v[40:41], v[54:55], v[40:41], v[58:59]
	v_pk_fma_f32 v[32:33], v[42:43], s[24:25], v[32:33] op_sel_hi:[1,0,1]
	v_pk_fma_f32 v[34:35], v[40:41], s[24:25], v[34:35] op_sel_hi:[1,0,1]
	v_pk_add_f32 v[40:41], v[60:61], v[32:33]
	v_pk_add_f32 v[42:43], v[62:63], v[34:35]
	v_mul_f32_e32 v33, v41, v41
	v_add_f32_e32 v32, v40, v41
	v_fmac_f32_e32 v33, v40, v40
	v_add_f32_e32 v32, v42, v32
	v_fmac_f32_e32 v33, v42, v42
	v_add_f32_e32 v32, v43, v32
	v_fmac_f32_e32 v33, v43, v43
	v_add_f32_e32 v32, v44, v32
	v_add_f32_e32 v33, v45, v33
	ds_bpermute_b32 v34, v118, v32
	ds_bpermute_b32 v35, v118, v33
	global_store_dwordx4 v[50:51], v[40:43], off offset:528
	v_cvt_pk_bf16_f32 v38, v40, v41
	v_cvt_pk_bf16_f32 v39, v42, v43
	s_waitcnt lgkmcnt(0)
	v_add_f32_e32 v32, v32, v34
	v_add_f32_e32 v33, v33, v35
	ds_bpermute_b32 v34, v119, v32
	ds_bpermute_b32 v35, v119, v33
	flat_store_dwordx4 v[72:73], v[36:39] offset:256
	s_mov_b32 s100, -1
	s_mov_b32 s101, 0
	s_mov_b32 s98, 0xffff0000
	s_mov_b32 s99, 0
	s_and_saveexec_b64 s[36:37], s[100:101]
	s_cbranch_execz .LBB0_1995
	s_waitcnt lgkmcnt(0)
	v_add_f32_e32 v35, v33, v35
	v_add_f32_e32 v34, v32, v34
	v_lshl_add_u64 v[32:33], s[8:9], 0, v[48:49]
	v_cndmask_b32_e64 v34, v34, v35, s[98:99]
	v_cndmask_b32_e64 v35, 0, 4, s[98:99]
	v_or_b32_e32 v32, v32, v35
	flat_atomic_add_f32 v[32:33], v34
.LBB0_1995:
	s_or_b64 exec, exec, s[36:37]
	v_add_u32_e32 v56, 0xa0, v154
	v_ashrrev_i32_e32 v57, 31, v56
	v_lshlrev_b64 v[32:33], 3, v[56:57]
	s_waitcnt lgkmcnt(0)
	v_lshl_add_u64 v[34:35], s[6:7], 0, v[32:33]
	flat_load_dwordx2 v[58:59], v[34:35]
	v_lshlrev_b64 v[34:35], 12, v[56:57]
	v_lshl_add_u64 v[34:35], s[46:47], 0, v[34:35]
	v_lshl_add_u64 v[34:35], v[144:145], 2, v[34:35]
	global_load_dwordx4 v[36:39], v[34:35], off
	global_load_dwordx4 v[40:43], v[150:151], off
	global_load_dwordx4 v[44:47], v[152:153], off
	global_load_dwordx4 v[48:51], v[156:157], off
	global_load_dwordx4 v[52:55], v[34:35], off offset:16
	s_waitcnt vmcnt(0) lgkmcnt(0)
	v_pk_mul_f32 v[58:59], v[58:59], s[22:23] op_sel:[1,0] op_sel_hi:[0,0]
	v_fma_f32 v58, -v59, v59, v58
	v_max_f32_e32 v58, 0, v58
	v_add_f32_e32 v58, 0x3727c5ac, v58
	v_mul_f32_e32 v60, 0x4b800000, v58
	v_cmp_gt_f32_e32 vcc, s72, v58
	v_sub_f32_e32 v39, v39, v59
	v_sub_f32_e32 v38, v38, v59
	v_cndmask_b32_e32 v58, v58, v60, vcc
	v_rsq_f32_e32 v58, v58
	v_sub_f32_e32 v37, v37, v59
	v_sub_f32_e32 v36, v36, v59
	v_mul_f32_e32 v60, 0x45800000, v58
	v_cndmask_b32_e32 v58, v58, v60, vcc
	v_pk_mul_f32 v[36:37], v[36:37], v[58:59] op_sel_hi:[1,0]
	v_pk_mul_f32 v[38:39], v[38:39], v[58:59] op_sel_hi:[1,0]
	v_pk_fma_f32 v[36:37], v[40:41], v[36:37], v[44:45]
	v_pk_fma_f32 v[38:39], v[42:43], v[38:39], v[46:47]
	v_pk_fma_f32 v[28:29], v[36:37], s[24:25], v[28:29] op_sel_hi:[1,0,1]
	v_pk_fma_f32 v[30:31], v[38:39], s[24:25], v[30:31] op_sel_hi:[1,0,1]
	v_pk_add_f32 v[28:29], v[48:49], v[28:29]
	v_pk_add_f32 v[30:31], v[50:51], v[30:31]
	global_store_dwordx4 v[34:35], v[28:31], off
	global_load_dwordx4 v[36:39], v[146:147], off
	global_load_dwordx4 v[40:43], v[148:149], off
	global_load_dwordx4 v[44:47], v[124:125], off
	v_lshlrev_b64 v[48:49], 11, v[56:57]
	v_lshl_add_u64 v[48:49], s[10:11], 0, v[48:49]
	v_lshl_add_u64 v[56:57], v[144:145], 1, v[48:49]
	v_sub_f32_e32 v49, v55, v59
	v_sub_f32_e32 v48, v54, v59
	v_sub_f32_e32 v51, v53, v59
	v_sub_f32_e32 v50, v52, v59
	v_pk_mul_f32 v[50:51], v[50:51], v[58:59] op_sel_hi:[1,0]
	v_pk_mul_f32 v[52:53], v[48:49], v[58:59] op_sel_hi:[1,0]
	v_cvt_pk_bf16_f32 v48, v28, v29
	v_cvt_pk_bf16_f32 v49, v30, v31
	s_waitcnt vmcnt(1)
; DEVI unsigned pk2(float lo, float hi) { unsigned r; asm("v_cvt_pk_bf16_f32 %0, %1, %2" : "=v"(r) : "v"(lo), "v"(hi)); return r; }
; DEVI void row_stats(const float* stats, int row, float& mu, float& rs) {
;     if (stats) { const float2 st = *(const float2*)(stats + 2 * (size_t)row); mu = st.x * (1.0f / 1024.0f); const float var = st.y * (1.0f / 1024.0f) - mu * mu; rs = rsqrtf(fmaxf(var, 0.f) + LN_EPS); }
;     DEVI void operator()(const f32x4 (&acc)[2][2][4][2], const pg8::Unit& u, int wr, int wc, int fr, int fq) const {
;     ...
;                 const int row = row0 + ai * 128 + m * 16; float mu, rs; row_stats(stin, row, mu, rs);
;                 float sum = 0.f, sq = 0.f;
; #pragma unroll
;                 for (int bj = 0; bj < 2; ++bj) {
;                     f32x4 z[2];
; #pragma unroll
;                     for (int n = 0; n < 2; ++n) {
;                         const int col = colb + bj * 128 + 4 * n;
;                         f32x4 xv = *(const f32x4*)(zsrc + (size_t)row * DM + col);
;                         if (stin) { const f32x4 gv = *(const f32x4*)(gin + col), bv = *(const f32x4*)(bin + col); xv = (xv - mu) * rs * gv + bv; }
;                         f32x4 zz = ALPHA * xv + acc[ai][bj][m][n];
;                         if (bias) zz += *(const f32x4*)(bias + col);
;                         *(f32x4*)(zdst + (size_t)row * DM + col) = zz;
;                         sum += zz[0] + zz[1] + zz[2] + zz[3]; sq += zz[0] * zz[0] + zz[1] * zz[1] + zz[2] * zz[2] + zz[3] * zz[3];
;                         z[n] = zz;
;                     }
;                     u32x4 o; o.x = pk2(z[0][0], z[0][1]); o.y = pk2(z[0][2], z[0][3]); o.z = pk2(z[1][0], z[1][1]); o.w = pk2(z[1][2], z[1][3]);
;                     if (zb) *(u32x4*)(zb + (size_t)row * DM + colb + bj * 128) = o;
;                 }
;                 sum += __shfl_xor(sum, 16); sq += __shfl_xor(sq, 16);
;                 sum += __shfl_xor(sum, 32); sq += __shfl_xor(sq, 32);
;                 if (fq == 0) { atomicAdd(stout + 2 * (size_t)row, sum); atomicAdd(stout + 2 * (size_t)row + 1, sq); }
	v_pk_fma_f32 v[36:37], v[36:37], v[50:51], v[40:41]
	v_pk_fma_f32 v[38:39], v[38:39], v[52:53], v[42:43]
	v_pk_fma_f32 v[24:25], v[36:37], s[24:25], v[24:25] op_sel_hi:[1,0,1]
	v_pk_fma_f32 v[26:27], v[38:39], s[24:25], v[26:27] op_sel_hi:[1,0,1]
	s_waitcnt vmcnt(0)
	v_pk_add_f32 v[24:25], v[44:45], v[24:25]
	v_pk_add_f32 v[26:27], v[46:47], v[26:27]
	global_store_dwordx4 v[34:35], v[24:27], off offset:16
	v_cvt_pk_bf16_f32 v50, v24, v25
	v_cvt_pk_bf16_f32 v51, v26, v27
	flat_store_dwordx4 v[56:57], v[48:51]
	global_load_dwordx4 v[36:39], v[34:35], off offset:512
	global_load_dwordx4 v[40:43], v[126:127], off
	global_load_dwordx4 v[44:47], v[158:159], off
	s_nop 0
	global_load_dwordx4 v[48:51], v[160:161], off
	global_load_dwordx4 v[52:55], v[34:35], off offset:528
	s_waitcnt vmcnt(0)
	v_sub_f32_e32 v39, v39, v59
	v_sub_f32_e32 v38, v38, v59
	v_sub_f32_e32 v37, v37, v59
	v_sub_f32_e32 v36, v36, v59
	v_pk_mul_f32 v[36:37], v[58:59], v[36:37] op_sel_hi:[0,1]
	v_pk_mul_f32 v[38:39], v[58:59], v[38:39] op_sel_hi:[0,1]
	v_pk_fma_f32 v[38:39], v[42:43], v[38:39], v[46:47]
	v_pk_fma_f32 v[36:37], v[40:41], v[36:37], v[44:45]
	v_pk_fma_f32 v[22:23], v[38:39], s[24:25], v[22:23] op_sel_hi:[1,0,1]
	v_pk_fma_f32 v[20:21], v[36:37], s[24:25], v[20:21] op_sel_hi:[1,0,1]
	v_pk_add_f32 v[22:23], v[50:51], v[22:23]
	v_pk_add_f32 v[20:21], v[48:49], v[20:21]
	global_store_dwordx4 v[34:35], v[20:23], off offset:512
	global_load_dwordx4 v[36:39], v[120:121], off
	global_load_dwordx4 v[40:43], v[122:123], off
	global_load_dwordx4 v[44:47], v[116:117], off
	v_add_f32_e32 v48, v28, v29
	v_mul_f32_e32 v29, v29, v29
	v_fmac_f32_e32 v29, v28, v28
	v_add_f32_e32 v48, v30, v48
	v_fmac_f32_e32 v29, v30, v30
	v_add_f32_e32 v30, v24, v25
	v_mul_f32_e32 v25, v25, v25
	v_fmac_f32_e32 v25, v24, v24
	v_add_f32_e32 v28, v31, v48
	v_add_f32_e32 v30, v26, v30
	v_fmac_f32_e32 v25, v26, v26
	v_add_f32_e32 v28, 0, v28
	v_fmac_f32_e32 v29, v31, v31
	v_add_f32_e32 v24, v27, v30
	v_fmac_f32_e32 v25, v27, v27
	v_sub_f32_e32 v27, v53, v59
	v_sub_f32_e32 v26, v52, v59
	v_add_f32_e32 v28, v24, v28
	v_add_f32_e32 v29, v29, v25
	v_sub_f32_e32 v25, v55, v59
	v_sub_f32_e32 v24, v54, v59
	v_pk_mul_f32 v[26:27], v[58:59], v[26:27] op_sel_hi:[0,1]
	v_pk_mul_f32 v[24:25], v[58:59], v[24:25] op_sel_hi:[0,1]
	v_mul_f32_e32 v31, v21, v21
	v_add_f32_e32 v30, v20, v21
	v_fmac_f32_e32 v31, v20, v20
	v_add_f32_e32 v30, v22, v30
	v_fmac_f32_e32 v31, v22, v22
	v_add_f32_e32 v30, v23, v30
	v_fmac_f32_e32 v31, v23, v23
	v_add_f32_e32 v28, v28, v30
	v_add_f32_e32 v29, v29, v31
	v_cvt_pk_bf16_f32 v20, v20, v21
	v_cvt_pk_bf16_f32 v21, v22, v23
	s_waitcnt vmcnt(0)
	v_pk_fma_f32 v[26:27], v[36:37], v[26:27], v[40:41]
	v_pk_fma_f32 v[24:25], v[38:39], v[24:25], v[42:43]
	v_pk_fma_f32 v[16:17], v[26:27], s[24:25], v[16:17] op_sel_hi:[1,0,1]
	v_pk_fma_f32 v[18:19], v[24:25], s[24:25], v[18:19] op_sel_hi:[1,0,1]
	v_pk_add_f32 v[24:25], v[44:45], v[16:17]
	v_pk_add_f32 v[26:27], v[46:47], v[18:19]
	v_mul_f32_e32 v17, v25, v25
	v_add_f32_e32 v16, v24, v25
	v_fmac_f32_e32 v17, v24, v24
	v_add_f32_e32 v16, v26, v16
	v_fmac_f32_e32 v17, v26, v26
	v_add_f32_e32 v16, v27, v16
	v_fmac_f32_e32 v17, v27, v27
	v_add_f32_e32 v16, v28, v16
	v_add_f32_e32 v17, v29, v17
	ds_bpermute_b32 v18, v118, v16
	ds_bpermute_b32 v19, v118, v17
	global_store_dwordx4 v[34:35], v[24:27], off offset:528
	v_cvt_pk_bf16_f32 v22, v24, v25
	v_cvt_pk_bf16_f32 v23, v26, v27
	s_waitcnt lgkmcnt(0)
	v_add_f32_e32 v16, v16, v18
	v_add_f32_e32 v17, v17, v19
	ds_bpermute_b32 v18, v119, v16
	ds_bpermute_b32 v19, v119, v17
	flat_store_dwordx4 v[56:57], v[20:23] offset:256
	s_mov_b32 s100, -1
	s_mov_b32 s101, 0
	s_mov_b32 s98, 0xffff0000
	s_mov_b32 s99, 0
	s_and_saveexec_b64 s[36:37], s[100:101]
	s_cbranch_execz .LBB0_1997
	s_waitcnt lgkmcnt(0)
	v_add_f32_e32 v19, v17, v19
	v_add_f32_e32 v18, v16, v18
	v_lshl_add_u64 v[16:17], s[8:9], 0, v[32:33]
	v_cndmask_b32_e64 v18, v18, v19, s[98:99]
	v_cndmask_b32_e64 v19, 0, 4, s[98:99]
	v_or_b32_e32 v16, v16, v19
	flat_atomic_add_f32 v[16:17], v18
; DEVI unsigned pk2(float lo, float hi) { unsigned r; asm("v_cvt_pk_bf16_f32 %0, %1, %2" : "=v"(r) : "v"(lo), "v"(hi)); return r; }
; DEVI void row_stats(const float* stats, int row, float& mu, float& rs) {
;     if (stats) { const float2 st = *(const float2*)(stats + 2 * (size_t)row); mu = st.x * (1.0f / 1024.0f); const float var = st.y * (1.0f / 1024.0f) - mu * mu; rs = rsqrtf(fmaxf(var, 0.f) + LN_EPS); }
;     DEVI void operator()(const f32x4 (&acc)[2][2][4][2], const pg8::Unit& u, int wr, int wc, int fr, int fq) const {
;     ...
;                 const int row = row0 + ai * 128 + m * 16; float mu, rs; row_stats(stin, row, mu, rs);
;                 float sum = 0.f, sq = 0.f;
; #pragma unroll
;                 for (int bj = 0; bj < 2; ++bj) {
;                     f32x4 z[2];
; #pragma unroll
;                     for (int n = 0; n < 2; ++n) {
;                         const int col = colb + bj * 128 + 4 * n;
;                         f32x4 xv = *(const f32x4*)(zsrc + (size_t)row * DM + col);
;                         if (stin) { const f32x4 gv = *(const f32x4*)(gin + col), bv = *(const f32x4*)(bin + col); xv = (xv - mu) * rs * gv + bv; }
;                         f32x4 zz = ALPHA * xv + acc[ai][bj][m][n];
;                         if (bias) zz += *(const f32x4*)(bias + col);
;                         *(f32x4*)(zdst + (size_t)row * DM + col) = zz;
;                         sum += zz[0] + zz[1] + zz[2] + zz[3]; sq += zz[0] * zz[0] + zz[1] * zz[1] + zz[2] * zz[2] + zz[3] * zz[3];
;                         z[n] = zz;
;                     }
;                     u32x4 o; o.x = pk2(z[0][0], z[0][1]); o.y = pk2(z[0][2], z[0][3]); o.z = pk2(z[1][0], z[1][1]); o.w = pk2(z[1][2], z[1][3]);
;                     if (zb) *(u32x4*)(zb + (size_t)row * DM + colb + bj * 128) = o;
;                 }
;                 sum += __shfl_xor(sum, 16); sq += __shfl_xor(sq, 16);
;                 sum += __shfl_xor(sum, 32); sq += __shfl_xor(sq, 32);
;                 if (fq == 0) { atomicAdd(stout + 2 * (size_t)row, sum); atomicAdd(stout + 2 * (size_t)row + 1, sq); }
.LBB0_1997:
	s_or_b64 exec, exec, s[36:37]
	v_add_u32_e32 v40, 0xb0, v154
	v_ashrrev_i32_e32 v41, 31, v40
	v_lshlrev_b64 v[16:17], 3, v[40:41]
	s_waitcnt lgkmcnt(0)
	v_lshl_add_u64 v[18:19], s[6:7], 0, v[16:17]
	flat_load_dwordx2 v[42:43], v[18:19]
	v_lshlrev_b64 v[18:19], 12, v[40:41]
	v_lshl_add_u64 v[18:19], s[46:47], 0, v[18:19]
	v_lshl_add_u64 v[18:19], v[144:145], 2, v[18:19]
	global_load_dwordx4 v[20:23], v[18:19], off
	global_load_dwordx4 v[24:27], v[150:151], off
	global_load_dwordx4 v[28:31], v[152:153], off
	global_load_dwordx4 v[32:35], v[156:157], off
	global_load_dwordx4 v[36:39], v[18:19], off offset:16
	s_waitcnt vmcnt(0) lgkmcnt(0)
	v_pk_mul_f32 v[42:43], v[42:43], s[22:23] op_sel:[1,0] op_sel_hi:[0,0]
	v_fma_f32 v42, -v43, v43, v42
	v_max_f32_e32 v42, 0, v42
	v_add_f32_e32 v42, 0x3727c5ac, v42
	v_mul_f32_e32 v44, 0x4b800000, v42
	v_cmp_gt_f32_e32 vcc, s72, v42
	v_sub_f32_e32 v23, v23, v43
	v_sub_f32_e32 v22, v22, v43
	v_cndmask_b32_e32 v42, v42, v44, vcc
	v_rsq_f32_e32 v42, v42
	v_sub_f32_e32 v21, v21, v43
	v_sub_f32_e32 v20, v20, v43
	v_mul_f32_e32 v44, 0x45800000, v42
	v_cndmask_b32_e32 v42, v42, v44, vcc
	v_pk_mul_f32 v[20:21], v[20:21], v[42:43] op_sel_hi:[1,0]
	v_pk_mul_f32 v[22:23], v[22:23], v[42:43] op_sel_hi:[1,0]
	v_pk_fma_f32 v[20:21], v[24:25], v[20:21], v[28:29]
	v_pk_fma_f32 v[22:23], v[26:27], v[22:23], v[30:31]
	v_pk_fma_f32 v[12:13], v[20:21], s[24:25], v[12:13] op_sel_hi:[1,0,1]
	v_pk_fma_f32 v[14:15], v[22:23], s[24:25], v[14:15] op_sel_hi:[1,0,1]
	v_pk_add_f32 v[12:13], v[32:33], v[12:13]
	v_pk_add_f32 v[14:15], v[34:35], v[14:15]
	global_store_dwordx4 v[18:19], v[12:15], off
	global_load_dwordx4 v[20:23], v[146:147], off
	global_load_dwordx4 v[24:27], v[148:149], off
	global_load_dwordx4 v[28:31], v[124:125], off
	v_lshlrev_b64 v[32:33], 11, v[40:41]
	v_lshl_add_u64 v[32:33], s[10:11], 0, v[32:33]
	v_lshl_add_u64 v[40:41], v[144:145], 1, v[32:33]
	v_sub_f32_e32 v33, v39, v43
	v_sub_f32_e32 v32, v38, v43
	v_sub_f32_e32 v35, v37, v43
	v_sub_f32_e32 v34, v36, v43
	v_pk_mul_f32 v[34:35], v[34:35], v[42:43] op_sel_hi:[1,0]
	v_pk_mul_f32 v[36:37], v[32:33], v[42:43] op_sel_hi:[1,0]
	v_cvt_pk_bf16_f32 v32, v12, v13
	v_cvt_pk_bf16_f32 v33, v14, v15
	s_waitcnt vmcnt(1)
	v_pk_fma_f32 v[20:21], v[20:21], v[34:35], v[24:25]
	v_pk_fma_f32 v[22:23], v[22:23], v[36:37], v[26:27]
	v_pk_fma_f32 v[8:9], v[20:21], s[24:25], v[8:9] op_sel_hi:[1,0,1]
	v_pk_fma_f32 v[10:11], v[22:23], s[24:25], v[10:11] op_sel_hi:[1,0,1]
	s_waitcnt vmcnt(0)
	v_pk_add_f32 v[8:9], v[28:29], v[8:9]
	v_pk_add_f32 v[10:11], v[30:31], v[10:11]
	global_store_dwordx4 v[18:19], v[8:11], off offset:16
	v_cvt_pk_bf16_f32 v34, v8, v9
	v_cvt_pk_bf16_f32 v35, v10, v11
	flat_store_dwordx4 v[40:41], v[32:35]
	global_load_dwordx4 v[20:23], v[18:19], off offset:512
	global_load_dwordx4 v[24:27], v[126:127], off
	global_load_dwordx4 v[28:31], v[158:159], off
	s_nop 0
	global_load_dwordx4 v[32:35], v[160:161], off
	global_load_dwordx4 v[36:39], v[18:19], off offset:528
	s_waitcnt vmcnt(0)
	v_sub_f32_e32 v23, v23, v43
	v_sub_f32_e32 v22, v22, v43
	v_sub_f32_e32 v21, v21, v43
	v_sub_f32_e32 v20, v20, v43
	v_pk_mul_f32 v[20:21], v[42:43], v[20:21] op_sel_hi:[0,1]
	v_pk_mul_f32 v[22:23], v[42:43], v[22:23] op_sel_hi:[0,1]
	v_pk_fma_f32 v[22:23], v[26:27], v[22:23], v[30:31]
	v_pk_fma_f32 v[20:21], v[24:25], v[20:21], v[28:29]
	v_pk_fma_f32 v[6:7], v[22:23], s[24:25], v[6:7] op_sel_hi:[1,0,1]
	v_pk_fma_f32 v[4:5], v[20:21], s[24:25], v[4:5] op_sel_hi:[1,0,1]
	v_pk_add_f32 v[6:7], v[34:35], v[6:7]
	v_pk_add_f32 v[4:5], v[32:33], v[4:5]
	global_store_dwordx4 v[18:19], v[4:7], off offset:512
	global_load_dwordx4 v[20:23], v[120:121], off
	global_load_dwordx4 v[24:27], v[122:123], off
	global_load_dwordx4 v[28:31], v[116:117], off
	v_add_f32_e32 v32, v12, v13
	v_mul_f32_e32 v13, v13, v13
	v_fmac_f32_e32 v13, v12, v12
	v_add_f32_e32 v32, v14, v32
	v_fmac_f32_e32 v13, v14, v14
	v_add_f32_e32 v14, v8, v9
	v_mul_f32_e32 v9, v9, v9
	v_fmac_f32_e32 v9, v8, v8
	v_add_f32_e32 v12, v15, v32
	v_add_f32_e32 v14, v10, v14
	v_fmac_f32_e32 v9, v10, v10
	v_add_f32_e32 v12, 0, v12
	v_fmac_f32_e32 v13, v15, v15
	v_add_f32_e32 v8, v11, v14
	v_fmac_f32_e32 v9, v11, v11
	v_sub_f32_e32 v11, v37, v43
	v_sub_f32_e32 v10, v36, v43
	v_add_f32_e32 v12, v8, v12
	v_add_f32_e32 v13, v13, v9
	v_sub_f32_e32 v9, v39, v43
	v_sub_f32_e32 v8, v38, v43
	v_pk_mul_f32 v[10:11], v[42:43], v[10:11] op_sel_hi:[0,1]
	v_pk_mul_f32 v[8:9], v[42:43], v[8:9] op_sel_hi:[0,1]
	v_mul_f32_e32 v15, v5, v5
	v_add_f32_e32 v14, v4, v5
	v_fmac_f32_e32 v15, v4, v4
	v_add_f32_e32 v14, v6, v14
	v_fmac_f32_e32 v15, v6, v6
	v_add_f32_e32 v14, v7, v14
	v_fmac_f32_e32 v15, v7, v7
	v_add_f32_e32 v12, v12, v14
	v_add_f32_e32 v13, v13, v15
	v_cvt_pk_bf16_f32 v4, v4, v5
	v_cvt_pk_bf16_f32 v5, v6, v7
	s_waitcnt vmcnt(0)
	v_pk_fma_f32 v[10:11], v[20:21], v[10:11], v[24:25]
	v_pk_fma_f32 v[8:9], v[22:23], v[8:9], v[26:27]
	v_pk_fma_f32 v[0:1], v[10:11], s[24:25], v[0:1] op_sel_hi:[1,0,1]
	v_pk_fma_f32 v[2:3], v[8:9], s[24:25], v[2:3] op_sel_hi:[1,0,1]
	v_pk_add_f32 v[8:9], v[28:29], v[0:1]
	v_pk_add_f32 v[10:11], v[30:31], v[2:3]
	v_mul_f32_e32 v1, v9, v9
	v_add_f32_e32 v0, v8, v9
	v_fmac_f32_e32 v1, v8, v8
	v_add_f32_e32 v0, v10, v0
	v_fmac_f32_e32 v1, v10, v10
	v_add_f32_e32 v0, v11, v0
	v_fmac_f32_e32 v1, v11, v11
	v_add_f32_e32 v0, v12, v0
	v_add_f32_e32 v1, v13, v1
	ds_bpermute_b32 v2, v118, v0
	ds_bpermute_b32 v3, v118, v1
	global_store_dwordx4 v[18:19], v[8:11], off offset:528
	v_cvt_pk_bf16_f32 v6, v8, v9
	v_cvt_pk_bf16_f32 v7, v10, v11
	s_waitcnt lgkmcnt(0)
	v_add_f32_e32 v0, v0, v2
	v_add_f32_e32 v1, v1, v3
	ds_bpermute_b32 v2, v119, v0
	ds_bpermute_b32 v3, v119, v1
	flat_store_dwordx4 v[40:41], v[4:7] offset:256
	s_mov_b32 s100, -1
	s_mov_b32 s101, 0
	s_mov_b32 s98, 0xffff0000
	s_mov_b32 s99, 0
	s_and_saveexec_b64 s[36:37], s[100:101]
	s_cbranch_execz .LBB0_1999
	s_waitcnt lgkmcnt(0)
	v_add_f32_e32 v3, v1, v3
	v_add_f32_e32 v2, v0, v2
	v_lshl_add_u64 v[0:1], s[8:9], 0, v[16:17]
	v_cndmask_b32_e64 v2, v2, v3, s[98:99]
	v_cndmask_b32_e64 v3, 0, 4, s[98:99]
	v_or_b32_e32 v0, v0, v3
	flat_atomic_add_f32 v[0:1], v2

; DEVI void row_stats(const float* stats, int row, float& mu, float& rs) {
;     if (stats) { const float2 st = *(const float2*)(stats + 2 * (size_t)row); mu = st.x * (1.0f / 1024.0f); const float var = st.y * (1.0f / 1024.0f) - mu * mu; rs = rsqrtf(fmaxf(var, 0.f) + LN_EPS); }
;     DEVI void operator()(const f32x4 (&acc)[2][2][4][2], const pg8::Unit& u, int wr, int wc, int fr, int fq) const {
;         const int row0 = u.pm * 256 + wr * 64 + fr, colb = u.pn * 256 + wc * 32 + 8 * fq;
; #pragma unroll
;         for (int ai = 0; ai < 2; ++ai)
; #pragma unroll
;             for (int m = 0; m < 4; ++m) {
;                 const int row = row0 + ai * 128 + m * 16; float mu, rs; row_stats(stin, row, mu, rs);
;                 float sum = 0.f, sq = 0.f;
; #pragma unroll
;                 for (int bj = 0; bj < 2; ++bj) {
;                     f32x4 z[2];
; #pragma unroll
;                     for (int n = 0; n < 2; ++n) {
;                         const int col = colb + bj * 128 + 4 * n;
;                         f32x4 xv = *(const f32x4*)(zsrc + (size_t)row * DM + col);
;                         if (stin) { const f32x4 gv = *(const f32x4*)(gin + col), bv = *(const f32x4*)(bin + col); xv = (xv - mu) * rs * gv + bv; }
;                         f32x4 zz = ALPHA * xv + acc[ai][bj][m][n];
;                         if (bias) zz += *(const f32x4*)(bias + col);
;                         *(f32x4*)(zdst + (size_t)row * DM + col) = zz;
;                         sum += zz[0] + zz[1] + zz[2] + zz[3]; sq += zz[0] * zz[0] + zz[1] * zz[1] + zz[2] * zz[2] + zz[3] * zz[3];
;                         z[n] = zz;
.LBB0_2192:
	v_lshl_add_u32 v154, s64, 8, v162
	v_ashrrev_i32_e32 v155, 31, v154
	v_lshlrev_b64 v[156:157], 3, v[154:155]
	v_lshl_add_u64 v[146:147], s[12:13], 0, v[156:157]
	s_waitcnt vmcnt(0)
	flat_load_dwordx2 v[160:161], v[146:147]
	v_lshl_or_b32 v144, s65, 8, v164
	v_ashrrev_i32_e32 v145, 31, v144
	v_lshlrev_b64 v[146:147], 12, v[154:155]
	v_lshl_add_u64 v[146:147], s[46:47], 0, v[146:147]
	v_lshlrev_b64 v[148:149], 2, v[144:145]
	v_lshl_add_u64 v[158:159], v[146:147], 0, v[148:149]
	global_load_dwordx4 v[170:173], v[158:159], off
	v_lshl_add_u64 v[150:151], s[16:17], 0, v[148:149]
	v_lshl_add_u64 v[152:153], s[18:19], 0, v[148:149]
	global_load_dwordx4 v[174:177], v[150:151], off
	global_load_dwordx4 v[178:181], v[152:153], off
	global_load_dwordx4 v[182:185], v[158:159], off offset:16
	v_or_b32_e32 v146, 4, v144
	v_ashrrev_i32_e32 v147, 31, v146
	v_lshlrev_b64 v[148:149], 2, v[146:147]
	v_lshl_add_u64 v[146:147], s[16:17], 0, v[148:149]
	v_lshl_add_u64 v[148:149], s[18:19], 0, v[148:149]
	v_or_b32_e32 v186, 0x80, v144
	v_ashrrev_i32_e32 v187, 31, v186
	s_waitcnt vmcnt(0) lgkmcnt(0)
	v_pk_mul_f32 v[160:161], v[160:161], s[24:25] op_sel:[1,0] op_sel_hi:[0,0]
	v_fma_f32 v160, -v161, v161, v160
	v_max_f32_e32 v160, 0, v160
	v_add_f32_e32 v160, 0x3727c5ac, v160
	v_mul_f32_e32 v169, 0x4b800000, v160
	v_cmp_gt_f32_e32 vcc, s61, v160
	v_sub_f32_e32 v171, v171, v161
	s_nop 0
	v_cndmask_b32_e32 v160, v160, v169, vcc
	v_rsq_f32_e32 v160, v160
	v_sub_f32_e32 v170, v170, v161
	v_sub_f32_e32 v173, v173, v161
	v_sub_f32_e32 v172, v172, v161
	v_mul_f32_e32 v169, 0x45800000, v160
	v_cndmask_b32_e32 v160, v160, v169, vcc
	v_pk_mul_f32 v[172:173], v[172:173], v[160:161] op_sel_hi:[1,0]
	v_pk_mul_f32 v[170:171], v[170:171], v[160:161] op_sel_hi:[1,0]
	v_pk_fma_f32 v[172:173], v[176:177], v[172:173], v[180:181]
	v_pk_fma_f32 v[170:171], v[174:175], v[170:171], v[178:179]
	v_pk_fma_f32 v[172:173], v[172:173], s[26:27], v[126:127] op_sel_hi:[1,0,1]
	v_pk_fma_f32 v[170:171], v[170:171], s[26:27], v[124:125] op_sel_hi:[1,0,1]
	global_store_dwordx4 v[158:159], v[170:173], off
	global_load_dwordx4 v[124:127], v[146:147], off
	global_load_dwordx4 v[174:177], v[148:149], off
	v_lshlrev_b64 v[178:179], 11, v[154:155]
	v_lshl_add_u64 v[178:179], s[14:15], 0, v[178:179]
	v_lshl_add_u64 v[194:195], v[144:145], 1, v[178:179]
	v_sub_f32_e32 v179, v183, v161
	v_sub_f32_e32 v178, v182, v161
	v_sub_f32_e32 v181, v185, v161
	v_sub_f32_e32 v180, v184, v161
	v_pk_mul_f32 v[180:181], v[180:181], v[160:161] op_sel_hi:[1,0]
	v_pk_mul_f32 v[182:183], v[178:179], v[160:161] op_sel_hi:[1,0]
	v_cvt_pk_bf16_f32 v178, v170, v171
	v_cvt_pk_bf16_f32 v179, v172, v173
	s_waitcnt vmcnt(0)
	v_pk_fma_f32 v[126:127], v[126:127], v[180:181], v[176:177]
	v_pk_fma_f32 v[124:125], v[124:125], v[182:183], v[174:175]
	v_pk_fma_f32 v[176:177], v[126:127], s[26:27], v[122:123] op_sel_hi:[1,0,1]
	v_pk_fma_f32 v[174:175], v[124:125], s[26:27], v[120:121] op_sel_hi:[1,0,1]
	global_store_dwordx4 v[158:159], v[174:177], off offset:16
	v_cvt_pk_bf16_f32 v180, v174, v175
	v_cvt_pk_bf16_f32 v181, v176, v177
	flat_store_dwordx4 v[194:195], v[178:181]
	global_load_dwordx4 v[178:181], v[158:159], off offset:512
	v_lshlrev_b64 v[122:123], 2, v[186:187]
	v_lshl_add_u64 v[120:121], s[16:17], 0, v[122:123]
	v_lshl_add_u64 v[122:123], s[18:19], 0, v[122:123]
	global_load_dwordx4 v[182:185], v[120:121], off
	global_load_dwordx4 v[186:189], v[122:123], off
	global_load_dwordx4 v[190:193], v[158:159], off offset:528
	v_or_b32_e32 v124, 0x84, v144
	v_ashrrev_i32_e32 v125, 31, v124
	v_lshlrev_b64 v[126:127], 2, v[124:125]
	v_lshl_add_u64 v[124:125], s[16:17], 0, v[126:127]
	v_lshl_add_u64 v[126:127], s[18:19], 0, v[126:127]
	v_mul_f32_e32 v169, v175, v175
	v_add_f32_e32 v155, v174, v175
	v_fmac_f32_e32 v169, v174, v174
	v_add_f32_e32 v155, v176, v155
	v_fmac_f32_e32 v169, v176, v176
	v_add_f32_e32 v155, v177, v155
	v_fmac_f32_e32 v169, v177, v177
	s_waitcnt vmcnt(0)
	v_sub_f32_e32 v179, v179, v161
	v_sub_f32_e32 v178, v178, v161
	v_sub_f32_e32 v181, v181, v161
	v_sub_f32_e32 v180, v180, v161
	v_pk_mul_f32 v[180:181], v[160:161], v[180:181] op_sel_hi:[0,1]
	v_pk_mul_f32 v[178:179], v[160:161], v[178:179] op_sel_hi:[0,1]
	v_pk_fma_f32 v[178:179], v[182:183], v[178:179], v[186:187]
	v_pk_fma_f32 v[180:181], v[184:185], v[180:181], v[188:189]
	v_pk_fma_f32 v[178:179], v[178:179], s[26:27], v[116:117] op_sel_hi:[1,0,1]
	v_pk_fma_f32 v[180:181], v[180:181], s[26:27], v[118:119] op_sel_hi:[1,0,1]
	global_store_dwordx4 v[158:159], v[178:181], off offset:512
	global_load_dwordx4 v[182:185], v[124:125], off
	global_load_dwordx4 v[186:189], v[126:127], off
	v_and_b32_e32 v117, 64, v168
	v_xor_b32_e32 v116, 16, v168
	v_add_u32_e32 v117, 64, v117
	v_xor_b32_e32 v118, 32, v168
	v_cmp_lt_i32_e32 vcc, v116, v117
	v_mul_f32_e32 v119, v171, v171
	v_fmac_f32_e32 v119, v170, v170
	v_cndmask_b32_e32 v116, v168, v116, vcc
	v_cmp_lt_i32_e32 vcc, v118, v117
	v_fmac_f32_e32 v119, v172, v172
	v_fmac_f32_e32 v119, v173, v173
	v_cndmask_b32_e32 v117, v168, v118, vcc
	v_add_f32_e32 v118, v170, v171
	v_add_f32_e32 v118, v172, v118
	v_add_f32_e32 v118, v173, v118
	v_add_f32_e32 v118, 0, v118
	v_add_f32_e32 v155, v155, v118
	v_add_f32_e32 v169, v119, v169
	v_sub_f32_e32 v119, v191, v161
	v_sub_f32_e32 v118, v190, v161
	v_sub_f32_e32 v171, v193, v161
	v_sub_f32_e32 v170, v192, v161
	v_pk_mul_f32 v[170:171], v[160:161], v[170:171] op_sel_hi:[0,1]
	v_pk_mul_f32 v[118:119], v[160:161], v[118:119] op_sel_hi:[0,1]
	v_mul_f32_e32 v161, v179, v179
	v_add_f32_e32 v160, v178, v179
	v_fmac_f32_e32 v161, v178, v178
	v_add_f32_e32 v160, v180, v160
	v_fmac_f32_e32 v161, v180, v180
	v_add_f32_e32 v160, v181, v160
	v_fmac_f32_e32 v161, v181, v181
	v_add_f32_e32 v155, v155, v160
	v_add_f32_e32 v169, v169, v161
	v_lshlrev_b32_e32 v116, 2, v116
	v_lshlrev_b32_e32 v117, 2, v117
	v_cvt_pk_bf16_f32 v174, v178, v179
	v_cvt_pk_bf16_f32 v175, v180, v181
	s_waitcnt vmcnt(0)
; DEVI unsigned pk2(float lo, float hi) { unsigned r; asm("v_cvt_pk_bf16_f32 %0, %1, %2" : "=v"(r) : "v"(lo), "v"(hi)); return r; }
; DEVI void row_stats(const float* stats, int row, float& mu, float& rs) {
;     if (stats) { const float2 st = *(const float2*)(stats + 2 * (size_t)row); mu = st.x * (1.0f / 1024.0f); const float var = st.y * (1.0f / 1024.0f) - mu * mu; rs = rsqrtf(fmaxf(var, 0.f) + LN_EPS); }
;     DEVI void operator()(const f32x4 (&acc)[2][2][4][2], const pg8::Unit& u, int wr, int wc, int fr, int fq) const {
;     ...
;                 const int row = row0 + ai * 128 + m * 16; float mu, rs; row_stats(stin, row, mu, rs);
;                 float sum = 0.f, sq = 0.f;
; #pragma unroll
;                 for (int bj = 0; bj < 2; ++bj) {
;                     f32x4 z[2];
; #pragma unroll
;                     for (int n = 0; n < 2; ++n) {
;                         const int col = colb + bj * 128 + 4 * n;
;                         f32x4 xv = *(const f32x4*)(zsrc + (size_t)row * DM + col);
;                         if (stin) { const f32x4 gv = *(const f32x4*)(gin + col), bv = *(const f32x4*)(bin + col); xv = (xv - mu) * rs * gv + bv; }
;                         f32x4 zz = ALPHA * xv + acc[ai][bj][m][n];
;                         if (bias) zz += *(const f32x4*)(bias + col);
;                         *(f32x4*)(zdst + (size_t)row * DM + col) = zz;
;                         sum += zz[0] + zz[1] + zz[2] + zz[3]; sq += zz[0] * zz[0] + zz[1] * zz[1] + zz[2] * zz[2] + zz[3] * zz[3];
;                         z[n] = zz;
;                     }
;                     u32x4 o; o.x = pk2(z[0][0], z[0][1]); o.y = pk2(z[0][2], z[0][3]); o.z = pk2(z[1][0], z[1][1]); o.w = pk2(z[1][2], z[1][3]);
;                     if (zb) *(u32x4*)(zb + (size_t)row * DM + colb + bj * 128) = o;
;                 }
;                 sum += __shfl_xor(sum, 16); sq += __shfl_xor(sq, 16);
;                 sum += __shfl_xor(sum, 32); sq += __shfl_xor(sq, 32);
;                 if (fq == 0) { atomicAdd(stout + 2 * (size_t)row, sum); atomicAdd(stout + 2 * (size_t)row + 1, sq); }
	v_pk_fma_f32 v[118:119], v[182:183], v[118:119], v[186:187]
	v_pk_fma_f32 v[160:161], v[184:185], v[170:171], v[188:189]
	v_pk_fma_f32 v[170:171], v[118:119], s[26:27], v[112:113] op_sel_hi:[1,0,1]
	v_pk_fma_f32 v[172:173], v[160:161], s[26:27], v[114:115] op_sel_hi:[1,0,1]
	v_mul_f32_e32 v113, v171, v171
	v_add_f32_e32 v112, v170, v171
	v_fmac_f32_e32 v113, v170, v170
	v_add_f32_e32 v112, v172, v112
	v_fmac_f32_e32 v113, v172, v172
	v_add_f32_e32 v112, v173, v112
	v_fmac_f32_e32 v113, v173, v173
	v_add_f32_e32 v112, v155, v112
	v_add_f32_e32 v113, v169, v113
	ds_bpermute_b32 v114, v116, v112
	ds_bpermute_b32 v115, v116, v113
	global_store_dwordx4 v[158:159], v[170:173], off offset:528
	v_cvt_pk_bf16_f32 v176, v170, v171
	v_cvt_pk_bf16_f32 v177, v172, v173
	s_waitcnt lgkmcnt(0)
	v_add_f32_e32 v112, v112, v114
	v_add_f32_e32 v113, v113, v115
	ds_bpermute_b32 v114, v117, v112
	ds_bpermute_b32 v115, v117, v113
	flat_store_dwordx4 v[194:195], v[174:177] offset:256
	s_mov_b32 s100, -1
	s_mov_b32 s101, 0
	s_mov_b32 s98, 0xffff0000
	s_mov_b32 s99, 0
	s_and_saveexec_b64 s[30:31], s[100:101]
	s_cbranch_execz .LBB0_2194
	s_waitcnt lgkmcnt(0)
	v_add_f32_e32 v115, v113, v115
	v_add_f32_e32 v114, v112, v114
	v_lshl_add_u64 v[112:113], s[10:11], 0, v[156:157]
	v_cndmask_b32_e64 v114, v114, v115, s[98:99]
	v_cndmask_b32_e64 v115, 0, 4, s[98:99]
	v_or_b32_e32 v112, v112, v115
	flat_atomic_add_f32 v[112:113], v114
.LBB0_2194:
	s_or_b64 exec, exec, s[30:31]
	v_or_b32_e32 v118, 16, v154
	v_ashrrev_i32_e32 v119, 31, v118
	v_lshlrev_b64 v[112:113], 3, v[118:119]
	s_waitcnt lgkmcnt(0)
	v_lshl_add_u64 v[114:115], s[12:13], 0, v[112:113]
	flat_load_dwordx2 v[160:161], v[114:115]
	v_lshlrev_b64 v[114:115], 12, v[118:119]
	v_lshl_add_u64 v[114:115], s[46:47], 0, v[114:115]
	v_lshl_add_u64 v[114:115], v[144:145], 2, v[114:115]
	global_load_dwordx4 v[156:159], v[114:115], off
	global_load_dwordx4 v[170:173], v[150:151], off
	global_load_dwordx4 v[174:177], v[152:153], off
	global_load_dwordx4 v[178:181], v[114:115], off offset:16
	v_lshlrev_b64 v[118:119], 11, v[118:119]
	v_lshl_add_u64 v[118:119], s[14:15], 0, v[118:119]
	v_lshl_add_u64 v[118:119], v[144:145], 1, v[118:119]
	s_waitcnt vmcnt(0) lgkmcnt(0)
	v_pk_mul_f32 v[160:161], v[160:161], s[24:25] op_sel:[1,0] op_sel_hi:[0,0]
	v_fma_f32 v155, -v161, v161, v160
	v_max_f32_e32 v155, 0, v155
	v_add_f32_e32 v155, 0x3727c5ac, v155
	v_mul_f32_e32 v160, 0x4b800000, v155
	v_cmp_gt_f32_e32 vcc, s61, v155
	v_sub_f32_e32 v157, v157, v161
	v_sub_f32_e32 v156, v156, v161
	v_cndmask_b32_e32 v155, v155, v160, vcc
	v_rsq_f32_e32 v155, v155
	v_sub_f32_e32 v159, v159, v161
	v_sub_f32_e32 v158, v158, v161
	v_mul_f32_e32 v160, 0x45800000, v155
	v_cndmask_b32_e32 v160, v155, v160, vcc
	v_pk_mul_f32 v[158:159], v[158:159], v[160:161] op_sel_hi:[1,0]
	v_pk_mul_f32 v[156:157], v[156:157], v[160:161] op_sel_hi:[1,0]
	v_pk_fma_f32 v[158:159], v[172:173], v[158:159], v[176:177]
	v_pk_fma_f32 v[156:157], v[170:171], v[156:157], v[174:175]
	v_pk_fma_f32 v[110:111], v[158:159], s[26:27], v[110:111] op_sel_hi:[1,0,1]
	v_pk_fma_f32 v[108:109], v[156:157], s[26:27], v[108:109] op_sel_hi:[1,0,1]
	global_store_dwordx4 v[114:115], v[108:111], off
	global_load_dwordx4 v[156:159], v[146:147], off
	global_load_dwordx4 v[170:173], v[148:149], off
	v_sub_f32_e32 v175, v179, v161
	v_sub_f32_e32 v174, v178, v161
	v_sub_f32_e32 v177, v181, v161
	v_sub_f32_e32 v176, v180, v161
	v_pk_mul_f32 v[176:177], v[176:177], v[160:161] op_sel_hi:[1,0]
	v_pk_mul_f32 v[178:179], v[174:175], v[160:161] op_sel_hi:[1,0]
	v_cvt_pk_bf16_f32 v174, v108, v109
	v_cvt_pk_bf16_f32 v175, v110, v111
	v_add_f32_e32 v155, v108, v109
	v_mul_f32_e32 v109, v109, v109
	v_fmac_f32_e32 v109, v108, v108
	v_add_f32_e32 v155, v110, v155
	v_fmac_f32_e32 v109, v110, v110
	v_add_f32_e32 v108, v111, v155
	v_add_f32_e32 v108, 0, v108
	v_fmac_f32_e32 v109, v111, v111
	s_waitcnt vmcnt(0)
	v_pk_fma_f32 v[156:157], v[156:157], v[178:179], v[170:171]
	v_pk_fma_f32 v[158:159], v[158:159], v[176:177], v[172:173]
	v_pk_fma_f32 v[104:105], v[156:157], s[26:27], v[104:105] op_sel_hi:[1,0,1]
	v_pk_fma_f32 v[106:107], v[158:159], s[26:27], v[106:107] op_sel_hi:[1,0,1]
	global_store_dwordx4 v[114:115], v[104:107], off offset:16
	v_cvt_pk_bf16_f32 v176, v104, v105
	v_cvt_pk_bf16_f32 v177, v106, v107
	flat_store_dwordx4 v[118:119], v[174:177]
	global_load_dwordx4 v[156:159], v[114:115], off offset:512
	global_load_dwordx4 v[170:173], v[120:121], off
	s_nop 0
	global_load_dwordx4 v[174:177], v[122:123], off
	global_load_dwordx4 v[178:181], v[114:115], off offset:528
	v_add_f32_e32 v110, v104, v105
	v_mul_f32_e32 v105, v105, v105
	v_fmac_f32_e32 v105, v104, v104
	v_add_f32_e32 v110, v106, v110
	v_fmac_f32_e32 v105, v106, v106
	v_add_f32_e32 v104, v107, v110
	v_fmac_f32_e32 v105, v107, v107
	v_add_f32_e32 v108, v104, v108
	v_add_f32_e32 v109, v109, v105
	s_waitcnt vmcnt(0)
	v_sub_f32_e32 v157, v157, v161
	v_sub_f32_e32 v156, v156, v161
	v_sub_f32_e32 v159, v159, v161
	v_sub_f32_e32 v158, v158, v161
	v_pk_mul_f32 v[158:159], v[160:161], v[158:159] op_sel_hi:[0,1]
	v_pk_mul_f32 v[156:157], v[160:161], v[156:157] op_sel_hi:[0,1]
	v_pk_fma_f32 v[156:157], v[170:171], v[156:157], v[174:175]
	v_pk_fma_f32 v[158:159], v[172:173], v[158:159], v[176:177]
	v_pk_fma_f32 v[100:101], v[156:157], s[26:27], v[100:101] op_sel_hi:[1,0,1]
	v_pk_fma_f32 v[102:103], v[158:159], s[26:27], v[102:103] op_sel_hi:[1,0,1]
	global_store_dwordx4 v[114:115], v[100:103], off offset:512
	global_load_dwordx4 v[156:159], v[124:125], off
	global_load_dwordx4 v[170:173], v[126:127], off
	v_sub_f32_e32 v105, v179, v161
	v_sub_f32_e32 v104, v178, v161
	v_pk_mul_f32 v[104:105], v[160:161], v[104:105] op_sel_hi:[0,1]
	v_sub_f32_e32 v107, v181, v161
	v_sub_f32_e32 v106, v180, v161
	v_pk_mul_f32 v[106:107], v[160:161], v[106:107] op_sel_hi:[0,1]
	v_mul_f32_e32 v111, v101, v101
	v_add_f32_e32 v110, v100, v101
	v_fmac_f32_e32 v111, v100, v100
	v_add_f32_e32 v110, v102, v110
	v_fmac_f32_e32 v111, v102, v102
	v_add_f32_e32 v110, v103, v110
	v_fmac_f32_e32 v111, v103, v103
	v_add_f32_e32 v108, v108, v110
	v_add_f32_e32 v109, v109, v111
	v_cvt_pk_bf16_f32 v100, v100, v101
	v_cvt_pk_bf16_f32 v101, v102, v103
	s_waitcnt vmcnt(0)
; DEVI unsigned pk2(float lo, float hi) { unsigned r; asm("v_cvt_pk_bf16_f32 %0, %1, %2" : "=v"(r) : "v"(lo), "v"(hi)); return r; }
; DEVI void row_stats(const float* stats, int row, float& mu, float& rs) {
;     if (stats) { const float2 st = *(const float2*)(stats + 2 * (size_t)row); mu = st.x * (1.0f / 1024.0f); const float var = st.y * (1.0f / 1024.0f) - mu * mu; rs = rsqrtf(fmaxf(var, 0.f) + LN_EPS); }
;     DEVI void operator()(const f32x4 (&acc)[2][2][4][2], const pg8::Unit& u, int wr, int wc, int fr, int fq) const {
;     ...
;                 const int row = row0 + ai * 128 + m * 16; float mu, rs; row_stats(stin, row, mu, rs);
;                 float sum = 0.f, sq = 0.f;
; #pragma unroll
;                 for (int bj = 0; bj < 2; ++bj) {
;                     f32x4 z[2];
; #pragma unroll
;                     for (int n = 0; n < 2; ++n) {
;                         const int col = colb + bj * 128 + 4 * n;
;                         f32x4 xv = *(const f32x4*)(zsrc + (size_t)row * DM + col);
;                         if (stin) { const f32x4 gv = *(const f32x4*)(gin + col), bv = *(const f32x4*)(bin + col); xv = (xv - mu) * rs * gv + bv; }
;                         f32x4 zz = ALPHA * xv + acc[ai][bj][m][n];
;                         if (bias) zz += *(const f32x4*)(bias + col);
;                         *(f32x4*)(zdst + (size_t)row * DM + col) = zz;
;                         sum += zz[0] + zz[1] + zz[2] + zz[3]; sq += zz[0] * zz[0] + zz[1] * zz[1] + zz[2] * zz[2] + zz[3] * zz[3];
;                         z[n] = zz;
;                     }
;                     u32x4 o; o.x = pk2(z[0][0], z[0][1]); o.y = pk2(z[0][2], z[0][3]); o.z = pk2(z[1][0], z[1][1]); o.w = pk2(z[1][2], z[1][3]);
;                     if (zb) *(u32x4*)(zb + (size_t)row * DM + colb + bj * 128) = o;
;                 }
;                 sum += __shfl_xor(sum, 16); sq += __shfl_xor(sq, 16);
;                 sum += __shfl_xor(sum, 32); sq += __shfl_xor(sq, 32);
;                 if (fq == 0) { atomicAdd(stout + 2 * (size_t)row, sum); atomicAdd(stout + 2 * (size_t)row + 1, sq); }
	v_pk_fma_f32 v[104:105], v[156:157], v[104:105], v[170:171]
	s_nop 0
	v_pk_fma_f32 v[104:105], v[104:105], s[26:27], v[96:97] op_sel_hi:[1,0,1]
	v_pk_fma_f32 v[106:107], v[158:159], v[106:107], v[172:173]
	v_mul_f32_e32 v97, v105, v105
	v_pk_fma_f32 v[106:107], v[106:107], s[26:27], v[98:99] op_sel_hi:[1,0,1]
	v_add_f32_e32 v96, v104, v105
	v_fmac_f32_e32 v97, v104, v104
	v_add_f32_e32 v96, v106, v96
	v_fmac_f32_e32 v97, v106, v106
	v_add_f32_e32 v96, v107, v96
	v_fmac_f32_e32 v97, v107, v107
	v_add_f32_e32 v96, v108, v96
	v_add_f32_e32 v97, v109, v97
	ds_bpermute_b32 v98, v116, v96
	ds_bpermute_b32 v99, v116, v97
	global_store_dwordx4 v[114:115], v[104:107], off offset:528
	v_cvt_pk_bf16_f32 v102, v104, v105
	v_cvt_pk_bf16_f32 v103, v106, v107
	s_waitcnt lgkmcnt(0)
	v_add_f32_e32 v96, v96, v98
	v_add_f32_e32 v97, v97, v99
	ds_bpermute_b32 v98, v117, v96
	ds_bpermute_b32 v99, v117, v97
	flat_store_dwordx4 v[118:119], v[100:103] offset:256
	s_mov_b32 s100, -1
	s_mov_b32 s101, 0
	s_mov_b32 s98, 0xffff0000
	s_mov_b32 s99, 0
	s_and_saveexec_b64 s[30:31], s[100:101]
	s_cbranch_execz .LBB0_2196
	s_waitcnt lgkmcnt(0)
	v_add_f32_e32 v99, v97, v99
	v_add_f32_e32 v98, v96, v98
	v_lshl_add_u64 v[96:97], s[10:11], 0, v[112:113]
	v_cndmask_b32_e64 v98, v98, v99, s[98:99]
	v_cndmask_b32_e64 v99, 0, 4, s[98:99]
	v_or_b32_e32 v96, v96, v99
	flat_atomic_add_f32 v[96:97], v98
.LBB0_2196:
	s_or_b64 exec, exec, s[30:31]
	v_or_b32_e32 v118, 32, v154
	v_ashrrev_i32_e32 v119, 31, v118
	v_lshlrev_b64 v[96:97], 3, v[118:119]
	s_waitcnt lgkmcnt(0)
	v_lshl_add_u64 v[98:99], s[12:13], 0, v[96:97]
	flat_load_dwordx2 v[156:157], v[98:99]
	v_lshlrev_b64 v[98:99], 12, v[118:119]
	v_lshl_add_u64 v[98:99], s[46:47], 0, v[98:99]
	v_lshl_add_u64 v[98:99], v[144:145], 2, v[98:99]
	global_load_dwordx4 v[100:103], v[98:99], off
	global_load_dwordx4 v[104:107], v[150:151], off
	global_load_dwordx4 v[108:111], v[152:153], off
	global_load_dwordx4 v[112:115], v[98:99], off offset:16
	s_waitcnt vmcnt(0) lgkmcnt(0)
	v_pk_mul_f32 v[156:157], v[156:157], s[24:25] op_sel:[1,0] op_sel_hi:[0,0]
	v_fma_f32 v155, -v157, v157, v156
	v_max_f32_e32 v155, 0, v155
	v_add_f32_e32 v155, 0x3727c5ac, v155
	v_mul_f32_e32 v156, 0x4b800000, v155
	v_cmp_gt_f32_e32 vcc, s61, v155
	v_sub_f32_e32 v101, v101, v157
	v_sub_f32_e32 v100, v100, v157
	v_cndmask_b32_e32 v155, v155, v156, vcc
	v_rsq_f32_e32 v155, v155
	v_sub_f32_e32 v103, v103, v157
	v_sub_f32_e32 v102, v102, v157
	v_mul_f32_e32 v156, 0x45800000, v155
	v_cndmask_b32_e32 v156, v155, v156, vcc
	v_pk_mul_f32 v[102:103], v[102:103], v[156:157] op_sel_hi:[1,0]
	v_pk_mul_f32 v[100:101], v[100:101], v[156:157] op_sel_hi:[1,0]
	v_pk_fma_f32 v[102:103], v[106:107], v[102:103], v[110:111]
	v_pk_fma_f32 v[100:101], v[104:105], v[100:101], v[108:109]
	v_pk_fma_f32 v[94:95], v[102:103], s[26:27], v[94:95] op_sel_hi:[1,0,1]
	v_pk_fma_f32 v[92:93], v[100:101], s[26:27], v[92:93] op_sel_hi:[1,0,1]
	global_store_dwordx4 v[98:99], v[92:95], off
	global_load_dwordx4 v[100:103], v[146:147], off
	global_load_dwordx4 v[104:107], v[148:149], off
	v_lshlrev_b64 v[108:109], 11, v[118:119]
	v_lshl_add_u64 v[108:109], s[14:15], 0, v[108:109]
	v_lshl_add_u64 v[118:119], v[144:145], 1, v[108:109]
	v_sub_f32_e32 v109, v113, v157
	v_sub_f32_e32 v108, v112, v157
	v_sub_f32_e32 v111, v115, v157
	v_sub_f32_e32 v110, v114, v157
	v_pk_mul_f32 v[110:111], v[110:111], v[156:157] op_sel_hi:[1,0]
	v_pk_mul_f32 v[112:113], v[108:109], v[156:157] op_sel_hi:[1,0]
	v_cvt_pk_bf16_f32 v108, v92, v93
	v_cvt_pk_bf16_f32 v109, v94, v95
	s_waitcnt vmcnt(0)
	v_pk_fma_f32 v[102:103], v[102:103], v[110:111], v[106:107]
	v_pk_fma_f32 v[100:101], v[100:101], v[112:113], v[104:105]
	v_pk_fma_f32 v[90:91], v[102:103], s[26:27], v[90:91] op_sel_hi:[1,0,1]
	v_pk_fma_f32 v[88:89], v[100:101], s[26:27], v[88:89] op_sel_hi:[1,0,1]
	global_store_dwordx4 v[98:99], v[88:91], off offset:16
	v_cvt_pk_bf16_f32 v110, v88, v89
	v_cvt_pk_bf16_f32 v111, v90, v91
	flat_store_dwordx4 v[118:119], v[108:111]
	global_load_dwordx4 v[100:103], v[98:99], off offset:512
	global_load_dwordx4 v[104:107], v[120:121], off
	s_nop 0
	global_load_dwordx4 v[108:111], v[122:123], off
	global_load_dwordx4 v[112:115], v[98:99], off offset:528
	s_waitcnt vmcnt(0)
	v_sub_f32_e32 v101, v101, v157
	v_sub_f32_e32 v100, v100, v157
	v_sub_f32_e32 v103, v103, v157
	v_sub_f32_e32 v102, v102, v157
	v_pk_mul_f32 v[102:103], v[156:157], v[102:103] op_sel_hi:[0,1]
	v_pk_mul_f32 v[100:101], v[156:157], v[100:101] op_sel_hi:[0,1]
	v_pk_fma_f32 v[100:101], v[104:105], v[100:101], v[108:109]
	v_pk_fma_f32 v[102:103], v[106:107], v[102:103], v[110:111]
	v_pk_fma_f32 v[84:85], v[100:101], s[26:27], v[84:85] op_sel_hi:[1,0,1]
	v_pk_fma_f32 v[86:87], v[102:103], s[26:27], v[86:87] op_sel_hi:[1,0,1]
	global_store_dwordx4 v[98:99], v[84:87], off offset:512
	global_load_dwordx4 v[100:103], v[124:125], off
	global_load_dwordx4 v[104:107], v[126:127], off
	v_add_f32_e32 v108, v92, v93
	v_mul_f32_e32 v93, v93, v93
	v_fmac_f32_e32 v93, v92, v92
	v_add_f32_e32 v108, v94, v108
	v_fmac_f32_e32 v93, v94, v94
	v_add_f32_e32 v94, v88, v89
	v_mul_f32_e32 v89, v89, v89
	v_fmac_f32_e32 v89, v88, v88
	v_add_f32_e32 v92, v95, v108
	v_add_f32_e32 v94, v90, v94
	v_fmac_f32_e32 v89, v90, v90
	v_add_f32_e32 v92, 0, v92
	v_fmac_f32_e32 v93, v95, v95
	v_add_f32_e32 v88, v91, v94
	v_fmac_f32_e32 v89, v91, v91
	v_add_f32_e32 v92, v88, v92
	v_add_f32_e32 v93, v93, v89
	v_sub_f32_e32 v89, v113, v157
	v_sub_f32_e32 v88, v112, v157
	v_pk_mul_f32 v[88:89], v[156:157], v[88:89] op_sel_hi:[0,1]
	v_sub_f32_e32 v91, v115, v157
	v_sub_f32_e32 v90, v114, v157
	v_pk_mul_f32 v[90:91], v[156:157], v[90:91] op_sel_hi:[0,1]
	v_mul_f32_e32 v95, v85, v85
	v_add_f32_e32 v94, v84, v85
	v_fmac_f32_e32 v95, v84, v84
	v_add_f32_e32 v94, v86, v94
	v_fmac_f32_e32 v95, v86, v86
	v_add_f32_e32 v94, v87, v94
	v_fmac_f32_e32 v95, v87, v87
	v_add_f32_e32 v92, v92, v94
	v_add_f32_e32 v93, v93, v95
	v_cvt_pk_bf16_f32 v84, v84, v85
	v_cvt_pk_bf16_f32 v85, v86, v87
	s_waitcnt vmcnt(0)
; DEVI unsigned pk2(float lo, float hi) { unsigned r; asm("v_cvt_pk_bf16_f32 %0, %1, %2" : "=v"(r) : "v"(lo), "v"(hi)); return r; }
; DEVI void row_stats(const float* stats, int row, float& mu, float& rs) {
;     if (stats) { const float2 st = *(const float2*)(stats + 2 * (size_t)row); mu = st.x * (1.0f / 1024.0f); const float var = st.y * (1.0f / 1024.0f) - mu * mu; rs = rsqrtf(fmaxf(var, 0.f) + LN_EPS); }
;     DEVI void operator()(const f32x4 (&acc)[2][2][4][2], const pg8::Unit& u, int wr, int wc, int fr, int fq) const {
;     ...
;                 const int row = row0 + ai * 128 + m * 16; float mu, rs; row_stats(stin, row, mu, rs);
;                 float sum = 0.f, sq = 0.f;
; #pragma unroll
;                 for (int bj = 0; bj < 2; ++bj) {
;                     f32x4 z[2];
; #pragma unroll
;                     for (int n = 0; n < 2; ++n) {
;                         const int col = colb + bj * 128 + 4 * n;
;                         f32x4 xv = *(const f32x4*)(zsrc + (size_t)row * DM + col);
;                         if (stin) { const f32x4 gv = *(const f32x4*)(gin + col), bv = *(const f32x4*)(bin + col); xv = (xv - mu) * rs * gv + bv; }
;                         f32x4 zz = ALPHA * xv + acc[ai][bj][m][n];
;                         if (bias) zz += *(const f32x4*)(bias + col);
;                         *(f32x4*)(zdst + (size_t)row * DM + col) = zz;
;                         sum += zz[0] + zz[1] + zz[2] + zz[3]; sq += zz[0] * zz[0] + zz[1] * zz[1] + zz[2] * zz[2] + zz[3] * zz[3];
;                         z[n] = zz;
;                     }
;                     u32x4 o; o.x = pk2(z[0][0], z[0][1]); o.y = pk2(z[0][2], z[0][3]); o.z = pk2(z[1][0], z[1][1]); o.w = pk2(z[1][2], z[1][3]);
;                     if (zb) *(u32x4*)(zb + (size_t)row * DM + colb + bj * 128) = o;
;                 }
;                 sum += __shfl_xor(sum, 16); sq += __shfl_xor(sq, 16);
;                 sum += __shfl_xor(sum, 32); sq += __shfl_xor(sq, 32);
;                 if (fq == 0) { atomicAdd(stout + 2 * (size_t)row, sum); atomicAdd(stout + 2 * (size_t)row + 1, sq); }
	v_pk_fma_f32 v[88:89], v[100:101], v[88:89], v[104:105]
	s_nop 0
	v_pk_fma_f32 v[88:89], v[88:89], s[26:27], v[80:81] op_sel_hi:[1,0,1]
	v_pk_fma_f32 v[90:91], v[102:103], v[90:91], v[106:107]
	v_mul_f32_e32 v81, v89, v89
	v_pk_fma_f32 v[90:91], v[90:91], s[26:27], v[82:83] op_sel_hi:[1,0,1]
	v_add_f32_e32 v80, v88, v89
	v_fmac_f32_e32 v81, v88, v88
	v_add_f32_e32 v80, v90, v80
	v_fmac_f32_e32 v81, v90, v90
	v_add_f32_e32 v80, v91, v80
	v_fmac_f32_e32 v81, v91, v91
	v_add_f32_e32 v80, v92, v80
	v_add_f32_e32 v81, v93, v81
	ds_bpermute_b32 v82, v116, v80
	ds_bpermute_b32 v83, v116, v81
	global_store_dwordx4 v[98:99], v[88:91], off offset:528
	v_cvt_pk_bf16_f32 v86, v88, v89
	v_cvt_pk_bf16_f32 v87, v90, v91
	s_waitcnt lgkmcnt(0)
	v_add_f32_e32 v80, v80, v82
	v_add_f32_e32 v81, v81, v83
	ds_bpermute_b32 v82, v117, v80
	ds_bpermute_b32 v83, v117, v81
	flat_store_dwordx4 v[118:119], v[84:87] offset:256
	s_mov_b32 s100, -1
	s_mov_b32 s101, 0
	s_mov_b32 s98, 0xffff0000
	s_mov_b32 s99, 0
	s_and_saveexec_b64 s[30:31], s[100:101]
	s_cbranch_execz .LBB0_2198
	s_waitcnt lgkmcnt(0)
	v_add_f32_e32 v83, v81, v83
	v_add_f32_e32 v82, v80, v82
	v_lshl_add_u64 v[80:81], s[10:11], 0, v[96:97]
	v_cndmask_b32_e64 v82, v82, v83, s[98:99]
	v_cndmask_b32_e64 v83, 0, 4, s[98:99]
	v_or_b32_e32 v80, v80, v83
	flat_atomic_add_f32 v[80:81], v82
.LBB0_2198:
	s_or_b64 exec, exec, s[30:31]
	v_or_b32_e32 v100, 48, v154
	v_ashrrev_i32_e32 v101, 31, v100
	v_lshlrev_b64 v[80:81], 3, v[100:101]
	s_waitcnt lgkmcnt(0)
	v_lshl_add_u64 v[82:83], s[12:13], 0, v[80:81]
	flat_load_dwordx2 v[102:103], v[82:83]
	v_lshlrev_b64 v[82:83], 12, v[100:101]
	v_lshl_add_u64 v[82:83], s[46:47], 0, v[82:83]
	v_lshl_add_u64 v[82:83], v[144:145], 2, v[82:83]
	global_load_dwordx4 v[84:87], v[82:83], off
	global_load_dwordx4 v[88:91], v[150:151], off
	global_load_dwordx4 v[92:95], v[152:153], off
	global_load_dwordx4 v[96:99], v[82:83], off offset:16
	s_waitcnt vmcnt(0) lgkmcnt(0)
	v_pk_mul_f32 v[102:103], v[102:103], s[24:25] op_sel:[1,0] op_sel_hi:[0,0]
	v_fma_f32 v102, -v103, v103, v102
	v_max_f32_e32 v102, 0, v102
	v_add_f32_e32 v102, 0x3727c5ac, v102
	v_mul_f32_e32 v104, 0x4b800000, v102
	v_cmp_gt_f32_e32 vcc, s61, v102
	v_sub_f32_e32 v85, v85, v103
	v_sub_f32_e32 v84, v84, v103
	v_cndmask_b32_e32 v102, v102, v104, vcc
	v_rsq_f32_e32 v102, v102
	v_sub_f32_e32 v87, v87, v103
	v_sub_f32_e32 v86, v86, v103
	v_mul_f32_e32 v104, 0x45800000, v102
	v_cndmask_b32_e32 v102, v102, v104, vcc
	v_pk_mul_f32 v[86:87], v[86:87], v[102:103] op_sel_hi:[1,0]
	v_pk_mul_f32 v[84:85], v[84:85], v[102:103] op_sel_hi:[1,0]
	v_pk_fma_f32 v[86:87], v[90:91], v[86:87], v[94:95]
	v_pk_fma_f32 v[84:85], v[88:89], v[84:85], v[92:93]
	v_pk_fma_f32 v[78:79], v[86:87], s[26:27], v[78:79] op_sel_hi:[1,0,1]
	v_pk_fma_f32 v[76:77], v[84:85], s[26:27], v[76:77] op_sel_hi:[1,0,1]
	global_store_dwordx4 v[82:83], v[76:79], off
	global_load_dwordx4 v[84:87], v[146:147], off
	global_load_dwordx4 v[88:91], v[148:149], off
	v_lshlrev_b64 v[92:93], 11, v[100:101]
	v_lshl_add_u64 v[92:93], s[14:15], 0, v[92:93]
	v_lshl_add_u64 v[100:101], v[144:145], 1, v[92:93]
	v_sub_f32_e32 v93, v97, v103
	v_sub_f32_e32 v92, v96, v103
	v_sub_f32_e32 v95, v99, v103
	v_sub_f32_e32 v94, v98, v103
	v_pk_mul_f32 v[94:95], v[94:95], v[102:103] op_sel_hi:[1,0]
	v_pk_mul_f32 v[96:97], v[92:93], v[102:103] op_sel_hi:[1,0]
	v_cvt_pk_bf16_f32 v92, v76, v77
	v_cvt_pk_bf16_f32 v93, v78, v79
	s_waitcnt vmcnt(0)
	v_pk_fma_f32 v[86:87], v[86:87], v[94:95], v[90:91]
	v_pk_fma_f32 v[84:85], v[84:85], v[96:97], v[88:89]
	v_pk_fma_f32 v[74:75], v[86:87], s[26:27], v[74:75] op_sel_hi:[1,0,1]
	v_pk_fma_f32 v[72:73], v[84:85], s[26:27], v[72:73] op_sel_hi:[1,0,1]
	global_store_dwordx4 v[82:83], v[72:75], off offset:16
	v_cvt_pk_bf16_f32 v94, v72, v73
	v_cvt_pk_bf16_f32 v95, v74, v75
	flat_store_dwordx4 v[100:101], v[92:95]
	global_load_dwordx4 v[84:87], v[82:83], off offset:512
	global_load_dwordx4 v[88:91], v[120:121], off
	s_nop 0
	global_load_dwordx4 v[92:95], v[122:123], off
	global_load_dwordx4 v[96:99], v[82:83], off offset:528
	s_waitcnt vmcnt(0)
	v_sub_f32_e32 v85, v85, v103
	v_sub_f32_e32 v84, v84, v103
	v_sub_f32_e32 v87, v87, v103
	v_sub_f32_e32 v86, v86, v103
	v_pk_mul_f32 v[86:87], v[102:103], v[86:87] op_sel_hi:[0,1]
	v_pk_mul_f32 v[84:85], v[102:103], v[84:85] op_sel_hi:[0,1]
	v_pk_fma_f32 v[84:85], v[88:89], v[84:85], v[92:93]
	v_pk_fma_f32 v[86:87], v[90:91], v[86:87], v[94:95]
	v_pk_fma_f32 v[68:69], v[84:85], s[26:27], v[68:69] op_sel_hi:[1,0,1]
	v_pk_fma_f32 v[70:71], v[86:87], s[26:27], v[70:71] op_sel_hi:[1,0,1]
	global_store_dwordx4 v[82:83], v[68:71], off offset:512
	global_load_dwordx4 v[84:87], v[124:125], off
	global_load_dwordx4 v[88:91], v[126:127], off
	v_add_f32_e32 v92, v76, v77
	v_mul_f32_e32 v77, v77, v77
	v_fmac_f32_e32 v77, v76, v76
	v_add_f32_e32 v92, v78, v92
	v_fmac_f32_e32 v77, v78, v78
	v_add_f32_e32 v78, v72, v73
	v_mul_f32_e32 v73, v73, v73
	v_fmac_f32_e32 v73, v72, v72
	v_add_f32_e32 v76, v79, v92
	v_add_f32_e32 v78, v74, v78
	v_fmac_f32_e32 v73, v74, v74
	v_add_f32_e32 v76, 0, v76
	v_fmac_f32_e32 v77, v79, v79
	v_add_f32_e32 v72, v75, v78
	v_fmac_f32_e32 v73, v75, v75
	v_add_f32_e32 v76, v72, v76
	v_add_f32_e32 v77, v77, v73
	v_sub_f32_e32 v73, v97, v103
	v_sub_f32_e32 v72, v96, v103
	v_pk_mul_f32 v[72:73], v[102:103], v[72:73] op_sel_hi:[0,1]
	v_sub_f32_e32 v75, v99, v103
	v_sub_f32_e32 v74, v98, v103
	v_pk_mul_f32 v[74:75], v[102:103], v[74:75] op_sel_hi:[0,1]
	v_mul_f32_e32 v79, v69, v69
	v_add_f32_e32 v78, v68, v69
	v_fmac_f32_e32 v79, v68, v68
	v_add_f32_e32 v78, v70, v78
	v_fmac_f32_e32 v79, v70, v70
	v_add_f32_e32 v78, v71, v78
	v_fmac_f32_e32 v79, v71, v71
	v_add_f32_e32 v76, v76, v78
	v_add_f32_e32 v77, v77, v79
	v_cvt_pk_bf16_f32 v68, v68, v69
	v_cvt_pk_bf16_f32 v69, v70, v71
	s_waitcnt vmcnt(0)
	v_pk_fma_f32 v[72:73], v[84:85], v[72:73], v[88:89]
	s_nop 0
	v_pk_fma_f32 v[72:73], v[72:73], s[26:27], v[64:65] op_sel_hi:[1,0,1]
	v_pk_fma_f32 v[74:75], v[86:87], v[74:75], v[90:91]
	v_mul_f32_e32 v65, v73, v73
	v_pk_fma_f32 v[74:75], v[74:75], s[26:27], v[66:67] op_sel_hi:[1,0,1]
	v_add_f32_e32 v64, v72, v73
	v_fmac_f32_e32 v65, v72, v72
	v_add_f32_e32 v64, v74, v64
	v_fmac_f32_e32 v65, v74, v74
	v_add_f32_e32 v64, v75, v64
	v_fmac_f32_e32 v65, v75, v75
	v_add_f32_e32 v64, v76, v64
	v_add_f32_e32 v65, v77, v65
	ds_bpermute_b32 v66, v116, v64
	ds_bpermute_b32 v67, v116, v65
	global_store_dwordx4 v[82:83], v[72:75], off offset:528
	v_cvt_pk_bf16_f32 v70, v72, v73
	v_cvt_pk_bf16_f32 v71, v74, v75
	s_waitcnt lgkmcnt(0)
	v_add_f32_e32 v64, v64, v66
	v_add_f32_e32 v65, v65, v67
	ds_bpermute_b32 v66, v117, v64
	ds_bpermute_b32 v67, v117, v65
	flat_store_dwordx4 v[100:101], v[68:71] offset:256
	s_mov_b32 s100, -1
	s_mov_b32 s101, 0
	s_mov_b32 s98, 0xffff0000
	s_mov_b32 s99, 0
	s_and_saveexec_b64 s[30:31], s[100:101]
	s_cbranch_execz .LBB0_2200
; DEVI unsigned pk2(float lo, float hi) { unsigned r; asm("v_cvt_pk_bf16_f32 %0, %1, %2" : "=v"(r) : "v"(lo), "v"(hi)); return r; }
; DEVI void row_stats(const float* stats, int row, float& mu, float& rs) {
;     if (stats) { const float2 st = *(const float2*)(stats + 2 * (size_t)row); mu = st.x * (1.0f / 1024.0f); const float var = st.y * (1.0f / 1024.0f) - mu * mu; rs = rsqrtf(fmaxf(var, 0.f) + LN_EPS); }
;     DEVI void operator()(const f32x4 (&acc)[2][2][4][2], const pg8::Unit& u, int wr, int wc, int fr, int fq) const {
;     ...
;                 const int row = row0 + ai * 128 + m * 16; float mu, rs; row_stats(stin, row, mu, rs);
;                 float sum = 0.f, sq = 0.f;
; #pragma unroll
;                 for (int bj = 0; bj < 2; ++bj) {
;                     f32x4 z[2];
; #pragma unroll
;                     for (int n = 0; n < 2; ++n) {
;                         const int col = colb + bj * 128 + 4 * n;
;                         f32x4 xv = *(const f32x4*)(zsrc + (size_t)row * DM + col);
;                         if (stin) { const f32x4 gv = *(const f32x4*)(gin + col), bv = *(const f32x4*)(bin + col); xv = (xv - mu) * rs * gv + bv; }
;                         f32x4 zz = ALPHA * xv + acc[ai][bj][m][n];
;                         if (bias) zz += *(const f32x4*)(bias + col);
;                         *(f32x4*)(zdst + (size_t)row * DM + col) = zz;
;                         sum += zz[0] + zz[1] + zz[2] + zz[3]; sq += zz[0] * zz[0] + zz[1] * zz[1] + zz[2] * zz[2] + zz[3] * zz[3];
;                         z[n] = zz;
;                     }
;                     u32x4 o; o.x = pk2(z[0][0], z[0][1]); o.y = pk2(z[0][2], z[0][3]); o.z = pk2(z[1][0], z[1][1]); o.w = pk2(z[1][2], z[1][3]);
;                     if (zb) *(u32x4*)(zb + (size_t)row * DM + colb + bj * 128) = o;
;                 }
;                 sum += __shfl_xor(sum, 16); sq += __shfl_xor(sq, 16);
;                 sum += __shfl_xor(sum, 32); sq += __shfl_xor(sq, 32);
;                 if (fq == 0) { atomicAdd(stout + 2 * (size_t)row, sum); atomicAdd(stout + 2 * (size_t)row + 1, sq); }
	s_waitcnt lgkmcnt(0)
	v_add_f32_e32 v67, v65, v67
	v_add_f32_e32 v66, v64, v66
	v_lshl_add_u64 v[64:65], s[10:11], 0, v[80:81]
	v_cndmask_b32_e64 v66, v66, v67, s[98:99]
	v_cndmask_b32_e64 v67, 0, 4, s[98:99]
	v_or_b32_e32 v64, v64, v67
	flat_atomic_add_f32 v[64:65], v66
.LBB0_2200:
	s_or_b64 exec, exec, s[30:31]
	v_add_u32_e32 v84, 0x80, v154
	v_ashrrev_i32_e32 v85, 31, v84
	v_lshlrev_b64 v[64:65], 3, v[84:85]
	s_waitcnt lgkmcnt(0)
	v_lshl_add_u64 v[66:67], s[12:13], 0, v[64:65]
	flat_load_dwordx2 v[86:87], v[66:67]
	v_lshlrev_b64 v[66:67], 12, v[84:85]
	v_lshl_add_u64 v[66:67], s[46:47], 0, v[66:67]
	v_lshl_add_u64 v[66:67], v[144:145], 2, v[66:67]
	global_load_dwordx4 v[68:71], v[66:67], off
	global_load_dwordx4 v[72:75], v[150:151], off
	global_load_dwordx4 v[76:79], v[152:153], off
	global_load_dwordx4 v[80:83], v[66:67], off offset:16
	s_waitcnt vmcnt(0) lgkmcnt(0)
	v_pk_mul_f32 v[86:87], v[86:87], s[24:25] op_sel:[1,0] op_sel_hi:[0,0]
	v_fma_f32 v86, -v87, v87, v86
	v_max_f32_e32 v86, 0, v86
	v_add_f32_e32 v86, 0x3727c5ac, v86
	v_mul_f32_e32 v88, 0x4b800000, v86
	v_cmp_gt_f32_e32 vcc, s61, v86
	v_sub_f32_e32 v69, v69, v87
	v_sub_f32_e32 v68, v68, v87
	v_cndmask_b32_e32 v86, v86, v88, vcc
	v_rsq_f32_e32 v86, v86
	v_sub_f32_e32 v71, v71, v87
	v_sub_f32_e32 v70, v70, v87
	v_mul_f32_e32 v88, 0x45800000, v86
	v_cndmask_b32_e32 v86, v86, v88, vcc
	v_pk_mul_f32 v[70:71], v[70:71], v[86:87] op_sel_hi:[1,0]
	v_pk_mul_f32 v[68:69], v[68:69], v[86:87] op_sel_hi:[1,0]
	v_pk_fma_f32 v[70:71], v[74:75], v[70:71], v[78:79]
	v_pk_fma_f32 v[68:69], v[72:73], v[68:69], v[76:77]
	v_pk_fma_f32 v[62:63], v[70:71], s[26:27], v[62:63] op_sel_hi:[1,0,1]
	v_pk_fma_f32 v[60:61], v[68:69], s[26:27], v[60:61] op_sel_hi:[1,0,1]
	global_store_dwordx4 v[66:67], v[60:63], off
	global_load_dwordx4 v[68:71], v[146:147], off
	global_load_dwordx4 v[72:75], v[148:149], off
	v_lshlrev_b64 v[76:77], 11, v[84:85]
	v_lshl_add_u64 v[76:77], s[14:15], 0, v[76:77]
	v_lshl_add_u64 v[84:85], v[144:145], 1, v[76:77]
	v_sub_f32_e32 v77, v81, v87
	v_sub_f32_e32 v76, v80, v87
	v_sub_f32_e32 v79, v83, v87
	v_sub_f32_e32 v78, v82, v87
	v_pk_mul_f32 v[78:79], v[78:79], v[86:87] op_sel_hi:[1,0]
	v_pk_mul_f32 v[80:81], v[76:77], v[86:87] op_sel_hi:[1,0]
	v_cvt_pk_bf16_f32 v76, v60, v61
	v_cvt_pk_bf16_f32 v77, v62, v63
	s_waitcnt vmcnt(0)
	v_pk_fma_f32 v[70:71], v[70:71], v[78:79], v[74:75]
	v_pk_fma_f32 v[68:69], v[68:69], v[80:81], v[72:73]
	v_pk_fma_f32 v[58:59], v[70:71], s[26:27], v[58:59] op_sel_hi:[1,0,1]
	v_pk_fma_f32 v[56:57], v[68:69], s[26:27], v[56:57] op_sel_hi:[1,0,1]
	global_store_dwordx4 v[66:67], v[56:59], off offset:16
	v_cvt_pk_bf16_f32 v78, v56, v57
	v_cvt_pk_bf16_f32 v79, v58, v59
	flat_store_dwordx4 v[84:85], v[76:79]
	global_load_dwordx4 v[68:71], v[66:67], off offset:512
	global_load_dwordx4 v[72:75], v[120:121], off
	s_nop 0
	global_load_dwordx4 v[76:79], v[122:123], off
	global_load_dwordx4 v[80:83], v[66:67], off offset:528
	s_waitcnt vmcnt(0)
	v_sub_f32_e32 v69, v69, v87
	v_sub_f32_e32 v68, v68, v87
	v_sub_f32_e32 v71, v71, v87
	v_sub_f32_e32 v70, v70, v87
	v_pk_mul_f32 v[70:71], v[86:87], v[70:71] op_sel_hi:[0,1]
	v_pk_mul_f32 v[68:69], v[86:87], v[68:69] op_sel_hi:[0,1]
	v_pk_fma_f32 v[68:69], v[72:73], v[68:69], v[76:77]
	v_pk_fma_f32 v[70:71], v[74:75], v[70:71], v[78:79]
	v_pk_fma_f32 v[52:53], v[68:69], s[26:27], v[52:53] op_sel_hi:[1,0,1]
	v_pk_fma_f32 v[54:55], v[70:71], s[26:27], v[54:55] op_sel_hi:[1,0,1]
	global_store_dwordx4 v[66:67], v[52:55], off offset:512
	global_load_dwordx4 v[68:71], v[124:125], off
	global_load_dwordx4 v[72:75], v[126:127], off
	v_add_f32_e32 v76, v60, v61
	v_mul_f32_e32 v61, v61, v61
	v_fmac_f32_e32 v61, v60, v60
	v_add_f32_e32 v76, v62, v76
	v_fmac_f32_e32 v61, v62, v62
	v_add_f32_e32 v62, v56, v57
	v_mul_f32_e32 v57, v57, v57
	v_fmac_f32_e32 v57, v56, v56
	v_add_f32_e32 v60, v63, v76
	v_add_f32_e32 v62, v58, v62
	v_fmac_f32_e32 v57, v58, v58
	v_add_f32_e32 v60, 0, v60
	v_fmac_f32_e32 v61, v63, v63
	v_add_f32_e32 v56, v59, v62
	v_fmac_f32_e32 v57, v59, v59
	v_add_f32_e32 v60, v56, v60
	v_add_f32_e32 v61, v61, v57
	v_sub_f32_e32 v57, v81, v87
	v_sub_f32_e32 v56, v80, v87
	v_pk_mul_f32 v[56:57], v[86:87], v[56:57] op_sel_hi:[0,1]
	v_sub_f32_e32 v59, v83, v87
	v_sub_f32_e32 v58, v82, v87
	v_pk_mul_f32 v[58:59], v[86:87], v[58:59] op_sel_hi:[0,1]
	v_mul_f32_e32 v63, v53, v53
	v_add_f32_e32 v62, v52, v53
	v_fmac_f32_e32 v63, v52, v52
	v_add_f32_e32 v62, v54, v62
	v_fmac_f32_e32 v63, v54, v54
	v_add_f32_e32 v62, v55, v62
	v_fmac_f32_e32 v63, v55, v55
	v_add_f32_e32 v60, v60, v62
	v_add_f32_e32 v61, v61, v63
	v_cvt_pk_bf16_f32 v52, v52, v53
	v_cvt_pk_bf16_f32 v53, v54, v55
	s_waitcnt vmcnt(0)
	v_pk_fma_f32 v[56:57], v[68:69], v[56:57], v[72:73]
	s_nop 0
	v_pk_fma_f32 v[56:57], v[56:57], s[26:27], v[48:49] op_sel_hi:[1,0,1]
	v_pk_fma_f32 v[58:59], v[70:71], v[58:59], v[74:75]
	v_mul_f32_e32 v49, v57, v57
	v_pk_fma_f32 v[58:59], v[58:59], s[26:27], v[50:51] op_sel_hi:[1,0,1]
	v_add_f32_e32 v48, v56, v57
	v_fmac_f32_e32 v49, v56, v56
	v_add_f32_e32 v48, v58, v48
	v_fmac_f32_e32 v49, v58, v58
	v_add_f32_e32 v48, v59, v48
	v_fmac_f32_e32 v49, v59, v59
	v_add_f32_e32 v48, v60, v48
	v_add_f32_e32 v49, v61, v49
	ds_bpermute_b32 v50, v116, v48
	ds_bpermute_b32 v51, v116, v49
	global_store_dwordx4 v[66:67], v[56:59], off offset:528
	v_cvt_pk_bf16_f32 v54, v56, v57
	v_cvt_pk_bf16_f32 v55, v58, v59
	s_waitcnt lgkmcnt(0)
	v_add_f32_e32 v48, v48, v50
	v_add_f32_e32 v49, v49, v51
	ds_bpermute_b32 v50, v117, v48
	ds_bpermute_b32 v51, v117, v49
	flat_store_dwordx4 v[84:85], v[52:55] offset:256
	s_mov_b32 s100, -1
	s_mov_b32 s101, 0
	s_mov_b32 s98, 0xffff0000
	s_mov_b32 s99, 0
	s_and_saveexec_b64 s[30:31], s[100:101]
	s_cbranch_execz .LBB0_2202
	s_waitcnt lgkmcnt(0)
	v_add_f32_e32 v51, v49, v51
	v_add_f32_e32 v50, v48, v50
	v_lshl_add_u64 v[48:49], s[10:11], 0, v[64:65]
	v_cndmask_b32_e64 v50, v50, v51, s[98:99]
	v_cndmask_b32_e64 v51, 0, 4, s[98:99]
	v_or_b32_e32 v48, v48, v51
	flat_atomic_add_f32 v[48:49], v50
; DEVI unsigned pk2(float lo, float hi) { unsigned r; asm("v_cvt_pk_bf16_f32 %0, %1, %2" : "=v"(r) : "v"(lo), "v"(hi)); return r; }
; DEVI void row_stats(const float* stats, int row, float& mu, float& rs) {
;     if (stats) { const float2 st = *(const float2*)(stats + 2 * (size_t)row); mu = st.x * (1.0f / 1024.0f); const float var = st.y * (1.0f / 1024.0f) - mu * mu; rs = rsqrtf(fmaxf(var, 0.f) + LN_EPS); }
;     DEVI void operator()(const f32x4 (&acc)[2][2][4][2], const pg8::Unit& u, int wr, int wc, int fr, int fq) const {
;     ...
;                 const int row = row0 + ai * 128 + m * 16; float mu, rs; row_stats(stin, row, mu, rs);
;                 float sum = 0.f, sq = 0.f;
; #pragma unroll
;                 for (int bj = 0; bj < 2; ++bj) {
;                     f32x4 z[2];
; #pragma unroll
;                     for (int n = 0; n < 2; ++n) {
;                         const int col = colb + bj * 128 + 4 * n;
;                         f32x4 xv = *(const f32x4*)(zsrc + (size_t)row * DM + col);
;                         if (stin) { const f32x4 gv = *(const f32x4*)(gin + col), bv = *(const f32x4*)(bin + col); xv = (xv - mu) * rs * gv + bv; }
;                         f32x4 zz = ALPHA * xv + acc[ai][bj][m][n];
;                         if (bias) zz += *(const f32x4*)(bias + col);
;                         *(f32x4*)(zdst + (size_t)row * DM + col) = zz;
;                         sum += zz[0] + zz[1] + zz[2] + zz[3]; sq += zz[0] * zz[0] + zz[1] * zz[1] + zz[2] * zz[2] + zz[3] * zz[3];
;                         z[n] = zz;
;                     }
;                     u32x4 o; o.x = pk2(z[0][0], z[0][1]); o.y = pk2(z[0][2], z[0][3]); o.z = pk2(z[1][0], z[1][1]); o.w = pk2(z[1][2], z[1][3]);
;                     if (zb) *(u32x4*)(zb + (size_t)row * DM + colb + bj * 128) = o;
;                 }
;                 sum += __shfl_xor(sum, 16); sq += __shfl_xor(sq, 16);
;                 sum += __shfl_xor(sum, 32); sq += __shfl_xor(sq, 32);
;                 if (fq == 0) { atomicAdd(stout + 2 * (size_t)row, sum); atomicAdd(stout + 2 * (size_t)row + 1, sq); }
.LBB0_2202:
	s_or_b64 exec, exec, s[30:31]
	v_add_u32_e32 v68, 0x90, v154
	v_ashrrev_i32_e32 v69, 31, v68
	v_lshlrev_b64 v[48:49], 3, v[68:69]
	s_waitcnt lgkmcnt(0)
	v_lshl_add_u64 v[50:51], s[12:13], 0, v[48:49]
	flat_load_dwordx2 v[70:71], v[50:51]
	v_lshlrev_b64 v[50:51], 12, v[68:69]
	v_lshl_add_u64 v[50:51], s[46:47], 0, v[50:51]
	v_lshl_add_u64 v[50:51], v[144:145], 2, v[50:51]
	global_load_dwordx4 v[52:55], v[50:51], off
	global_load_dwordx4 v[56:59], v[150:151], off
	global_load_dwordx4 v[60:63], v[152:153], off
	global_load_dwordx4 v[64:67], v[50:51], off offset:16
	s_waitcnt vmcnt(0) lgkmcnt(0)
	v_pk_mul_f32 v[70:71], v[70:71], s[24:25] op_sel:[1,0] op_sel_hi:[0,0]
	v_fma_f32 v70, -v71, v71, v70
	v_max_f32_e32 v70, 0, v70
	v_add_f32_e32 v70, 0x3727c5ac, v70
	v_mul_f32_e32 v72, 0x4b800000, v70
	v_cmp_gt_f32_e32 vcc, s61, v70
	v_sub_f32_e32 v53, v53, v71
	v_sub_f32_e32 v52, v52, v71
	v_cndmask_b32_e32 v70, v70, v72, vcc
	v_rsq_f32_e32 v70, v70
	v_sub_f32_e32 v55, v55, v71
	v_sub_f32_e32 v54, v54, v71
	v_mul_f32_e32 v72, 0x45800000, v70
	v_cndmask_b32_e32 v70, v70, v72, vcc
	v_pk_mul_f32 v[54:55], v[54:55], v[70:71] op_sel_hi:[1,0]
	v_pk_mul_f32 v[52:53], v[52:53], v[70:71] op_sel_hi:[1,0]
	v_pk_fma_f32 v[54:55], v[58:59], v[54:55], v[62:63]
	v_pk_fma_f32 v[52:53], v[56:57], v[52:53], v[60:61]
	v_pk_fma_f32 v[46:47], v[54:55], s[26:27], v[46:47] op_sel_hi:[1,0,1]
	v_pk_fma_f32 v[44:45], v[52:53], s[26:27], v[44:45] op_sel_hi:[1,0,1]
	global_store_dwordx4 v[50:51], v[44:47], off
	global_load_dwordx4 v[52:55], v[146:147], off
	global_load_dwordx4 v[56:59], v[148:149], off
	v_lshlrev_b64 v[60:61], 11, v[68:69]
	v_lshl_add_u64 v[60:61], s[14:15], 0, v[60:61]
	v_lshl_add_u64 v[68:69], v[144:145], 1, v[60:61]
	v_sub_f32_e32 v61, v65, v71
	v_sub_f32_e32 v60, v64, v71
	v_sub_f32_e32 v63, v67, v71
	v_sub_f32_e32 v62, v66, v71
	v_pk_mul_f32 v[62:63], v[62:63], v[70:71] op_sel_hi:[1,0]
	v_pk_mul_f32 v[64:65], v[60:61], v[70:71] op_sel_hi:[1,0]
	v_cvt_pk_bf16_f32 v60, v44, v45
	v_cvt_pk_bf16_f32 v61, v46, v47
	s_waitcnt vmcnt(0)
	v_pk_fma_f32 v[54:55], v[54:55], v[62:63], v[58:59]
	v_pk_fma_f32 v[52:53], v[52:53], v[64:65], v[56:57]
	v_pk_fma_f32 v[42:43], v[54:55], s[26:27], v[42:43] op_sel_hi:[1,0,1]
	v_pk_fma_f32 v[40:41], v[52:53], s[26:27], v[40:41] op_sel_hi:[1,0,1]
	global_store_dwordx4 v[50:51], v[40:43], off offset:16
	v_cvt_pk_bf16_f32 v62, v40, v41
	v_cvt_pk_bf16_f32 v63, v42, v43
	flat_store_dwordx4 v[68:69], v[60:63]
	global_load_dwordx4 v[52:55], v[50:51], off offset:512
	global_load_dwordx4 v[56:59], v[120:121], off
	s_nop 0
	global_load_dwordx4 v[60:63], v[122:123], off
	global_load_dwordx4 v[64:67], v[50:51], off offset:528
	s_waitcnt vmcnt(0)
	v_sub_f32_e32 v53, v53, v71
	v_sub_f32_e32 v52, v52, v71
	v_sub_f32_e32 v55, v55, v71
	v_sub_f32_e32 v54, v54, v71
	v_pk_mul_f32 v[54:55], v[70:71], v[54:55] op_sel_hi:[0,1]
	v_pk_mul_f32 v[52:53], v[70:71], v[52:53] op_sel_hi:[0,1]
	v_pk_fma_f32 v[52:53], v[56:57], v[52:53], v[60:61]
	v_pk_fma_f32 v[54:55], v[58:59], v[54:55], v[62:63]
	v_pk_fma_f32 v[36:37], v[52:53], s[26:27], v[36:37] op_sel_hi:[1,0,1]
	v_pk_fma_f32 v[38:39], v[54:55], s[26:27], v[38:39] op_sel_hi:[1,0,1]
	global_store_dwordx4 v[50:51], v[36:39], off offset:512
	global_load_dwordx4 v[52:55], v[124:125], off
	global_load_dwordx4 v[56:59], v[126:127], off
	v_add_f32_e32 v60, v44, v45
	v_mul_f32_e32 v45, v45, v45
	v_fmac_f32_e32 v45, v44, v44
	v_add_f32_e32 v60, v46, v60
	v_fmac_f32_e32 v45, v46, v46
	v_add_f32_e32 v46, v40, v41
	v_mul_f32_e32 v41, v41, v41
	v_fmac_f32_e32 v41, v40, v40
	v_add_f32_e32 v44, v47, v60
	v_add_f32_e32 v46, v42, v46
	v_fmac_f32_e32 v41, v42, v42
	v_add_f32_e32 v44, 0, v44
	v_fmac_f32_e32 v45, v47, v47
	v_add_f32_e32 v40, v43, v46
	v_fmac_f32_e32 v41, v43, v43
	v_add_f32_e32 v44, v40, v44
	v_add_f32_e32 v45, v45, v41
	v_sub_f32_e32 v41, v65, v71
	v_sub_f32_e32 v40, v64, v71
	v_pk_mul_f32 v[40:41], v[70:71], v[40:41] op_sel_hi:[0,1]
	v_sub_f32_e32 v43, v67, v71
	v_sub_f32_e32 v42, v66, v71
	v_pk_mul_f32 v[42:43], v[70:71], v[42:43] op_sel_hi:[0,1]
	v_mul_f32_e32 v47, v37, v37
	v_add_f32_e32 v46, v36, v37
	v_fmac_f32_e32 v47, v36, v36
	v_add_f32_e32 v46, v38, v46
	v_fmac_f32_e32 v47, v38, v38
	v_add_f32_e32 v46, v39, v46
	v_fmac_f32_e32 v47, v39, v39
	v_add_f32_e32 v44, v44, v46
	v_add_f32_e32 v45, v45, v47
	v_cvt_pk_bf16_f32 v36, v36, v37
	v_cvt_pk_bf16_f32 v37, v38, v39
	s_waitcnt vmcnt(0)
	v_pk_fma_f32 v[40:41], v[52:53], v[40:41], v[56:57]
	s_nop 0
	v_pk_fma_f32 v[40:41], v[40:41], s[26:27], v[32:33] op_sel_hi:[1,0,1]
	v_pk_fma_f32 v[42:43], v[54:55], v[42:43], v[58:59]
	v_mul_f32_e32 v33, v41, v41
	v_pk_fma_f32 v[42:43], v[42:43], s[26:27], v[34:35] op_sel_hi:[1,0,1]
	v_add_f32_e32 v32, v40, v41
	v_fmac_f32_e32 v33, v40, v40
	v_add_f32_e32 v32, v42, v32
	v_fmac_f32_e32 v33, v42, v42
	v_add_f32_e32 v32, v43, v32
	v_fmac_f32_e32 v33, v43, v43
	v_add_f32_e32 v32, v44, v32
	v_add_f32_e32 v33, v45, v33
	ds_bpermute_b32 v34, v116, v32
	ds_bpermute_b32 v35, v116, v33
	global_store_dwordx4 v[50:51], v[40:43], off offset:528
	v_cvt_pk_bf16_f32 v38, v40, v41
	v_cvt_pk_bf16_f32 v39, v42, v43
	s_waitcnt lgkmcnt(0)
	v_add_f32_e32 v32, v32, v34
	v_add_f32_e32 v33, v33, v35
	ds_bpermute_b32 v34, v117, v32
	ds_bpermute_b32 v35, v117, v33
	flat_store_dwordx4 v[68:69], v[36:39] offset:256
	s_mov_b32 s100, -1
	s_mov_b32 s101, 0
	s_mov_b32 s98, 0xffff0000
	s_mov_b32 s99, 0
	s_and_saveexec_b64 s[30:31], s[100:101]
	s_cbranch_execz .LBB0_2204
	s_waitcnt lgkmcnt(0)
	v_add_f32_e32 v35, v33, v35
	v_add_f32_e32 v34, v32, v34
	v_lshl_add_u64 v[32:33], s[10:11], 0, v[48:49]
	v_cndmask_b32_e64 v34, v34, v35, s[98:99]
	v_cndmask_b32_e64 v35, 0, 4, s[98:99]
	v_or_b32_e32 v32, v32, v35
	flat_atomic_add_f32 v[32:33], v34
; DEVI unsigned pk2(float lo, float hi) { unsigned r; asm("v_cvt_pk_bf16_f32 %0, %1, %2" : "=v"(r) : "v"(lo), "v"(hi)); return r; }
; DEVI void row_stats(const float* stats, int row, float& mu, float& rs) {
;     if (stats) { const float2 st = *(const float2*)(stats + 2 * (size_t)row); mu = st.x * (1.0f / 1024.0f); const float var = st.y * (1.0f / 1024.0f) - mu * mu; rs = rsqrtf(fmaxf(var, 0.f) + LN_EPS); }
;     DEVI void operator()(const f32x4 (&acc)[2][2][4][2], const pg8::Unit& u, int wr, int wc, int fr, int fq) const {
;     ...
;                 const int row = row0 + ai * 128 + m * 16; float mu, rs; row_stats(stin, row, mu, rs);
;                 float sum = 0.f, sq = 0.f;
; #pragma unroll
;                 for (int bj = 0; bj < 2; ++bj) {
;                     f32x4 z[2];
; #pragma unroll
;                     for (int n = 0; n < 2; ++n) {
;                         const int col = colb + bj * 128 + 4 * n;
;                         f32x4 xv = *(const f32x4*)(zsrc + (size_t)row * DM + col);
;                         if (stin) { const f32x4 gv = *(const f32x4*)(gin + col), bv = *(const f32x4*)(bin + col); xv = (xv - mu) * rs * gv + bv; }
;                         f32x4 zz = ALPHA * xv + acc[ai][bj][m][n];
;                         if (bias) zz += *(const f32x4*)(bias + col);
;                         *(f32x4*)(zdst + (size_t)row * DM + col) = zz;
;                         sum += zz[0] + zz[1] + zz[2] + zz[3]; sq += zz[0] * zz[0] + zz[1] * zz[1] + zz[2] * zz[2] + zz[3] * zz[3];
;                         z[n] = zz;
;                     }
;                     u32x4 o; o.x = pk2(z[0][0], z[0][1]); o.y = pk2(z[0][2], z[0][3]); o.z = pk2(z[1][0], z[1][1]); o.w = pk2(z[1][2], z[1][3]);
;                     if (zb) *(u32x4*)(zb + (size_t)row * DM + colb + bj * 128) = o;
;                 }
;                 sum += __shfl_xor(sum, 16); sq += __shfl_xor(sq, 16);
;                 sum += __shfl_xor(sum, 32); sq += __shfl_xor(sq, 32);
;                 if (fq == 0) { atomicAdd(stout + 2 * (size_t)row, sum); atomicAdd(stout + 2 * (size_t)row + 1, sq); }
.LBB0_2204:
	s_or_b64 exec, exec, s[30:31]
	v_add_u32_e32 v52, 0xa0, v154
	v_ashrrev_i32_e32 v53, 31, v52
	v_lshlrev_b64 v[32:33], 3, v[52:53]
	s_waitcnt lgkmcnt(0)
	v_lshl_add_u64 v[34:35], s[12:13], 0, v[32:33]
	flat_load_dwordx2 v[54:55], v[34:35]
	v_lshlrev_b64 v[34:35], 12, v[52:53]
	v_lshl_add_u64 v[34:35], s[46:47], 0, v[34:35]
	v_lshl_add_u64 v[34:35], v[144:145], 2, v[34:35]
	global_load_dwordx4 v[36:39], v[34:35], off
	global_load_dwordx4 v[40:43], v[150:151], off
	global_load_dwordx4 v[44:47], v[152:153], off
	global_load_dwordx4 v[48:51], v[34:35], off offset:16
	s_waitcnt vmcnt(0) lgkmcnt(0)
	v_pk_mul_f32 v[54:55], v[54:55], s[24:25] op_sel:[1,0] op_sel_hi:[0,0]
	v_fma_f32 v54, -v55, v55, v54
	v_max_f32_e32 v54, 0, v54
	v_add_f32_e32 v54, 0x3727c5ac, v54
	v_mul_f32_e32 v56, 0x4b800000, v54
	v_cmp_gt_f32_e32 vcc, s61, v54
	v_sub_f32_e32 v37, v37, v55
	v_sub_f32_e32 v36, v36, v55
	v_cndmask_b32_e32 v54, v54, v56, vcc
	v_rsq_f32_e32 v54, v54
	v_sub_f32_e32 v39, v39, v55
	v_sub_f32_e32 v38, v38, v55
	v_mul_f32_e32 v56, 0x45800000, v54
	v_cndmask_b32_e32 v54, v54, v56, vcc
	v_pk_mul_f32 v[38:39], v[38:39], v[54:55] op_sel_hi:[1,0]
	v_pk_mul_f32 v[36:37], v[36:37], v[54:55] op_sel_hi:[1,0]
	v_pk_fma_f32 v[38:39], v[42:43], v[38:39], v[46:47]
	v_pk_fma_f32 v[36:37], v[40:41], v[36:37], v[44:45]
	v_pk_fma_f32 v[30:31], v[38:39], s[26:27], v[30:31] op_sel_hi:[1,0,1]
	v_pk_fma_f32 v[28:29], v[36:37], s[26:27], v[28:29] op_sel_hi:[1,0,1]
	global_store_dwordx4 v[34:35], v[28:31], off
	global_load_dwordx4 v[36:39], v[146:147], off
	global_load_dwordx4 v[40:43], v[148:149], off
	v_lshlrev_b64 v[44:45], 11, v[52:53]
	v_lshl_add_u64 v[44:45], s[14:15], 0, v[44:45]
	v_lshl_add_u64 v[52:53], v[144:145], 1, v[44:45]
	v_sub_f32_e32 v45, v49, v55
	v_sub_f32_e32 v44, v48, v55
	v_sub_f32_e32 v47, v51, v55
	v_sub_f32_e32 v46, v50, v55
	v_pk_mul_f32 v[46:47], v[46:47], v[54:55] op_sel_hi:[1,0]
	v_pk_mul_f32 v[48:49], v[44:45], v[54:55] op_sel_hi:[1,0]
	v_cvt_pk_bf16_f32 v44, v28, v29
	v_cvt_pk_bf16_f32 v45, v30, v31
	s_waitcnt vmcnt(0)
	v_pk_fma_f32 v[38:39], v[38:39], v[46:47], v[42:43]
	v_pk_fma_f32 v[36:37], v[36:37], v[48:49], v[40:41]
	v_pk_fma_f32 v[26:27], v[38:39], s[26:27], v[26:27] op_sel_hi:[1,0,1]
	v_pk_fma_f32 v[24:25], v[36:37], s[26:27], v[24:25] op_sel_hi:[1,0,1]
	global_store_dwordx4 v[34:35], v[24:27], off offset:16
	v_cvt_pk_bf16_f32 v46, v24, v25
	v_cvt_pk_bf16_f32 v47, v26, v27
	flat_store_dwordx4 v[52:53], v[44:47]
	global_load_dwordx4 v[36:39], v[34:35], off offset:512
	global_load_dwordx4 v[40:43], v[120:121], off
	s_nop 0
	global_load_dwordx4 v[44:47], v[122:123], off
	global_load_dwordx4 v[48:51], v[34:35], off offset:528
	s_waitcnt vmcnt(0)
	v_sub_f32_e32 v37, v37, v55
	v_sub_f32_e32 v36, v36, v55
	v_sub_f32_e32 v39, v39, v55
	v_sub_f32_e32 v38, v38, v55
	v_pk_mul_f32 v[38:39], v[54:55], v[38:39] op_sel_hi:[0,1]
	v_pk_mul_f32 v[36:37], v[54:55], v[36:37] op_sel_hi:[0,1]
	v_pk_fma_f32 v[36:37], v[40:41], v[36:37], v[44:45]
	v_pk_fma_f32 v[38:39], v[42:43], v[38:39], v[46:47]
	v_pk_fma_f32 v[20:21], v[36:37], s[26:27], v[20:21] op_sel_hi:[1,0,1]
	v_pk_fma_f32 v[22:23], v[38:39], s[26:27], v[22:23] op_sel_hi:[1,0,1]
	global_store_dwordx4 v[34:35], v[20:23], off offset:512
	global_load_dwordx4 v[36:39], v[124:125], off
	global_load_dwordx4 v[40:43], v[126:127], off
	v_add_f32_e32 v44, v28, v29
	v_mul_f32_e32 v29, v29, v29
	v_fmac_f32_e32 v29, v28, v28
	v_add_f32_e32 v44, v30, v44
	v_fmac_f32_e32 v29, v30, v30
	v_add_f32_e32 v30, v24, v25
	v_mul_f32_e32 v25, v25, v25
	v_fmac_f32_e32 v25, v24, v24
	v_add_f32_e32 v28, v31, v44
	v_add_f32_e32 v30, v26, v30
	v_fmac_f32_e32 v25, v26, v26
	v_add_f32_e32 v28, 0, v28
	v_fmac_f32_e32 v29, v31, v31
	v_add_f32_e32 v24, v27, v30
	v_fmac_f32_e32 v25, v27, v27
	v_add_f32_e32 v28, v24, v28
	v_add_f32_e32 v29, v29, v25
	v_sub_f32_e32 v25, v49, v55
	v_sub_f32_e32 v24, v48, v55
	v_pk_mul_f32 v[24:25], v[54:55], v[24:25] op_sel_hi:[0,1]
	v_sub_f32_e32 v27, v51, v55
	v_sub_f32_e32 v26, v50, v55
	v_pk_mul_f32 v[26:27], v[54:55], v[26:27] op_sel_hi:[0,1]
	v_mul_f32_e32 v31, v21, v21
	v_add_f32_e32 v30, v20, v21
	v_fmac_f32_e32 v31, v20, v20
	v_add_f32_e32 v30, v22, v30
	v_fmac_f32_e32 v31, v22, v22
	v_add_f32_e32 v30, v23, v30
	v_fmac_f32_e32 v31, v23, v23
	v_add_f32_e32 v28, v28, v30
	v_add_f32_e32 v29, v29, v31
	v_cvt_pk_bf16_f32 v20, v20, v21
	v_cvt_pk_bf16_f32 v21, v22, v23
	s_waitcnt vmcnt(0)
	v_pk_fma_f32 v[24:25], v[36:37], v[24:25], v[40:41]
	s_nop 0
	v_pk_fma_f32 v[24:25], v[24:25], s[26:27], v[16:17] op_sel_hi:[1,0,1]
	v_pk_fma_f32 v[26:27], v[38:39], v[26:27], v[42:43]
	v_mul_f32_e32 v17, v25, v25
	v_pk_fma_f32 v[26:27], v[26:27], s[26:27], v[18:19] op_sel_hi:[1,0,1]
	v_add_f32_e32 v16, v24, v25
	v_fmac_f32_e32 v17, v24, v24
	v_add_f32_e32 v16, v26, v16
	v_fmac_f32_e32 v17, v26, v26
	v_add_f32_e32 v16, v27, v16
	v_fmac_f32_e32 v17, v27, v27
	v_add_f32_e32 v16, v28, v16
	v_add_f32_e32 v17, v29, v17
	ds_bpermute_b32 v18, v116, v16
	ds_bpermute_b32 v19, v116, v17
	global_store_dwordx4 v[34:35], v[24:27], off offset:528
	v_cvt_pk_bf16_f32 v22, v24, v25
	v_cvt_pk_bf16_f32 v23, v26, v27
	s_waitcnt lgkmcnt(0)
	v_add_f32_e32 v16, v16, v18
	v_add_f32_e32 v17, v17, v19
	ds_bpermute_b32 v18, v117, v16
	ds_bpermute_b32 v19, v117, v17
	flat_store_dwordx4 v[52:53], v[20:23] offset:256
	s_mov_b32 s100, -1
	s_mov_b32 s101, 0
	s_mov_b32 s98, 0xffff0000
	s_mov_b32 s99, 0
	s_and_saveexec_b64 s[30:31], s[100:101]
	s_cbranch_execz .LBB0_2206
	s_waitcnt lgkmcnt(0)
	v_add_f32_e32 v19, v17, v19
	v_add_f32_e32 v18, v16, v18
	v_lshl_add_u64 v[16:17], s[10:11], 0, v[32:33]
	v_cndmask_b32_e64 v18, v18, v19, s[98:99]
	v_cndmask_b32_e64 v19, 0, 4, s[98:99]
	v_or_b32_e32 v16, v16, v19
	flat_atomic_add_f32 v[16:17], v18
; DEVI unsigned pk2(float lo, float hi) { unsigned r; asm("v_cvt_pk_bf16_f32 %0, %1, %2" : "=v"(r) : "v"(lo), "v"(hi)); return r; }
; DEVI void row_stats(const float* stats, int row, float& mu, float& rs) {
;     if (stats) { const float2 st = *(const float2*)(stats + 2 * (size_t)row); mu = st.x * (1.0f / 1024.0f); const float var = st.y * (1.0f / 1024.0f) - mu * mu; rs = rsqrtf(fmaxf(var, 0.f) + LN_EPS); }
;     DEVI void operator()(const f32x4 (&acc)[2][2][4][2], const pg8::Unit& u, int wr, int wc, int fr, int fq) const {
;     ...
;                 const int row = row0 + ai * 128 + m * 16; float mu, rs; row_stats(stin, row, mu, rs);
;                 float sum = 0.f, sq = 0.f;
; #pragma unroll
;                 for (int bj = 0; bj < 2; ++bj) {
;                     f32x4 z[2];
; #pragma unroll
;                     for (int n = 0; n < 2; ++n) {
;                         const int col = colb + bj * 128 + 4 * n;
;                         f32x4 xv = *(const f32x4*)(zsrc + (size_t)row * DM + col);
;                         if (stin) { const f32x4 gv = *(const f32x4*)(gin + col), bv = *(const f32x4*)(bin + col); xv = (xv - mu) * rs * gv + bv; }
;                         f32x4 zz = ALPHA * xv + acc[ai][bj][m][n];
;                         if (bias) zz += *(const f32x4*)(bias + col);
;                         *(f32x4*)(zdst + (size_t)row * DM + col) = zz;
;                         sum += zz[0] + zz[1] + zz[2] + zz[3]; sq += zz[0] * zz[0] + zz[1] * zz[1] + zz[2] * zz[2] + zz[3] * zz[3];
;                         z[n] = zz;
;                     }
;                     u32x4 o; o.x = pk2(z[0][0], z[0][1]); o.y = pk2(z[0][2], z[0][3]); o.z = pk2(z[1][0], z[1][1]); o.w = pk2(z[1][2], z[1][3]);
;                     if (zb) *(u32x4*)(zb + (size_t)row * DM + colb + bj * 128) = o;
;                 }
;                 sum += __shfl_xor(sum, 16); sq += __shfl_xor(sq, 16);
;                 sum += __shfl_xor(sum, 32); sq += __shfl_xor(sq, 32);
;                 if (fq == 0) { atomicAdd(stout + 2 * (size_t)row, sum); atomicAdd(stout + 2 * (size_t)row + 1, sq); }
.LBB0_2206:
	s_or_b64 exec, exec, s[30:31]
	v_add_u32_e32 v36, 0xb0, v154
	v_ashrrev_i32_e32 v37, 31, v36
	v_lshlrev_b64 v[16:17], 3, v[36:37]
	s_waitcnt lgkmcnt(0)
	v_lshl_add_u64 v[18:19], s[12:13], 0, v[16:17]
	flat_load_dwordx2 v[38:39], v[18:19]
	v_lshlrev_b64 v[18:19], 12, v[36:37]
	v_lshl_add_u64 v[18:19], s[46:47], 0, v[18:19]
	v_lshl_add_u64 v[18:19], v[144:145], 2, v[18:19]
	global_load_dwordx4 v[20:23], v[18:19], off
	global_load_dwordx4 v[24:27], v[150:151], off
	global_load_dwordx4 v[28:31], v[152:153], off
	global_load_dwordx4 v[32:35], v[18:19], off offset:16
	s_waitcnt vmcnt(0) lgkmcnt(0)
	v_pk_mul_f32 v[38:39], v[38:39], s[24:25] op_sel:[1,0] op_sel_hi:[0,0]
	v_fma_f32 v38, -v39, v39, v38
	v_max_f32_e32 v38, 0, v38
	v_add_f32_e32 v38, 0x3727c5ac, v38
	v_mul_f32_e32 v40, 0x4b800000, v38
	v_cmp_gt_f32_e32 vcc, s61, v38
	v_sub_f32_e32 v21, v21, v39
	v_sub_f32_e32 v20, v20, v39
	v_cndmask_b32_e32 v38, v38, v40, vcc
	v_rsq_f32_e32 v38, v38
	v_sub_f32_e32 v23, v23, v39
	v_sub_f32_e32 v22, v22, v39
	v_mul_f32_e32 v40, 0x45800000, v38
	v_cndmask_b32_e32 v38, v38, v40, vcc
	v_pk_mul_f32 v[22:23], v[22:23], v[38:39] op_sel_hi:[1,0]
	v_pk_mul_f32 v[20:21], v[20:21], v[38:39] op_sel_hi:[1,0]
	v_pk_fma_f32 v[22:23], v[26:27], v[22:23], v[30:31]
	v_pk_fma_f32 v[20:21], v[24:25], v[20:21], v[28:29]
	v_pk_fma_f32 v[14:15], v[22:23], s[26:27], v[14:15] op_sel_hi:[1,0,1]
	v_pk_fma_f32 v[12:13], v[20:21], s[26:27], v[12:13] op_sel_hi:[1,0,1]
	global_store_dwordx4 v[18:19], v[12:15], off
	global_load_dwordx4 v[20:23], v[146:147], off
	global_load_dwordx4 v[24:27], v[148:149], off
	v_lshlrev_b64 v[28:29], 11, v[36:37]
	v_lshl_add_u64 v[28:29], s[14:15], 0, v[28:29]
	v_lshl_add_u64 v[36:37], v[144:145], 1, v[28:29]
	v_sub_f32_e32 v29, v33, v39
	v_sub_f32_e32 v28, v32, v39
	v_sub_f32_e32 v31, v35, v39
	v_sub_f32_e32 v30, v34, v39
	v_pk_mul_f32 v[30:31], v[30:31], v[38:39] op_sel_hi:[1,0]
	v_pk_mul_f32 v[32:33], v[28:29], v[38:39] op_sel_hi:[1,0]
	v_cvt_pk_bf16_f32 v28, v12, v13
	v_cvt_pk_bf16_f32 v29, v14, v15
	s_waitcnt vmcnt(0)
	v_pk_fma_f32 v[22:23], v[22:23], v[30:31], v[26:27]
	v_pk_fma_f32 v[20:21], v[20:21], v[32:33], v[24:25]
	v_pk_fma_f32 v[10:11], v[22:23], s[26:27], v[10:11] op_sel_hi:[1,0,1]
	v_pk_fma_f32 v[8:9], v[20:21], s[26:27], v[8:9] op_sel_hi:[1,0,1]
	global_store_dwordx4 v[18:19], v[8:11], off offset:16
	v_cvt_pk_bf16_f32 v30, v8, v9
	v_cvt_pk_bf16_f32 v31, v10, v11
	flat_store_dwordx4 v[36:37], v[28:31]
	global_load_dwordx4 v[20:23], v[18:19], off offset:512
	global_load_dwordx4 v[24:27], v[120:121], off
	s_nop 0
	global_load_dwordx4 v[28:31], v[122:123], off
	global_load_dwordx4 v[32:35], v[18:19], off offset:528
	s_waitcnt vmcnt(0)
	v_sub_f32_e32 v21, v21, v39
	v_sub_f32_e32 v20, v20, v39
	v_sub_f32_e32 v23, v23, v39
	v_sub_f32_e32 v22, v22, v39
	v_pk_mul_f32 v[22:23], v[38:39], v[22:23] op_sel_hi:[0,1]
	v_pk_mul_f32 v[20:21], v[38:39], v[20:21] op_sel_hi:[0,1]
	v_pk_fma_f32 v[20:21], v[24:25], v[20:21], v[28:29]
	v_pk_fma_f32 v[22:23], v[26:27], v[22:23], v[30:31]
	v_pk_fma_f32 v[4:5], v[20:21], s[26:27], v[4:5] op_sel_hi:[1,0,1]
	v_pk_fma_f32 v[6:7], v[22:23], s[26:27], v[6:7] op_sel_hi:[1,0,1]
	global_store_dwordx4 v[18:19], v[4:7], off offset:512
	global_load_dwordx4 v[20:23], v[124:125], off
	global_load_dwordx4 v[24:27], v[126:127], off
	v_add_f32_e32 v28, v12, v13
	v_mul_f32_e32 v13, v13, v13
	v_fmac_f32_e32 v13, v12, v12
	v_add_f32_e32 v28, v14, v28
	v_fmac_f32_e32 v13, v14, v14
	v_add_f32_e32 v14, v8, v9
	v_mul_f32_e32 v9, v9, v9
	v_fmac_f32_e32 v9, v8, v8
	v_add_f32_e32 v12, v15, v28
	v_add_f32_e32 v14, v10, v14
	v_fmac_f32_e32 v9, v10, v10
	v_add_f32_e32 v12, 0, v12
	v_fmac_f32_e32 v13, v15, v15
	v_add_f32_e32 v8, v11, v14
	v_fmac_f32_e32 v9, v11, v11
	v_add_f32_e32 v12, v8, v12
	v_add_f32_e32 v13, v13, v9
	v_sub_f32_e32 v9, v33, v39
	v_sub_f32_e32 v8, v32, v39
	v_pk_mul_f32 v[8:9], v[38:39], v[8:9] op_sel_hi:[0,1]
	v_sub_f32_e32 v11, v35, v39
	v_sub_f32_e32 v10, v34, v39
	v_pk_mul_f32 v[10:11], v[38:39], v[10:11] op_sel_hi:[0,1]
	v_mul_f32_e32 v15, v5, v5
	v_add_f32_e32 v14, v4, v5
	v_fmac_f32_e32 v15, v4, v4
	v_add_f32_e32 v14, v6, v14
	v_fmac_f32_e32 v15, v6, v6
	v_add_f32_e32 v14, v7, v14
	v_fmac_f32_e32 v15, v7, v7
	v_add_f32_e32 v12, v12, v14
	v_add_f32_e32 v13, v13, v15
	v_cvt_pk_bf16_f32 v4, v4, v5
	v_cvt_pk_bf16_f32 v5, v6, v7
	s_waitcnt vmcnt(0)
	v_pk_fma_f32 v[8:9], v[20:21], v[8:9], v[24:25]
	s_nop 0
	v_pk_fma_f32 v[8:9], v[8:9], s[26:27], v[0:1] op_sel_hi:[1,0,1]
	v_pk_fma_f32 v[10:11], v[22:23], v[10:11], v[26:27]
	v_mul_f32_e32 v1, v9, v9
	v_pk_fma_f32 v[10:11], v[10:11], s[26:27], v[2:3] op_sel_hi:[1,0,1]
	v_add_f32_e32 v0, v8, v9
	v_fmac_f32_e32 v1, v8, v8
	v_add_f32_e32 v0, v10, v0
	v_fmac_f32_e32 v1, v10, v10
	v_add_f32_e32 v0, v11, v0
	v_fmac_f32_e32 v1, v11, v11
	v_add_f32_e32 v0, v12, v0
	v_add_f32_e32 v1, v13, v1
	ds_bpermute_b32 v2, v116, v0
	ds_bpermute_b32 v3, v116, v1
	global_store_dwordx4 v[18:19], v[8:11], off offset:528
	v_cvt_pk_bf16_f32 v6, v8, v9
	v_cvt_pk_bf16_f32 v7, v10, v11
	s_waitcnt lgkmcnt(0)
	v_add_f32_e32 v0, v0, v2
	v_add_f32_e32 v1, v1, v3
	ds_bpermute_b32 v2, v117, v0
	ds_bpermute_b32 v3, v117, v1
	flat_store_dwordx4 v[36:37], v[4:7] offset:256
	s_mov_b32 s100, -1
	s_mov_b32 s101, 0
	s_mov_b32 s98, 0xffff0000
	s_mov_b32 s99, 0
	s_and_saveexec_b64 s[30:31], s[100:101]
	s_cbranch_execz .LBB0_2208
	s_waitcnt lgkmcnt(0)
	v_add_f32_e32 v3, v1, v3
	v_add_f32_e32 v2, v0, v2
	v_lshl_add_u64 v[0:1], s[10:11], 0, v[16:17]
	v_cndmask_b32_e64 v2, v2, v3, s[98:99]
	v_cndmask_b32_e64 v3, 0, 4, s[98:99]
	v_or_b32_e32 v0, v0, v3
	flat_atomic_add_f32 v[0:1], v2

; DEVI unsigned pk2(float lo, float hi) { unsigned r; asm("v_cvt_pk_bf16_f32 %0, %1, %2" : "=v"(r) : "v"(lo), "v"(hi)); return r; }
; DEVI void row_stats(const float* stats, int row, float& mu, float& rs) {
;     if (stats) { const float2 st = *(const float2*)(stats + 2 * (size_t)row); mu = st.x * (1.0f / 1024.0f); const float var = st.y * (1.0f / 1024.0f) - mu * mu; rs = rsqrtf(fmaxf(var, 0.f) + LN_EPS); }
;     else { mu = 0.f; rs = 1.f; }
; }
;     DEVI void operator()(const f32x4 (&acc)[2][2][4][2], const pg8::Unit& u, int wr, int wc, int fr, int fq) const {
;     ...
;                 const int row = row0 + ai * 128 + m * 16; float mu, rs; row_stats(stin, row, mu, rs);
;                 float sum = 0.f, sq = 0.f;
; #pragma unroll
;                 for (int bj = 0; bj < 2; ++bj) {
;                     f32x4 z[2];
; #pragma unroll
;                     for (int n = 0; n < 2; ++n) {
;                         const int col = colb + bj * 128 + 4 * n;
;                         f32x4 xv = *(const f32x4*)(zsrc + (size_t)row * DM + col);
;                         if (stin) { const f32x4 gv = *(const f32x4*)(gin + col), bv = *(const f32x4*)(bin + col); xv = (xv - mu) * rs * gv + bv; }
;                         f32x4 zz = ALPHA * xv + acc[ai][bj][m][n];
;                         if (bias) zz += *(const f32x4*)(bias + col);
;                         *(f32x4*)(zdst + (size_t)row * DM + col) = zz;
;                         sum += zz[0] + zz[1] + zz[2] + zz[3]; sq += zz[0] * zz[0] + zz[1] * zz[1] + zz[2] * zz[2] + zz[3] * zz[3];
;                         z[n] = zz;
;                     }
;                     u32x4 o; o.x = pk2(z[0][0], z[0][1]); o.y = pk2(z[0][2], z[0][3]); o.z = pk2(z[1][0], z[1][1]); o.w = pk2(z[1][2], z[1][3]);
;                     if (zb) *(u32x4*)(zb + (size_t)row * DM + colb + bj * 128) = o;
.LBB0_2636:
	v_lshl_add_u32 v154, s36, 8, v168
	v_ashrrev_i32_e32 v155, 31, v154
	v_lshlrev_b64 v[162:163], 3, v[154:155]
	v_lshl_add_u64 v[146:147], s[6:7], 0, v[162:163]
	s_waitcnt vmcnt(0)
	flat_load_dwordx2 v[166:167], v[146:147]
	v_lshl_or_b32 v144, s38, 8, v170
	v_ashrrev_i32_e32 v145, 31, v144
	v_lshlrev_b64 v[146:147], 12, v[154:155]
	v_lshl_add_u64 v[146:147], s[46:47], 0, v[146:147]
	v_lshlrev_b64 v[148:149], 2, v[144:145]
	v_lshl_add_u64 v[164:165], v[146:147], 0, v[148:149]
	global_load_dwordx4 v[158:161], v[164:165], off
	v_lshl_add_u64 v[150:151], s[12:13], 0, v[148:149]
	v_lshl_add_u64 v[152:153], s[14:15], 0, v[148:149]
	global_load_dwordx4 v[176:179], v[150:151], off
	global_load_dwordx4 v[180:183], v[152:153], off
	v_lshl_add_u64 v[156:157], s[16:17], 0, v[148:149]
	global_load_dwordx4 v[184:187], v[156:157], off
	global_load_dwordx4 v[188:191], v[164:165], off offset:16
	v_or_b32_e32 v146, 4, v144
	v_ashrrev_i32_e32 v147, 31, v146
	v_lshlrev_b64 v[192:193], 2, v[146:147]
	v_lshl_add_u64 v[146:147], s[12:13], 0, v[192:193]
	v_lshl_add_u64 v[148:149], s[14:15], 0, v[192:193]
	s_waitcnt vmcnt(0) lgkmcnt(0)
	v_pk_mul_f32 v[166:167], v[166:167], s[22:23] op_sel:[1,0] op_sel_hi:[0,0]
	v_fma_f32 v166, -v167, v167, v166
	v_max_f32_e32 v166, 0, v166
	v_add_f32_e32 v166, 0x3727c5ac, v166
	v_mul_f32_e32 v175, 0x4b800000, v166
	v_cmp_gt_f32_e32 vcc, s64, v166
	v_sub_f32_e32 v161, v161, v167
	s_nop 0
	v_cndmask_b32_e32 v166, v166, v175, vcc
	v_rsq_f32_e32 v166, v166
	v_sub_f32_e32 v160, v160, v167
	v_sub_f32_e32 v159, v159, v167
	v_sub_f32_e32 v158, v158, v167
	v_mul_f32_e32 v175, 0x45800000, v166
	v_cndmask_b32_e32 v166, v166, v175, vcc
	v_pk_mul_f32 v[158:159], v[158:159], v[166:167] op_sel_hi:[1,0]
	v_pk_mul_f32 v[160:161], v[160:161], v[166:167] op_sel_hi:[1,0]
	v_pk_fma_f32 v[158:159], v[176:177], v[158:159], v[180:181]
	v_pk_fma_f32 v[160:161], v[178:179], v[160:161], v[182:183]
	v_pk_fma_f32 v[124:125], v[158:159], s[24:25], v[124:125] op_sel_hi:[1,0,1]
	v_pk_fma_f32 v[126:127], v[160:161], s[24:25], v[126:127] op_sel_hi:[1,0,1]
	v_pk_add_f32 v[176:177], v[184:185], v[124:125]
	v_pk_add_f32 v[178:179], v[186:187], v[126:127]
	global_store_dwordx4 v[164:165], v[176:179], off
	global_load_dwordx4 v[158:161], v[146:147], off
	global_load_dwordx4 v[180:183], v[148:149], off
	v_lshl_add_u64 v[124:125], s[16:17], 0, v[192:193]
	global_load_dwordx4 v[184:187], v[124:125], off
	v_lshlrev_b64 v[192:193], 11, v[154:155]
	v_lshl_add_u64 v[192:193], s[10:11], 0, v[192:193]
	v_sub_f32_e32 v191, v191, v167
	v_sub_f32_e32 v190, v190, v167
	v_sub_f32_e32 v189, v189, v167
	v_sub_f32_e32 v188, v188, v167
	v_lshl_add_u64 v[204:205], v[144:145], 1, v[192:193]
	v_pk_mul_f32 v[192:193], v[188:189], v[166:167] op_sel_hi:[1,0]
	v_pk_mul_f32 v[190:191], v[190:191], v[166:167] op_sel_hi:[1,0]
	v_or_b32_e32 v126, 0x80, v144
	v_cvt_pk_bf16_f32 v188, v176, v177
	v_cvt_pk_bf16_f32 v189, v178, v179
	v_ashrrev_i32_e32 v127, 31, v126
	v_xor_b32_e32 v155, 32, v174
	v_mul_f32_e32 v175, v177, v177
	v_fmac_f32_e32 v175, v176, v176
	v_fmac_f32_e32 v175, v178, v178
	v_fmac_f32_e32 v175, v179, v179
	s_waitcnt vmcnt(1)
	v_pk_fma_f32 v[160:161], v[160:161], v[190:191], v[182:183]
	v_pk_fma_f32 v[158:159], v[158:159], v[192:193], v[180:181]
	v_pk_fma_f32 v[122:123], v[160:161], s[24:25], v[122:123] op_sel_hi:[1,0,1]
	v_pk_fma_f32 v[120:121], v[158:159], s[24:25], v[120:121] op_sel_hi:[1,0,1]
	s_waitcnt vmcnt(0)
	v_pk_add_f32 v[182:183], v[186:187], v[122:123]
	v_pk_add_f32 v[180:181], v[184:185], v[120:121]
	global_store_dwordx4 v[164:165], v[180:183], off offset:16
	v_cvt_pk_bf16_f32 v190, v180, v181
	v_cvt_pk_bf16_f32 v191, v182, v183
	flat_store_dwordx4 v[204:205], v[188:191]
	global_load_dwordx4 v[184:187], v[164:165], off offset:512
	v_lshlrev_b64 v[120:121], 2, v[126:127]
	v_lshl_add_u64 v[126:127], s[12:13], 0, v[120:121]
	v_lshl_add_u64 v[158:159], s[14:15], 0, v[120:121]
	global_load_dwordx4 v[188:191], v[126:127], off
	global_load_dwordx4 v[192:195], v[158:159], off
	v_lshl_add_u64 v[160:161], s[16:17], 0, v[120:121]
	global_load_dwordx4 v[196:199], v[160:161], off
	global_load_dwordx4 v[200:203], v[164:165], off offset:528
	v_or_b32_e32 v120, 0x84, v144
	v_ashrrev_i32_e32 v121, 31, v120
	v_lshlrev_b64 v[206:207], 2, v[120:121]
	v_lshl_add_u64 v[120:121], s[12:13], 0, v[206:207]
	v_lshl_add_u64 v[122:123], s[14:15], 0, v[206:207]
	s_waitcnt vmcnt(0)
	v_sub_f32_e32 v187, v187, v167
	v_sub_f32_e32 v186, v186, v167
	v_sub_f32_e32 v185, v185, v167
	v_sub_f32_e32 v184, v184, v167
	v_pk_mul_f32 v[184:185], v[166:167], v[184:185] op_sel_hi:[0,1]
	v_pk_mul_f32 v[186:187], v[166:167], v[186:187] op_sel_hi:[0,1]
	v_pk_fma_f32 v[186:187], v[190:191], v[186:187], v[194:195]
	v_pk_fma_f32 v[184:185], v[188:189], v[184:185], v[192:193]
	v_pk_fma_f32 v[118:119], v[186:187], s[24:25], v[118:119] op_sel_hi:[1,0,1]
	v_pk_fma_f32 v[116:117], v[184:185], s[24:25], v[116:117] op_sel_hi:[1,0,1]
	v_pk_add_f32 v[186:187], v[198:199], v[118:119]
	v_pk_add_f32 v[184:185], v[196:197], v[116:117]
	global_store_dwordx4 v[164:165], v[184:187], off offset:512
	global_load_dwordx4 v[188:191], v[120:121], off
	global_load_dwordx4 v[192:195], v[122:123], off
	v_lshl_add_u64 v[116:117], s[16:17], 0, v[206:207]
	global_load_dwordx4 v[196:199], v[116:117], off
	v_and_b32_e32 v119, 64, v174
	v_xor_b32_e32 v118, 16, v174
	v_add_u32_e32 v119, 64, v119
	v_cmp_lt_i32_e32 vcc, v118, v119
	s_nop 1
	v_cndmask_b32_e32 v118, v174, v118, vcc
	v_cmp_lt_i32_e32 vcc, v155, v119
	v_lshlrev_b32_e32 v118, 2, v118
	s_nop 0
	v_cndmask_b32_e32 v119, v174, v155, vcc
	v_add_f32_e32 v155, v176, v177
	v_mul_f32_e32 v177, v181, v181
	v_add_f32_e32 v155, v178, v155
	v_add_f32_e32 v176, v180, v181
	v_fmac_f32_e32 v177, v180, v180
	v_add_f32_e32 v155, v179, v155
	v_add_f32_e32 v176, v182, v176
	v_fmac_f32_e32 v177, v182, v182
	v_add_f32_e32 v155, 0, v155
	v_add_f32_e32 v176, v183, v176
	v_fmac_f32_e32 v177, v183, v183
	v_add_f32_e32 v155, v176, v155
	v_add_f32_e32 v175, v175, v177
	v_sub_f32_e32 v177, v203, v167
	v_sub_f32_e32 v176, v202, v167
	v_sub_f32_e32 v179, v201, v167
	v_sub_f32_e32 v178, v200, v167
	v_pk_mul_f32 v[178:179], v[166:167], v[178:179] op_sel_hi:[0,1]
	v_pk_mul_f32 v[166:167], v[166:167], v[176:177] op_sel_hi:[0,1]
	v_mul_f32_e32 v177, v185, v185
	v_add_f32_e32 v176, v184, v185
	v_fmac_f32_e32 v177, v184, v184
	v_add_f32_e32 v176, v186, v176
	v_fmac_f32_e32 v177, v186, v186
	v_add_f32_e32 v176, v187, v176
	v_fmac_f32_e32 v177, v187, v187
	v_add_f32_e32 v155, v155, v176
	v_add_f32_e32 v175, v175, v177
	v_lshlrev_b32_e32 v119, 2, v119
	v_cvt_pk_bf16_f32 v180, v184, v185
	v_cvt_pk_bf16_f32 v181, v186, v187
	s_waitcnt vmcnt(0)
; DEVI unsigned pk2(float lo, float hi) { unsigned r; asm("v_cvt_pk_bf16_f32 %0, %1, %2" : "=v"(r) : "v"(lo), "v"(hi)); return r; }
;     DEVI void operator()(const f32x4 (&acc)[2][2][4][2], const pg8::Unit& u, int wr, int wc, int fr, int fq) const {
;     ...
;                 const int row = row0 + ai * 128 + m * 16; float mu, rs; row_stats(stin, row, mu, rs);
;                 float sum = 0.f, sq = 0.f;
; #pragma unroll
;                 for (int bj = 0; bj < 2; ++bj) {
;                     f32x4 z[2];
; #pragma unroll
;                     for (int n = 0; n < 2; ++n) {
;                         const int col = colb + bj * 128 + 4 * n;
;                         f32x4 xv = *(const f32x4*)(zsrc + (size_t)row * DM + col);
;                         if (stin) { const f32x4 gv = *(const f32x4*)(gin + col), bv = *(const f32x4*)(bin + col); xv = (xv - mu) * rs * gv + bv; }
;                         f32x4 zz = ALPHA * xv + acc[ai][bj][m][n];
;                         if (bias) zz += *(const f32x4*)(bias + col);
;                         *(f32x4*)(zdst + (size_t)row * DM + col) = zz;
;                         sum += zz[0] + zz[1] + zz[2] + zz[3]; sq += zz[0] * zz[0] + zz[1] * zz[1] + zz[2] * zz[2] + zz[3] * zz[3];
;                         z[n] = zz;
;                     }
;                     u32x4 o; o.x = pk2(z[0][0], z[0][1]); o.y = pk2(z[0][2], z[0][3]); o.z = pk2(z[1][0], z[1][1]); o.w = pk2(z[1][2], z[1][3]);
;                     if (zb) *(u32x4*)(zb + (size_t)row * DM + colb + bj * 128) = o;
;                 }
;                 sum += __shfl_xor(sum, 16); sq += __shfl_xor(sq, 16);
;                 sum += __shfl_xor(sum, 32); sq += __shfl_xor(sq, 32);
;                 if (fq == 0) { atomicAdd(stout + 2 * (size_t)row, sum); atomicAdd(stout + 2 * (size_t)row + 1, sq); }
	v_pk_fma_f32 v[176:177], v[188:189], v[178:179], v[192:193]
	s_nop 0
	v_pk_fma_f32 v[112:113], v[176:177], s[24:25], v[112:113] op_sel_hi:[1,0,1]
	v_pk_fma_f32 v[166:167], v[190:191], v[166:167], v[194:195]
	v_pk_add_f32 v[176:177], v[196:197], v[112:113]
	v_pk_fma_f32 v[114:115], v[166:167], s[24:25], v[114:115] op_sel_hi:[1,0,1]
	v_mul_f32_e32 v113, v177, v177
	v_pk_add_f32 v[178:179], v[198:199], v[114:115]
	v_add_f32_e32 v112, v176, v177
	v_fmac_f32_e32 v113, v176, v176
	v_add_f32_e32 v112, v178, v112
	v_fmac_f32_e32 v113, v178, v178
	v_add_f32_e32 v112, v179, v112
	v_fmac_f32_e32 v113, v179, v179
	v_add_f32_e32 v112, v155, v112
	v_add_f32_e32 v113, v175, v113
	ds_bpermute_b32 v114, v118, v112
	ds_bpermute_b32 v115, v118, v113
	global_store_dwordx4 v[164:165], v[176:179], off offset:528
	v_cvt_pk_bf16_f32 v182, v176, v177
	v_cvt_pk_bf16_f32 v183, v178, v179
	s_waitcnt lgkmcnt(0)
	v_add_f32_e32 v112, v112, v114
	v_add_f32_e32 v113, v113, v115
	ds_bpermute_b32 v114, v119, v112
	ds_bpermute_b32 v115, v119, v113
	flat_store_dwordx4 v[204:205], v[180:183] offset:256
	s_mov_b32 s100, -1
	s_mov_b32 s101, 0
	s_mov_b32 s98, 0xffff0000
	s_mov_b32 s99, 0
	s_and_saveexec_b64 s[36:37], s[100:101]
	s_cbranch_execz .LBB0_2638
	v_lshl_add_u64 v[162:163], s[8:9], 0, v[162:163]
	s_waitcnt lgkmcnt(0)
	v_add_f32_e32 v112, v112, v114
	v_add_f32_e32 v113, v113, v115
	v_cndmask_b32_e64 v112, v112, v113, s[98:99]
	v_cndmask_b32_e64 v113, 0, 4, s[98:99]
	v_or_b32_e32 v162, v162, v113
	flat_atomic_add_f32 v[162:163], v112
.LBB0_2638:
	s_or_b64 exec, exec, s[36:37]
	v_or_b32_e32 v166, 16, v154
	v_ashrrev_i32_e32 v167, 31, v166
	v_lshlrev_b64 v[112:113], 3, v[166:167]
	s_waitcnt lgkmcnt(0)
	v_lshl_add_u64 v[114:115], s[6:7], 0, v[112:113]
	flat_load_dwordx2 v[192:193], v[114:115]
	v_lshlrev_b64 v[114:115], 12, v[166:167]
	v_lshl_add_u64 v[114:115], s[46:47], 0, v[114:115]
	v_lshl_add_u64 v[114:115], v[144:145], 2, v[114:115]
	global_load_dwordx4 v[162:165], v[114:115], off
	global_load_dwordx4 v[176:179], v[150:151], off
	global_load_dwordx4 v[180:183], v[152:153], off
	global_load_dwordx4 v[184:187], v[156:157], off
	global_load_dwordx4 v[188:191], v[114:115], off offset:16
	v_lshlrev_b64 v[166:167], 11, v[166:167]
	v_lshl_add_u64 v[166:167], s[10:11], 0, v[166:167]
	v_lshl_add_u64 v[166:167], v[144:145], 1, v[166:167]
	s_waitcnt vmcnt(0) lgkmcnt(0)
	v_pk_mul_f32 v[192:193], v[192:193], s[22:23] op_sel:[1,0] op_sel_hi:[0,0]
	v_fma_f32 v155, -v193, v193, v192
	v_max_f32_e32 v155, 0, v155
	v_add_f32_e32 v155, 0x3727c5ac, v155
	v_mul_f32_e32 v175, 0x4b800000, v155
	v_cmp_gt_f32_e32 vcc, s64, v155
	v_sub_f32_e32 v165, v165, v193
	v_sub_f32_e32 v164, v164, v193
	v_cndmask_b32_e32 v155, v155, v175, vcc
	v_rsq_f32_e32 v155, v155
	v_sub_f32_e32 v163, v163, v193
	v_sub_f32_e32 v162, v162, v193
	v_mul_f32_e32 v175, 0x45800000, v155
	v_cndmask_b32_e32 v192, v155, v175, vcc
	v_pk_mul_f32 v[162:163], v[162:163], v[192:193] op_sel_hi:[1,0]
	v_pk_mul_f32 v[164:165], v[164:165], v[192:193] op_sel_hi:[1,0]
	v_pk_fma_f32 v[162:163], v[176:177], v[162:163], v[180:181]
	v_pk_fma_f32 v[164:165], v[178:179], v[164:165], v[182:183]
	v_pk_fma_f32 v[108:109], v[162:163], s[24:25], v[108:109] op_sel_hi:[1,0,1]
	v_pk_fma_f32 v[110:111], v[164:165], s[24:25], v[110:111] op_sel_hi:[1,0,1]
	v_pk_add_f32 v[108:109], v[184:185], v[108:109]
	v_pk_add_f32 v[110:111], v[186:187], v[110:111]
	global_store_dwordx4 v[114:115], v[108:111], off
	global_load_dwordx4 v[162:165], v[146:147], off
	global_load_dwordx4 v[176:179], v[148:149], off
	global_load_dwordx4 v[180:183], v[124:125], off
	v_sub_f32_e32 v185, v191, v193
	v_sub_f32_e32 v184, v190, v193
	v_sub_f32_e32 v187, v189, v193
	v_sub_f32_e32 v186, v188, v193
	v_pk_mul_f32 v[186:187], v[186:187], v[192:193] op_sel_hi:[1,0]
	v_pk_mul_f32 v[188:189], v[184:185], v[192:193] op_sel_hi:[1,0]
	v_cvt_pk_bf16_f32 v184, v108, v109
	v_cvt_pk_bf16_f32 v185, v110, v111
	v_add_f32_e32 v155, v108, v109
	v_mul_f32_e32 v109, v109, v109
	v_fmac_f32_e32 v109, v108, v108
	v_add_f32_e32 v155, v110, v155
	v_fmac_f32_e32 v109, v110, v110
	v_add_f32_e32 v108, v111, v155
	v_add_f32_e32 v108, 0, v108
	v_fmac_f32_e32 v109, v111, v111
	s_waitcnt vmcnt(1)
	v_pk_fma_f32 v[164:165], v[164:165], v[188:189], v[178:179]
	v_pk_fma_f32 v[162:163], v[162:163], v[186:187], v[176:177]
	v_pk_fma_f32 v[106:107], v[164:165], s[24:25], v[106:107] op_sel_hi:[1,0,1]
	v_pk_fma_f32 v[104:105], v[162:163], s[24:25], v[104:105] op_sel_hi:[1,0,1]
	s_waitcnt vmcnt(0)
	v_pk_add_f32 v[106:107], v[182:183], v[106:107]
	v_pk_add_f32 v[104:105], v[180:181], v[104:105]
	global_store_dwordx4 v[114:115], v[104:107], off offset:16
	v_cvt_pk_bf16_f32 v186, v104, v105
	v_cvt_pk_bf16_f32 v187, v106, v107
	flat_store_dwordx4 v[166:167], v[184:187]
	global_load_dwordx4 v[162:165], v[114:115], off offset:512
	global_load_dwordx4 v[176:179], v[126:127], off
	global_load_dwordx4 v[180:183], v[158:159], off
	s_nop 0
	global_load_dwordx4 v[184:187], v[160:161], off
	global_load_dwordx4 v[188:191], v[114:115], off offset:528
	v_add_f32_e32 v110, v104, v105
	v_mul_f32_e32 v105, v105, v105
	v_fmac_f32_e32 v105, v104, v104
	v_add_f32_e32 v110, v106, v110
	v_fmac_f32_e32 v105, v106, v106
	v_add_f32_e32 v104, v107, v110
	v_fmac_f32_e32 v105, v107, v107
	v_add_f32_e32 v108, v104, v108
	v_add_f32_e32 v109, v109, v105
	s_waitcnt vmcnt(0)
; DEVI unsigned pk2(float lo, float hi) { unsigned r; asm("v_cvt_pk_bf16_f32 %0, %1, %2" : "=v"(r) : "v"(lo), "v"(hi)); return r; }
;     DEVI void operator()(const f32x4 (&acc)[2][2][4][2], const pg8::Unit& u, int wr, int wc, int fr, int fq) const {
;     ...
;                 const int row = row0 + ai * 128 + m * 16; float mu, rs; row_stats(stin, row, mu, rs);
;                 float sum = 0.f, sq = 0.f;
; #pragma unroll
;                 for (int bj = 0; bj < 2; ++bj) {
;                     f32x4 z[2];
; #pragma unroll
;                     for (int n = 0; n < 2; ++n) {
;                         const int col = colb + bj * 128 + 4 * n;
;                         f32x4 xv = *(const f32x4*)(zsrc + (size_t)row * DM + col);
;                         if (stin) { const f32x4 gv = *(const f32x4*)(gin + col), bv = *(const f32x4*)(bin + col); xv = (xv - mu) * rs * gv + bv; }
;                         f32x4 zz = ALPHA * xv + acc[ai][bj][m][n];
;                         if (bias) zz += *(const f32x4*)(bias + col);
;                         *(f32x4*)(zdst + (size_t)row * DM + col) = zz;
;                         sum += zz[0] + zz[1] + zz[2] + zz[3]; sq += zz[0] * zz[0] + zz[1] * zz[1] + zz[2] * zz[2] + zz[3] * zz[3];
;                         z[n] = zz;
;                     }
;                     u32x4 o; o.x = pk2(z[0][0], z[0][1]); o.y = pk2(z[0][2], z[0][3]); o.z = pk2(z[1][0], z[1][1]); o.w = pk2(z[1][2], z[1][3]);
;                     if (zb) *(u32x4*)(zb + (size_t)row * DM + colb + bj * 128) = o;
;                 }
;                 sum += __shfl_xor(sum, 16); sq += __shfl_xor(sq, 16);
;                 sum += __shfl_xor(sum, 32); sq += __shfl_xor(sq, 32);
;                 if (fq == 0) { atomicAdd(stout + 2 * (size_t)row, sum); atomicAdd(stout + 2 * (size_t)row + 1, sq); }
	v_sub_f32_e32 v165, v165, v193
	v_sub_f32_e32 v164, v164, v193
	v_sub_f32_e32 v163, v163, v193
	v_sub_f32_e32 v162, v162, v193
	v_pk_mul_f32 v[162:163], v[192:193], v[162:163] op_sel_hi:[0,1]
	v_pk_mul_f32 v[164:165], v[192:193], v[164:165] op_sel_hi:[0,1]
	v_pk_fma_f32 v[164:165], v[178:179], v[164:165], v[182:183]
	v_pk_fma_f32 v[162:163], v[176:177], v[162:163], v[180:181]
	v_pk_fma_f32 v[102:103], v[164:165], s[24:25], v[102:103] op_sel_hi:[1,0,1]
	v_pk_fma_f32 v[100:101], v[162:163], s[24:25], v[100:101] op_sel_hi:[1,0,1]
	v_pk_add_f32 v[102:103], v[186:187], v[102:103]
	v_pk_add_f32 v[100:101], v[184:185], v[100:101]
	global_store_dwordx4 v[114:115], v[100:103], off offset:512
	global_load_dwordx4 v[162:165], v[120:121], off
	global_load_dwordx4 v[176:179], v[122:123], off
	global_load_dwordx4 v[180:183], v[116:117], off
	v_sub_f32_e32 v107, v189, v193
	v_sub_f32_e32 v106, v188, v193
	v_sub_f32_e32 v105, v191, v193
	v_sub_f32_e32 v104, v190, v193
	v_pk_mul_f32 v[106:107], v[192:193], v[106:107] op_sel_hi:[0,1]
	v_pk_mul_f32 v[104:105], v[192:193], v[104:105] op_sel_hi:[0,1]
	v_mul_f32_e32 v111, v101, v101
	v_add_f32_e32 v110, v100, v101
	v_fmac_f32_e32 v111, v100, v100
	v_add_f32_e32 v110, v102, v110
	v_fmac_f32_e32 v111, v102, v102
	v_add_f32_e32 v110, v103, v110
	v_fmac_f32_e32 v111, v103, v103
	v_add_f32_e32 v108, v108, v110
	v_add_f32_e32 v109, v109, v111
	v_cvt_pk_bf16_f32 v100, v100, v101
	v_cvt_pk_bf16_f32 v101, v102, v103
	s_waitcnt vmcnt(0)
	v_pk_fma_f32 v[106:107], v[162:163], v[106:107], v[176:177]
	v_pk_fma_f32 v[104:105], v[164:165], v[104:105], v[178:179]
	v_pk_fma_f32 v[96:97], v[106:107], s[24:25], v[96:97] op_sel_hi:[1,0,1]
	v_pk_fma_f32 v[98:99], v[104:105], s[24:25], v[98:99] op_sel_hi:[1,0,1]
	v_pk_add_f32 v[104:105], v[180:181], v[96:97]
	v_pk_add_f32 v[106:107], v[182:183], v[98:99]
	v_mul_f32_e32 v97, v105, v105
	v_add_f32_e32 v96, v104, v105
	v_fmac_f32_e32 v97, v104, v104
	v_add_f32_e32 v96, v106, v96
	v_fmac_f32_e32 v97, v106, v106
	v_add_f32_e32 v96, v107, v96
	v_fmac_f32_e32 v97, v107, v107
	v_add_f32_e32 v96, v108, v96
	v_add_f32_e32 v97, v109, v97
	ds_bpermute_b32 v98, v118, v96
	ds_bpermute_b32 v99, v118, v97
	global_store_dwordx4 v[114:115], v[104:107], off offset:528
	v_cvt_pk_bf16_f32 v102, v104, v105
	v_cvt_pk_bf16_f32 v103, v106, v107
	s_waitcnt lgkmcnt(0)
	v_add_f32_e32 v96, v96, v98
	v_add_f32_e32 v97, v97, v99
	ds_bpermute_b32 v98, v119, v96
	ds_bpermute_b32 v99, v119, v97
	flat_store_dwordx4 v[166:167], v[100:103] offset:256
	s_mov_b32 s100, -1
	s_mov_b32 s101, 0
	s_mov_b32 s98, 0xffff0000
	s_mov_b32 s99, 0
	s_and_saveexec_b64 s[36:37], s[100:101]
	s_cbranch_execz .LBB0_2640
	v_lshl_add_u64 v[100:101], s[8:9], 0, v[112:113]
	s_waitcnt lgkmcnt(0)
	v_add_f32_e32 v96, v96, v98
	v_add_f32_e32 v97, v97, v99
	v_cndmask_b32_e64 v96, v96, v97, s[98:99]
	v_cndmask_b32_e64 v97, 0, 4, s[98:99]
	v_or_b32_e32 v100, v100, v97
	flat_atomic_add_f32 v[100:101], v96
.LBB0_2640:
	s_or_b64 exec, exec, s[36:37]
	v_or_b32_e32 v166, 32, v154
	v_ashrrev_i32_e32 v167, 31, v166
	v_lshlrev_b64 v[96:97], 3, v[166:167]
	s_waitcnt lgkmcnt(0)
	v_lshl_add_u64 v[98:99], s[6:7], 0, v[96:97]
	flat_load_dwordx2 v[176:177], v[98:99]
	v_lshlrev_b64 v[98:99], 12, v[166:167]
	v_lshl_add_u64 v[98:99], s[46:47], 0, v[98:99]
	v_lshl_add_u64 v[98:99], v[144:145], 2, v[98:99]
	global_load_dwordx4 v[100:103], v[98:99], off
	global_load_dwordx4 v[104:107], v[150:151], off
	global_load_dwordx4 v[108:111], v[152:153], off
	global_load_dwordx4 v[112:115], v[156:157], off
	global_load_dwordx4 v[162:165], v[98:99], off offset:16
	s_waitcnt vmcnt(0) lgkmcnt(0)
	v_pk_mul_f32 v[176:177], v[176:177], s[22:23] op_sel:[1,0] op_sel_hi:[0,0]
	v_fma_f32 v155, -v177, v177, v176
	v_max_f32_e32 v155, 0, v155
	v_add_f32_e32 v155, 0x3727c5ac, v155
	v_mul_f32_e32 v175, 0x4b800000, v155
	v_cmp_gt_f32_e32 vcc, s64, v155
	v_sub_f32_e32 v103, v103, v177
	v_sub_f32_e32 v102, v102, v177
	v_cndmask_b32_e32 v155, v155, v175, vcc
	v_rsq_f32_e32 v155, v155
	v_sub_f32_e32 v101, v101, v177
	v_sub_f32_e32 v100, v100, v177
	v_mul_f32_e32 v175, 0x45800000, v155
	v_cndmask_b32_e32 v176, v155, v175, vcc
	v_pk_mul_f32 v[100:101], v[100:101], v[176:177] op_sel_hi:[1,0]
	v_pk_mul_f32 v[102:103], v[102:103], v[176:177] op_sel_hi:[1,0]
	v_pk_fma_f32 v[100:101], v[104:105], v[100:101], v[108:109]
	v_pk_fma_f32 v[102:103], v[106:107], v[102:103], v[110:111]
	v_pk_fma_f32 v[92:93], v[100:101], s[24:25], v[92:93] op_sel_hi:[1,0,1]
	v_pk_fma_f32 v[94:95], v[102:103], s[24:25], v[94:95] op_sel_hi:[1,0,1]
	v_pk_add_f32 v[92:93], v[112:113], v[92:93]
	v_pk_add_f32 v[94:95], v[114:115], v[94:95]
	global_store_dwordx4 v[98:99], v[92:95], off
	global_load_dwordx4 v[100:103], v[146:147], off
	global_load_dwordx4 v[104:107], v[148:149], off
	global_load_dwordx4 v[108:111], v[124:125], off
	v_lshlrev_b64 v[112:113], 11, v[166:167]
	v_lshl_add_u64 v[112:113], s[10:11], 0, v[112:113]
	v_lshl_add_u64 v[166:167], v[144:145], 1, v[112:113]
	v_sub_f32_e32 v113, v165, v177
	v_sub_f32_e32 v112, v164, v177
	v_sub_f32_e32 v115, v163, v177
	v_sub_f32_e32 v114, v162, v177
	v_pk_mul_f32 v[114:115], v[114:115], v[176:177] op_sel_hi:[1,0]
	v_pk_mul_f32 v[162:163], v[112:113], v[176:177] op_sel_hi:[1,0]
	v_cvt_pk_bf16_f32 v112, v92, v93
	v_cvt_pk_bf16_f32 v113, v94, v95
	s_waitcnt vmcnt(1)
	v_pk_fma_f32 v[100:101], v[100:101], v[114:115], v[104:105]
	v_pk_fma_f32 v[102:103], v[102:103], v[162:163], v[106:107]
	v_pk_fma_f32 v[88:89], v[100:101], s[24:25], v[88:89] op_sel_hi:[1,0,1]
	v_pk_fma_f32 v[90:91], v[102:103], s[24:25], v[90:91] op_sel_hi:[1,0,1]
	s_waitcnt vmcnt(0)
; DEVI unsigned pk2(float lo, float hi) { unsigned r; asm("v_cvt_pk_bf16_f32 %0, %1, %2" : "=v"(r) : "v"(lo), "v"(hi)); return r; }
;     DEVI void operator()(const f32x4 (&acc)[2][2][4][2], const pg8::Unit& u, int wr, int wc, int fr, int fq) const {
;     ...
;                 const int row = row0 + ai * 128 + m * 16; float mu, rs; row_stats(stin, row, mu, rs);
;                 float sum = 0.f, sq = 0.f;
; #pragma unroll
;                 for (int bj = 0; bj < 2; ++bj) {
;                     f32x4 z[2];
; #pragma unroll
;                     for (int n = 0; n < 2; ++n) {
;                         const int col = colb + bj * 128 + 4 * n;
;                         f32x4 xv = *(const f32x4*)(zsrc + (size_t)row * DM + col);
;                         if (stin) { const f32x4 gv = *(const f32x4*)(gin + col), bv = *(const f32x4*)(bin + col); xv = (xv - mu) * rs * gv + bv; }
;                         f32x4 zz = ALPHA * xv + acc[ai][bj][m][n];
;                         if (bias) zz += *(const f32x4*)(bias + col);
;                         *(f32x4*)(zdst + (size_t)row * DM + col) = zz;
;                         sum += zz[0] + zz[1] + zz[2] + zz[3]; sq += zz[0] * zz[0] + zz[1] * zz[1] + zz[2] * zz[2] + zz[3] * zz[3];
;                         z[n] = zz;
;                     }
;                     u32x4 o; o.x = pk2(z[0][0], z[0][1]); o.y = pk2(z[0][2], z[0][3]); o.z = pk2(z[1][0], z[1][1]); o.w = pk2(z[1][2], z[1][3]);
;                     if (zb) *(u32x4*)(zb + (size_t)row * DM + colb + bj * 128) = o;
;                 }
;                 sum += __shfl_xor(sum, 16); sq += __shfl_xor(sq, 16);
;                 sum += __shfl_xor(sum, 32); sq += __shfl_xor(sq, 32);
;                 if (fq == 0) { atomicAdd(stout + 2 * (size_t)row, sum); atomicAdd(stout + 2 * (size_t)row + 1, sq); }
	v_pk_add_f32 v[88:89], v[108:109], v[88:89]
	v_pk_add_f32 v[90:91], v[110:111], v[90:91]
	global_store_dwordx4 v[98:99], v[88:91], off offset:16
	v_cvt_pk_bf16_f32 v114, v88, v89
	v_cvt_pk_bf16_f32 v115, v90, v91
	flat_store_dwordx4 v[166:167], v[112:115]
	global_load_dwordx4 v[100:103], v[98:99], off offset:512
	global_load_dwordx4 v[104:107], v[126:127], off
	global_load_dwordx4 v[108:111], v[158:159], off
	s_nop 0
	global_load_dwordx4 v[112:115], v[160:161], off
	global_load_dwordx4 v[162:165], v[98:99], off offset:528
	s_waitcnt vmcnt(0)
	v_sub_f32_e32 v103, v103, v177
	v_sub_f32_e32 v102, v102, v177
	v_sub_f32_e32 v101, v101, v177
	v_sub_f32_e32 v100, v100, v177
	v_pk_mul_f32 v[100:101], v[176:177], v[100:101] op_sel_hi:[0,1]
	v_pk_mul_f32 v[102:103], v[176:177], v[102:103] op_sel_hi:[0,1]
	v_pk_fma_f32 v[102:103], v[106:107], v[102:103], v[110:111]
	v_pk_fma_f32 v[100:101], v[104:105], v[100:101], v[108:109]
	v_pk_fma_f32 v[86:87], v[102:103], s[24:25], v[86:87] op_sel_hi:[1,0,1]
	v_pk_fma_f32 v[84:85], v[100:101], s[24:25], v[84:85] op_sel_hi:[1,0,1]
	v_pk_add_f32 v[86:87], v[114:115], v[86:87]
	v_pk_add_f32 v[84:85], v[112:113], v[84:85]
	global_store_dwordx4 v[98:99], v[84:87], off offset:512
	global_load_dwordx4 v[100:103], v[120:121], off
	global_load_dwordx4 v[104:107], v[122:123], off
	global_load_dwordx4 v[108:111], v[116:117], off
	v_add_f32_e32 v112, v92, v93
	v_mul_f32_e32 v93, v93, v93
	v_fmac_f32_e32 v93, v92, v92
	v_add_f32_e32 v112, v94, v112
	v_fmac_f32_e32 v93, v94, v94
	v_add_f32_e32 v94, v88, v89
	v_mul_f32_e32 v89, v89, v89
	v_fmac_f32_e32 v89, v88, v88
	v_add_f32_e32 v92, v95, v112
	v_add_f32_e32 v94, v90, v94
	v_fmac_f32_e32 v89, v90, v90
	v_add_f32_e32 v92, 0, v92
	v_fmac_f32_e32 v93, v95, v95
	v_add_f32_e32 v88, v91, v94
	v_fmac_f32_e32 v89, v91, v91
	v_sub_f32_e32 v91, v163, v177
	v_sub_f32_e32 v90, v162, v177
	v_add_f32_e32 v92, v88, v92
	v_add_f32_e32 v93, v93, v89
	v_sub_f32_e32 v89, v165, v177
	v_sub_f32_e32 v88, v164, v177
	v_pk_mul_f32 v[90:91], v[176:177], v[90:91] op_sel_hi:[0,1]
	v_pk_mul_f32 v[88:89], v[176:177], v[88:89] op_sel_hi:[0,1]
	v_mul_f32_e32 v95, v85, v85
	v_add_f32_e32 v94, v84, v85
	v_fmac_f32_e32 v95, v84, v84
	v_add_f32_e32 v94, v86, v94
	v_fmac_f32_e32 v95, v86, v86
	v_add_f32_e32 v94, v87, v94
	v_fmac_f32_e32 v95, v87, v87
	v_add_f32_e32 v92, v92, v94
	v_add_f32_e32 v93, v93, v95
	v_cvt_pk_bf16_f32 v84, v84, v85
	v_cvt_pk_bf16_f32 v85, v86, v87
	s_waitcnt vmcnt(0)
	v_pk_fma_f32 v[90:91], v[100:101], v[90:91], v[104:105]
	v_pk_fma_f32 v[88:89], v[102:103], v[88:89], v[106:107]
	v_pk_fma_f32 v[80:81], v[90:91], s[24:25], v[80:81] op_sel_hi:[1,0,1]
	v_pk_fma_f32 v[82:83], v[88:89], s[24:25], v[82:83] op_sel_hi:[1,0,1]
	v_pk_add_f32 v[88:89], v[108:109], v[80:81]
	v_pk_add_f32 v[90:91], v[110:111], v[82:83]
	v_mul_f32_e32 v81, v89, v89
	v_add_f32_e32 v80, v88, v89
	v_fmac_f32_e32 v81, v88, v88
	v_add_f32_e32 v80, v90, v80
	v_fmac_f32_e32 v81, v90, v90
	v_add_f32_e32 v80, v91, v80
	v_fmac_f32_e32 v81, v91, v91
	v_add_f32_e32 v80, v92, v80
	v_add_f32_e32 v81, v93, v81
	ds_bpermute_b32 v82, v118, v80
	ds_bpermute_b32 v83, v118, v81
	global_store_dwordx4 v[98:99], v[88:91], off offset:528
	v_cvt_pk_bf16_f32 v86, v88, v89
	v_cvt_pk_bf16_f32 v87, v90, v91
	s_waitcnt lgkmcnt(0)
	v_add_f32_e32 v80, v80, v82
	v_add_f32_e32 v81, v81, v83
	ds_bpermute_b32 v82, v119, v80
	ds_bpermute_b32 v83, v119, v81
	flat_store_dwordx4 v[166:167], v[84:87] offset:256
	s_mov_b32 s100, -1
	s_mov_b32 s101, 0
	s_mov_b32 s98, 0xffff0000
	s_mov_b32 s99, 0
	s_and_saveexec_b64 s[36:37], s[100:101]
	s_cbranch_execz .LBB0_2642
	v_lshl_add_u64 v[84:85], s[8:9], 0, v[96:97]
	s_waitcnt lgkmcnt(0)
	v_add_f32_e32 v80, v80, v82
	v_add_f32_e32 v81, v81, v83
	v_cndmask_b32_e64 v80, v80, v81, s[98:99]
	v_cndmask_b32_e64 v81, 0, 4, s[98:99]
	v_or_b32_e32 v84, v84, v81
	flat_atomic_add_f32 v[84:85], v80
.LBB0_2642:
	s_or_b64 exec, exec, s[36:37]
	v_or_b32_e32 v104, 48, v154
	v_ashrrev_i32_e32 v105, 31, v104
	v_lshlrev_b64 v[80:81], 3, v[104:105]
	s_waitcnt lgkmcnt(0)
	v_lshl_add_u64 v[82:83], s[6:7], 0, v[80:81]
	flat_load_dwordx2 v[106:107], v[82:83]
	v_lshlrev_b64 v[82:83], 12, v[104:105]
	v_lshl_add_u64 v[82:83], s[46:47], 0, v[82:83]
	v_lshl_add_u64 v[82:83], v[144:145], 2, v[82:83]
	global_load_dwordx4 v[84:87], v[82:83], off
	global_load_dwordx4 v[88:91], v[150:151], off
	global_load_dwordx4 v[92:95], v[152:153], off
	global_load_dwordx4 v[96:99], v[156:157], off
	global_load_dwordx4 v[100:103], v[82:83], off offset:16
	s_waitcnt vmcnt(0) lgkmcnt(0)
	v_pk_mul_f32 v[106:107], v[106:107], s[22:23] op_sel:[1,0] op_sel_hi:[0,0]
	v_fma_f32 v106, -v107, v107, v106
	v_max_f32_e32 v106, 0, v106
	v_add_f32_e32 v106, 0x3727c5ac, v106
	v_mul_f32_e32 v108, 0x4b800000, v106
	v_cmp_gt_f32_e32 vcc, s64, v106
	v_sub_f32_e32 v87, v87, v107
	v_sub_f32_e32 v86, v86, v107
	v_cndmask_b32_e32 v106, v106, v108, vcc
	v_rsq_f32_e32 v106, v106
	v_sub_f32_e32 v85, v85, v107
	v_sub_f32_e32 v84, v84, v107
	v_mul_f32_e32 v108, 0x45800000, v106
	v_cndmask_b32_e32 v106, v106, v108, vcc
	v_pk_mul_f32 v[84:85], v[84:85], v[106:107] op_sel_hi:[1,0]
	v_pk_mul_f32 v[86:87], v[86:87], v[106:107] op_sel_hi:[1,0]
	v_pk_fma_f32 v[84:85], v[88:89], v[84:85], v[92:93]
	v_pk_fma_f32 v[86:87], v[90:91], v[86:87], v[94:95]
	v_pk_fma_f32 v[76:77], v[84:85], s[24:25], v[76:77] op_sel_hi:[1,0,1]
	v_pk_fma_f32 v[78:79], v[86:87], s[24:25], v[78:79] op_sel_hi:[1,0,1]
	v_pk_add_f32 v[76:77], v[96:97], v[76:77]
	v_pk_add_f32 v[78:79], v[98:99], v[78:79]
	global_store_dwordx4 v[82:83], v[76:79], off
	global_load_dwordx4 v[84:87], v[146:147], off
	global_load_dwordx4 v[88:91], v[148:149], off
	global_load_dwordx4 v[92:95], v[124:125], off
	v_lshlrev_b64 v[96:97], 11, v[104:105]
	v_lshl_add_u64 v[96:97], s[10:11], 0, v[96:97]
	v_lshl_add_u64 v[104:105], v[144:145], 1, v[96:97]
	v_sub_f32_e32 v97, v103, v107
	v_sub_f32_e32 v96, v102, v107
	v_sub_f32_e32 v99, v101, v107
	v_sub_f32_e32 v98, v100, v107
	v_pk_mul_f32 v[98:99], v[98:99], v[106:107] op_sel_hi:[1,0]
	v_pk_mul_f32 v[100:101], v[96:97], v[106:107] op_sel_hi:[1,0]
	v_cvt_pk_bf16_f32 v96, v76, v77
	v_cvt_pk_bf16_f32 v97, v78, v79
	s_waitcnt vmcnt(1)
; DEVI unsigned pk2(float lo, float hi) { unsigned r; asm("v_cvt_pk_bf16_f32 %0, %1, %2" : "=v"(r) : "v"(lo), "v"(hi)); return r; }
;     DEVI void operator()(const f32x4 (&acc)[2][2][4][2], const pg8::Unit& u, int wr, int wc, int fr, int fq) const {
;     ...
;                 const int row = row0 + ai * 128 + m * 16; float mu, rs; row_stats(stin, row, mu, rs);
;                 float sum = 0.f, sq = 0.f;
; #pragma unroll
;                 for (int bj = 0; bj < 2; ++bj) {
;                     f32x4 z[2];
; #pragma unroll
;                     for (int n = 0; n < 2; ++n) {
;                         const int col = colb + bj * 128 + 4 * n;
;                         f32x4 xv = *(const f32x4*)(zsrc + (size_t)row * DM + col);
;                         if (stin) { const f32x4 gv = *(const f32x4*)(gin + col), bv = *(const f32x4*)(bin + col); xv = (xv - mu) * rs * gv + bv; }
;                         f32x4 zz = ALPHA * xv + acc[ai][bj][m][n];
;                         if (bias) zz += *(const f32x4*)(bias + col);
;                         *(f32x4*)(zdst + (size_t)row * DM + col) = zz;
;                         sum += zz[0] + zz[1] + zz[2] + zz[3]; sq += zz[0] * zz[0] + zz[1] * zz[1] + zz[2] * zz[2] + zz[3] * zz[3];
;                         z[n] = zz;
;                     }
;                     u32x4 o; o.x = pk2(z[0][0], z[0][1]); o.y = pk2(z[0][2], z[0][3]); o.z = pk2(z[1][0], z[1][1]); o.w = pk2(z[1][2], z[1][3]);
;                     if (zb) *(u32x4*)(zb + (size_t)row * DM + colb + bj * 128) = o;
;                 }
;                 sum += __shfl_xor(sum, 16); sq += __shfl_xor(sq, 16);
;                 sum += __shfl_xor(sum, 32); sq += __shfl_xor(sq, 32);
;                 if (fq == 0) { atomicAdd(stout + 2 * (size_t)row, sum); atomicAdd(stout + 2 * (size_t)row + 1, sq); }
	v_pk_fma_f32 v[84:85], v[84:85], v[98:99], v[88:89]
	v_pk_fma_f32 v[86:87], v[86:87], v[100:101], v[90:91]
	v_pk_fma_f32 v[72:73], v[84:85], s[24:25], v[72:73] op_sel_hi:[1,0,1]
	v_pk_fma_f32 v[74:75], v[86:87], s[24:25], v[74:75] op_sel_hi:[1,0,1]
	s_waitcnt vmcnt(0)
	v_pk_add_f32 v[72:73], v[92:93], v[72:73]
	v_pk_add_f32 v[74:75], v[94:95], v[74:75]
	global_store_dwordx4 v[82:83], v[72:75], off offset:16
	v_cvt_pk_bf16_f32 v98, v72, v73
	v_cvt_pk_bf16_f32 v99, v74, v75
	flat_store_dwordx4 v[104:105], v[96:99]
	global_load_dwordx4 v[84:87], v[82:83], off offset:512
	global_load_dwordx4 v[88:91], v[126:127], off
	global_load_dwordx4 v[92:95], v[158:159], off
	s_nop 0
	global_load_dwordx4 v[96:99], v[160:161], off
	global_load_dwordx4 v[100:103], v[82:83], off offset:528
	s_waitcnt vmcnt(0)
	v_sub_f32_e32 v87, v87, v107
	v_sub_f32_e32 v86, v86, v107
	v_sub_f32_e32 v85, v85, v107
	v_sub_f32_e32 v84, v84, v107
	v_pk_mul_f32 v[84:85], v[106:107], v[84:85] op_sel_hi:[0,1]
	v_pk_mul_f32 v[86:87], v[106:107], v[86:87] op_sel_hi:[0,1]
	v_pk_fma_f32 v[86:87], v[90:91], v[86:87], v[94:95]
	v_pk_fma_f32 v[84:85], v[88:89], v[84:85], v[92:93]
	v_pk_fma_f32 v[70:71], v[86:87], s[24:25], v[70:71] op_sel_hi:[1,0,1]
	v_pk_fma_f32 v[68:69], v[84:85], s[24:25], v[68:69] op_sel_hi:[1,0,1]
	v_pk_add_f32 v[70:71], v[98:99], v[70:71]
	v_pk_add_f32 v[68:69], v[96:97], v[68:69]
	global_store_dwordx4 v[82:83], v[68:71], off offset:512
	global_load_dwordx4 v[84:87], v[120:121], off
	global_load_dwordx4 v[88:91], v[122:123], off
	global_load_dwordx4 v[92:95], v[116:117], off
	v_add_f32_e32 v96, v76, v77
	v_mul_f32_e32 v77, v77, v77
	v_fmac_f32_e32 v77, v76, v76
	v_add_f32_e32 v96, v78, v96
	v_fmac_f32_e32 v77, v78, v78
	v_add_f32_e32 v78, v72, v73
	v_mul_f32_e32 v73, v73, v73
	v_fmac_f32_e32 v73, v72, v72
	v_add_f32_e32 v76, v79, v96
	v_add_f32_e32 v78, v74, v78
	v_fmac_f32_e32 v73, v74, v74
	v_add_f32_e32 v76, 0, v76
	v_fmac_f32_e32 v77, v79, v79
	v_add_f32_e32 v72, v75, v78
	v_fmac_f32_e32 v73, v75, v75
	v_sub_f32_e32 v75, v101, v107
	v_sub_f32_e32 v74, v100, v107
	v_add_f32_e32 v76, v72, v76
	v_add_f32_e32 v77, v77, v73
	v_sub_f32_e32 v73, v103, v107
	v_sub_f32_e32 v72, v102, v107
	v_pk_mul_f32 v[74:75], v[106:107], v[74:75] op_sel_hi:[0,1]
	v_pk_mul_f32 v[72:73], v[106:107], v[72:73] op_sel_hi:[0,1]
	v_mul_f32_e32 v79, v69, v69
	v_add_f32_e32 v78, v68, v69
	v_fmac_f32_e32 v79, v68, v68
	v_add_f32_e32 v78, v70, v78
	v_fmac_f32_e32 v79, v70, v70
	v_add_f32_e32 v78, v71, v78
	v_fmac_f32_e32 v79, v71, v71
	v_add_f32_e32 v76, v76, v78
	v_add_f32_e32 v77, v77, v79
	v_cvt_pk_bf16_f32 v68, v68, v69
	v_cvt_pk_bf16_f32 v69, v70, v71
	s_waitcnt vmcnt(0)
	v_pk_fma_f32 v[74:75], v[84:85], v[74:75], v[88:89]
	v_pk_fma_f32 v[72:73], v[86:87], v[72:73], v[90:91]
	v_pk_fma_f32 v[64:65], v[74:75], s[24:25], v[64:65] op_sel_hi:[1,0,1]
	v_pk_fma_f32 v[66:67], v[72:73], s[24:25], v[66:67] op_sel_hi:[1,0,1]
	v_pk_add_f32 v[72:73], v[92:93], v[64:65]
	v_pk_add_f32 v[74:75], v[94:95], v[66:67]
	v_mul_f32_e32 v65, v73, v73
	v_add_f32_e32 v64, v72, v73
	v_fmac_f32_e32 v65, v72, v72
	v_add_f32_e32 v64, v74, v64
	v_fmac_f32_e32 v65, v74, v74
	v_add_f32_e32 v64, v75, v64
	v_fmac_f32_e32 v65, v75, v75
	v_add_f32_e32 v64, v76, v64
	v_add_f32_e32 v65, v77, v65
	ds_bpermute_b32 v66, v118, v64
	ds_bpermute_b32 v67, v118, v65
	global_store_dwordx4 v[82:83], v[72:75], off offset:528
	v_cvt_pk_bf16_f32 v70, v72, v73
	v_cvt_pk_bf16_f32 v71, v74, v75
	s_waitcnt lgkmcnt(0)
	v_add_f32_e32 v64, v64, v66
	v_add_f32_e32 v65, v65, v67
	ds_bpermute_b32 v66, v119, v64
	ds_bpermute_b32 v67, v119, v65
	flat_store_dwordx4 v[104:105], v[68:71] offset:256
	s_mov_b32 s100, -1
	s_mov_b32 s101, 0
	s_mov_b32 s98, 0xffff0000
	s_mov_b32 s99, 0
	s_and_saveexec_b64 s[36:37], s[100:101]
	s_cbranch_execz .LBB0_2644
	v_lshl_add_u64 v[68:69], s[8:9], 0, v[80:81]
	s_waitcnt lgkmcnt(0)
	v_add_f32_e32 v64, v64, v66
	v_add_f32_e32 v65, v65, v67
	v_cndmask_b32_e64 v64, v64, v65, s[98:99]
	v_cndmask_b32_e64 v65, 0, 4, s[98:99]
	v_or_b32_e32 v68, v68, v65
	flat_atomic_add_f32 v[68:69], v64
.LBB0_2644:
	s_or_b64 exec, exec, s[36:37]
	v_add_u32_e32 v88, 0x80, v154
	v_ashrrev_i32_e32 v89, 31, v88
	v_lshlrev_b64 v[64:65], 3, v[88:89]
	s_waitcnt lgkmcnt(0)
	v_lshl_add_u64 v[66:67], s[6:7], 0, v[64:65]
	flat_load_dwordx2 v[90:91], v[66:67]
	v_lshlrev_b64 v[66:67], 12, v[88:89]
	v_lshl_add_u64 v[66:67], s[46:47], 0, v[66:67]
	v_lshl_add_u64 v[66:67], v[144:145], 2, v[66:67]
	global_load_dwordx4 v[68:71], v[66:67], off
	global_load_dwordx4 v[72:75], v[150:151], off
	global_load_dwordx4 v[76:79], v[152:153], off
	global_load_dwordx4 v[80:83], v[156:157], off
	global_load_dwordx4 v[84:87], v[66:67], off offset:16
	s_waitcnt vmcnt(0) lgkmcnt(0)
	v_pk_mul_f32 v[90:91], v[90:91], s[22:23] op_sel:[1,0] op_sel_hi:[0,0]
	v_fma_f32 v90, -v91, v91, v90
	v_max_f32_e32 v90, 0, v90
	v_add_f32_e32 v90, 0x3727c5ac, v90
	v_mul_f32_e32 v92, 0x4b800000, v90
	v_cmp_gt_f32_e32 vcc, s64, v90
	v_sub_f32_e32 v71, v71, v91
	v_sub_f32_e32 v70, v70, v91
	v_cndmask_b32_e32 v90, v90, v92, vcc
	v_rsq_f32_e32 v90, v90
	v_sub_f32_e32 v69, v69, v91
	v_sub_f32_e32 v68, v68, v91
	v_mul_f32_e32 v92, 0x45800000, v90
	v_cndmask_b32_e32 v90, v90, v92, vcc
	v_pk_mul_f32 v[68:69], v[68:69], v[90:91] op_sel_hi:[1,0]
	v_pk_mul_f32 v[70:71], v[70:71], v[90:91] op_sel_hi:[1,0]
	v_pk_fma_f32 v[68:69], v[72:73], v[68:69], v[76:77]
	v_pk_fma_f32 v[70:71], v[74:75], v[70:71], v[78:79]
	v_pk_fma_f32 v[60:61], v[68:69], s[24:25], v[60:61] op_sel_hi:[1,0,1]
	v_pk_fma_f32 v[62:63], v[70:71], s[24:25], v[62:63] op_sel_hi:[1,0,1]
	v_pk_add_f32 v[60:61], v[80:81], v[60:61]
	v_pk_add_f32 v[62:63], v[82:83], v[62:63]
	global_store_dwordx4 v[66:67], v[60:63], off
	global_load_dwordx4 v[68:71], v[146:147], off
	global_load_dwordx4 v[72:75], v[148:149], off
	global_load_dwordx4 v[76:79], v[124:125], off
	v_lshlrev_b64 v[80:81], 11, v[88:89]
	v_lshl_add_u64 v[80:81], s[10:11], 0, v[80:81]
	v_lshl_add_u64 v[88:89], v[144:145], 1, v[80:81]
	v_sub_f32_e32 v81, v87, v91
	v_sub_f32_e32 v80, v86, v91
	v_sub_f32_e32 v83, v85, v91
	v_sub_f32_e32 v82, v84, v91
	v_pk_mul_f32 v[82:83], v[82:83], v[90:91] op_sel_hi:[1,0]
	v_pk_mul_f32 v[84:85], v[80:81], v[90:91] op_sel_hi:[1,0]
	v_cvt_pk_bf16_f32 v80, v60, v61
	v_cvt_pk_bf16_f32 v81, v62, v63
	s_waitcnt vmcnt(1)
; DEVI unsigned pk2(float lo, float hi) { unsigned r; asm("v_cvt_pk_bf16_f32 %0, %1, %2" : "=v"(r) : "v"(lo), "v"(hi)); return r; }
;     DEVI void operator()(const f32x4 (&acc)[2][2][4][2], const pg8::Unit& u, int wr, int wc, int fr, int fq) const {
;     ...
;                 const int row = row0 + ai * 128 + m * 16; float mu, rs; row_stats(stin, row, mu, rs);
;                 float sum = 0.f, sq = 0.f;
; #pragma unroll
;                 for (int bj = 0; bj < 2; ++bj) {
;                     f32x4 z[2];
; #pragma unroll
;                     for (int n = 0; n < 2; ++n) {
;                         const int col = colb + bj * 128 + 4 * n;
;                         f32x4 xv = *(const f32x4*)(zsrc + (size_t)row * DM + col);
;                         if (stin) { const f32x4 gv = *(const f32x4*)(gin + col), bv = *(const f32x4*)(bin + col); xv = (xv - mu) * rs * gv + bv; }
;                         f32x4 zz = ALPHA * xv + acc[ai][bj][m][n];
;                         if (bias) zz += *(const f32x4*)(bias + col);
;                         *(f32x4*)(zdst + (size_t)row * DM + col) = zz;
;                         sum += zz[0] + zz[1] + zz[2] + zz[3]; sq += zz[0] * zz[0] + zz[1] * zz[1] + zz[2] * zz[2] + zz[3] * zz[3];
;                         z[n] = zz;
;                     }
;                     u32x4 o; o.x = pk2(z[0][0], z[0][1]); o.y = pk2(z[0][2], z[0][3]); o.z = pk2(z[1][0], z[1][1]); o.w = pk2(z[1][2], z[1][3]);
;                     if (zb) *(u32x4*)(zb + (size_t)row * DM + colb + bj * 128) = o;
;                 }
;                 sum += __shfl_xor(sum, 16); sq += __shfl_xor(sq, 16);
;                 sum += __shfl_xor(sum, 32); sq += __shfl_xor(sq, 32);
;                 if (fq == 0) { atomicAdd(stout + 2 * (size_t)row, sum); atomicAdd(stout + 2 * (size_t)row + 1, sq); }
	v_pk_fma_f32 v[68:69], v[68:69], v[82:83], v[72:73]
	v_pk_fma_f32 v[70:71], v[70:71], v[84:85], v[74:75]
	v_pk_fma_f32 v[56:57], v[68:69], s[24:25], v[56:57] op_sel_hi:[1,0,1]
	v_pk_fma_f32 v[58:59], v[70:71], s[24:25], v[58:59] op_sel_hi:[1,0,1]
	s_waitcnt vmcnt(0)
	v_pk_add_f32 v[56:57], v[76:77], v[56:57]
	v_pk_add_f32 v[58:59], v[78:79], v[58:59]
	global_store_dwordx4 v[66:67], v[56:59], off offset:16
	v_cvt_pk_bf16_f32 v82, v56, v57
	v_cvt_pk_bf16_f32 v83, v58, v59
	flat_store_dwordx4 v[88:89], v[80:83]
	global_load_dwordx4 v[68:71], v[66:67], off offset:512
	global_load_dwordx4 v[72:75], v[126:127], off
	global_load_dwordx4 v[76:79], v[158:159], off
	s_nop 0
	global_load_dwordx4 v[80:83], v[160:161], off
	global_load_dwordx4 v[84:87], v[66:67], off offset:528
	s_waitcnt vmcnt(0)
	v_sub_f32_e32 v71, v71, v91
	v_sub_f32_e32 v70, v70, v91
	v_sub_f32_e32 v69, v69, v91
	v_sub_f32_e32 v68, v68, v91
	v_pk_mul_f32 v[68:69], v[90:91], v[68:69] op_sel_hi:[0,1]
	v_pk_mul_f32 v[70:71], v[90:91], v[70:71] op_sel_hi:[0,1]
	v_pk_fma_f32 v[70:71], v[74:75], v[70:71], v[78:79]
	v_pk_fma_f32 v[68:69], v[72:73], v[68:69], v[76:77]
	v_pk_fma_f32 v[54:55], v[70:71], s[24:25], v[54:55] op_sel_hi:[1,0,1]
	v_pk_fma_f32 v[52:53], v[68:69], s[24:25], v[52:53] op_sel_hi:[1,0,1]
	v_pk_add_f32 v[54:55], v[82:83], v[54:55]
	v_pk_add_f32 v[52:53], v[80:81], v[52:53]
	global_store_dwordx4 v[66:67], v[52:55], off offset:512
	global_load_dwordx4 v[68:71], v[120:121], off
	global_load_dwordx4 v[72:75], v[122:123], off
	global_load_dwordx4 v[76:79], v[116:117], off
	v_add_f32_e32 v80, v60, v61
	v_mul_f32_e32 v61, v61, v61
	v_fmac_f32_e32 v61, v60, v60
	v_add_f32_e32 v80, v62, v80
	v_fmac_f32_e32 v61, v62, v62
	v_add_f32_e32 v62, v56, v57
	v_mul_f32_e32 v57, v57, v57
	v_fmac_f32_e32 v57, v56, v56
	v_add_f32_e32 v60, v63, v80
	v_add_f32_e32 v62, v58, v62
	v_fmac_f32_e32 v57, v58, v58
	v_add_f32_e32 v60, 0, v60
	v_fmac_f32_e32 v61, v63, v63
	v_add_f32_e32 v56, v59, v62
	v_fmac_f32_e32 v57, v59, v59
	v_sub_f32_e32 v59, v85, v91
	v_sub_f32_e32 v58, v84, v91
	v_add_f32_e32 v60, v56, v60
	v_add_f32_e32 v61, v61, v57
	v_sub_f32_e32 v57, v87, v91
	v_sub_f32_e32 v56, v86, v91
	v_pk_mul_f32 v[58:59], v[90:91], v[58:59] op_sel_hi:[0,1]
	v_pk_mul_f32 v[56:57], v[90:91], v[56:57] op_sel_hi:[0,1]
	v_mul_f32_e32 v63, v53, v53
	v_add_f32_e32 v62, v52, v53
	v_fmac_f32_e32 v63, v52, v52
	v_add_f32_e32 v62, v54, v62
	v_fmac_f32_e32 v63, v54, v54
	v_add_f32_e32 v62, v55, v62
	v_fmac_f32_e32 v63, v55, v55
	v_add_f32_e32 v60, v60, v62
	v_add_f32_e32 v61, v61, v63
	v_cvt_pk_bf16_f32 v52, v52, v53
	v_cvt_pk_bf16_f32 v53, v54, v55
	s_waitcnt vmcnt(0)
	v_pk_fma_f32 v[58:59], v[68:69], v[58:59], v[72:73]
	v_pk_fma_f32 v[56:57], v[70:71], v[56:57], v[74:75]
	v_pk_fma_f32 v[48:49], v[58:59], s[24:25], v[48:49] op_sel_hi:[1,0,1]
	v_pk_fma_f32 v[50:51], v[56:57], s[24:25], v[50:51] op_sel_hi:[1,0,1]
	v_pk_add_f32 v[56:57], v[76:77], v[48:49]
	v_pk_add_f32 v[58:59], v[78:79], v[50:51]
	v_mul_f32_e32 v49, v57, v57
	v_add_f32_e32 v48, v56, v57
	v_fmac_f32_e32 v49, v56, v56
	v_add_f32_e32 v48, v58, v48
	v_fmac_f32_e32 v49, v58, v58
	v_add_f32_e32 v48, v59, v48
	v_fmac_f32_e32 v49, v59, v59
	v_add_f32_e32 v48, v60, v48
	v_add_f32_e32 v49, v61, v49
	ds_bpermute_b32 v50, v118, v48
	ds_bpermute_b32 v51, v118, v49
	global_store_dwordx4 v[66:67], v[56:59], off offset:528
	v_cvt_pk_bf16_f32 v54, v56, v57
	v_cvt_pk_bf16_f32 v55, v58, v59
	s_waitcnt lgkmcnt(0)
	v_add_f32_e32 v48, v48, v50
	v_add_f32_e32 v49, v49, v51
	ds_bpermute_b32 v50, v119, v48
	ds_bpermute_b32 v51, v119, v49
	flat_store_dwordx4 v[88:89], v[52:55] offset:256
	s_mov_b32 s100, -1
	s_mov_b32 s101, 0
	s_mov_b32 s98, 0xffff0000
	s_mov_b32 s99, 0
	s_and_saveexec_b64 s[36:37], s[100:101]
	s_cbranch_execz .LBB0_2646
	v_lshl_add_u64 v[52:53], s[8:9], 0, v[64:65]
	s_waitcnt lgkmcnt(0)
	v_add_f32_e32 v48, v48, v50
	v_add_f32_e32 v49, v49, v51
	v_cndmask_b32_e64 v48, v48, v49, s[98:99]
	v_cndmask_b32_e64 v49, 0, 4, s[98:99]
	v_or_b32_e32 v52, v52, v49
	flat_atomic_add_f32 v[52:53], v48
.LBB0_2646:
	s_or_b64 exec, exec, s[36:37]
	v_add_u32_e32 v72, 0x90, v154
	v_ashrrev_i32_e32 v73, 31, v72
	v_lshlrev_b64 v[48:49], 3, v[72:73]
	s_waitcnt lgkmcnt(0)
	v_lshl_add_u64 v[50:51], s[6:7], 0, v[48:49]
	flat_load_dwordx2 v[74:75], v[50:51]
	v_lshlrev_b64 v[50:51], 12, v[72:73]
	v_lshl_add_u64 v[50:51], s[46:47], 0, v[50:51]
	v_lshl_add_u64 v[50:51], v[144:145], 2, v[50:51]
	global_load_dwordx4 v[52:55], v[50:51], off
	global_load_dwordx4 v[56:59], v[150:151], off
	global_load_dwordx4 v[60:63], v[152:153], off
	global_load_dwordx4 v[64:67], v[156:157], off
	global_load_dwordx4 v[68:71], v[50:51], off offset:16
	s_waitcnt vmcnt(0) lgkmcnt(0)
	v_pk_mul_f32 v[74:75], v[74:75], s[22:23] op_sel:[1,0] op_sel_hi:[0,0]
	v_fma_f32 v74, -v75, v75, v74
	v_max_f32_e32 v74, 0, v74
	v_add_f32_e32 v74, 0x3727c5ac, v74
	v_mul_f32_e32 v76, 0x4b800000, v74
	v_cmp_gt_f32_e32 vcc, s64, v74
	v_sub_f32_e32 v55, v55, v75
	v_sub_f32_e32 v54, v54, v75
	v_cndmask_b32_e32 v74, v74, v76, vcc
	v_rsq_f32_e32 v74, v74
	v_sub_f32_e32 v53, v53, v75
	v_sub_f32_e32 v52, v52, v75
	v_mul_f32_e32 v76, 0x45800000, v74
	v_cndmask_b32_e32 v74, v74, v76, vcc
	v_pk_mul_f32 v[52:53], v[52:53], v[74:75] op_sel_hi:[1,0]
	v_pk_mul_f32 v[54:55], v[54:55], v[74:75] op_sel_hi:[1,0]
	v_pk_fma_f32 v[52:53], v[56:57], v[52:53], v[60:61]
	v_pk_fma_f32 v[54:55], v[58:59], v[54:55], v[62:63]
	v_pk_fma_f32 v[44:45], v[52:53], s[24:25], v[44:45] op_sel_hi:[1,0,1]
	v_pk_fma_f32 v[46:47], v[54:55], s[24:25], v[46:47] op_sel_hi:[1,0,1]
	v_pk_add_f32 v[44:45], v[64:65], v[44:45]
	v_pk_add_f32 v[46:47], v[66:67], v[46:47]
	global_store_dwordx4 v[50:51], v[44:47], off
	global_load_dwordx4 v[52:55], v[146:147], off
	global_load_dwordx4 v[56:59], v[148:149], off
	global_load_dwordx4 v[60:63], v[124:125], off
	v_lshlrev_b64 v[64:65], 11, v[72:73]
	v_lshl_add_u64 v[64:65], s[10:11], 0, v[64:65]
	v_lshl_add_u64 v[72:73], v[144:145], 1, v[64:65]
	v_sub_f32_e32 v65, v71, v75
	v_sub_f32_e32 v64, v70, v75
	v_sub_f32_e32 v67, v69, v75
	v_sub_f32_e32 v66, v68, v75
	v_pk_mul_f32 v[66:67], v[66:67], v[74:75] op_sel_hi:[1,0]
	v_pk_mul_f32 v[68:69], v[64:65], v[74:75] op_sel_hi:[1,0]
	v_cvt_pk_bf16_f32 v64, v44, v45
	v_cvt_pk_bf16_f32 v65, v46, v47
	s_waitcnt vmcnt(1)
; DEVI unsigned pk2(float lo, float hi) { unsigned r; asm("v_cvt_pk_bf16_f32 %0, %1, %2" : "=v"(r) : "v"(lo), "v"(hi)); return r; }
;     DEVI void operator()(const f32x4 (&acc)[2][2][4][2], const pg8::Unit& u, int wr, int wc, int fr, int fq) const {
;     ...
;                 const int row = row0 + ai * 128 + m * 16; float mu, rs; row_stats(stin, row, mu, rs);
;                 float sum = 0.f, sq = 0.f;
; #pragma unroll
;                 for (int bj = 0; bj < 2; ++bj) {
;                     f32x4 z[2];
; #pragma unroll
;                     for (int n = 0; n < 2; ++n) {
;                         const int col = colb + bj * 128 + 4 * n;
;                         f32x4 xv = *(const f32x4*)(zsrc + (size_t)row * DM + col);
;                         if (stin) { const f32x4 gv = *(const f32x4*)(gin + col), bv = *(const f32x4*)(bin + col); xv = (xv - mu) * rs * gv + bv; }
;                         f32x4 zz = ALPHA * xv + acc[ai][bj][m][n];
;                         if (bias) zz += *(const f32x4*)(bias + col);
;                         *(f32x4*)(zdst + (size_t)row * DM + col) = zz;
;                         sum += zz[0] + zz[1] + zz[2] + zz[3]; sq += zz[0] * zz[0] + zz[1] * zz[1] + zz[2] * zz[2] + zz[3] * zz[3];
;                         z[n] = zz;
;                     }
;                     u32x4 o; o.x = pk2(z[0][0], z[0][1]); o.y = pk2(z[0][2], z[0][3]); o.z = pk2(z[1][0], z[1][1]); o.w = pk2(z[1][2], z[1][3]);
;                     if (zb) *(u32x4*)(zb + (size_t)row * DM + colb + bj * 128) = o;
;                 }
;                 sum += __shfl_xor(sum, 16); sq += __shfl_xor(sq, 16);
;                 sum += __shfl_xor(sum, 32); sq += __shfl_xor(sq, 32);
;                 if (fq == 0) { atomicAdd(stout + 2 * (size_t)row, sum); atomicAdd(stout + 2 * (size_t)row + 1, sq); }
	v_pk_fma_f32 v[52:53], v[52:53], v[66:67], v[56:57]
	v_pk_fma_f32 v[54:55], v[54:55], v[68:69], v[58:59]
	v_pk_fma_f32 v[40:41], v[52:53], s[24:25], v[40:41] op_sel_hi:[1,0,1]
	v_pk_fma_f32 v[42:43], v[54:55], s[24:25], v[42:43] op_sel_hi:[1,0,1]
	s_waitcnt vmcnt(0)
	v_pk_add_f32 v[40:41], v[60:61], v[40:41]
	v_pk_add_f32 v[42:43], v[62:63], v[42:43]
	global_store_dwordx4 v[50:51], v[40:43], off offset:16
	v_cvt_pk_bf16_f32 v66, v40, v41
	v_cvt_pk_bf16_f32 v67, v42, v43
	flat_store_dwordx4 v[72:73], v[64:67]
	global_load_dwordx4 v[52:55], v[50:51], off offset:512
	global_load_dwordx4 v[56:59], v[126:127], off
	global_load_dwordx4 v[60:63], v[158:159], off
	s_nop 0
	global_load_dwordx4 v[64:67], v[160:161], off
	global_load_dwordx4 v[68:71], v[50:51], off offset:528
	s_waitcnt vmcnt(0)
	v_sub_f32_e32 v55, v55, v75
	v_sub_f32_e32 v54, v54, v75
	v_sub_f32_e32 v53, v53, v75
	v_sub_f32_e32 v52, v52, v75
	v_pk_mul_f32 v[52:53], v[74:75], v[52:53] op_sel_hi:[0,1]
	v_pk_mul_f32 v[54:55], v[74:75], v[54:55] op_sel_hi:[0,1]
	v_pk_fma_f32 v[54:55], v[58:59], v[54:55], v[62:63]
	v_pk_fma_f32 v[52:53], v[56:57], v[52:53], v[60:61]
	v_pk_fma_f32 v[38:39], v[54:55], s[24:25], v[38:39] op_sel_hi:[1,0,1]
	v_pk_fma_f32 v[36:37], v[52:53], s[24:25], v[36:37] op_sel_hi:[1,0,1]
	v_pk_add_f32 v[38:39], v[66:67], v[38:39]
	v_pk_add_f32 v[36:37], v[64:65], v[36:37]
	global_store_dwordx4 v[50:51], v[36:39], off offset:512
	global_load_dwordx4 v[52:55], v[120:121], off
	global_load_dwordx4 v[56:59], v[122:123], off
	global_load_dwordx4 v[60:63], v[116:117], off
	v_add_f32_e32 v64, v44, v45
	v_mul_f32_e32 v45, v45, v45
	v_fmac_f32_e32 v45, v44, v44
	v_add_f32_e32 v64, v46, v64
	v_fmac_f32_e32 v45, v46, v46
	v_add_f32_e32 v46, v40, v41
	v_mul_f32_e32 v41, v41, v41
	v_fmac_f32_e32 v41, v40, v40
	v_add_f32_e32 v44, v47, v64
	v_add_f32_e32 v46, v42, v46
	v_fmac_f32_e32 v41, v42, v42
	v_add_f32_e32 v44, 0, v44
	v_fmac_f32_e32 v45, v47, v47
	v_add_f32_e32 v40, v43, v46
	v_fmac_f32_e32 v41, v43, v43
	v_sub_f32_e32 v43, v69, v75
	v_sub_f32_e32 v42, v68, v75
	v_add_f32_e32 v44, v40, v44
	v_add_f32_e32 v45, v45, v41
	v_sub_f32_e32 v41, v71, v75
	v_sub_f32_e32 v40, v70, v75
	v_pk_mul_f32 v[42:43], v[74:75], v[42:43] op_sel_hi:[0,1]
	v_pk_mul_f32 v[40:41], v[74:75], v[40:41] op_sel_hi:[0,1]
	v_mul_f32_e32 v47, v37, v37
	v_add_f32_e32 v46, v36, v37
	v_fmac_f32_e32 v47, v36, v36
	v_add_f32_e32 v46, v38, v46
	v_fmac_f32_e32 v47, v38, v38
	v_add_f32_e32 v46, v39, v46
	v_fmac_f32_e32 v47, v39, v39
	v_add_f32_e32 v44, v44, v46
	v_add_f32_e32 v45, v45, v47
	v_cvt_pk_bf16_f32 v36, v36, v37
	v_cvt_pk_bf16_f32 v37, v38, v39
	s_waitcnt vmcnt(0)
	v_pk_fma_f32 v[42:43], v[52:53], v[42:43], v[56:57]
	v_pk_fma_f32 v[40:41], v[54:55], v[40:41], v[58:59]
	v_pk_fma_f32 v[32:33], v[42:43], s[24:25], v[32:33] op_sel_hi:[1,0,1]
	v_pk_fma_f32 v[34:35], v[40:41], s[24:25], v[34:35] op_sel_hi:[1,0,1]
	v_pk_add_f32 v[40:41], v[60:61], v[32:33]
	v_pk_add_f32 v[42:43], v[62:63], v[34:35]
	v_mul_f32_e32 v33, v41, v41
	v_add_f32_e32 v32, v40, v41
	v_fmac_f32_e32 v33, v40, v40
	v_add_f32_e32 v32, v42, v32
	v_fmac_f32_e32 v33, v42, v42
	v_add_f32_e32 v32, v43, v32
	v_fmac_f32_e32 v33, v43, v43
	v_add_f32_e32 v32, v44, v32
	v_add_f32_e32 v33, v45, v33
	ds_bpermute_b32 v34, v118, v32
	ds_bpermute_b32 v35, v118, v33
	global_store_dwordx4 v[50:51], v[40:43], off offset:528
	v_cvt_pk_bf16_f32 v38, v40, v41
	v_cvt_pk_bf16_f32 v39, v42, v43
	s_waitcnt lgkmcnt(0)
	v_add_f32_e32 v32, v32, v34
	v_add_f32_e32 v33, v33, v35
	ds_bpermute_b32 v34, v119, v32
	ds_bpermute_b32 v35, v119, v33
	flat_store_dwordx4 v[72:73], v[36:39] offset:256
	s_mov_b32 s100, -1
	s_mov_b32 s101, 0
	s_mov_b32 s98, 0xffff0000
	s_mov_b32 s99, 0
	s_and_saveexec_b64 s[36:37], s[100:101]
	s_cbranch_execz .LBB0_2648
	v_lshl_add_u64 v[36:37], s[8:9], 0, v[48:49]
	s_waitcnt lgkmcnt(0)
	v_add_f32_e32 v32, v32, v34
	v_add_f32_e32 v33, v33, v35
	v_cndmask_b32_e64 v32, v32, v33, s[98:99]
	v_cndmask_b32_e64 v33, 0, 4, s[98:99]
	v_or_b32_e32 v36, v36, v33
	flat_atomic_add_f32 v[36:37], v32
.LBB0_2648:
	s_or_b64 exec, exec, s[36:37]
	v_add_u32_e32 v56, 0xa0, v154
	v_ashrrev_i32_e32 v57, 31, v56
	v_lshlrev_b64 v[32:33], 3, v[56:57]
	s_waitcnt lgkmcnt(0)
	v_lshl_add_u64 v[34:35], s[6:7], 0, v[32:33]
	flat_load_dwordx2 v[58:59], v[34:35]
	v_lshlrev_b64 v[34:35], 12, v[56:57]
	v_lshl_add_u64 v[34:35], s[46:47], 0, v[34:35]
	v_lshl_add_u64 v[34:35], v[144:145], 2, v[34:35]
	global_load_dwordx4 v[36:39], v[34:35], off
	global_load_dwordx4 v[40:43], v[150:151], off
	global_load_dwordx4 v[44:47], v[152:153], off
	global_load_dwordx4 v[48:51], v[156:157], off
	global_load_dwordx4 v[52:55], v[34:35], off offset:16
	s_waitcnt vmcnt(0) lgkmcnt(0)
	v_pk_mul_f32 v[58:59], v[58:59], s[22:23] op_sel:[1,0] op_sel_hi:[0,0]
	v_fma_f32 v58, -v59, v59, v58
	v_max_f32_e32 v58, 0, v58
	v_add_f32_e32 v58, 0x3727c5ac, v58
	v_mul_f32_e32 v60, 0x4b800000, v58
	v_cmp_gt_f32_e32 vcc, s64, v58
	v_sub_f32_e32 v39, v39, v59
	v_sub_f32_e32 v38, v38, v59
	v_cndmask_b32_e32 v58, v58, v60, vcc
	v_rsq_f32_e32 v58, v58
	v_sub_f32_e32 v37, v37, v59
	v_sub_f32_e32 v36, v36, v59
	v_mul_f32_e32 v60, 0x45800000, v58
	v_cndmask_b32_e32 v58, v58, v60, vcc
	v_pk_mul_f32 v[36:37], v[36:37], v[58:59] op_sel_hi:[1,0]
	v_pk_mul_f32 v[38:39], v[38:39], v[58:59] op_sel_hi:[1,0]
	v_pk_fma_f32 v[36:37], v[40:41], v[36:37], v[44:45]
	v_pk_fma_f32 v[38:39], v[42:43], v[38:39], v[46:47]
	v_pk_fma_f32 v[28:29], v[36:37], s[24:25], v[28:29] op_sel_hi:[1,0,1]
	v_pk_fma_f32 v[30:31], v[38:39], s[24:25], v[30:31] op_sel_hi:[1,0,1]
	v_pk_add_f32 v[28:29], v[48:49], v[28:29]
	v_pk_add_f32 v[30:31], v[50:51], v[30:31]
	global_store_dwordx4 v[34:35], v[28:31], off
	global_load_dwordx4 v[36:39], v[146:147], off
	global_load_dwordx4 v[40:43], v[148:149], off
	global_load_dwordx4 v[44:47], v[124:125], off
	v_lshlrev_b64 v[48:49], 11, v[56:57]
	v_lshl_add_u64 v[48:49], s[10:11], 0, v[48:49]
	v_lshl_add_u64 v[56:57], v[144:145], 1, v[48:49]
	v_sub_f32_e32 v49, v55, v59
	v_sub_f32_e32 v48, v54, v59
	v_sub_f32_e32 v51, v53, v59
	v_sub_f32_e32 v50, v52, v59
	v_pk_mul_f32 v[50:51], v[50:51], v[58:59] op_sel_hi:[1,0]
	v_pk_mul_f32 v[52:53], v[48:49], v[58:59] op_sel_hi:[1,0]
	v_cvt_pk_bf16_f32 v48, v28, v29
	v_cvt_pk_bf16_f32 v49, v30, v31
	s_waitcnt vmcnt(1)
; DEVI unsigned pk2(float lo, float hi) { unsigned r; asm("v_cvt_pk_bf16_f32 %0, %1, %2" : "=v"(r) : "v"(lo), "v"(hi)); return r; }
;     DEVI void operator()(const f32x4 (&acc)[2][2][4][2], const pg8::Unit& u, int wr, int wc, int fr, int fq) const {
;     ...
;                 const int row = row0 + ai * 128 + m * 16; float mu, rs; row_stats(stin, row, mu, rs);
;                 float sum = 0.f, sq = 0.f;
; #pragma unroll
;                 for (int bj = 0; bj < 2; ++bj) {
;                     f32x4 z[2];
; #pragma unroll
;                     for (int n = 0; n < 2; ++n) {
;                         const int col = colb + bj * 128 + 4 * n;
;                         f32x4 xv = *(const f32x4*)(zsrc + (size_t)row * DM + col);
;                         if (stin) { const f32x4 gv = *(const f32x4*)(gin + col), bv = *(const f32x4*)(bin + col); xv = (xv - mu) * rs * gv + bv; }
;                         f32x4 zz = ALPHA * xv + acc[ai][bj][m][n];
;                         if (bias) zz += *(const f32x4*)(bias + col);
;                         *(f32x4*)(zdst + (size_t)row * DM + col) = zz;
;                         sum += zz[0] + zz[1] + zz[2] + zz[3]; sq += zz[0] * zz[0] + zz[1] * zz[1] + zz[2] * zz[2] + zz[3] * zz[3];
;                         z[n] = zz;
;                     }
;                     u32x4 o; o.x = pk2(z[0][0], z[0][1]); o.y = pk2(z[0][2], z[0][3]); o.z = pk2(z[1][0], z[1][1]); o.w = pk2(z[1][2], z[1][3]);
;                     if (zb) *(u32x4*)(zb + (size_t)row * DM + colb + bj * 128) = o;
;                 }
;                 sum += __shfl_xor(sum, 16); sq += __shfl_xor(sq, 16);
;                 sum += __shfl_xor(sum, 32); sq += __shfl_xor(sq, 32);
;                 if (fq == 0) { atomicAdd(stout + 2 * (size_t)row, sum); atomicAdd(stout + 2 * (size_t)row + 1, sq); }
	v_pk_fma_f32 v[36:37], v[36:37], v[50:51], v[40:41]
	v_pk_fma_f32 v[38:39], v[38:39], v[52:53], v[42:43]
	v_pk_fma_f32 v[24:25], v[36:37], s[24:25], v[24:25] op_sel_hi:[1,0,1]
	v_pk_fma_f32 v[26:27], v[38:39], s[24:25], v[26:27] op_sel_hi:[1,0,1]
	s_waitcnt vmcnt(0)
	v_pk_add_f32 v[24:25], v[44:45], v[24:25]
	v_pk_add_f32 v[26:27], v[46:47], v[26:27]
	global_store_dwordx4 v[34:35], v[24:27], off offset:16
	v_cvt_pk_bf16_f32 v50, v24, v25
	v_cvt_pk_bf16_f32 v51, v26, v27
	flat_store_dwordx4 v[56:57], v[48:51]
	global_load_dwordx4 v[36:39], v[34:35], off offset:512
	global_load_dwordx4 v[40:43], v[126:127], off
	global_load_dwordx4 v[44:47], v[158:159], off
	s_nop 0
	global_load_dwordx4 v[48:51], v[160:161], off
	global_load_dwordx4 v[52:55], v[34:35], off offset:528
	s_waitcnt vmcnt(0)
	v_sub_f32_e32 v39, v39, v59
	v_sub_f32_e32 v38, v38, v59
	v_sub_f32_e32 v37, v37, v59
	v_sub_f32_e32 v36, v36, v59
	v_pk_mul_f32 v[36:37], v[58:59], v[36:37] op_sel_hi:[0,1]
	v_pk_mul_f32 v[38:39], v[58:59], v[38:39] op_sel_hi:[0,1]
	v_pk_fma_f32 v[38:39], v[42:43], v[38:39], v[46:47]
	v_pk_fma_f32 v[36:37], v[40:41], v[36:37], v[44:45]
	v_pk_fma_f32 v[22:23], v[38:39], s[24:25], v[22:23] op_sel_hi:[1,0,1]
	v_pk_fma_f32 v[20:21], v[36:37], s[24:25], v[20:21] op_sel_hi:[1,0,1]
	v_pk_add_f32 v[22:23], v[50:51], v[22:23]
	v_pk_add_f32 v[20:21], v[48:49], v[20:21]
	global_store_dwordx4 v[34:35], v[20:23], off offset:512
	global_load_dwordx4 v[36:39], v[120:121], off
	global_load_dwordx4 v[40:43], v[122:123], off
	global_load_dwordx4 v[44:47], v[116:117], off
	v_add_f32_e32 v48, v28, v29
	v_mul_f32_e32 v29, v29, v29
	v_fmac_f32_e32 v29, v28, v28
	v_add_f32_e32 v48, v30, v48
	v_fmac_f32_e32 v29, v30, v30
	v_add_f32_e32 v30, v24, v25
	v_mul_f32_e32 v25, v25, v25
	v_fmac_f32_e32 v25, v24, v24
	v_add_f32_e32 v28, v31, v48
	v_add_f32_e32 v30, v26, v30
	v_fmac_f32_e32 v25, v26, v26
	v_add_f32_e32 v28, 0, v28
	v_fmac_f32_e32 v29, v31, v31
	v_add_f32_e32 v24, v27, v30
	v_fmac_f32_e32 v25, v27, v27
	v_sub_f32_e32 v27, v53, v59
	v_sub_f32_e32 v26, v52, v59
	v_add_f32_e32 v28, v24, v28
	v_add_f32_e32 v29, v29, v25
	v_sub_f32_e32 v25, v55, v59
	v_sub_f32_e32 v24, v54, v59
	v_pk_mul_f32 v[26:27], v[58:59], v[26:27] op_sel_hi:[0,1]
	v_pk_mul_f32 v[24:25], v[58:59], v[24:25] op_sel_hi:[0,1]
	v_mul_f32_e32 v31, v21, v21
	v_add_f32_e32 v30, v20, v21
	v_fmac_f32_e32 v31, v20, v20
	v_add_f32_e32 v30, v22, v30
	v_fmac_f32_e32 v31, v22, v22
	v_add_f32_e32 v30, v23, v30
	v_fmac_f32_e32 v31, v23, v23
	v_add_f32_e32 v28, v28, v30
	v_add_f32_e32 v29, v29, v31
	v_cvt_pk_bf16_f32 v20, v20, v21
	v_cvt_pk_bf16_f32 v21, v22, v23
	s_waitcnt vmcnt(0)
	v_pk_fma_f32 v[26:27], v[36:37], v[26:27], v[40:41]
	v_pk_fma_f32 v[24:25], v[38:39], v[24:25], v[42:43]
	v_pk_fma_f32 v[16:17], v[26:27], s[24:25], v[16:17] op_sel_hi:[1,0,1]
	v_pk_fma_f32 v[18:19], v[24:25], s[24:25], v[18:19] op_sel_hi:[1,0,1]
	v_pk_add_f32 v[24:25], v[44:45], v[16:17]
	v_pk_add_f32 v[26:27], v[46:47], v[18:19]
	v_mul_f32_e32 v17, v25, v25
	v_add_f32_e32 v16, v24, v25
	v_fmac_f32_e32 v17, v24, v24
	v_add_f32_e32 v16, v26, v16
	v_fmac_f32_e32 v17, v26, v26
	v_add_f32_e32 v16, v27, v16
	v_fmac_f32_e32 v17, v27, v27
	v_add_f32_e32 v16, v28, v16
	v_add_f32_e32 v17, v29, v17
	ds_bpermute_b32 v18, v118, v16
	ds_bpermute_b32 v19, v118, v17
	global_store_dwordx4 v[34:35], v[24:27], off offset:528
	v_cvt_pk_bf16_f32 v22, v24, v25
	v_cvt_pk_bf16_f32 v23, v26, v27
	s_waitcnt lgkmcnt(0)
	v_add_f32_e32 v16, v16, v18
	v_add_f32_e32 v17, v17, v19
	ds_bpermute_b32 v18, v119, v16
	ds_bpermute_b32 v19, v119, v17
	flat_store_dwordx4 v[56:57], v[20:23] offset:256
	s_mov_b32 s100, -1
	s_mov_b32 s101, 0
	s_mov_b32 s98, 0xffff0000
	s_mov_b32 s99, 0
	s_and_saveexec_b64 s[36:37], s[100:101]
	s_cbranch_execz .LBB0_2650
	v_lshl_add_u64 v[20:21], s[8:9], 0, v[32:33]
	s_waitcnt lgkmcnt(0)
	v_add_f32_e32 v16, v16, v18
	v_add_f32_e32 v17, v17, v19
	v_cndmask_b32_e64 v16, v16, v17, s[98:99]
	v_cndmask_b32_e64 v17, 0, 4, s[98:99]
	v_or_b32_e32 v20, v20, v17
	flat_atomic_add_f32 v[20:21], v16
; DEVI unsigned pk2(float lo, float hi) { unsigned r; asm("v_cvt_pk_bf16_f32 %0, %1, %2" : "=v"(r) : "v"(lo), "v"(hi)); return r; }
;     DEVI void operator()(const f32x4 (&acc)[2][2][4][2], const pg8::Unit& u, int wr, int wc, int fr, int fq) const {
;     ...
;                 const int row = row0 + ai * 128 + m * 16; float mu, rs; row_stats(stin, row, mu, rs);
;                 float sum = 0.f, sq = 0.f;
; #pragma unroll
;                 for (int bj = 0; bj < 2; ++bj) {
;                     f32x4 z[2];
; #pragma unroll
;                     for (int n = 0; n < 2; ++n) {
;                         const int col = colb + bj * 128 + 4 * n;
;                         f32x4 xv = *(const f32x4*)(zsrc + (size_t)row * DM + col);
;                         if (stin) { const f32x4 gv = *(const f32x4*)(gin + col), bv = *(const f32x4*)(bin + col); xv = (xv - mu) * rs * gv + bv; }
;                         f32x4 zz = ALPHA * xv + acc[ai][bj][m][n];
;                         if (bias) zz += *(const f32x4*)(bias + col);
;                         *(f32x4*)(zdst + (size_t)row * DM + col) = zz;
;                         sum += zz[0] + zz[1] + zz[2] + zz[3]; sq += zz[0] * zz[0] + zz[1] * zz[1] + zz[2] * zz[2] + zz[3] * zz[3];
;                         z[n] = zz;
;                     }
;                     u32x4 o; o.x = pk2(z[0][0], z[0][1]); o.y = pk2(z[0][2], z[0][3]); o.z = pk2(z[1][0], z[1][1]); o.w = pk2(z[1][2], z[1][3]);
;                     if (zb) *(u32x4*)(zb + (size_t)row * DM + colb + bj * 128) = o;
;                 }
;                 sum += __shfl_xor(sum, 16); sq += __shfl_xor(sq, 16);
;                 sum += __shfl_xor(sum, 32); sq += __shfl_xor(sq, 32);
;                 if (fq == 0) { atomicAdd(stout + 2 * (size_t)row, sum); atomicAdd(stout + 2 * (size_t)row + 1, sq); }
.LBB0_2650:
	s_or_b64 exec, exec, s[36:37]
	v_add_u32_e32 v40, 0xb0, v154
	v_ashrrev_i32_e32 v41, 31, v40
	v_lshlrev_b64 v[16:17], 3, v[40:41]
	s_waitcnt lgkmcnt(0)
	v_lshl_add_u64 v[18:19], s[6:7], 0, v[16:17]
	flat_load_dwordx2 v[42:43], v[18:19]
	v_lshlrev_b64 v[18:19], 12, v[40:41]
	v_lshl_add_u64 v[18:19], s[46:47], 0, v[18:19]
	v_lshl_add_u64 v[18:19], v[144:145], 2, v[18:19]
	global_load_dwordx4 v[20:23], v[18:19], off
	global_load_dwordx4 v[24:27], v[150:151], off
	global_load_dwordx4 v[28:31], v[152:153], off
	global_load_dwordx4 v[32:35], v[156:157], off
	global_load_dwordx4 v[36:39], v[18:19], off offset:16
	s_waitcnt vmcnt(0) lgkmcnt(0)
	v_pk_mul_f32 v[42:43], v[42:43], s[22:23] op_sel:[1,0] op_sel_hi:[0,0]
	v_fma_f32 v42, -v43, v43, v42
	v_max_f32_e32 v42, 0, v42
	v_add_f32_e32 v42, 0x3727c5ac, v42
	v_mul_f32_e32 v44, 0x4b800000, v42
	v_cmp_gt_f32_e32 vcc, s64, v42
	v_sub_f32_e32 v23, v23, v43
	v_sub_f32_e32 v22, v22, v43
	v_cndmask_b32_e32 v42, v42, v44, vcc
	v_rsq_f32_e32 v42, v42
	v_sub_f32_e32 v21, v21, v43
	v_sub_f32_e32 v20, v20, v43
	v_mul_f32_e32 v44, 0x45800000, v42
	v_cndmask_b32_e32 v42, v42, v44, vcc
	v_pk_mul_f32 v[20:21], v[20:21], v[42:43] op_sel_hi:[1,0]
	v_pk_mul_f32 v[22:23], v[22:23], v[42:43] op_sel_hi:[1,0]
	v_pk_fma_f32 v[20:21], v[24:25], v[20:21], v[28:29]
	v_pk_fma_f32 v[22:23], v[26:27], v[22:23], v[30:31]
	v_pk_fma_f32 v[12:13], v[20:21], s[24:25], v[12:13] op_sel_hi:[1,0,1]
	v_pk_fma_f32 v[14:15], v[22:23], s[24:25], v[14:15] op_sel_hi:[1,0,1]
	v_pk_add_f32 v[12:13], v[32:33], v[12:13]
	v_pk_add_f32 v[14:15], v[34:35], v[14:15]
	global_store_dwordx4 v[18:19], v[12:15], off
	global_load_dwordx4 v[20:23], v[146:147], off
	global_load_dwordx4 v[24:27], v[148:149], off
	global_load_dwordx4 v[28:31], v[124:125], off
	v_lshlrev_b64 v[32:33], 11, v[40:41]
	v_lshl_add_u64 v[32:33], s[10:11], 0, v[32:33]
	v_lshl_add_u64 v[40:41], v[144:145], 1, v[32:33]
	v_sub_f32_e32 v33, v39, v43
	v_sub_f32_e32 v32, v38, v43
	v_sub_f32_e32 v35, v37, v43
	v_sub_f32_e32 v34, v36, v43
	v_pk_mul_f32 v[34:35], v[34:35], v[42:43] op_sel_hi:[1,0]
	v_pk_mul_f32 v[36:37], v[32:33], v[42:43] op_sel_hi:[1,0]
	v_cvt_pk_bf16_f32 v32, v12, v13
	v_cvt_pk_bf16_f32 v33, v14, v15
	s_waitcnt vmcnt(1)
	v_pk_fma_f32 v[20:21], v[20:21], v[34:35], v[24:25]
	v_pk_fma_f32 v[22:23], v[22:23], v[36:37], v[26:27]
	v_pk_fma_f32 v[8:9], v[20:21], s[24:25], v[8:9] op_sel_hi:[1,0,1]
	v_pk_fma_f32 v[10:11], v[22:23], s[24:25], v[10:11] op_sel_hi:[1,0,1]
	s_waitcnt vmcnt(0)
	v_pk_add_f32 v[8:9], v[28:29], v[8:9]
	v_pk_add_f32 v[10:11], v[30:31], v[10:11]
	global_store_dwordx4 v[18:19], v[8:11], off offset:16
	v_cvt_pk_bf16_f32 v34, v8, v9
	v_cvt_pk_bf16_f32 v35, v10, v11
	flat_store_dwordx4 v[40:41], v[32:35]
	global_load_dwordx4 v[20:23], v[18:19], off offset:512
	global_load_dwordx4 v[24:27], v[126:127], off
	global_load_dwordx4 v[28:31], v[158:159], off
	s_nop 0
	global_load_dwordx4 v[32:35], v[160:161], off
	global_load_dwordx4 v[36:39], v[18:19], off offset:528
	s_waitcnt vmcnt(0)
	v_sub_f32_e32 v23, v23, v43
	v_sub_f32_e32 v22, v22, v43
	v_sub_f32_e32 v21, v21, v43
	v_sub_f32_e32 v20, v20, v43
	v_pk_mul_f32 v[20:21], v[42:43], v[20:21] op_sel_hi:[0,1]
	v_pk_mul_f32 v[22:23], v[42:43], v[22:23] op_sel_hi:[0,1]
	v_pk_fma_f32 v[22:23], v[26:27], v[22:23], v[30:31]
	v_pk_fma_f32 v[20:21], v[24:25], v[20:21], v[28:29]
	v_pk_fma_f32 v[6:7], v[22:23], s[24:25], v[6:7] op_sel_hi:[1,0,1]
	v_pk_fma_f32 v[4:5], v[20:21], s[24:25], v[4:5] op_sel_hi:[1,0,1]
	v_pk_add_f32 v[6:7], v[34:35], v[6:7]
	v_pk_add_f32 v[4:5], v[32:33], v[4:5]
	global_store_dwordx4 v[18:19], v[4:7], off offset:512
	global_load_dwordx4 v[20:23], v[120:121], off
	global_load_dwordx4 v[24:27], v[122:123], off
	global_load_dwordx4 v[28:31], v[116:117], off
	v_add_f32_e32 v32, v12, v13
	v_mul_f32_e32 v13, v13, v13
	v_fmac_f32_e32 v13, v12, v12
	v_add_f32_e32 v32, v14, v32
	v_fmac_f32_e32 v13, v14, v14
	v_add_f32_e32 v14, v8, v9
	v_mul_f32_e32 v9, v9, v9
	v_fmac_f32_e32 v9, v8, v8
	v_add_f32_e32 v12, v15, v32
	v_add_f32_e32 v14, v10, v14
	v_fmac_f32_e32 v9, v10, v10
	v_add_f32_e32 v12, 0, v12
	v_fmac_f32_e32 v13, v15, v15
	v_add_f32_e32 v8, v11, v14
	v_fmac_f32_e32 v9, v11, v11
	v_sub_f32_e32 v11, v37, v43
	v_sub_f32_e32 v10, v36, v43
	v_add_f32_e32 v12, v8, v12
	v_add_f32_e32 v13, v13, v9
	v_sub_f32_e32 v9, v39, v43
	v_sub_f32_e32 v8, v38, v43
	v_pk_mul_f32 v[10:11], v[42:43], v[10:11] op_sel_hi:[0,1]
	v_pk_mul_f32 v[8:9], v[42:43], v[8:9] op_sel_hi:[0,1]
	v_mul_f32_e32 v15, v5, v5
	v_add_f32_e32 v14, v4, v5
	v_fmac_f32_e32 v15, v4, v4
	v_add_f32_e32 v14, v6, v14
	v_fmac_f32_e32 v15, v6, v6
	v_add_f32_e32 v14, v7, v14
	v_fmac_f32_e32 v15, v7, v7
	v_add_f32_e32 v12, v12, v14
	v_add_f32_e32 v13, v13, v15
	v_cvt_pk_bf16_f32 v4, v4, v5
	v_cvt_pk_bf16_f32 v5, v6, v7
	s_waitcnt vmcnt(0)
	v_pk_fma_f32 v[10:11], v[20:21], v[10:11], v[24:25]
	v_pk_fma_f32 v[8:9], v[22:23], v[8:9], v[26:27]
	v_pk_fma_f32 v[0:1], v[10:11], s[24:25], v[0:1] op_sel_hi:[1,0,1]
	v_pk_fma_f32 v[2:3], v[8:9], s[24:25], v[2:3] op_sel_hi:[1,0,1]
	v_pk_add_f32 v[8:9], v[28:29], v[0:1]
	v_pk_add_f32 v[10:11], v[30:31], v[2:3]
	v_mul_f32_e32 v1, v9, v9
	v_add_f32_e32 v0, v8, v9
	v_fmac_f32_e32 v1, v8, v8
	v_add_f32_e32 v0, v10, v0
	v_fmac_f32_e32 v1, v10, v10
	v_add_f32_e32 v0, v11, v0
	v_fmac_f32_e32 v1, v11, v11
	v_add_f32_e32 v0, v12, v0
	v_add_f32_e32 v1, v13, v1
	ds_bpermute_b32 v2, v118, v0
	ds_bpermute_b32 v3, v118, v1
	global_store_dwordx4 v[18:19], v[8:11], off offset:528
	v_cvt_pk_bf16_f32 v6, v8, v9
	v_cvt_pk_bf16_f32 v7, v10, v11
	s_waitcnt lgkmcnt(0)
	v_add_f32_e32 v0, v0, v2
	v_add_f32_e32 v1, v1, v3
	ds_bpermute_b32 v2, v119, v0
	ds_bpermute_b32 v3, v119, v1
	flat_store_dwordx4 v[40:41], v[4:7] offset:256
	s_mov_b32 s100, -1
	s_mov_b32 s101, 0
	s_mov_b32 s98, 0xffff0000
	s_mov_b32 s99, 0
	s_and_saveexec_b64 s[36:37], s[100:101]
	s_cbranch_execz .LBB0_2652
	v_lshl_add_u64 v[4:5], s[8:9], 0, v[16:17]
	s_waitcnt lgkmcnt(0)
	v_add_f32_e32 v0, v0, v2
	v_add_f32_e32 v1, v1, v3
	v_cndmask_b32_e64 v0, v0, v1, s[98:99]
	v_cndmask_b32_e64 v1, 0, 4, s[98:99]
	v_or_b32_e32 v4, v4, v1
	flat_atomic_add_f32 v[4:5], v0

; DEVI unsigned pk2(float lo, float hi) { unsigned r; asm("v_cvt_pk_bf16_f32 %0, %1, %2" : "=v"(r) : "v"(lo), "v"(hi)); return r; }
;     DEVI void operator()(const f32x4 (&acc)[2][2][4][2], const pg8::Unit& u, int wr, int wc, int fr, int fq) const {
;     ...
;                 const int row = row0 + ai * 128 + m * 16; float mu, rs; row_stats(stin, row, mu, rs);
;                 float sum = 0.f, sq = 0.f;
; #pragma unroll
;                 for (int bj = 0; bj < 2; ++bj) {
;                     f32x4 z[2];
; #pragma unroll
;                     for (int n = 0; n < 2; ++n) {
;                         const int col = colb + bj * 128 + 4 * n;
;                         f32x4 xv = *(const f32x4*)(zsrc + (size_t)row * DM + col);
;                         if (stin) { const f32x4 gv = *(const f32x4*)(gin + col), bv = *(const f32x4*)(bin + col); xv = (xv - mu) * rs * gv + bv; }
;                         f32x4 zz = ALPHA * xv + acc[ai][bj][m][n];
;                         if (bias) zz += *(const f32x4*)(bias + col);
;                         *(f32x4*)(zdst + (size_t)row * DM + col) = zz;
;                         sum += zz[0] + zz[1] + zz[2] + zz[3]; sq += zz[0] * zz[0] + zz[1] * zz[1] + zz[2] * zz[2] + zz[3] * zz[3];
;                         z[n] = zz;
;                     }
;                     u32x4 o; o.x = pk2(z[0][0], z[0][1]); o.y = pk2(z[0][2], z[0][3]); o.z = pk2(z[1][0], z[1][1]); o.w = pk2(z[1][2], z[1][3]);
;                     if (zb) *(u32x4*)(zb + (size_t)row * DM + colb + bj * 128) = o;
;                 }
;                 sum += __shfl_xor(sum, 16); sq += __shfl_xor(sq, 16);
;                 sum += __shfl_xor(sum, 32); sq += __shfl_xor(sq, 32);
;                 if (fq == 0) { atomicAdd(stout + 2 * (size_t)row, sum); atomicAdd(stout + 2 * (size_t)row + 1, sq); }
.LBB0_2845:
	v_lshl_add_u32 v154, s58, 8, v160
	v_ashrrev_i32_e32 v155, 31, v154
	v_lshlrev_b64 v[156:157], 3, v[154:155]
	v_lshl_add_u64 v[146:147], s[12:13], 0, v[156:157]
	s_waitcnt vmcnt(0)
	flat_load_dwordx2 v[184:185], v[146:147]
	v_lshl_or_b32 v144, s59, 8, v162
	v_ashrrev_i32_e32 v145, 31, v144
	v_lshlrev_b64 v[146:147], 12, v[154:155]
	v_lshl_add_u64 v[146:147], s[46:47], 0, v[146:147]
	v_lshlrev_b64 v[148:149], 2, v[144:145]
	v_lshl_add_u64 v[158:159], v[146:147], 0, v[148:149]
	global_load_dwordx4 v[168:171], v[158:159], off
	v_lshl_add_u64 v[150:151], s[14:15], 0, v[148:149]
	v_lshl_add_u64 v[152:153], s[16:17], 0, v[148:149]
	global_load_dwordx4 v[172:175], v[150:151], off
	global_load_dwordx4 v[176:179], v[152:153], off
	global_load_dwordx4 v[180:183], v[158:159], off offset:16
	v_or_b32_e32 v146, 4, v144
	v_ashrrev_i32_e32 v147, 31, v146
	v_lshlrev_b64 v[148:149], 2, v[146:147]
	v_lshl_add_u64 v[146:147], s[14:15], 0, v[148:149]
	v_lshl_add_u64 v[148:149], s[16:17], 0, v[148:149]
	s_waitcnt vmcnt(0) lgkmcnt(0)
	v_pk_mul_f32 v[192:193], v[184:185], s[22:23] op_sel:[1,0] op_sel_hi:[0,0]
	v_fma_f32 v155, -v193, v193, v192
	v_max_f32_e32 v155, 0, v155
	v_add_f32_e32 v155, 0x3727c5ac, v155
	v_mul_f32_e32 v167, 0x4b800000, v155
	v_cmp_gt_f32_e32 vcc, s55, v155
	v_sub_f32_e32 v169, v169, v193
	s_nop 0
	v_cndmask_b32_e32 v155, v155, v167, vcc
	v_rsq_f32_e32 v155, v155
	v_sub_f32_e32 v168, v168, v193
	v_sub_f32_e32 v171, v171, v193
	v_sub_f32_e32 v170, v170, v193
	v_mul_f32_e32 v167, 0x45800000, v155
	v_cndmask_b32_e32 v192, v155, v167, vcc
	v_pk_mul_f32 v[170:171], v[170:171], v[192:193] op_sel_hi:[1,0]
	v_pk_mul_f32 v[168:169], v[168:169], v[192:193] op_sel_hi:[1,0]
	v_pk_fma_f32 v[170:171], v[174:175], v[170:171], v[178:179]
	v_pk_fma_f32 v[168:169], v[172:173], v[168:169], v[176:177]
	v_pk_fma_f32 v[170:171], v[170:171], s[24:25], v[126:127] op_sel_hi:[1,0,1]
	v_pk_fma_f32 v[168:169], v[168:169], s[24:25], v[124:125] op_sel_hi:[1,0,1]
	global_store_dwordx4 v[158:159], v[168:171], off
	global_load_dwordx4 v[172:175], v[146:147], off
	global_load_dwordx4 v[176:179], v[148:149], off
	v_sub_f32_e32 v181, v181, v193
	v_sub_f32_e32 v180, v180, v193
	v_sub_f32_e32 v183, v183, v193
	v_sub_f32_e32 v182, v182, v193
	v_or_b32_e32 v124, 0x80, v144
	v_pk_mul_f32 v[182:183], v[182:183], v[192:193] op_sel_hi:[1,0]
	v_pk_mul_f32 v[180:181], v[180:181], v[192:193] op_sel_hi:[1,0]
	v_ashrrev_i32_e32 v125, 31, v124
	global_load_dwordx4 v[184:187], v[158:159], off offset:512
	v_lshlrev_b64 v[126:127], 2, v[124:125]
	v_lshl_add_u64 v[124:125], s[14:15], 0, v[126:127]
	v_lshl_add_u64 v[126:127], s[16:17], 0, v[126:127]
	v_add_f32_e32 v167, v168, v169
	v_mul_f32_e32 v169, v169, v169
	v_fmac_f32_e32 v169, v168, v168
	v_add_f32_e32 v167, v170, v167
	v_fmac_f32_e32 v169, v170, v170
	v_add_f32_e32 v167, v171, v167
	v_add_f32_e32 v167, 0, v167
	v_fmac_f32_e32 v169, v171, v171
	v_xor_b32_e32 v155, 32, v166
	s_waitcnt vmcnt(1)
	v_pk_fma_f32 v[172:173], v[172:173], v[180:181], v[176:177]
	v_pk_fma_f32 v[174:175], v[174:175], v[182:183], v[178:179]
	v_pk_fma_f32 v[172:173], v[172:173], s[24:25], v[120:121] op_sel_hi:[1,0,1]
	v_pk_fma_f32 v[174:175], v[174:175], s[24:25], v[122:123] op_sel_hi:[1,0,1]
	global_store_dwordx4 v[158:159], v[172:175], off offset:16
	global_load_dwordx4 v[176:179], v[124:125], off
	global_load_dwordx4 v[180:183], v[126:127], off
	global_load_dwordx4 v[188:191], v[158:159], off offset:528
	v_or_b32_e32 v120, 0x84, v144
	v_ashrrev_i32_e32 v121, 31, v120
	v_lshlrev_b64 v[122:123], 2, v[120:121]
	s_waitcnt vmcnt(4)
	v_sub_f32_e32 v185, v185, v193
	v_sub_f32_e32 v184, v184, v193
	v_sub_f32_e32 v187, v187, v193
	v_sub_f32_e32 v186, v186, v193
	v_pk_mul_f32 v[186:187], v[192:193], v[186:187] op_sel_hi:[0,1]
	v_pk_mul_f32 v[184:185], v[192:193], v[184:185] op_sel_hi:[0,1]
	v_lshl_add_u64 v[120:121], s[14:15], 0, v[122:123]
	v_lshl_add_u64 v[122:123], s[16:17], 0, v[122:123]
	v_mul_f32_e32 v170, v173, v173
	v_add_f32_e32 v168, v172, v173
	v_fmac_f32_e32 v170, v172, v172
	v_add_f32_e32 v168, v174, v168
	v_fmac_f32_e32 v170, v174, v174
	v_add_f32_e32 v168, v175, v168
	v_fmac_f32_e32 v170, v175, v175
	v_add_f32_e32 v167, v168, v167
	v_add_f32_e32 v168, v169, v170
	s_waitcnt vmcnt(1)
	v_pk_fma_f32 v[176:177], v[176:177], v[184:185], v[180:181]
	v_pk_fma_f32 v[178:179], v[178:179], v[186:187], v[182:183]
	v_pk_fma_f32 v[176:177], v[176:177], s[24:25], v[116:117] op_sel_hi:[1,0,1]
	v_pk_fma_f32 v[178:179], v[178:179], s[24:25], v[118:119] op_sel_hi:[1,0,1]
	global_store_dwordx4 v[158:159], v[176:179], off offset:512
	global_load_dwordx4 v[180:183], v[120:121], off
	global_load_dwordx4 v[184:187], v[122:123], off
	v_mul_f32_e32 v170, v177, v177
	v_add_f32_e32 v169, v176, v177
	v_fmac_f32_e32 v170, v176, v176
	s_waitcnt vmcnt(3)
	v_sub_f32_e32 v119, v189, v193
	v_sub_f32_e32 v118, v188, v193
	v_sub_f32_e32 v189, v191, v193
	v_sub_f32_e32 v188, v190, v193
	v_add_f32_e32 v169, v178, v169
	v_fmac_f32_e32 v170, v178, v178
	v_pk_mul_f32 v[188:189], v[192:193], v[188:189] op_sel_hi:[0,1]
	v_pk_mul_f32 v[118:119], v[192:193], v[118:119] op_sel_hi:[0,1]
	v_add_f32_e32 v169, v179, v169
	v_fmac_f32_e32 v170, v179, v179
	v_add_f32_e32 v167, v167, v169
	v_add_f32_e32 v172, v168, v170
	v_and_b32_e32 v117, 64, v166
	v_xor_b32_e32 v116, 16, v166
	v_add_u32_e32 v117, 64, v117
	v_cmp_lt_i32_e32 vcc, v116, v117
	s_waitcnt vmcnt(0)
	v_pk_fma_f32 v[118:119], v[180:181], v[118:119], v[184:185]
	v_pk_fma_f32 v[168:169], v[182:183], v[188:189], v[186:187]
	v_cndmask_b32_e32 v116, v166, v116, vcc
	v_pk_fma_f32 v[170:171], v[168:169], s[24:25], v[114:115] op_sel_hi:[1,0,1]
	v_pk_fma_f32 v[168:169], v[118:119], s[24:25], v[112:113] op_sel_hi:[1,0,1]
	v_lshlrev_b32_e32 v116, 2, v116
	v_mul_f32_e32 v113, v169, v169
	v_add_f32_e32 v112, v168, v169
	v_fmac_f32_e32 v113, v168, v168
	v_add_f32_e32 v112, v170, v112
	v_fmac_f32_e32 v113, v170, v170
	v_add_f32_e32 v112, v171, v112
	v_fmac_f32_e32 v113, v171, v171
	v_add_f32_e32 v112, v167, v112
	v_add_f32_e32 v113, v172, v113
	ds_bpermute_b32 v115, v116, v112
	ds_bpermute_b32 v118, v116, v113
	v_cmp_lt_i32_e32 vcc, v155, v117
	global_store_dwordx4 v[158:159], v[168:171], off offset:528
	s_waitcnt lgkmcnt(1)
	v_add_f32_e32 v112, v112, v115
	v_cndmask_b32_e32 v114, v166, v155, vcc
	v_lshlrev_b32_e32 v114, 2, v114
	s_waitcnt lgkmcnt(0)
	v_add_f32_e32 v113, v113, v118
	ds_bpermute_b32 v115, v114, v112
	ds_bpermute_b32 v117, v114, v113
	s_mov_b32 s100, -1
	s_mov_b32 s101, 0
	s_mov_b32 s98, 0xffff0000
	s_mov_b32 s99, 0
	s_and_saveexec_b64 s[28:29], s[100:101]
	s_cbranch_execz .LBB0_2847
	v_lshl_add_u64 v[118:119], s[10:11], 0, v[156:157]
	s_waitcnt lgkmcnt(1)
	v_add_f32_e32 v112, v112, v115
	s_waitcnt lgkmcnt(0)
	v_add_f32_e32 v113, v113, v117
	v_cndmask_b32_e64 v112, v112, v113, s[98:99]
	v_cndmask_b32_e64 v113, 0, 4, s[98:99]
	v_or_b32_e32 v118, v118, v113
	flat_atomic_add_f32 v[118:119], v112
; DEVI unsigned pk2(float lo, float hi) { unsigned r; asm("v_cvt_pk_bf16_f32 %0, %1, %2" : "=v"(r) : "v"(lo), "v"(hi)); return r; }
;     DEVI void operator()(const f32x4 (&acc)[2][2][4][2], const pg8::Unit& u, int wr, int wc, int fr, int fq) const {
;     ...
;                 const int row = row0 + ai * 128 + m * 16; float mu, rs; row_stats(stin, row, mu, rs);
;                 float sum = 0.f, sq = 0.f;
; #pragma unroll
;                 for (int bj = 0; bj < 2; ++bj) {
;                     f32x4 z[2];
; #pragma unroll
;                     for (int n = 0; n < 2; ++n) {
;                         const int col = colb + bj * 128 + 4 * n;
;                         f32x4 xv = *(const f32x4*)(zsrc + (size_t)row * DM + col);
;                         if (stin) { const f32x4 gv = *(const f32x4*)(gin + col), bv = *(const f32x4*)(bin + col); xv = (xv - mu) * rs * gv + bv; }
;                         f32x4 zz = ALPHA * xv + acc[ai][bj][m][n];
;                         if (bias) zz += *(const f32x4*)(bias + col);
;                         *(f32x4*)(zdst + (size_t)row * DM + col) = zz;
;                         sum += zz[0] + zz[1] + zz[2] + zz[3]; sq += zz[0] * zz[0] + zz[1] * zz[1] + zz[2] * zz[2] + zz[3] * zz[3];
;                         z[n] = zz;
;                     }
;                     u32x4 o; o.x = pk2(z[0][0], z[0][1]); o.y = pk2(z[0][2], z[0][3]); o.z = pk2(z[1][0], z[1][1]); o.w = pk2(z[1][2], z[1][3]);
;                     if (zb) *(u32x4*)(zb + (size_t)row * DM + colb + bj * 128) = o;
;                 }
;                 sum += __shfl_xor(sum, 16); sq += __shfl_xor(sq, 16);
;                 sum += __shfl_xor(sum, 32); sq += __shfl_xor(sq, 32);
;                 if (fq == 0) { atomicAdd(stout + 2 * (size_t)row, sum); atomicAdd(stout + 2 * (size_t)row + 1, sq); }
.LBB0_2847:
	s_or_b64 exec, exec, s[28:29]
	v_or_b32_e32 v118, 16, v154
	v_ashrrev_i32_e32 v119, 31, v118
	v_lshlrev_b64 v[112:113], 3, v[118:119]
	v_lshl_add_u64 v[156:157], s[12:13], 0, v[112:113]
	flat_load_dwordx2 v[180:181], v[156:157]
	v_lshlrev_b64 v[118:119], 12, v[118:119]
	v_lshl_add_u64 v[118:119], s[46:47], 0, v[118:119]
	v_lshl_add_u64 v[118:119], v[144:145], 2, v[118:119]
	global_load_dwordx4 v[156:159], v[118:119], off
	global_load_dwordx4 v[168:171], v[150:151], off
	global_load_dwordx4 v[172:175], v[152:153], off
	global_load_dwordx4 v[176:179], v[118:119], off offset:16
	s_waitcnt vmcnt(0) lgkmcnt(0)
	v_pk_mul_f32 v[180:181], v[180:181], s[22:23] op_sel:[1,0] op_sel_hi:[0,0]
	v_fma_f32 v115, -v181, v181, v180
	v_max_f32_e32 v115, 0, v115
	v_add_f32_e32 v115, 0x3727c5ac, v115
	v_mul_f32_e32 v117, 0x4b800000, v115
	v_cmp_gt_f32_e32 vcc, s55, v115
	v_sub_f32_e32 v157, v157, v181
	v_sub_f32_e32 v156, v156, v181
	v_cndmask_b32_e32 v115, v115, v117, vcc
	v_rsq_f32_e32 v115, v115
	v_sub_f32_e32 v159, v159, v181
	v_sub_f32_e32 v158, v158, v181
	v_sub_f32_e32 v177, v177, v181
	v_mul_f32_e32 v117, 0x45800000, v115
	v_cndmask_b32_e32 v180, v115, v117, vcc
	v_pk_mul_f32 v[158:159], v[158:159], v[180:181] op_sel_hi:[1,0]
	v_pk_mul_f32 v[156:157], v[156:157], v[180:181] op_sel_hi:[1,0]
	v_pk_fma_f32 v[158:159], v[170:171], v[158:159], v[174:175]
	v_pk_fma_f32 v[156:157], v[168:169], v[156:157], v[172:173]
	v_pk_fma_f32 v[110:111], v[158:159], s[24:25], v[110:111] op_sel_hi:[1,0,1]
	v_pk_fma_f32 v[108:109], v[156:157], s[24:25], v[108:109] op_sel_hi:[1,0,1]
	global_store_dwordx4 v[118:119], v[108:111], off
	global_load_dwordx4 v[156:159], v[146:147], off
	global_load_dwordx4 v[168:171], v[148:149], off
	global_load_dwordx4 v[172:175], v[118:119], off offset:512
	v_sub_f32_e32 v176, v176, v181
	v_sub_f32_e32 v179, v179, v181
	v_sub_f32_e32 v178, v178, v181
	v_pk_mul_f32 v[178:179], v[178:179], v[180:181] op_sel_hi:[1,0]
	v_pk_mul_f32 v[176:177], v[176:177], v[180:181] op_sel_hi:[1,0]
	v_add_f32_e32 v115, v108, v109
	v_mul_f32_e32 v109, v109, v109
	v_fmac_f32_e32 v109, v108, v108
	v_add_f32_e32 v115, v110, v115
	v_fmac_f32_e32 v109, v110, v110
	v_add_f32_e32 v108, v111, v115
	v_add_f32_e32 v108, 0, v108
	v_fmac_f32_e32 v109, v111, v111
	s_waitcnt vmcnt(1)
	v_pk_fma_f32 v[156:157], v[156:157], v[176:177], v[168:169]
	v_pk_fma_f32 v[158:159], v[158:159], v[178:179], v[170:171]
	v_pk_fma_f32 v[104:105], v[156:157], s[24:25], v[104:105] op_sel_hi:[1,0,1]
	v_pk_fma_f32 v[106:107], v[158:159], s[24:25], v[106:107] op_sel_hi:[1,0,1]
	global_store_dwordx4 v[118:119], v[104:107], off offset:16
	global_load_dwordx4 v[156:159], v[124:125], off
	global_load_dwordx4 v[168:171], v[126:127], off
	global_load_dwordx4 v[176:179], v[118:119], off offset:528
	s_waitcnt vmcnt(4)
	v_sub_f32_e32 v173, v173, v181
	v_sub_f32_e32 v172, v172, v181
	v_sub_f32_e32 v175, v175, v181
	v_sub_f32_e32 v174, v174, v181
	v_pk_mul_f32 v[174:175], v[180:181], v[174:175] op_sel_hi:[0,1]
	v_pk_mul_f32 v[172:173], v[180:181], v[172:173] op_sel_hi:[0,1]
	v_add_f32_e32 v110, v104, v105
	v_mul_f32_e32 v105, v105, v105
	v_fmac_f32_e32 v105, v104, v104
	v_add_f32_e32 v110, v106, v110
	v_fmac_f32_e32 v105, v106, v106
	v_add_f32_e32 v104, v107, v110
	v_fmac_f32_e32 v105, v107, v107
	v_add_f32_e32 v104, v104, v108
	v_add_f32_e32 v105, v109, v105
	s_waitcnt vmcnt(1)
	v_pk_fma_f32 v[156:157], v[156:157], v[172:173], v[168:169]
	v_pk_fma_f32 v[158:159], v[158:159], v[174:175], v[170:171]
	v_pk_fma_f32 v[100:101], v[156:157], s[24:25], v[100:101] op_sel_hi:[1,0,1]
	v_pk_fma_f32 v[102:103], v[158:159], s[24:25], v[102:103] op_sel_hi:[1,0,1]
	global_store_dwordx4 v[118:119], v[100:103], off offset:512
	global_load_dwordx4 v[156:159], v[120:121], off
	global_load_dwordx4 v[168:171], v[122:123], off
	v_add_f32_e32 v106, v100, v101
	v_mul_f32_e32 v101, v101, v101
	v_fmac_f32_e32 v101, v100, v100
	s_waitcnt vmcnt(3)
	v_sub_f32_e32 v173, v177, v181
	v_sub_f32_e32 v172, v176, v181
	v_add_f32_e32 v106, v102, v106
	v_fmac_f32_e32 v101, v102, v102
	v_pk_mul_f32 v[172:173], v[180:181], v[172:173] op_sel_hi:[0,1]
	v_add_f32_e32 v100, v103, v106
	v_fmac_f32_e32 v101, v103, v103
	v_sub_f32_e32 v175, v179, v181
	v_sub_f32_e32 v174, v178, v181
	v_add_f32_e32 v104, v104, v100
	v_add_f32_e32 v105, v105, v101
	v_pk_mul_f32 v[174:175], v[180:181], v[174:175] op_sel_hi:[0,1]
	s_waitcnt vmcnt(0)
	v_pk_fma_f32 v[100:101], v[156:157], v[172:173], v[168:169]
	s_nop 0
	v_pk_fma_f32 v[100:101], v[100:101], s[24:25], v[96:97] op_sel_hi:[1,0,1]
	v_pk_fma_f32 v[102:103], v[158:159], v[174:175], v[170:171]
	v_mul_f32_e32 v97, v101, v101
	v_pk_fma_f32 v[102:103], v[102:103], s[24:25], v[98:99] op_sel_hi:[1,0,1]
	v_add_f32_e32 v96, v100, v101
	v_fmac_f32_e32 v97, v100, v100
	v_add_f32_e32 v96, v102, v96
	v_fmac_f32_e32 v97, v102, v102
	v_add_f32_e32 v96, v103, v96
	v_fmac_f32_e32 v97, v103, v103
	v_add_f32_e32 v96, v104, v96
	v_add_f32_e32 v97, v105, v97
	ds_bpermute_b32 v98, v116, v96
	ds_bpermute_b32 v99, v116, v97
	global_store_dwordx4 v[118:119], v[100:103], off offset:528
	s_waitcnt lgkmcnt(1)
	v_add_f32_e32 v96, v96, v98
	s_waitcnt lgkmcnt(0)
	v_add_f32_e32 v97, v97, v99
	ds_bpermute_b32 v98, v114, v96
	ds_bpermute_b32 v99, v114, v97
	s_mov_b32 s100, -1
	s_mov_b32 s101, 0
	s_mov_b32 s98, 0xffff0000
	s_mov_b32 s99, 0
	s_and_saveexec_b64 s[28:29], s[100:101]
	s_cbranch_execz .LBB0_2849
	v_lshl_add_u64 v[100:101], s[10:11], 0, v[112:113]
	s_waitcnt lgkmcnt(1)
	v_add_f32_e32 v96, v96, v98
	s_waitcnt lgkmcnt(0)
	v_add_f32_e32 v97, v97, v99
	v_cndmask_b32_e64 v96, v96, v97, s[98:99]
	v_cndmask_b32_e64 v97, 0, 4, s[98:99]
	v_or_b32_e32 v100, v100, v97
	flat_atomic_add_f32 v[100:101], v96
; DEVI unsigned pk2(float lo, float hi) { unsigned r; asm("v_cvt_pk_bf16_f32 %0, %1, %2" : "=v"(r) : "v"(lo), "v"(hi)); return r; }
;     DEVI void operator()(const f32x4 (&acc)[2][2][4][2], const pg8::Unit& u, int wr, int wc, int fr, int fq) const {
;     ...
;                 const int row = row0 + ai * 128 + m * 16; float mu, rs; row_stats(stin, row, mu, rs);
;                 float sum = 0.f, sq = 0.f;
; #pragma unroll
;                 for (int bj = 0; bj < 2; ++bj) {
;                     f32x4 z[2];
; #pragma unroll
;                     for (int n = 0; n < 2; ++n) {
;                         const int col = colb + bj * 128 + 4 * n;
;                         f32x4 xv = *(const f32x4*)(zsrc + (size_t)row * DM + col);
;                         if (stin) { const f32x4 gv = *(const f32x4*)(gin + col), bv = *(const f32x4*)(bin + col); xv = (xv - mu) * rs * gv + bv; }
;                         f32x4 zz = ALPHA * xv + acc[ai][bj][m][n];
;                         if (bias) zz += *(const f32x4*)(bias + col);
;                         *(f32x4*)(zdst + (size_t)row * DM + col) = zz;
;                         sum += zz[0] + zz[1] + zz[2] + zz[3]; sq += zz[0] * zz[0] + zz[1] * zz[1] + zz[2] * zz[2] + zz[3] * zz[3];
;                         z[n] = zz;
;                     }
;                     u32x4 o; o.x = pk2(z[0][0], z[0][1]); o.y = pk2(z[0][2], z[0][3]); o.z = pk2(z[1][0], z[1][1]); o.w = pk2(z[1][2], z[1][3]);
;                     if (zb) *(u32x4*)(zb + (size_t)row * DM + colb + bj * 128) = o;
;                 }
;                 sum += __shfl_xor(sum, 16); sq += __shfl_xor(sq, 16);
;                 sum += __shfl_xor(sum, 32); sq += __shfl_xor(sq, 32);
;                 if (fq == 0) { atomicAdd(stout + 2 * (size_t)row, sum); atomicAdd(stout + 2 * (size_t)row + 1, sq); }
.LBB0_2849:
	s_or_b64 exec, exec, s[28:29]
	s_waitcnt lgkmcnt(0)
	v_or_b32_e32 v98, 32, v154
	v_ashrrev_i32_e32 v99, 31, v98
	v_lshlrev_b64 v[96:97], 3, v[98:99]
	v_lshl_add_u64 v[100:101], s[12:13], 0, v[96:97]
	flat_load_dwordx2 v[118:119], v[100:101]
	v_lshlrev_b64 v[98:99], 12, v[98:99]
	v_lshl_add_u64 v[98:99], s[46:47], 0, v[98:99]
	v_lshl_add_u64 v[156:157], v[144:145], 2, v[98:99]
	global_load_dwordx4 v[98:101], v[156:157], off
	global_load_dwordx4 v[102:105], v[150:151], off
	global_load_dwordx4 v[106:109], v[152:153], off
	global_load_dwordx4 v[110:113], v[156:157], off offset:16
	s_waitcnt vmcnt(0) lgkmcnt(0)
	v_pk_mul_f32 v[118:119], v[118:119], s[22:23] op_sel:[1,0] op_sel_hi:[0,0]
	v_fma_f32 v115, -v119, v119, v118
	v_max_f32_e32 v115, 0, v115
	v_add_f32_e32 v115, 0x3727c5ac, v115
	v_mul_f32_e32 v117, 0x4b800000, v115
	v_cmp_gt_f32_e32 vcc, s55, v115
	v_sub_f32_e32 v99, v99, v119
	v_sub_f32_e32 v98, v98, v119
	v_cndmask_b32_e32 v115, v115, v117, vcc
	v_rsq_f32_e32 v115, v115
	v_sub_f32_e32 v101, v101, v119
	v_sub_f32_e32 v100, v100, v119
	v_sub_f32_e32 v111, v111, v119
	v_mul_f32_e32 v117, 0x45800000, v115
	v_cndmask_b32_e32 v118, v115, v117, vcc
	v_pk_mul_f32 v[100:101], v[100:101], v[118:119] op_sel_hi:[1,0]
	v_pk_mul_f32 v[98:99], v[98:99], v[118:119] op_sel_hi:[1,0]
	v_pk_fma_f32 v[100:101], v[104:105], v[100:101], v[108:109]
	v_pk_fma_f32 v[98:99], v[102:103], v[98:99], v[106:107]
	v_pk_fma_f32 v[94:95], v[100:101], s[24:25], v[94:95] op_sel_hi:[1,0,1]
	v_pk_fma_f32 v[92:93], v[98:99], s[24:25], v[92:93] op_sel_hi:[1,0,1]
	global_store_dwordx4 v[156:157], v[92:95], off
	global_load_dwordx4 v[98:101], v[146:147], off
	global_load_dwordx4 v[102:105], v[148:149], off
	global_load_dwordx4 v[106:109], v[156:157], off offset:512
	v_sub_f32_e32 v110, v110, v119
	v_sub_f32_e32 v113, v113, v119
	v_sub_f32_e32 v112, v112, v119
	v_pk_mul_f32 v[112:113], v[112:113], v[118:119] op_sel_hi:[1,0]
	v_pk_mul_f32 v[110:111], v[110:111], v[118:119] op_sel_hi:[1,0]
	s_waitcnt vmcnt(1)
	v_pk_fma_f32 v[100:101], v[100:101], v[112:113], v[104:105]
	v_pk_fma_f32 v[98:99], v[98:99], v[110:111], v[102:103]
	v_pk_fma_f32 v[90:91], v[100:101], s[24:25], v[90:91] op_sel_hi:[1,0,1]
	v_pk_fma_f32 v[88:89], v[98:99], s[24:25], v[88:89] op_sel_hi:[1,0,1]
	global_store_dwordx4 v[156:157], v[88:91], off offset:16
	global_load_dwordx4 v[98:101], v[124:125], off
	global_load_dwordx4 v[102:105], v[126:127], off
	global_load_dwordx4 v[110:113], v[156:157], off offset:528
	s_waitcnt vmcnt(4)
	v_sub_f32_e32 v107, v107, v119
	v_sub_f32_e32 v106, v106, v119
	v_sub_f32_e32 v109, v109, v119
	v_sub_f32_e32 v108, v108, v119
	v_pk_mul_f32 v[108:109], v[118:119], v[108:109] op_sel_hi:[0,1]
	v_pk_mul_f32 v[106:107], v[118:119], v[106:107] op_sel_hi:[0,1]
	s_waitcnt vmcnt(1)
	v_pk_fma_f32 v[98:99], v[98:99], v[106:107], v[102:103]
	v_pk_fma_f32 v[100:101], v[100:101], v[108:109], v[104:105]
	v_pk_fma_f32 v[84:85], v[98:99], s[24:25], v[84:85] op_sel_hi:[1,0,1]
	v_pk_fma_f32 v[86:87], v[100:101], s[24:25], v[86:87] op_sel_hi:[1,0,1]
	global_store_dwordx4 v[156:157], v[84:87], off offset:512
	global_load_dwordx4 v[98:101], v[120:121], off
	global_load_dwordx4 v[102:105], v[122:123], off
	s_waitcnt vmcnt(3)
	v_sub_f32_e32 v106, v110, v119
	v_add_f32_e32 v110, v92, v93
	v_mul_f32_e32 v93, v93, v93
	v_fmac_f32_e32 v93, v92, v92
	v_add_f32_e32 v110, v94, v110
	v_fmac_f32_e32 v93, v94, v94
	v_add_f32_e32 v94, v88, v89
	v_mul_f32_e32 v89, v89, v89
	v_fmac_f32_e32 v89, v88, v88
	v_add_f32_e32 v94, v90, v94
	v_fmac_f32_e32 v89, v90, v90
	v_add_f32_e32 v90, v84, v85
	v_mul_f32_e32 v85, v85, v85
	v_add_f32_e32 v92, v95, v110
	v_fmac_f32_e32 v85, v84, v84
	v_sub_f32_e32 v107, v111, v119
	v_add_f32_e32 v92, 0, v92
	v_fmac_f32_e32 v93, v95, v95
	v_add_f32_e32 v88, v91, v94
	v_fmac_f32_e32 v89, v91, v91
	v_add_f32_e32 v90, v86, v90
	v_fmac_f32_e32 v85, v86, v86
	v_pk_mul_f32 v[106:107], v[118:119], v[106:107] op_sel_hi:[0,1]
	v_add_f32_e32 v88, v88, v92
	v_add_f32_e32 v89, v93, v89
	v_add_f32_e32 v84, v87, v90
	v_fmac_f32_e32 v85, v87, v87
	v_sub_f32_e32 v109, v113, v119
	v_sub_f32_e32 v108, v112, v119
	v_add_f32_e32 v88, v88, v84
	v_add_f32_e32 v89, v89, v85
	v_pk_mul_f32 v[108:109], v[118:119], v[108:109] op_sel_hi:[0,1]
	s_waitcnt vmcnt(0)
	v_pk_fma_f32 v[84:85], v[98:99], v[106:107], v[102:103]
	s_nop 0
	v_pk_fma_f32 v[84:85], v[84:85], s[24:25], v[80:81] op_sel_hi:[1,0,1]
	v_pk_fma_f32 v[86:87], v[100:101], v[108:109], v[104:105]
	v_mul_f32_e32 v81, v85, v85
	v_pk_fma_f32 v[86:87], v[86:87], s[24:25], v[82:83] op_sel_hi:[1,0,1]
	v_add_f32_e32 v80, v84, v85
	v_fmac_f32_e32 v81, v84, v84
	v_add_f32_e32 v80, v86, v80
	v_fmac_f32_e32 v81, v86, v86
	v_add_f32_e32 v80, v87, v80
	v_fmac_f32_e32 v81, v87, v87
	v_add_f32_e32 v80, v88, v80
	v_add_f32_e32 v81, v89, v81
	ds_bpermute_b32 v82, v116, v80
	ds_bpermute_b32 v83, v116, v81
	global_store_dwordx4 v[156:157], v[84:87], off offset:528
	s_waitcnt lgkmcnt(1)
	v_add_f32_e32 v80, v80, v82
	s_waitcnt lgkmcnt(0)
	v_add_f32_e32 v81, v81, v83
	ds_bpermute_b32 v82, v114, v80
	ds_bpermute_b32 v83, v114, v81
	s_mov_b32 s100, -1
	s_mov_b32 s101, 0
	s_mov_b32 s98, 0xffff0000
	s_mov_b32 s99, 0
	s_and_saveexec_b64 s[28:29], s[100:101]
	s_cbranch_execz .LBB0_2851
	v_lshl_add_u64 v[84:85], s[10:11], 0, v[96:97]
	s_waitcnt lgkmcnt(1)
	v_add_f32_e32 v80, v80, v82
	s_waitcnt lgkmcnt(0)
	v_add_f32_e32 v81, v81, v83
	v_cndmask_b32_e64 v80, v80, v81, s[98:99]
	v_cndmask_b32_e64 v81, 0, 4, s[98:99]
	v_or_b32_e32 v84, v84, v81
	flat_atomic_add_f32 v[84:85], v80
; DEVI unsigned pk2(float lo, float hi) { unsigned r; asm("v_cvt_pk_bf16_f32 %0, %1, %2" : "=v"(r) : "v"(lo), "v"(hi)); return r; }
;     DEVI void operator()(const f32x4 (&acc)[2][2][4][2], const pg8::Unit& u, int wr, int wc, int fr, int fq) const {
;     ...
;                 const int row = row0 + ai * 128 + m * 16; float mu, rs; row_stats(stin, row, mu, rs);
;                 float sum = 0.f, sq = 0.f;
; #pragma unroll
;                 for (int bj = 0; bj < 2; ++bj) {
;                     f32x4 z[2];
; #pragma unroll
;                     for (int n = 0; n < 2; ++n) {
;                         const int col = colb + bj * 128 + 4 * n;
;                         f32x4 xv = *(const f32x4*)(zsrc + (size_t)row * DM + col);
;                         if (stin) { const f32x4 gv = *(const f32x4*)(gin + col), bv = *(const f32x4*)(bin + col); xv = (xv - mu) * rs * gv + bv; }
;                         f32x4 zz = ALPHA * xv + acc[ai][bj][m][n];
;                         if (bias) zz += *(const f32x4*)(bias + col);
;                         *(f32x4*)(zdst + (size_t)row * DM + col) = zz;
;                         sum += zz[0] + zz[1] + zz[2] + zz[3]; sq += zz[0] * zz[0] + zz[1] * zz[1] + zz[2] * zz[2] + zz[3] * zz[3];
;                         z[n] = zz;
;                     }
;                     u32x4 o; o.x = pk2(z[0][0], z[0][1]); o.y = pk2(z[0][2], z[0][3]); o.z = pk2(z[1][0], z[1][1]); o.w = pk2(z[1][2], z[1][3]);
;                     if (zb) *(u32x4*)(zb + (size_t)row * DM + colb + bj * 128) = o;
;                 }
;                 sum += __shfl_xor(sum, 16); sq += __shfl_xor(sq, 16);
;                 sum += __shfl_xor(sum, 32); sq += __shfl_xor(sq, 32);
;                 if (fq == 0) { atomicAdd(stout + 2 * (size_t)row, sum); atomicAdd(stout + 2 * (size_t)row + 1, sq); }
.LBB0_2851:
	s_or_b64 exec, exec, s[28:29]
	s_waitcnt lgkmcnt(0)
	v_or_b32_e32 v82, 48, v154
	v_ashrrev_i32_e32 v83, 31, v82
	v_lshlrev_b64 v[80:81], 3, v[82:83]
	v_lshl_add_u64 v[84:85], s[12:13], 0, v[80:81]
	flat_load_dwordx2 v[98:99], v[84:85]
	v_lshlrev_b64 v[82:83], 12, v[82:83]
	v_lshl_add_u64 v[82:83], s[46:47], 0, v[82:83]
	v_lshl_add_u64 v[100:101], v[144:145], 2, v[82:83]
	global_load_dwordx4 v[82:85], v[100:101], off
	global_load_dwordx4 v[86:89], v[150:151], off
	global_load_dwordx4 v[90:93], v[152:153], off
	global_load_dwordx4 v[94:97], v[100:101], off offset:16
	s_waitcnt vmcnt(0) lgkmcnt(0)
	v_pk_mul_f32 v[98:99], v[98:99], s[22:23] op_sel:[1,0] op_sel_hi:[0,0]
	v_fma_f32 v98, -v99, v99, v98
	v_max_f32_e32 v98, 0, v98
	v_add_f32_e32 v98, 0x3727c5ac, v98
	v_mul_f32_e32 v102, 0x4b800000, v98
	v_cmp_gt_f32_e32 vcc, s55, v98
	v_sub_f32_e32 v83, v83, v99
	v_sub_f32_e32 v82, v82, v99
	v_cndmask_b32_e32 v98, v98, v102, vcc
	v_rsq_f32_e32 v98, v98
	v_sub_f32_e32 v85, v85, v99
	v_sub_f32_e32 v84, v84, v99
	v_sub_f32_e32 v95, v95, v99
	v_mul_f32_e32 v102, 0x45800000, v98
	v_cndmask_b32_e32 v98, v98, v102, vcc
	v_pk_mul_f32 v[84:85], v[84:85], v[98:99] op_sel_hi:[1,0]
	v_pk_mul_f32 v[82:83], v[82:83], v[98:99] op_sel_hi:[1,0]
	v_pk_fma_f32 v[84:85], v[88:89], v[84:85], v[92:93]
	v_pk_fma_f32 v[82:83], v[86:87], v[82:83], v[90:91]
	v_pk_fma_f32 v[78:79], v[84:85], s[24:25], v[78:79] op_sel_hi:[1,0,1]
	v_pk_fma_f32 v[76:77], v[82:83], s[24:25], v[76:77] op_sel_hi:[1,0,1]
	global_store_dwordx4 v[100:101], v[76:79], off
	global_load_dwordx4 v[82:85], v[146:147], off
	global_load_dwordx4 v[86:89], v[148:149], off
	global_load_dwordx4 v[90:93], v[100:101], off offset:512
	v_sub_f32_e32 v94, v94, v99
	v_sub_f32_e32 v97, v97, v99
	v_sub_f32_e32 v96, v96, v99
	v_pk_mul_f32 v[96:97], v[96:97], v[98:99] op_sel_hi:[1,0]
	v_pk_mul_f32 v[94:95], v[94:95], v[98:99] op_sel_hi:[1,0]
	s_waitcnt vmcnt(1)
	v_pk_fma_f32 v[84:85], v[84:85], v[96:97], v[88:89]
	v_pk_fma_f32 v[82:83], v[82:83], v[94:95], v[86:87]
	v_pk_fma_f32 v[74:75], v[84:85], s[24:25], v[74:75] op_sel_hi:[1,0,1]
	v_pk_fma_f32 v[72:73], v[82:83], s[24:25], v[72:73] op_sel_hi:[1,0,1]
	global_store_dwordx4 v[100:101], v[72:75], off offset:16
	global_load_dwordx4 v[82:85], v[124:125], off
	global_load_dwordx4 v[86:89], v[126:127], off
	global_load_dwordx4 v[94:97], v[100:101], off offset:528
	s_waitcnt vmcnt(4)
	v_sub_f32_e32 v91, v91, v99
	v_sub_f32_e32 v90, v90, v99
	v_sub_f32_e32 v93, v93, v99
	v_sub_f32_e32 v92, v92, v99
	v_pk_mul_f32 v[92:93], v[98:99], v[92:93] op_sel_hi:[0,1]
	v_pk_mul_f32 v[90:91], v[98:99], v[90:91] op_sel_hi:[0,1]
	s_waitcnt vmcnt(1)
	v_pk_fma_f32 v[82:83], v[82:83], v[90:91], v[86:87]
	v_pk_fma_f32 v[84:85], v[84:85], v[92:93], v[88:89]
	v_pk_fma_f32 v[68:69], v[82:83], s[24:25], v[68:69] op_sel_hi:[1,0,1]
	v_pk_fma_f32 v[70:71], v[84:85], s[24:25], v[70:71] op_sel_hi:[1,0,1]
	global_store_dwordx4 v[100:101], v[68:71], off offset:512
	global_load_dwordx4 v[82:85], v[120:121], off
	global_load_dwordx4 v[86:89], v[122:123], off
	s_waitcnt vmcnt(3)
	v_sub_f32_e32 v90, v94, v99
	v_add_f32_e32 v94, v76, v77
	v_mul_f32_e32 v77, v77, v77
	v_fmac_f32_e32 v77, v76, v76
	v_add_f32_e32 v94, v78, v94
	v_fmac_f32_e32 v77, v78, v78
	v_add_f32_e32 v78, v72, v73
	v_mul_f32_e32 v73, v73, v73
	v_fmac_f32_e32 v73, v72, v72
	v_add_f32_e32 v78, v74, v78
	v_fmac_f32_e32 v73, v74, v74
	v_add_f32_e32 v74, v68, v69
	v_mul_f32_e32 v69, v69, v69
	v_add_f32_e32 v76, v79, v94
	v_fmac_f32_e32 v69, v68, v68
	v_sub_f32_e32 v91, v95, v99
	v_add_f32_e32 v76, 0, v76
	v_fmac_f32_e32 v77, v79, v79
	v_add_f32_e32 v72, v75, v78
	v_fmac_f32_e32 v73, v75, v75
	v_add_f32_e32 v74, v70, v74
	v_fmac_f32_e32 v69, v70, v70
	v_pk_mul_f32 v[90:91], v[98:99], v[90:91] op_sel_hi:[0,1]
	v_add_f32_e32 v72, v72, v76
	v_add_f32_e32 v73, v77, v73
	v_add_f32_e32 v68, v71, v74
	v_fmac_f32_e32 v69, v71, v71
	v_sub_f32_e32 v93, v97, v99
	v_sub_f32_e32 v92, v96, v99
	v_add_f32_e32 v72, v72, v68
	v_add_f32_e32 v73, v73, v69
	v_pk_mul_f32 v[92:93], v[98:99], v[92:93] op_sel_hi:[0,1]
	s_waitcnt vmcnt(0)
	v_pk_fma_f32 v[68:69], v[82:83], v[90:91], v[86:87]
	s_nop 0
	v_pk_fma_f32 v[68:69], v[68:69], s[24:25], v[64:65] op_sel_hi:[1,0,1]
	v_pk_fma_f32 v[70:71], v[84:85], v[92:93], v[88:89]
	v_mul_f32_e32 v65, v69, v69
	v_pk_fma_f32 v[70:71], v[70:71], s[24:25], v[66:67] op_sel_hi:[1,0,1]
	v_add_f32_e32 v64, v68, v69
	v_fmac_f32_e32 v65, v68, v68
	v_add_f32_e32 v64, v70, v64
	v_fmac_f32_e32 v65, v70, v70
	v_add_f32_e32 v64, v71, v64
	v_fmac_f32_e32 v65, v71, v71
	v_add_f32_e32 v64, v72, v64
	v_add_f32_e32 v65, v73, v65
	ds_bpermute_b32 v66, v116, v64
	ds_bpermute_b32 v67, v116, v65
	global_store_dwordx4 v[100:101], v[68:71], off offset:528
	s_waitcnt lgkmcnt(1)
	v_add_f32_e32 v64, v64, v66
	s_waitcnt lgkmcnt(0)
	v_add_f32_e32 v65, v65, v67
	ds_bpermute_b32 v66, v114, v64
	ds_bpermute_b32 v67, v114, v65
	s_mov_b32 s100, -1
	s_mov_b32 s101, 0
	s_mov_b32 s98, 0xffff0000
	s_mov_b32 s99, 0
	s_and_saveexec_b64 s[28:29], s[100:101]
	s_cbranch_execz .LBB0_2853
	v_lshl_add_u64 v[68:69], s[10:11], 0, v[80:81]
	s_waitcnt lgkmcnt(1)
	v_add_f32_e32 v64, v64, v66
	s_waitcnt lgkmcnt(0)
	v_add_f32_e32 v65, v65, v67
	v_cndmask_b32_e64 v64, v64, v65, s[98:99]
	v_cndmask_b32_e64 v65, 0, 4, s[98:99]
	v_or_b32_e32 v68, v68, v65
	flat_atomic_add_f32 v[68:69], v64
; DEVI unsigned pk2(float lo, float hi) { unsigned r; asm("v_cvt_pk_bf16_f32 %0, %1, %2" : "=v"(r) : "v"(lo), "v"(hi)); return r; }
;     DEVI void operator()(const f32x4 (&acc)[2][2][4][2], const pg8::Unit& u, int wr, int wc, int fr, int fq) const {
;     ...
;                 const int row = row0 + ai * 128 + m * 16; float mu, rs; row_stats(stin, row, mu, rs);
;                 float sum = 0.f, sq = 0.f;
; #pragma unroll
;                 for (int bj = 0; bj < 2; ++bj) {
;                     f32x4 z[2];
; #pragma unroll
;                     for (int n = 0; n < 2; ++n) {
;                         const int col = colb + bj * 128 + 4 * n;
;                         f32x4 xv = *(const f32x4*)(zsrc + (size_t)row * DM + col);
;                         if (stin) { const f32x4 gv = *(const f32x4*)(gin + col), bv = *(const f32x4*)(bin + col); xv = (xv - mu) * rs * gv + bv; }
;                         f32x4 zz = ALPHA * xv + acc[ai][bj][m][n];
;                         if (bias) zz += *(const f32x4*)(bias + col);
;                         *(f32x4*)(zdst + (size_t)row * DM + col) = zz;
;                         sum += zz[0] + zz[1] + zz[2] + zz[3]; sq += zz[0] * zz[0] + zz[1] * zz[1] + zz[2] * zz[2] + zz[3] * zz[3];
;                         z[n] = zz;
;                     }
;                     u32x4 o; o.x = pk2(z[0][0], z[0][1]); o.y = pk2(z[0][2], z[0][3]); o.z = pk2(z[1][0], z[1][1]); o.w = pk2(z[1][2], z[1][3]);
;                     if (zb) *(u32x4*)(zb + (size_t)row * DM + colb + bj * 128) = o;
;                 }
;                 sum += __shfl_xor(sum, 16); sq += __shfl_xor(sq, 16);
;                 sum += __shfl_xor(sum, 32); sq += __shfl_xor(sq, 32);
;                 if (fq == 0) { atomicAdd(stout + 2 * (size_t)row, sum); atomicAdd(stout + 2 * (size_t)row + 1, sq); }
.LBB0_2853:
	s_or_b64 exec, exec, s[28:29]
	s_waitcnt lgkmcnt(0)
	v_add_u32_e32 v66, 0x80, v154
	v_ashrrev_i32_e32 v67, 31, v66
	v_lshlrev_b64 v[64:65], 3, v[66:67]
	v_lshl_add_u64 v[68:69], s[12:13], 0, v[64:65]
	flat_load_dwordx2 v[82:83], v[68:69]
	v_lshlrev_b64 v[66:67], 12, v[66:67]
	v_lshl_add_u64 v[66:67], s[46:47], 0, v[66:67]
	v_lshl_add_u64 v[84:85], v[144:145], 2, v[66:67]
	global_load_dwordx4 v[66:69], v[84:85], off
	global_load_dwordx4 v[70:73], v[150:151], off
	global_load_dwordx4 v[74:77], v[152:153], off
	global_load_dwordx4 v[78:81], v[84:85], off offset:16
	s_waitcnt vmcnt(0) lgkmcnt(0)
	v_pk_mul_f32 v[82:83], v[82:83], s[22:23] op_sel:[1,0] op_sel_hi:[0,0]
	v_fma_f32 v82, -v83, v83, v82
	v_max_f32_e32 v82, 0, v82
	v_add_f32_e32 v82, 0x3727c5ac, v82
	v_mul_f32_e32 v86, 0x4b800000, v82
	v_cmp_gt_f32_e32 vcc, s55, v82
	v_sub_f32_e32 v67, v67, v83
	v_sub_f32_e32 v66, v66, v83
	v_cndmask_b32_e32 v82, v82, v86, vcc
	v_rsq_f32_e32 v82, v82
	v_sub_f32_e32 v69, v69, v83
	v_sub_f32_e32 v68, v68, v83
	v_sub_f32_e32 v79, v79, v83
	v_mul_f32_e32 v86, 0x45800000, v82
	v_cndmask_b32_e32 v82, v82, v86, vcc
	v_pk_mul_f32 v[68:69], v[68:69], v[82:83] op_sel_hi:[1,0]
	v_pk_mul_f32 v[66:67], v[66:67], v[82:83] op_sel_hi:[1,0]
	v_pk_fma_f32 v[68:69], v[72:73], v[68:69], v[76:77]
	v_pk_fma_f32 v[66:67], v[70:71], v[66:67], v[74:75]
	v_pk_fma_f32 v[62:63], v[68:69], s[24:25], v[62:63] op_sel_hi:[1,0,1]
	v_pk_fma_f32 v[60:61], v[66:67], s[24:25], v[60:61] op_sel_hi:[1,0,1]
	global_store_dwordx4 v[84:85], v[60:63], off
	global_load_dwordx4 v[66:69], v[146:147], off
	global_load_dwordx4 v[70:73], v[148:149], off
	global_load_dwordx4 v[74:77], v[84:85], off offset:512
	v_sub_f32_e32 v78, v78, v83
	v_sub_f32_e32 v81, v81, v83
	v_sub_f32_e32 v80, v80, v83
	v_pk_mul_f32 v[80:81], v[80:81], v[82:83] op_sel_hi:[1,0]
	v_pk_mul_f32 v[78:79], v[78:79], v[82:83] op_sel_hi:[1,0]
	s_waitcnt vmcnt(1)
	v_pk_fma_f32 v[68:69], v[68:69], v[80:81], v[72:73]
	v_pk_fma_f32 v[66:67], v[66:67], v[78:79], v[70:71]
	v_pk_fma_f32 v[58:59], v[68:69], s[24:25], v[58:59] op_sel_hi:[1,0,1]
	v_pk_fma_f32 v[56:57], v[66:67], s[24:25], v[56:57] op_sel_hi:[1,0,1]
	global_store_dwordx4 v[84:85], v[56:59], off offset:16
	global_load_dwordx4 v[66:69], v[124:125], off
	global_load_dwordx4 v[70:73], v[126:127], off
	global_load_dwordx4 v[78:81], v[84:85], off offset:528
	s_waitcnt vmcnt(4)
	v_sub_f32_e32 v75, v75, v83
	v_sub_f32_e32 v74, v74, v83
	v_sub_f32_e32 v77, v77, v83
	v_sub_f32_e32 v76, v76, v83
	v_pk_mul_f32 v[76:77], v[82:83], v[76:77] op_sel_hi:[0,1]
	v_pk_mul_f32 v[74:75], v[82:83], v[74:75] op_sel_hi:[0,1]
	s_waitcnt vmcnt(1)
	v_pk_fma_f32 v[66:67], v[66:67], v[74:75], v[70:71]
	v_pk_fma_f32 v[68:69], v[68:69], v[76:77], v[72:73]
	v_pk_fma_f32 v[52:53], v[66:67], s[24:25], v[52:53] op_sel_hi:[1,0,1]
	v_pk_fma_f32 v[54:55], v[68:69], s[24:25], v[54:55] op_sel_hi:[1,0,1]
	global_store_dwordx4 v[84:85], v[52:55], off offset:512
	global_load_dwordx4 v[66:69], v[120:121], off
	global_load_dwordx4 v[70:73], v[122:123], off
	s_waitcnt vmcnt(3)
	v_sub_f32_e32 v74, v78, v83
	v_add_f32_e32 v78, v60, v61
	v_mul_f32_e32 v61, v61, v61
	v_fmac_f32_e32 v61, v60, v60
	v_add_f32_e32 v78, v62, v78
	v_fmac_f32_e32 v61, v62, v62
	v_add_f32_e32 v62, v56, v57
	v_mul_f32_e32 v57, v57, v57
	v_fmac_f32_e32 v57, v56, v56
	v_add_f32_e32 v62, v58, v62
	v_fmac_f32_e32 v57, v58, v58
	v_add_f32_e32 v58, v52, v53
	v_mul_f32_e32 v53, v53, v53
	v_add_f32_e32 v60, v63, v78
	v_fmac_f32_e32 v53, v52, v52
	v_sub_f32_e32 v75, v79, v83
	v_add_f32_e32 v60, 0, v60
	v_fmac_f32_e32 v61, v63, v63
	v_add_f32_e32 v56, v59, v62
	v_fmac_f32_e32 v57, v59, v59
	v_add_f32_e32 v58, v54, v58
	v_fmac_f32_e32 v53, v54, v54
	v_pk_mul_f32 v[74:75], v[82:83], v[74:75] op_sel_hi:[0,1]
	v_add_f32_e32 v56, v56, v60
	v_add_f32_e32 v57, v61, v57
	v_add_f32_e32 v52, v55, v58
	v_fmac_f32_e32 v53, v55, v55
	v_sub_f32_e32 v77, v81, v83
	v_sub_f32_e32 v76, v80, v83
	v_add_f32_e32 v56, v56, v52
	v_add_f32_e32 v57, v57, v53
	v_pk_mul_f32 v[76:77], v[82:83], v[76:77] op_sel_hi:[0,1]
	s_waitcnt vmcnt(0)
	v_pk_fma_f32 v[52:53], v[66:67], v[74:75], v[70:71]
	s_nop 0
	v_pk_fma_f32 v[52:53], v[52:53], s[24:25], v[48:49] op_sel_hi:[1,0,1]
	v_pk_fma_f32 v[54:55], v[68:69], v[76:77], v[72:73]
	v_mul_f32_e32 v49, v53, v53
	v_pk_fma_f32 v[54:55], v[54:55], s[24:25], v[50:51] op_sel_hi:[1,0,1]
	v_add_f32_e32 v48, v52, v53
	v_fmac_f32_e32 v49, v52, v52
	v_add_f32_e32 v48, v54, v48
	v_fmac_f32_e32 v49, v54, v54
	v_add_f32_e32 v48, v55, v48
	v_fmac_f32_e32 v49, v55, v55
	v_add_f32_e32 v48, v56, v48
	v_add_f32_e32 v49, v57, v49
	ds_bpermute_b32 v50, v116, v48
	ds_bpermute_b32 v51, v116, v49
	global_store_dwordx4 v[84:85], v[52:55], off offset:528
	s_waitcnt lgkmcnt(1)
	v_add_f32_e32 v48, v48, v50
	s_waitcnt lgkmcnt(0)
	v_add_f32_e32 v49, v49, v51
	ds_bpermute_b32 v50, v114, v48
	ds_bpermute_b32 v51, v114, v49
	s_mov_b32 s100, -1
	s_mov_b32 s101, 0
	s_mov_b32 s98, 0xffff0000
	s_mov_b32 s99, 0
	s_and_saveexec_b64 s[28:29], s[100:101]
	s_cbranch_execz .LBB0_2855
	v_lshl_add_u64 v[52:53], s[10:11], 0, v[64:65]
	s_waitcnt lgkmcnt(1)
	v_add_f32_e32 v48, v48, v50
	s_waitcnt lgkmcnt(0)
	v_add_f32_e32 v49, v49, v51
	v_cndmask_b32_e64 v48, v48, v49, s[98:99]
	v_cndmask_b32_e64 v49, 0, 4, s[98:99]
	v_or_b32_e32 v52, v52, v49
	flat_atomic_add_f32 v[52:53], v48
; DEVI unsigned pk2(float lo, float hi) { unsigned r; asm("v_cvt_pk_bf16_f32 %0, %1, %2" : "=v"(r) : "v"(lo), "v"(hi)); return r; }
;     DEVI void operator()(const f32x4 (&acc)[2][2][4][2], const pg8::Unit& u, int wr, int wc, int fr, int fq) const {
;     ...
;                 const int row = row0 + ai * 128 + m * 16; float mu, rs; row_stats(stin, row, mu, rs);
;                 float sum = 0.f, sq = 0.f;
; #pragma unroll
;                 for (int bj = 0; bj < 2; ++bj) {
;                     f32x4 z[2];
; #pragma unroll
;                     for (int n = 0; n < 2; ++n) {
;                         const int col = colb + bj * 128 + 4 * n;
;                         f32x4 xv = *(const f32x4*)(zsrc + (size_t)row * DM + col);
;                         if (stin) { const f32x4 gv = *(const f32x4*)(gin + col), bv = *(const f32x4*)(bin + col); xv = (xv - mu) * rs * gv + bv; }
;                         f32x4 zz = ALPHA * xv + acc[ai][bj][m][n];
;                         if (bias) zz += *(const f32x4*)(bias + col);
;                         *(f32x4*)(zdst + (size_t)row * DM + col) = zz;
;                         sum += zz[0] + zz[1] + zz[2] + zz[3]; sq += zz[0] * zz[0] + zz[1] * zz[1] + zz[2] * zz[2] + zz[3] * zz[3];
;                         z[n] = zz;
;                     }
;                     u32x4 o; o.x = pk2(z[0][0], z[0][1]); o.y = pk2(z[0][2], z[0][3]); o.z = pk2(z[1][0], z[1][1]); o.w = pk2(z[1][2], z[1][3]);
;                     if (zb) *(u32x4*)(zb + (size_t)row * DM + colb + bj * 128) = o;
;                 }
;                 sum += __shfl_xor(sum, 16); sq += __shfl_xor(sq, 16);
;                 sum += __shfl_xor(sum, 32); sq += __shfl_xor(sq, 32);
;                 if (fq == 0) { atomicAdd(stout + 2 * (size_t)row, sum); atomicAdd(stout + 2 * (size_t)row + 1, sq); }
.LBB0_2855:
	s_or_b64 exec, exec, s[28:29]
	s_waitcnt lgkmcnt(0)
	v_add_u32_e32 v50, 0x90, v154
	v_ashrrev_i32_e32 v51, 31, v50
	v_lshlrev_b64 v[48:49], 3, v[50:51]
	v_lshl_add_u64 v[52:53], s[12:13], 0, v[48:49]
	flat_load_dwordx2 v[66:67], v[52:53]
	v_lshlrev_b64 v[50:51], 12, v[50:51]
	v_lshl_add_u64 v[50:51], s[46:47], 0, v[50:51]
	v_lshl_add_u64 v[68:69], v[144:145], 2, v[50:51]
	global_load_dwordx4 v[50:53], v[68:69], off
	global_load_dwordx4 v[54:57], v[150:151], off
	global_load_dwordx4 v[58:61], v[152:153], off
	global_load_dwordx4 v[62:65], v[68:69], off offset:16
	s_waitcnt vmcnt(0) lgkmcnt(0)
	v_pk_mul_f32 v[66:67], v[66:67], s[22:23] op_sel:[1,0] op_sel_hi:[0,0]
	v_fma_f32 v66, -v67, v67, v66
	v_max_f32_e32 v66, 0, v66
	v_add_f32_e32 v66, 0x3727c5ac, v66
	v_mul_f32_e32 v70, 0x4b800000, v66
	v_cmp_gt_f32_e32 vcc, s55, v66
	v_sub_f32_e32 v51, v51, v67
	v_sub_f32_e32 v50, v50, v67
	v_cndmask_b32_e32 v66, v66, v70, vcc
	v_rsq_f32_e32 v66, v66
	v_sub_f32_e32 v53, v53, v67
	v_sub_f32_e32 v52, v52, v67
	v_sub_f32_e32 v63, v63, v67
	v_mul_f32_e32 v70, 0x45800000, v66
	v_cndmask_b32_e32 v66, v66, v70, vcc
	v_pk_mul_f32 v[52:53], v[52:53], v[66:67] op_sel_hi:[1,0]
	v_pk_mul_f32 v[50:51], v[50:51], v[66:67] op_sel_hi:[1,0]
	v_pk_fma_f32 v[52:53], v[56:57], v[52:53], v[60:61]
	v_pk_fma_f32 v[50:51], v[54:55], v[50:51], v[58:59]
	v_pk_fma_f32 v[46:47], v[52:53], s[24:25], v[46:47] op_sel_hi:[1,0,1]
	v_pk_fma_f32 v[44:45], v[50:51], s[24:25], v[44:45] op_sel_hi:[1,0,1]
	global_store_dwordx4 v[68:69], v[44:47], off
	global_load_dwordx4 v[50:53], v[146:147], off
	global_load_dwordx4 v[54:57], v[148:149], off
	global_load_dwordx4 v[58:61], v[68:69], off offset:512
	v_sub_f32_e32 v62, v62, v67
	v_sub_f32_e32 v65, v65, v67
	v_sub_f32_e32 v64, v64, v67
	v_pk_mul_f32 v[64:65], v[64:65], v[66:67] op_sel_hi:[1,0]
	v_pk_mul_f32 v[62:63], v[62:63], v[66:67] op_sel_hi:[1,0]
	s_waitcnt vmcnt(1)
	v_pk_fma_f32 v[52:53], v[52:53], v[64:65], v[56:57]
	v_pk_fma_f32 v[50:51], v[50:51], v[62:63], v[54:55]
	v_pk_fma_f32 v[42:43], v[52:53], s[24:25], v[42:43] op_sel_hi:[1,0,1]
	v_pk_fma_f32 v[40:41], v[50:51], s[24:25], v[40:41] op_sel_hi:[1,0,1]
	global_store_dwordx4 v[68:69], v[40:43], off offset:16
	global_load_dwordx4 v[50:53], v[124:125], off
	global_load_dwordx4 v[54:57], v[126:127], off
	global_load_dwordx4 v[62:65], v[68:69], off offset:528
	s_waitcnt vmcnt(4)
	v_sub_f32_e32 v59, v59, v67
	v_sub_f32_e32 v58, v58, v67
	v_sub_f32_e32 v61, v61, v67
	v_sub_f32_e32 v60, v60, v67
	v_pk_mul_f32 v[60:61], v[66:67], v[60:61] op_sel_hi:[0,1]
	v_pk_mul_f32 v[58:59], v[66:67], v[58:59] op_sel_hi:[0,1]
	s_waitcnt vmcnt(1)
	v_pk_fma_f32 v[50:51], v[50:51], v[58:59], v[54:55]
	v_pk_fma_f32 v[52:53], v[52:53], v[60:61], v[56:57]
	v_pk_fma_f32 v[36:37], v[50:51], s[24:25], v[36:37] op_sel_hi:[1,0,1]
	v_pk_fma_f32 v[38:39], v[52:53], s[24:25], v[38:39] op_sel_hi:[1,0,1]
	global_store_dwordx4 v[68:69], v[36:39], off offset:512
	global_load_dwordx4 v[50:53], v[120:121], off
	global_load_dwordx4 v[54:57], v[122:123], off
	s_waitcnt vmcnt(3)
	v_sub_f32_e32 v58, v62, v67
	v_add_f32_e32 v62, v44, v45
	v_mul_f32_e32 v45, v45, v45
	v_fmac_f32_e32 v45, v44, v44
	v_add_f32_e32 v62, v46, v62
	v_fmac_f32_e32 v45, v46, v46
	v_add_f32_e32 v46, v40, v41
	v_mul_f32_e32 v41, v41, v41
	v_fmac_f32_e32 v41, v40, v40
	v_add_f32_e32 v46, v42, v46
	v_fmac_f32_e32 v41, v42, v42
	v_add_f32_e32 v42, v36, v37
	v_mul_f32_e32 v37, v37, v37
	v_add_f32_e32 v44, v47, v62
	v_fmac_f32_e32 v37, v36, v36
	v_sub_f32_e32 v59, v63, v67
	v_add_f32_e32 v44, 0, v44
	v_fmac_f32_e32 v45, v47, v47
	v_add_f32_e32 v40, v43, v46
	v_fmac_f32_e32 v41, v43, v43
	v_add_f32_e32 v42, v38, v42
	v_fmac_f32_e32 v37, v38, v38
	v_pk_mul_f32 v[58:59], v[66:67], v[58:59] op_sel_hi:[0,1]
	v_add_f32_e32 v40, v40, v44
	v_add_f32_e32 v41, v45, v41
	v_add_f32_e32 v36, v39, v42
	v_fmac_f32_e32 v37, v39, v39
	v_sub_f32_e32 v61, v65, v67
	v_sub_f32_e32 v60, v64, v67
	v_add_f32_e32 v40, v40, v36
	v_add_f32_e32 v41, v41, v37
	v_pk_mul_f32 v[60:61], v[66:67], v[60:61] op_sel_hi:[0,1]
	s_waitcnt vmcnt(0)
	v_pk_fma_f32 v[36:37], v[50:51], v[58:59], v[54:55]
	s_nop 0
	v_pk_fma_f32 v[36:37], v[36:37], s[24:25], v[32:33] op_sel_hi:[1,0,1]
	v_pk_fma_f32 v[38:39], v[52:53], v[60:61], v[56:57]
	v_mul_f32_e32 v33, v37, v37
	v_pk_fma_f32 v[38:39], v[38:39], s[24:25], v[34:35] op_sel_hi:[1,0,1]
	v_add_f32_e32 v32, v36, v37
	v_fmac_f32_e32 v33, v36, v36
	v_add_f32_e32 v32, v38, v32
	v_fmac_f32_e32 v33, v38, v38
	v_add_f32_e32 v32, v39, v32
	v_fmac_f32_e32 v33, v39, v39
	v_add_f32_e32 v32, v40, v32
	v_add_f32_e32 v33, v41, v33
	ds_bpermute_b32 v34, v116, v32
	ds_bpermute_b32 v35, v116, v33
	global_store_dwordx4 v[68:69], v[36:39], off offset:528
	s_waitcnt lgkmcnt(1)
	v_add_f32_e32 v32, v32, v34
	s_waitcnt lgkmcnt(0)
	v_add_f32_e32 v33, v33, v35
	ds_bpermute_b32 v34, v114, v32
	ds_bpermute_b32 v35, v114, v33
	s_mov_b32 s100, -1
	s_mov_b32 s101, 0
	s_mov_b32 s98, 0xffff0000
	s_mov_b32 s99, 0
	s_and_saveexec_b64 s[28:29], s[100:101]
	s_cbranch_execz .LBB0_2857
	v_lshl_add_u64 v[36:37], s[10:11], 0, v[48:49]
	s_waitcnt lgkmcnt(1)
	v_add_f32_e32 v32, v32, v34
	s_waitcnt lgkmcnt(0)
	v_add_f32_e32 v33, v33, v35
	v_cndmask_b32_e64 v32, v32, v33, s[98:99]
	v_cndmask_b32_e64 v33, 0, 4, s[98:99]
	v_or_b32_e32 v36, v36, v33
	flat_atomic_add_f32 v[36:37], v32
; DEVI unsigned pk2(float lo, float hi) { unsigned r; asm("v_cvt_pk_bf16_f32 %0, %1, %2" : "=v"(r) : "v"(lo), "v"(hi)); return r; }
;     DEVI void operator()(const f32x4 (&acc)[2][2][4][2], const pg8::Unit& u, int wr, int wc, int fr, int fq) const {
;     ...
;                 const int row = row0 + ai * 128 + m * 16; float mu, rs; row_stats(stin, row, mu, rs);
;                 float sum = 0.f, sq = 0.f;
; #pragma unroll
;                 for (int bj = 0; bj < 2; ++bj) {
;                     f32x4 z[2];
; #pragma unroll
;                     for (int n = 0; n < 2; ++n) {
;                         const int col = colb + bj * 128 + 4 * n;
;                         f32x4 xv = *(const f32x4*)(zsrc + (size_t)row * DM + col);
;                         if (stin) { const f32x4 gv = *(const f32x4*)(gin + col), bv = *(const f32x4*)(bin + col); xv = (xv - mu) * rs * gv + bv; }
;                         f32x4 zz = ALPHA * xv + acc[ai][bj][m][n];
;                         if (bias) zz += *(const f32x4*)(bias + col);
;                         *(f32x4*)(zdst + (size_t)row * DM + col) = zz;
;                         sum += zz[0] + zz[1] + zz[2] + zz[3]; sq += zz[0] * zz[0] + zz[1] * zz[1] + zz[2] * zz[2] + zz[3] * zz[3];
;                         z[n] = zz;
;                     }
;                     u32x4 o; o.x = pk2(z[0][0], z[0][1]); o.y = pk2(z[0][2], z[0][3]); o.z = pk2(z[1][0], z[1][1]); o.w = pk2(z[1][2], z[1][3]);
;                     if (zb) *(u32x4*)(zb + (size_t)row * DM + colb + bj * 128) = o;
;                 }
;                 sum += __shfl_xor(sum, 16); sq += __shfl_xor(sq, 16);
;                 sum += __shfl_xor(sum, 32); sq += __shfl_xor(sq, 32);
;                 if (fq == 0) { atomicAdd(stout + 2 * (size_t)row, sum); atomicAdd(stout + 2 * (size_t)row + 1, sq); }
.LBB0_2857:
	s_or_b64 exec, exec, s[28:29]
	s_waitcnt lgkmcnt(0)
	v_add_u32_e32 v34, 0xa0, v154
	v_ashrrev_i32_e32 v35, 31, v34
	v_lshlrev_b64 v[32:33], 3, v[34:35]
	v_lshl_add_u64 v[36:37], s[12:13], 0, v[32:33]
	flat_load_dwordx2 v[50:51], v[36:37]
	v_lshlrev_b64 v[34:35], 12, v[34:35]
	v_lshl_add_u64 v[34:35], s[46:47], 0, v[34:35]
	v_lshl_add_u64 v[52:53], v[144:145], 2, v[34:35]
	global_load_dwordx4 v[34:37], v[52:53], off
	global_load_dwordx4 v[38:41], v[150:151], off
	global_load_dwordx4 v[42:45], v[152:153], off
	global_load_dwordx4 v[46:49], v[52:53], off offset:16
	s_waitcnt vmcnt(0) lgkmcnt(0)
	v_pk_mul_f32 v[50:51], v[50:51], s[22:23] op_sel:[1,0] op_sel_hi:[0,0]
	v_fma_f32 v50, -v51, v51, v50
	v_max_f32_e32 v50, 0, v50
	v_add_f32_e32 v50, 0x3727c5ac, v50
	v_mul_f32_e32 v54, 0x4b800000, v50
	v_cmp_gt_f32_e32 vcc, s55, v50
	v_sub_f32_e32 v35, v35, v51
	v_sub_f32_e32 v34, v34, v51
	v_cndmask_b32_e32 v50, v50, v54, vcc
	v_rsq_f32_e32 v50, v50
	v_sub_f32_e32 v37, v37, v51
	v_sub_f32_e32 v36, v36, v51
	v_sub_f32_e32 v47, v47, v51
	v_mul_f32_e32 v54, 0x45800000, v50
	v_cndmask_b32_e32 v50, v50, v54, vcc
	v_pk_mul_f32 v[36:37], v[36:37], v[50:51] op_sel_hi:[1,0]
	v_pk_mul_f32 v[34:35], v[34:35], v[50:51] op_sel_hi:[1,0]
	v_pk_fma_f32 v[36:37], v[40:41], v[36:37], v[44:45]
	v_pk_fma_f32 v[34:35], v[38:39], v[34:35], v[42:43]
	v_pk_fma_f32 v[30:31], v[36:37], s[24:25], v[30:31] op_sel_hi:[1,0,1]
	v_pk_fma_f32 v[28:29], v[34:35], s[24:25], v[28:29] op_sel_hi:[1,0,1]
	global_store_dwordx4 v[52:53], v[28:31], off
	global_load_dwordx4 v[34:37], v[146:147], off
	global_load_dwordx4 v[38:41], v[148:149], off
	global_load_dwordx4 v[42:45], v[52:53], off offset:512
	v_sub_f32_e32 v46, v46, v51
	v_sub_f32_e32 v49, v49, v51
	v_sub_f32_e32 v48, v48, v51
	v_pk_mul_f32 v[48:49], v[48:49], v[50:51] op_sel_hi:[1,0]
	v_pk_mul_f32 v[46:47], v[46:47], v[50:51] op_sel_hi:[1,0]
	s_waitcnt vmcnt(1)
	v_pk_fma_f32 v[36:37], v[36:37], v[48:49], v[40:41]
	v_pk_fma_f32 v[34:35], v[34:35], v[46:47], v[38:39]
	v_pk_fma_f32 v[26:27], v[36:37], s[24:25], v[26:27] op_sel_hi:[1,0,1]
	v_pk_fma_f32 v[24:25], v[34:35], s[24:25], v[24:25] op_sel_hi:[1,0,1]
	global_store_dwordx4 v[52:53], v[24:27], off offset:16
	global_load_dwordx4 v[34:37], v[124:125], off
	global_load_dwordx4 v[38:41], v[126:127], off
	global_load_dwordx4 v[46:49], v[52:53], off offset:528
	s_waitcnt vmcnt(4)
	v_sub_f32_e32 v43, v43, v51
	v_sub_f32_e32 v42, v42, v51
	v_sub_f32_e32 v45, v45, v51
	v_sub_f32_e32 v44, v44, v51
	v_pk_mul_f32 v[44:45], v[50:51], v[44:45] op_sel_hi:[0,1]
	v_pk_mul_f32 v[42:43], v[50:51], v[42:43] op_sel_hi:[0,1]
	s_waitcnt vmcnt(1)
	v_pk_fma_f32 v[34:35], v[34:35], v[42:43], v[38:39]
	v_pk_fma_f32 v[36:37], v[36:37], v[44:45], v[40:41]
	v_pk_fma_f32 v[20:21], v[34:35], s[24:25], v[20:21] op_sel_hi:[1,0,1]
	v_pk_fma_f32 v[22:23], v[36:37], s[24:25], v[22:23] op_sel_hi:[1,0,1]
	global_store_dwordx4 v[52:53], v[20:23], off offset:512
	global_load_dwordx4 v[34:37], v[120:121], off
	global_load_dwordx4 v[38:41], v[122:123], off
	s_waitcnt vmcnt(3)
	v_sub_f32_e32 v42, v46, v51
	v_add_f32_e32 v46, v28, v29
	v_mul_f32_e32 v29, v29, v29
	v_fmac_f32_e32 v29, v28, v28
	v_add_f32_e32 v46, v30, v46
	v_fmac_f32_e32 v29, v30, v30
	v_add_f32_e32 v30, v24, v25
	v_mul_f32_e32 v25, v25, v25
	v_fmac_f32_e32 v25, v24, v24
	v_add_f32_e32 v30, v26, v30
	v_fmac_f32_e32 v25, v26, v26
	v_add_f32_e32 v26, v20, v21
	v_mul_f32_e32 v21, v21, v21
	v_add_f32_e32 v28, v31, v46
	v_fmac_f32_e32 v21, v20, v20
	v_sub_f32_e32 v43, v47, v51
	v_add_f32_e32 v28, 0, v28
	v_fmac_f32_e32 v29, v31, v31
	v_add_f32_e32 v24, v27, v30
	v_fmac_f32_e32 v25, v27, v27
	v_add_f32_e32 v26, v22, v26
	v_fmac_f32_e32 v21, v22, v22
	v_pk_mul_f32 v[42:43], v[50:51], v[42:43] op_sel_hi:[0,1]
	v_add_f32_e32 v24, v24, v28
	v_add_f32_e32 v25, v29, v25
	v_add_f32_e32 v20, v23, v26
	v_fmac_f32_e32 v21, v23, v23
	v_sub_f32_e32 v45, v49, v51
	v_sub_f32_e32 v44, v48, v51
	v_add_f32_e32 v24, v24, v20
	v_add_f32_e32 v25, v25, v21
	v_pk_mul_f32 v[44:45], v[50:51], v[44:45] op_sel_hi:[0,1]
	s_waitcnt vmcnt(0)
	v_pk_fma_f32 v[20:21], v[34:35], v[42:43], v[38:39]
	s_nop 0
	v_pk_fma_f32 v[20:21], v[20:21], s[24:25], v[16:17] op_sel_hi:[1,0,1]
	v_pk_fma_f32 v[22:23], v[36:37], v[44:45], v[40:41]
	v_mul_f32_e32 v17, v21, v21
	v_pk_fma_f32 v[22:23], v[22:23], s[24:25], v[18:19] op_sel_hi:[1,0,1]
	v_add_f32_e32 v16, v20, v21
	v_fmac_f32_e32 v17, v20, v20
	v_add_f32_e32 v16, v22, v16
	v_fmac_f32_e32 v17, v22, v22
	v_add_f32_e32 v16, v23, v16
	v_fmac_f32_e32 v17, v23, v23
	v_add_f32_e32 v16, v24, v16
	v_add_f32_e32 v17, v25, v17
	ds_bpermute_b32 v18, v116, v16
	ds_bpermute_b32 v19, v116, v17
	global_store_dwordx4 v[52:53], v[20:23], off offset:528
	s_waitcnt lgkmcnt(1)
	v_add_f32_e32 v16, v16, v18
	s_waitcnt lgkmcnt(0)
	v_add_f32_e32 v17, v17, v19
	ds_bpermute_b32 v18, v114, v16
	ds_bpermute_b32 v19, v114, v17
	s_mov_b32 s100, -1
	s_mov_b32 s101, 0
	s_mov_b32 s98, 0xffff0000
	s_mov_b32 s99, 0
	s_and_saveexec_b64 s[28:29], s[100:101]
	s_cbranch_execz .LBB0_2859
	v_lshl_add_u64 v[20:21], s[10:11], 0, v[32:33]
	s_waitcnt lgkmcnt(1)
	v_add_f32_e32 v16, v16, v18
	s_waitcnt lgkmcnt(0)
	v_add_f32_e32 v17, v17, v19
	v_cndmask_b32_e64 v16, v16, v17, s[98:99]
	v_cndmask_b32_e64 v17, 0, 4, s[98:99]
	v_or_b32_e32 v20, v20, v17
	flat_atomic_add_f32 v[20:21], v16
; DEVI unsigned pk2(float lo, float hi) { unsigned r; asm("v_cvt_pk_bf16_f32 %0, %1, %2" : "=v"(r) : "v"(lo), "v"(hi)); return r; }
;     DEVI void operator()(const f32x4 (&acc)[2][2][4][2], const pg8::Unit& u, int wr, int wc, int fr, int fq) const {
;     ...
;                 const int row = row0 + ai * 128 + m * 16; float mu, rs; row_stats(stin, row, mu, rs);
;                 float sum = 0.f, sq = 0.f;
; #pragma unroll
;                 for (int bj = 0; bj < 2; ++bj) {
;                     f32x4 z[2];
; #pragma unroll
;                     for (int n = 0; n < 2; ++n) {
;                         const int col = colb + bj * 128 + 4 * n;
;                         f32x4 xv = *(const f32x4*)(zsrc + (size_t)row * DM + col);
;                         if (stin) { const f32x4 gv = *(const f32x4*)(gin + col), bv = *(const f32x4*)(bin + col); xv = (xv - mu) * rs * gv + bv; }
;                         f32x4 zz = ALPHA * xv + acc[ai][bj][m][n];
;                         if (bias) zz += *(const f32x4*)(bias + col);
;                         *(f32x4*)(zdst + (size_t)row * DM + col) = zz;
;                         sum += zz[0] + zz[1] + zz[2] + zz[3]; sq += zz[0] * zz[0] + zz[1] * zz[1] + zz[2] * zz[2] + zz[3] * zz[3];
;                         z[n] = zz;
;                     }
;                     u32x4 o; o.x = pk2(z[0][0], z[0][1]); o.y = pk2(z[0][2], z[0][3]); o.z = pk2(z[1][0], z[1][1]); o.w = pk2(z[1][2], z[1][3]);
;                     if (zb) *(u32x4*)(zb + (size_t)row * DM + colb + bj * 128) = o;
;                 }
;                 sum += __shfl_xor(sum, 16); sq += __shfl_xor(sq, 16);
;                 sum += __shfl_xor(sum, 32); sq += __shfl_xor(sq, 32);
;                 if (fq == 0) { atomicAdd(stout + 2 * (size_t)row, sum); atomicAdd(stout + 2 * (size_t)row + 1, sq); }
.LBB0_2859:
	s_or_b64 exec, exec, s[28:29]
	s_waitcnt lgkmcnt(0)
	v_add_u32_e32 v18, 0xb0, v154
	v_ashrrev_i32_e32 v19, 31, v18
	v_lshlrev_b64 v[16:17], 3, v[18:19]
	v_lshl_add_u64 v[20:21], s[12:13], 0, v[16:17]
	flat_load_dwordx2 v[34:35], v[20:21]
	v_lshlrev_b64 v[18:19], 12, v[18:19]
	v_lshl_add_u64 v[18:19], s[46:47], 0, v[18:19]
	v_lshl_add_u64 v[36:37], v[144:145], 2, v[18:19]
	global_load_dwordx4 v[18:21], v[36:37], off
	global_load_dwordx4 v[22:25], v[150:151], off
	global_load_dwordx4 v[26:29], v[152:153], off
	global_load_dwordx4 v[30:33], v[36:37], off offset:16
	s_waitcnt vmcnt(0) lgkmcnt(0)
	v_pk_mul_f32 v[34:35], v[34:35], s[22:23] op_sel:[1,0] op_sel_hi:[0,0]
	v_fma_f32 v34, -v35, v35, v34
	v_max_f32_e32 v34, 0, v34
	v_add_f32_e32 v34, 0x3727c5ac, v34
	v_mul_f32_e32 v38, 0x4b800000, v34
	v_cmp_gt_f32_e32 vcc, s55, v34
	v_sub_f32_e32 v19, v19, v35
	v_sub_f32_e32 v18, v18, v35
	v_cndmask_b32_e32 v34, v34, v38, vcc
	v_rsq_f32_e32 v34, v34
	v_sub_f32_e32 v21, v21, v35
	v_sub_f32_e32 v20, v20, v35
	v_sub_f32_e32 v31, v31, v35
	v_mul_f32_e32 v38, 0x45800000, v34
	v_cndmask_b32_e32 v34, v34, v38, vcc
	v_pk_mul_f32 v[20:21], v[20:21], v[34:35] op_sel_hi:[1,0]
	v_pk_mul_f32 v[18:19], v[18:19], v[34:35] op_sel_hi:[1,0]
	v_pk_fma_f32 v[20:21], v[24:25], v[20:21], v[28:29]
	v_pk_fma_f32 v[18:19], v[22:23], v[18:19], v[26:27]
	v_pk_fma_f32 v[14:15], v[20:21], s[24:25], v[14:15] op_sel_hi:[1,0,1]
	v_pk_fma_f32 v[12:13], v[18:19], s[24:25], v[12:13] op_sel_hi:[1,0,1]
	global_store_dwordx4 v[36:37], v[12:15], off
	global_load_dwordx4 v[18:21], v[146:147], off
	global_load_dwordx4 v[22:25], v[148:149], off
	global_load_dwordx4 v[26:29], v[36:37], off offset:512
	v_sub_f32_e32 v30, v30, v35
	v_sub_f32_e32 v33, v33, v35
	v_sub_f32_e32 v32, v32, v35
	v_pk_mul_f32 v[32:33], v[32:33], v[34:35] op_sel_hi:[1,0]
	v_pk_mul_f32 v[30:31], v[30:31], v[34:35] op_sel_hi:[1,0]
	s_waitcnt vmcnt(1)
	v_pk_fma_f32 v[20:21], v[20:21], v[32:33], v[24:25]
	v_pk_fma_f32 v[18:19], v[18:19], v[30:31], v[22:23]
	v_pk_fma_f32 v[10:11], v[20:21], s[24:25], v[10:11] op_sel_hi:[1,0,1]
	v_pk_fma_f32 v[8:9], v[18:19], s[24:25], v[8:9] op_sel_hi:[1,0,1]
	global_store_dwordx4 v[36:37], v[8:11], off offset:16
	global_load_dwordx4 v[18:21], v[124:125], off
	global_load_dwordx4 v[22:25], v[126:127], off
	global_load_dwordx4 v[30:33], v[36:37], off offset:528
	s_waitcnt vmcnt(4)
	v_sub_f32_e32 v27, v27, v35
	v_sub_f32_e32 v26, v26, v35
	v_sub_f32_e32 v29, v29, v35
	v_sub_f32_e32 v28, v28, v35
	v_pk_mul_f32 v[28:29], v[34:35], v[28:29] op_sel_hi:[0,1]
	v_pk_mul_f32 v[26:27], v[34:35], v[26:27] op_sel_hi:[0,1]
	s_waitcnt vmcnt(1)
	v_pk_fma_f32 v[18:19], v[18:19], v[26:27], v[22:23]
	v_pk_fma_f32 v[20:21], v[20:21], v[28:29], v[24:25]
	v_pk_fma_f32 v[4:5], v[18:19], s[24:25], v[4:5] op_sel_hi:[1,0,1]
	v_pk_fma_f32 v[6:7], v[20:21], s[24:25], v[6:7] op_sel_hi:[1,0,1]
	global_store_dwordx4 v[36:37], v[4:7], off offset:512
	global_load_dwordx4 v[18:21], v[120:121], off
	global_load_dwordx4 v[22:25], v[122:123], off
	s_waitcnt vmcnt(3)
	v_sub_f32_e32 v26, v30, v35
	v_add_f32_e32 v30, v12, v13
	v_mul_f32_e32 v13, v13, v13
	v_fmac_f32_e32 v13, v12, v12
	v_add_f32_e32 v30, v14, v30
	v_fmac_f32_e32 v13, v14, v14
	v_add_f32_e32 v14, v8, v9
	v_mul_f32_e32 v9, v9, v9
	v_fmac_f32_e32 v9, v8, v8
	v_add_f32_e32 v14, v10, v14
	v_fmac_f32_e32 v9, v10, v10
	v_add_f32_e32 v10, v4, v5
	v_mul_f32_e32 v5, v5, v5
	v_add_f32_e32 v12, v15, v30
	v_fmac_f32_e32 v5, v4, v4
	v_sub_f32_e32 v27, v31, v35
	v_add_f32_e32 v12, 0, v12
	v_fmac_f32_e32 v13, v15, v15
	v_add_f32_e32 v8, v11, v14
	v_fmac_f32_e32 v9, v11, v11
	v_add_f32_e32 v10, v6, v10
	v_fmac_f32_e32 v5, v6, v6
	v_pk_mul_f32 v[26:27], v[34:35], v[26:27] op_sel_hi:[0,1]
	v_add_f32_e32 v8, v8, v12
	v_add_f32_e32 v9, v13, v9
	v_add_f32_e32 v4, v7, v10
	v_fmac_f32_e32 v5, v7, v7
	v_sub_f32_e32 v29, v33, v35
	v_sub_f32_e32 v28, v32, v35
	v_add_f32_e32 v8, v8, v4
	v_add_f32_e32 v9, v9, v5
	v_pk_mul_f32 v[28:29], v[34:35], v[28:29] op_sel_hi:[0,1]
	s_waitcnt vmcnt(0)
	v_pk_fma_f32 v[4:5], v[18:19], v[26:27], v[22:23]
	s_nop 0
	v_pk_fma_f32 v[4:5], v[4:5], s[24:25], v[0:1] op_sel_hi:[1,0,1]
	v_pk_fma_f32 v[6:7], v[20:21], v[28:29], v[24:25]
	v_mul_f32_e32 v1, v5, v5
	v_pk_fma_f32 v[6:7], v[6:7], s[24:25], v[2:3] op_sel_hi:[1,0,1]
	v_add_f32_e32 v0, v4, v5
	v_fmac_f32_e32 v1, v4, v4
	v_add_f32_e32 v0, v6, v0
	v_fmac_f32_e32 v1, v6, v6
	v_add_f32_e32 v0, v7, v0
	v_fmac_f32_e32 v1, v7, v7
	v_add_f32_e32 v0, v8, v0
	v_add_f32_e32 v1, v9, v1
	ds_bpermute_b32 v2, v116, v0
	ds_bpermute_b32 v3, v116, v1
	global_store_dwordx4 v[36:37], v[4:7], off offset:528
	s_waitcnt lgkmcnt(1)
	v_add_f32_e32 v0, v0, v2
	s_waitcnt lgkmcnt(0)
	v_add_f32_e32 v1, v1, v3
	ds_bpermute_b32 v2, v114, v0
	ds_bpermute_b32 v3, v114, v1
	s_mov_b32 s100, -1
	s_mov_b32 s101, 0
	s_mov_b32 s98, 0xffff0000
	s_mov_b32 s99, 0
	s_and_saveexec_b64 s[28:29], s[100:101]
	s_cbranch_execz .LBB0_2861
	v_lshl_add_u64 v[4:5], s[10:11], 0, v[16:17]
	s_waitcnt lgkmcnt(1)
	v_add_f32_e32 v0, v0, v2
	s_waitcnt lgkmcnt(0)
	v_add_f32_e32 v1, v1, v3
	v_cndmask_b32_e64 v0, v0, v1, s[98:99]
	v_cndmask_b32_e64 v1, 0, 4, s[98:99]
	v_or_b32_e32 v4, v4, v1
	flat_atomic_add_f32 v[4:5], v0
